# v17 plus: no s_setprio 0/1 flip between the two 16-MFMA blocks of a compute segment
# baseline (speedup 1.0000x reference)
.Lpk354_peel:
	ds_read_b128 v[166:169], v139
	ds_read_b128 v[170:173], v139 offset:1024
	ds_read_b128 v[178:181], v139 offset:2048
	ds_read_b128 v[182:185], v139 offset:3072
	ds_read_b128 v[186:189], v164
	ds_read_b128 v[190:193], v164 offset:1024
	ds_read_b128 v[194:197], v164 offset:2048
	ds_read_b128 v[198:201], v164 offset:3072
	s_add_u32 s2, s26, 0xfffc0080
	s_addc_u32 s3, s27, -1
	s_cmp_eq_u32 s52, 12
	s_cselect_b32 s3, s11, s3
	s_cselect_b32 s2, s13, s2
	s_cselect_b32 s29, s44, s47
	s_cselect_b32 s28, s45, s46
	v_lshl_add_u64 v[148:149], s[26:27], 0, v[142:143]
	s_add_i32 m0, s34, 0xc000
	ds_read_b128 v[202:205], v165
	ds_read_b128 v[206:209], v165 offset:1024
	ds_read_b128 v[210:213], v165 offset:2048
	ds_read_b128 v[214:217], v165 offset:3072
	ds_read_b128 v[218:221], v165 offset:4096
	ds_read_b128 v[222:225], v165 offset:5120
	ds_read_b128 v[226:229], v165 offset:6144
	ds_read_b128 v[230:233], v165 offset:7168
	global_load_lds_dwordx4 v[148:149], off
	v_lshl_add_u64 v[148:149], s[26:27], 0, v[144:145]
	s_add_i32 m0, s34, 0xe000
	s_nop 0
	global_load_lds_dwordx4 v[148:149], off
	s_waitcnt vmcnt(8)
	s_waitcnt lgkmcnt(0)
	s_setprio 1
	s_barrier
	v_mfma_f32_16x16x32_bf16 v[126:129], v[166:169], v[202:205], 0
	v_mfma_f32_16x16x32_bf16 v[122:125], v[178:181], v[202:205], 0
	v_mfma_f32_16x16x32_bf16 v[110:113], v[166:169], v[210:213], 0
	v_mfma_f32_16x16x32_bf16 v[106:109], v[178:181], v[210:213], 0
	v_mfma_f32_16x16x32_bf16 v[94:97], v[166:169], v[218:221], 0
	v_mfma_f32_16x16x32_bf16 v[90:93], v[178:181], v[218:221], 0
	v_mfma_f32_16x16x32_bf16 v[78:81], v[166:169], v[226:229], 0
	v_mfma_f32_16x16x32_bf16 v[74:77], v[178:181], v[226:229], 0
	v_mfma_f32_16x16x32_bf16 v[126:129], v[170:173], v[206:209], v[126:129]
	v_mfma_f32_16x16x32_bf16 v[122:125], v[182:185], v[206:209], v[122:125]
	v_mfma_f32_16x16x32_bf16 v[110:113], v[170:173], v[214:217], v[110:113]
	v_mfma_f32_16x16x32_bf16 v[106:109], v[182:185], v[214:217], v[106:109]
	v_mfma_f32_16x16x32_bf16 v[94:97], v[170:173], v[222:225], v[94:97]
	v_mfma_f32_16x16x32_bf16 v[90:93], v[182:185], v[222:225], v[90:93]
	v_mfma_f32_16x16x32_bf16 v[78:81], v[170:173], v[230:233], v[78:81]
	v_mfma_f32_16x16x32_bf16 v[74:77], v[182:185], v[230:233], v[74:77]
	v_mfma_f32_16x16x32_bf16 v[118:121], v[186:189], v[202:205], 0
	v_mfma_f32_16x16x32_bf16 v[114:117], v[194:197], v[202:205], 0
	v_mfma_f32_16x16x32_bf16 v[102:105], v[186:189], v[210:213], 0
	v_mfma_f32_16x16x32_bf16 v[98:101], v[194:197], v[210:213], 0
	v_mfma_f32_16x16x32_bf16 v[86:89], v[186:189], v[218:221], 0
	v_mfma_f32_16x16x32_bf16 v[82:85], v[194:197], v[218:221], 0
	v_mfma_f32_16x16x32_bf16 v[70:73], v[186:189], v[226:229], 0
	v_mfma_f32_16x16x32_bf16 v[66:69], v[194:197], v[226:229], 0
	v_mfma_f32_16x16x32_bf16 v[118:121], v[190:193], v[206:209], v[118:121]
	v_mfma_f32_16x16x32_bf16 v[114:117], v[198:201], v[206:209], v[114:117]
	v_mfma_f32_16x16x32_bf16 v[102:105], v[190:193], v[214:217], v[102:105]
	v_mfma_f32_16x16x32_bf16 v[98:101], v[198:201], v[214:217], v[98:101]
	v_mfma_f32_16x16x32_bf16 v[86:89], v[190:193], v[222:225], v[86:89]
	v_mfma_f32_16x16x32_bf16 v[82:85], v[198:201], v[222:225], v[82:85]
	v_mfma_f32_16x16x32_bf16 v[70:73], v[190:193], v[230:233], v[70:73]
	v_mfma_f32_16x16x32_bf16 v[66:69], v[198:201], v[230:233], v[66:69]
	s_barrier
	s_setprio 0
	s_add_i32 s53, s41, s30
	v_lshl_add_u64 v[148:149], s[28:29], 0, v[132:133]
	s_mov_b32 m0, s53
	ds_read_b128 v[202:205], v165 offset:16384
	ds_read_b128 v[206:209], v165 offset:17408
	ds_read_b128 v[210:213], v165 offset:18432
	ds_read_b128 v[214:217], v165 offset:19456
	ds_read_b128 v[218:221], v165 offset:20480
	ds_read_b128 v[222:225], v165 offset:21504
	ds_read_b128 v[226:229], v165 offset:22528
	ds_read_b128 v[230:233], v165 offset:23552
	global_load_lds_dwordx4 v[148:149], off
	s_add_i32 m0, s53, 0x2000
	s_add_u32 s54, s28, 0x40000
	v_lshl_add_u64 v[174:175], s[28:29], 0, v[136:137]
	s_addc_u32 s55, s29, 0
	s_add_i32 s53, s42, s30
	global_load_lds_dwordx4 v[174:175], off
	v_lshl_add_u64 v[234:235], s[54:55], 0, v[132:133]
	s_mov_b32 m0, s53
	v_lshl_add_u64 v[236:237], s[2:3], 0, v[134:135]
	global_load_lds_dwordx4 v[234:235], off
	v_lshl_add_u64 v[234:235], s[54:55], 0, v[136:137]
	s_add_i32 m0, s53, 0x2000
	s_nop 0
	global_load_lds_dwordx4 v[234:235], off
	v_lshl_add_u64 v[234:235], s[2:3], 0, v[130:131]
	s_mov_b32 m0, s34
	s_nop 0
	global_load_lds_dwordx4 v[234:235], off
	s_mov_b32 m0, s25
	s_nop 0
	global_load_lds_dwordx4 v[236:237], off
	s_waitcnt vmcnt(8)
	s_waitcnt lgkmcnt(0)
	s_setprio 1
	s_barrier
	v_mfma_f32_16x16x32_bf16 v[62:65], v[166:169], v[202:205], 0
	v_mfma_f32_16x16x32_bf16 v[58:61], v[178:181], v[202:205], 0
	v_mfma_f32_16x16x32_bf16 v[46:49], v[166:169], v[210:213], 0
	v_mfma_f32_16x16x32_bf16 v[42:45], v[178:181], v[210:213], 0
	v_mfma_f32_16x16x32_bf16 v[30:33], v[166:169], v[218:221], 0
	v_mfma_f32_16x16x32_bf16 v[26:29], v[178:181], v[218:221], 0
	v_mfma_f32_16x16x32_bf16 v[14:17], v[166:169], v[226:229], 0
	v_mfma_f32_16x16x32_bf16 v[10:13], v[178:181], v[226:229], 0
	v_mfma_f32_16x16x32_bf16 v[62:65], v[170:173], v[206:209], v[62:65]
	v_mfma_f32_16x16x32_bf16 v[58:61], v[182:185], v[206:209], v[58:61]
	v_mfma_f32_16x16x32_bf16 v[46:49], v[170:173], v[214:217], v[46:49]
	v_mfma_f32_16x16x32_bf16 v[42:45], v[182:185], v[214:217], v[42:45]
	v_mfma_f32_16x16x32_bf16 v[30:33], v[170:173], v[222:225], v[30:33]
	v_mfma_f32_16x16x32_bf16 v[26:29], v[182:185], v[222:225], v[26:29]
	v_mfma_f32_16x16x32_bf16 v[14:17], v[170:173], v[230:233], v[14:17]
	v_mfma_f32_16x16x32_bf16 v[10:13], v[182:185], v[230:233], v[10:13]
	v_mfma_f32_16x16x32_bf16 v[54:57], v[186:189], v[202:205], 0
	v_mfma_f32_16x16x32_bf16 v[50:53], v[194:197], v[202:205], 0
	v_mfma_f32_16x16x32_bf16 v[38:41], v[186:189], v[210:213], 0
	v_mfma_f32_16x16x32_bf16 v[34:37], v[194:197], v[210:213], 0
	v_mfma_f32_16x16x32_bf16 v[22:25], v[186:189], v[218:221], 0
	v_mfma_f32_16x16x32_bf16 v[18:21], v[194:197], v[218:221], 0
	v_mfma_f32_16x16x32_bf16 v[6:9], v[186:189], v[226:229], 0
	v_mfma_f32_16x16x32_bf16 v[2:5], v[194:197], v[226:229], 0
	v_mfma_f32_16x16x32_bf16 v[54:57], v[190:193], v[206:209], v[54:57]
	v_mfma_f32_16x16x32_bf16 v[50:53], v[198:201], v[206:209], v[50:53]
	v_mfma_f32_16x16x32_bf16 v[38:41], v[190:193], v[214:217], v[38:41]
	v_mfma_f32_16x16x32_bf16 v[34:37], v[198:201], v[214:217], v[34:37]
	v_mfma_f32_16x16x32_bf16 v[22:25], v[190:193], v[222:225], v[22:25]
	v_mfma_f32_16x16x32_bf16 v[18:21], v[198:201], v[222:225], v[18:21]
	v_mfma_f32_16x16x32_bf16 v[6:9], v[190:193], v[230:233], v[6:9]
	v_mfma_f32_16x16x32_bf16 v[2:5], v[198:201], v[230:233], v[2:5]
	s_barrier
	s_setprio 0
	s_add_i32 s53, 0, 0x18000
	v_add_u32_e32 v176, s53, v163
	s_add_i32 s54, 0, 0x1c000
	ds_read_b128 v[166:169], v176
	ds_read_b128 v[170:173], v176 offset:1024
	ds_read_b128 v[178:181], v176 offset:2048
	ds_read_b128 v[182:185], v176 offset:3072
	v_add_u32_e32 v176, s54, v163
	ds_read_b128 v[186:189], v176
	ds_read_b128 v[190:193], v176 offset:1024
	ds_read_b128 v[194:197], v176 offset:2048
	ds_read_b128 v[198:201], v176 offset:3072
	s_add_u32 s2, s2, 0x40000
	s_addc_u32 s3, s3, 0
	s_mov_b32 m0, s35
	v_lshl_add_u64 v[238:239], s[2:3], 0, v[130:131]
	ds_read_b128 v[202:205], v165 offset:32768
	ds_read_b128 v[206:209], v165 offset:33792
	ds_read_b128 v[210:213], v165 offset:34816
	ds_read_b128 v[214:217], v165 offset:35840
	ds_read_b128 v[218:221], v165 offset:36864
	ds_read_b128 v[222:225], v165 offset:37888
	ds_read_b128 v[226:229], v165 offset:38912
	ds_read_b128 v[230:233], v165 offset:39936
	global_load_lds_dwordx4 v[238:239], off
	v_lshl_add_u64 v[238:239], s[2:3], 0, v[134:135]
	s_mov_b32 m0, s36
	s_nop 0
	global_load_lds_dwordx4 v[238:239], off
	s_waitcnt vmcnt(8)
	s_waitcnt lgkmcnt(0)
	s_setprio 1
	s_barrier
	v_mfma_f32_16x16x32_bf16 v[126:129], v[166:169], v[202:205], v[126:129]
	v_mfma_f32_16x16x32_bf16 v[122:125], v[178:181], v[202:205], v[122:125]
	v_mfma_f32_16x16x32_bf16 v[110:113], v[166:169], v[210:213], v[110:113]
	v_mfma_f32_16x16x32_bf16 v[106:109], v[178:181], v[210:213], v[106:109]
	v_mfma_f32_16x16x32_bf16 v[94:97], v[166:169], v[218:221], v[94:97]
	v_mfma_f32_16x16x32_bf16 v[90:93], v[178:181], v[218:221], v[90:93]
	v_mfma_f32_16x16x32_bf16 v[78:81], v[166:169], v[226:229], v[78:81]
	v_mfma_f32_16x16x32_bf16 v[74:77], v[178:181], v[226:229], v[74:77]
	v_mfma_f32_16x16x32_bf16 v[126:129], v[170:173], v[206:209], v[126:129]
	v_mfma_f32_16x16x32_bf16 v[122:125], v[182:185], v[206:209], v[122:125]
	v_mfma_f32_16x16x32_bf16 v[110:113], v[170:173], v[214:217], v[110:113]
	v_mfma_f32_16x16x32_bf16 v[106:109], v[182:185], v[214:217], v[106:109]
	v_mfma_f32_16x16x32_bf16 v[94:97], v[170:173], v[222:225], v[94:97]
	v_mfma_f32_16x16x32_bf16 v[90:93], v[182:185], v[222:225], v[90:93]
	v_mfma_f32_16x16x32_bf16 v[78:81], v[170:173], v[230:233], v[78:81]
	v_mfma_f32_16x16x32_bf16 v[74:77], v[182:185], v[230:233], v[74:77]
	v_mfma_f32_16x16x32_bf16 v[118:121], v[186:189], v[202:205], v[118:121]
	v_mfma_f32_16x16x32_bf16 v[114:117], v[194:197], v[202:205], v[114:117]
	v_mfma_f32_16x16x32_bf16 v[102:105], v[186:189], v[210:213], v[102:105]
	v_mfma_f32_16x16x32_bf16 v[98:101], v[194:197], v[210:213], v[98:101]
	v_mfma_f32_16x16x32_bf16 v[86:89], v[186:189], v[218:221], v[86:89]
	v_mfma_f32_16x16x32_bf16 v[82:85], v[194:197], v[218:221], v[82:85]
	v_mfma_f32_16x16x32_bf16 v[70:73], v[186:189], v[226:229], v[70:73]
	v_mfma_f32_16x16x32_bf16 v[66:69], v[194:197], v[226:229], v[66:69]
	v_mfma_f32_16x16x32_bf16 v[118:121], v[190:193], v[206:209], v[118:121]
	v_mfma_f32_16x16x32_bf16 v[114:117], v[198:201], v[206:209], v[114:117]
	v_mfma_f32_16x16x32_bf16 v[102:105], v[190:193], v[214:217], v[102:105]
	v_mfma_f32_16x16x32_bf16 v[98:101], v[198:201], v[214:217], v[98:101]
	v_mfma_f32_16x16x32_bf16 v[86:89], v[190:193], v[222:225], v[86:89]
	v_mfma_f32_16x16x32_bf16 v[82:85], v[198:201], v[222:225], v[82:85]
	v_mfma_f32_16x16x32_bf16 v[70:73], v[190:193], v[230:233], v[70:73]
	v_mfma_f32_16x16x32_bf16 v[66:69], v[198:201], v[230:233], v[66:69]
	s_barrier
	s_setprio 0
	s_add_i32 s2, s53, s30
	v_lshl_add_u64 v[148:149], v[148:149], 0, s[6:7]
	s_mov_b32 m0, s2
	ds_read_b128 v[202:205], v165 offset:49152
	ds_read_b128 v[206:209], v165 offset:50176
	ds_read_b128 v[210:213], v165 offset:51200
	ds_read_b128 v[214:217], v165 offset:52224
	ds_read_b128 v[218:221], v165 offset:53248
	ds_read_b128 v[222:225], v165 offset:54272
	ds_read_b128 v[226:229], v165 offset:55296
	ds_read_b128 v[230:233], v165 offset:56320
	global_load_lds_dwordx4 v[148:149], off
	s_add_i32 m0, s2, 0x2000
	s_add_u32 s2, s28, 0x40080
	v_lshl_add_u64 v[148:149], v[174:175], 0, s[6:7]
	s_addc_u32 s3, s29, 0
	s_add_i32 s28, s54, s30
	global_load_lds_dwordx4 v[148:149], off
	v_lshl_add_u64 v[148:149], s[2:3], 0, v[132:133]
	s_mov_b32 m0, s28
	s_nop 0
	global_load_lds_dwordx4 v[148:149], off
	v_lshl_add_u64 v[148:149], s[2:3], 0, v[136:137]
	s_add_i32 m0, s28, 0x2000
	s_nop 0
	global_load_lds_dwordx4 v[148:149], off
	v_lshl_add_u64 v[148:149], v[234:235], 0, s[6:7]
	s_mov_b32 m0, s38
	s_nop 0
	global_load_lds_dwordx4 v[148:149], off
	v_lshl_add_u64 v[148:149], v[236:237], 0, s[6:7]
	s_mov_b32 m0, s39
	s_nop 0
	global_load_lds_dwordx4 v[148:149], off
	s_waitcnt vmcnt(8)
	s_waitcnt lgkmcnt(0)
	s_setprio 1
	s_barrier
	v_mfma_f32_16x16x32_bf16 v[62:65], v[166:169], v[202:205], v[62:65]
	v_mfma_f32_16x16x32_bf16 v[58:61], v[178:181], v[202:205], v[58:61]
	v_mfma_f32_16x16x32_bf16 v[46:49], v[166:169], v[210:213], v[46:49]
	v_mfma_f32_16x16x32_bf16 v[42:45], v[178:181], v[210:213], v[42:45]
	v_mfma_f32_16x16x32_bf16 v[30:33], v[166:169], v[218:221], v[30:33]
	v_mfma_f32_16x16x32_bf16 v[26:29], v[178:181], v[218:221], v[26:29]
	v_mfma_f32_16x16x32_bf16 v[14:17], v[166:169], v[226:229], v[14:17]
	v_mfma_f32_16x16x32_bf16 v[10:13], v[178:181], v[226:229], v[10:13]
	v_mfma_f32_16x16x32_bf16 v[62:65], v[170:173], v[206:209], v[62:65]
	v_mfma_f32_16x16x32_bf16 v[58:61], v[182:185], v[206:209], v[58:61]
	v_mfma_f32_16x16x32_bf16 v[46:49], v[170:173], v[214:217], v[46:49]
	v_mfma_f32_16x16x32_bf16 v[42:45], v[182:185], v[214:217], v[42:45]
	v_mfma_f32_16x16x32_bf16 v[30:33], v[170:173], v[222:225], v[30:33]
	v_mfma_f32_16x16x32_bf16 v[26:29], v[182:185], v[222:225], v[26:29]
	v_mfma_f32_16x16x32_bf16 v[14:17], v[170:173], v[230:233], v[14:17]
	v_mfma_f32_16x16x32_bf16 v[10:13], v[182:185], v[230:233], v[10:13]
	v_mfma_f32_16x16x32_bf16 v[54:57], v[186:189], v[202:205], v[54:57]
	v_mfma_f32_16x16x32_bf16 v[50:53], v[194:197], v[202:205], v[50:53]
	v_mfma_f32_16x16x32_bf16 v[38:41], v[186:189], v[210:213], v[38:41]
	v_mfma_f32_16x16x32_bf16 v[34:37], v[194:197], v[210:213], v[34:37]
	v_mfma_f32_16x16x32_bf16 v[22:25], v[186:189], v[218:221], v[22:25]
	v_mfma_f32_16x16x32_bf16 v[18:21], v[194:197], v[218:221], v[18:21]
	v_mfma_f32_16x16x32_bf16 v[6:9], v[186:189], v[226:229], v[6:9]
	v_mfma_f32_16x16x32_bf16 v[2:5], v[194:197], v[226:229], v[2:5]
	v_mfma_f32_16x16x32_bf16 v[54:57], v[190:193], v[206:209], v[54:57]
	v_mfma_f32_16x16x32_bf16 v[50:53], v[198:201], v[206:209], v[50:53]
	v_mfma_f32_16x16x32_bf16 v[38:41], v[190:193], v[214:217], v[38:41]
	v_mfma_f32_16x16x32_bf16 v[34:37], v[198:201], v[214:217], v[34:37]
	v_mfma_f32_16x16x32_bf16 v[22:25], v[190:193], v[222:225], v[22:25]
	v_mfma_f32_16x16x32_bf16 v[18:21], v[198:201], v[222:225], v[18:21]
	v_mfma_f32_16x16x32_bf16 v[6:9], v[190:193], v[230:233], v[6:9]
	v_mfma_f32_16x16x32_bf16 v[2:5], v[198:201], v[230:233], v[2:5]
	s_barrier
	s_setprio 0
	s_add_i32 s52, s52, 2
	s_add_u32 s26, s26, 0x100
	s_addc_u32 s27, s27, 0
	s_add_u32 s46, s46, 0x100
	s_addc_u32 s47, s47, 0
	s_cmp_gt_u32 s52, 13
	s_cbranch_scc0 .LBB0_354
	s_branch .Lpk354_exit
.LBB0_354:
	ds_read_b128 v[166:169], v139
	ds_read_b128 v[170:173], v139 offset:1024
	ds_read_b128 v[178:181], v139 offset:2048
	ds_read_b128 v[182:185], v139 offset:3072
	ds_read_b128 v[186:189], v164
	ds_read_b128 v[190:193], v164 offset:1024
	ds_read_b128 v[194:197], v164 offset:2048
	ds_read_b128 v[198:201], v164 offset:3072
	s_add_u32 s2, s26, 0xfffc0080
	s_addc_u32 s3, s27, -1
	s_cmp_eq_u32 s52, 12
	s_cselect_b32 s3, s11, s3
	s_cselect_b32 s2, s13, s2
	s_cselect_b32 s29, s44, s47
	s_cselect_b32 s28, s45, s46
	v_lshl_add_u64 v[148:149], s[26:27], 0, v[142:143]
	s_add_i32 m0, s34, 0xc000
	ds_read_b128 v[202:205], v165
	ds_read_b128 v[206:209], v165 offset:1024
	ds_read_b128 v[210:213], v165 offset:2048
	ds_read_b128 v[214:217], v165 offset:3072
	ds_read_b128 v[218:221], v165 offset:4096
	ds_read_b128 v[222:225], v165 offset:5120
	ds_read_b128 v[226:229], v165 offset:6144
	ds_read_b128 v[230:233], v165 offset:7168
	global_load_lds_dwordx4 v[148:149], off
	v_lshl_add_u64 v[148:149], s[26:27], 0, v[144:145]
	s_add_i32 m0, s34, 0xe000
	s_nop 0
	global_load_lds_dwordx4 v[148:149], off
	s_waitcnt vmcnt(8)
	s_waitcnt lgkmcnt(0)
	s_setprio 1
	s_barrier
	v_mfma_f32_16x16x32_bf16 v[126:129], v[166:169], v[202:205], v[126:129]
	v_mfma_f32_16x16x32_bf16 v[122:125], v[178:181], v[202:205], v[122:125]
	v_mfma_f32_16x16x32_bf16 v[110:113], v[166:169], v[210:213], v[110:113]
	v_mfma_f32_16x16x32_bf16 v[106:109], v[178:181], v[210:213], v[106:109]
	v_mfma_f32_16x16x32_bf16 v[94:97], v[166:169], v[218:221], v[94:97]
	v_mfma_f32_16x16x32_bf16 v[90:93], v[178:181], v[218:221], v[90:93]
	v_mfma_f32_16x16x32_bf16 v[78:81], v[166:169], v[226:229], v[78:81]
	v_mfma_f32_16x16x32_bf16 v[74:77], v[178:181], v[226:229], v[74:77]
	v_mfma_f32_16x16x32_bf16 v[126:129], v[170:173], v[206:209], v[126:129]
	v_mfma_f32_16x16x32_bf16 v[122:125], v[182:185], v[206:209], v[122:125]
	v_mfma_f32_16x16x32_bf16 v[110:113], v[170:173], v[214:217], v[110:113]
	v_mfma_f32_16x16x32_bf16 v[106:109], v[182:185], v[214:217], v[106:109]
	v_mfma_f32_16x16x32_bf16 v[94:97], v[170:173], v[222:225], v[94:97]
	v_mfma_f32_16x16x32_bf16 v[90:93], v[182:185], v[222:225], v[90:93]
	v_mfma_f32_16x16x32_bf16 v[78:81], v[170:173], v[230:233], v[78:81]
	v_mfma_f32_16x16x32_bf16 v[74:77], v[182:185], v[230:233], v[74:77]
	v_mfma_f32_16x16x32_bf16 v[118:121], v[186:189], v[202:205], v[118:121]
	v_mfma_f32_16x16x32_bf16 v[114:117], v[194:197], v[202:205], v[114:117]
	v_mfma_f32_16x16x32_bf16 v[102:105], v[186:189], v[210:213], v[102:105]
	v_mfma_f32_16x16x32_bf16 v[98:101], v[194:197], v[210:213], v[98:101]
	v_mfma_f32_16x16x32_bf16 v[86:89], v[186:189], v[218:221], v[86:89]
	v_mfma_f32_16x16x32_bf16 v[82:85], v[194:197], v[218:221], v[82:85]
	v_mfma_f32_16x16x32_bf16 v[70:73], v[186:189], v[226:229], v[70:73]
	v_mfma_f32_16x16x32_bf16 v[66:69], v[194:197], v[226:229], v[66:69]
	v_mfma_f32_16x16x32_bf16 v[118:121], v[190:193], v[206:209], v[118:121]
	v_mfma_f32_16x16x32_bf16 v[114:117], v[198:201], v[206:209], v[114:117]
	v_mfma_f32_16x16x32_bf16 v[102:105], v[190:193], v[214:217], v[102:105]
	v_mfma_f32_16x16x32_bf16 v[98:101], v[198:201], v[214:217], v[98:101]
	v_mfma_f32_16x16x32_bf16 v[86:89], v[190:193], v[222:225], v[86:89]
	v_mfma_f32_16x16x32_bf16 v[82:85], v[198:201], v[222:225], v[82:85]
	v_mfma_f32_16x16x32_bf16 v[70:73], v[190:193], v[230:233], v[70:73]
	v_mfma_f32_16x16x32_bf16 v[66:69], v[198:201], v[230:233], v[66:69]
	s_barrier
	s_setprio 0
	s_add_i32 s53, s41, s30
	v_lshl_add_u64 v[148:149], s[28:29], 0, v[132:133]
	s_mov_b32 m0, s53
	ds_read_b128 v[202:205], v165 offset:16384
	ds_read_b128 v[206:209], v165 offset:17408
	ds_read_b128 v[210:213], v165 offset:18432
	ds_read_b128 v[214:217], v165 offset:19456
	ds_read_b128 v[218:221], v165 offset:20480
	ds_read_b128 v[222:225], v165 offset:21504
	ds_read_b128 v[226:229], v165 offset:22528
	ds_read_b128 v[230:233], v165 offset:23552
	global_load_lds_dwordx4 v[148:149], off
	s_add_i32 m0, s53, 0x2000
	s_add_u32 s54, s28, 0x40000
	v_lshl_add_u64 v[174:175], s[28:29], 0, v[136:137]
	s_addc_u32 s55, s29, 0
	s_add_i32 s53, s42, s30
	global_load_lds_dwordx4 v[174:175], off
	v_lshl_add_u64 v[234:235], s[54:55], 0, v[132:133]
	s_mov_b32 m0, s53
	v_lshl_add_u64 v[236:237], s[2:3], 0, v[134:135]
	global_load_lds_dwordx4 v[234:235], off
	v_lshl_add_u64 v[234:235], s[54:55], 0, v[136:137]
	s_add_i32 m0, s53, 0x2000
	s_nop 0
	global_load_lds_dwordx4 v[234:235], off
	v_lshl_add_u64 v[234:235], s[2:3], 0, v[130:131]
	s_mov_b32 m0, s34
	s_nop 0
	global_load_lds_dwordx4 v[234:235], off
	s_mov_b32 m0, s25
	s_nop 0
	global_load_lds_dwordx4 v[236:237], off
	s_waitcnt vmcnt(8)
	s_waitcnt lgkmcnt(0)
	s_setprio 1
	s_barrier
	v_mfma_f32_16x16x32_bf16 v[62:65], v[166:169], v[202:205], v[62:65]
	v_mfma_f32_16x16x32_bf16 v[58:61], v[178:181], v[202:205], v[58:61]
	v_mfma_f32_16x16x32_bf16 v[46:49], v[166:169], v[210:213], v[46:49]
	v_mfma_f32_16x16x32_bf16 v[42:45], v[178:181], v[210:213], v[42:45]
	v_mfma_f32_16x16x32_bf16 v[30:33], v[166:169], v[218:221], v[30:33]
	v_mfma_f32_16x16x32_bf16 v[26:29], v[178:181], v[218:221], v[26:29]
	v_mfma_f32_16x16x32_bf16 v[14:17], v[166:169], v[226:229], v[14:17]
	v_mfma_f32_16x16x32_bf16 v[10:13], v[178:181], v[226:229], v[10:13]
	v_mfma_f32_16x16x32_bf16 v[62:65], v[170:173], v[206:209], v[62:65]
	v_mfma_f32_16x16x32_bf16 v[58:61], v[182:185], v[206:209], v[58:61]
	v_mfma_f32_16x16x32_bf16 v[46:49], v[170:173], v[214:217], v[46:49]
	v_mfma_f32_16x16x32_bf16 v[42:45], v[182:185], v[214:217], v[42:45]
	v_mfma_f32_16x16x32_bf16 v[30:33], v[170:173], v[222:225], v[30:33]
	v_mfma_f32_16x16x32_bf16 v[26:29], v[182:185], v[222:225], v[26:29]
	v_mfma_f32_16x16x32_bf16 v[14:17], v[170:173], v[230:233], v[14:17]
	v_mfma_f32_16x16x32_bf16 v[10:13], v[182:185], v[230:233], v[10:13]
	v_mfma_f32_16x16x32_bf16 v[54:57], v[186:189], v[202:205], v[54:57]
	v_mfma_f32_16x16x32_bf16 v[50:53], v[194:197], v[202:205], v[50:53]
	v_mfma_f32_16x16x32_bf16 v[38:41], v[186:189], v[210:213], v[38:41]
	v_mfma_f32_16x16x32_bf16 v[34:37], v[194:197], v[210:213], v[34:37]
	v_mfma_f32_16x16x32_bf16 v[22:25], v[186:189], v[218:221], v[22:25]
	v_mfma_f32_16x16x32_bf16 v[18:21], v[194:197], v[218:221], v[18:21]
	v_mfma_f32_16x16x32_bf16 v[6:9], v[186:189], v[226:229], v[6:9]
	v_mfma_f32_16x16x32_bf16 v[2:5], v[194:197], v[226:229], v[2:5]
	v_mfma_f32_16x16x32_bf16 v[54:57], v[190:193], v[206:209], v[54:57]
	v_mfma_f32_16x16x32_bf16 v[50:53], v[198:201], v[206:209], v[50:53]
	v_mfma_f32_16x16x32_bf16 v[38:41], v[190:193], v[214:217], v[38:41]
	v_mfma_f32_16x16x32_bf16 v[34:37], v[198:201], v[214:217], v[34:37]
	v_mfma_f32_16x16x32_bf16 v[22:25], v[190:193], v[222:225], v[22:25]
	v_mfma_f32_16x16x32_bf16 v[18:21], v[198:201], v[222:225], v[18:21]
	v_mfma_f32_16x16x32_bf16 v[6:9], v[190:193], v[230:233], v[6:9]
	v_mfma_f32_16x16x32_bf16 v[2:5], v[198:201], v[230:233], v[2:5]
	s_barrier
	s_setprio 0
	s_add_i32 s53, 0, 0x18000
	v_add_u32_e32 v176, s53, v163
	s_add_i32 s54, 0, 0x1c000
	ds_read_b128 v[166:169], v176
	ds_read_b128 v[170:173], v176 offset:1024
	ds_read_b128 v[178:181], v176 offset:2048
	ds_read_b128 v[182:185], v176 offset:3072
	v_add_u32_e32 v176, s54, v163
	ds_read_b128 v[186:189], v176
	ds_read_b128 v[190:193], v176 offset:1024
	ds_read_b128 v[194:197], v176 offset:2048
	ds_read_b128 v[198:201], v176 offset:3072
	s_add_u32 s2, s2, 0x40000
	s_addc_u32 s3, s3, 0
	s_mov_b32 m0, s35
	v_lshl_add_u64 v[238:239], s[2:3], 0, v[130:131]
	ds_read_b128 v[202:205], v165 offset:32768
	ds_read_b128 v[206:209], v165 offset:33792
	ds_read_b128 v[210:213], v165 offset:34816
	ds_read_b128 v[214:217], v165 offset:35840
	ds_read_b128 v[218:221], v165 offset:36864
	ds_read_b128 v[222:225], v165 offset:37888
	ds_read_b128 v[226:229], v165 offset:38912
	ds_read_b128 v[230:233], v165 offset:39936
	global_load_lds_dwordx4 v[238:239], off
	v_lshl_add_u64 v[238:239], s[2:3], 0, v[134:135]
	s_mov_b32 m0, s36
	s_nop 0
	global_load_lds_dwordx4 v[238:239], off
	s_waitcnt vmcnt(8)
	s_waitcnt lgkmcnt(0)
	s_setprio 1
	s_barrier
	v_mfma_f32_16x16x32_bf16 v[126:129], v[166:169], v[202:205], v[126:129]
	v_mfma_f32_16x16x32_bf16 v[122:125], v[178:181], v[202:205], v[122:125]
	v_mfma_f32_16x16x32_bf16 v[110:113], v[166:169], v[210:213], v[110:113]
	v_mfma_f32_16x16x32_bf16 v[106:109], v[178:181], v[210:213], v[106:109]
	v_mfma_f32_16x16x32_bf16 v[94:97], v[166:169], v[218:221], v[94:97]
	v_mfma_f32_16x16x32_bf16 v[90:93], v[178:181], v[218:221], v[90:93]
	v_mfma_f32_16x16x32_bf16 v[78:81], v[166:169], v[226:229], v[78:81]
	v_mfma_f32_16x16x32_bf16 v[74:77], v[178:181], v[226:229], v[74:77]
	v_mfma_f32_16x16x32_bf16 v[126:129], v[170:173], v[206:209], v[126:129]
	v_mfma_f32_16x16x32_bf16 v[122:125], v[182:185], v[206:209], v[122:125]
	v_mfma_f32_16x16x32_bf16 v[110:113], v[170:173], v[214:217], v[110:113]
	v_mfma_f32_16x16x32_bf16 v[106:109], v[182:185], v[214:217], v[106:109]
	v_mfma_f32_16x16x32_bf16 v[94:97], v[170:173], v[222:225], v[94:97]
	v_mfma_f32_16x16x32_bf16 v[90:93], v[182:185], v[222:225], v[90:93]
	v_mfma_f32_16x16x32_bf16 v[78:81], v[170:173], v[230:233], v[78:81]
	v_mfma_f32_16x16x32_bf16 v[74:77], v[182:185], v[230:233], v[74:77]
	v_mfma_f32_16x16x32_bf16 v[118:121], v[186:189], v[202:205], v[118:121]
	v_mfma_f32_16x16x32_bf16 v[114:117], v[194:197], v[202:205], v[114:117]
	v_mfma_f32_16x16x32_bf16 v[102:105], v[186:189], v[210:213], v[102:105]
	v_mfma_f32_16x16x32_bf16 v[98:101], v[194:197], v[210:213], v[98:101]
	v_mfma_f32_16x16x32_bf16 v[86:89], v[186:189], v[218:221], v[86:89]
	v_mfma_f32_16x16x32_bf16 v[82:85], v[194:197], v[218:221], v[82:85]
	v_mfma_f32_16x16x32_bf16 v[70:73], v[186:189], v[226:229], v[70:73]
	v_mfma_f32_16x16x32_bf16 v[66:69], v[194:197], v[226:229], v[66:69]
	v_mfma_f32_16x16x32_bf16 v[118:121], v[190:193], v[206:209], v[118:121]
	v_mfma_f32_16x16x32_bf16 v[114:117], v[198:201], v[206:209], v[114:117]
	v_mfma_f32_16x16x32_bf16 v[102:105], v[190:193], v[214:217], v[102:105]
	v_mfma_f32_16x16x32_bf16 v[98:101], v[198:201], v[214:217], v[98:101]
	v_mfma_f32_16x16x32_bf16 v[86:89], v[190:193], v[222:225], v[86:89]
	v_mfma_f32_16x16x32_bf16 v[82:85], v[198:201], v[222:225], v[82:85]
	v_mfma_f32_16x16x32_bf16 v[70:73], v[190:193], v[230:233], v[70:73]
	v_mfma_f32_16x16x32_bf16 v[66:69], v[198:201], v[230:233], v[66:69]
	s_barrier
	s_setprio 0
	s_add_i32 s2, s53, s30
	v_lshl_add_u64 v[148:149], v[148:149], 0, s[6:7]
	s_mov_b32 m0, s2
	ds_read_b128 v[202:205], v165 offset:49152
	ds_read_b128 v[206:209], v165 offset:50176
	ds_read_b128 v[210:213], v165 offset:51200
	ds_read_b128 v[214:217], v165 offset:52224
	ds_read_b128 v[218:221], v165 offset:53248
	ds_read_b128 v[222:225], v165 offset:54272
	ds_read_b128 v[226:229], v165 offset:55296
	ds_read_b128 v[230:233], v165 offset:56320
	global_load_lds_dwordx4 v[148:149], off
	s_add_i32 m0, s2, 0x2000
	s_add_u32 s2, s28, 0x40080
	v_lshl_add_u64 v[148:149], v[174:175], 0, s[6:7]
	s_addc_u32 s3, s29, 0
	s_add_i32 s28, s54, s30
	global_load_lds_dwordx4 v[148:149], off
	v_lshl_add_u64 v[148:149], s[2:3], 0, v[132:133]
	s_mov_b32 m0, s28
	s_nop 0
	global_load_lds_dwordx4 v[148:149], off
	v_lshl_add_u64 v[148:149], s[2:3], 0, v[136:137]
	s_add_i32 m0, s28, 0x2000
	s_nop 0
	global_load_lds_dwordx4 v[148:149], off
	v_lshl_add_u64 v[148:149], v[234:235], 0, s[6:7]
	s_mov_b32 m0, s38
	s_nop 0
	global_load_lds_dwordx4 v[148:149], off
	v_lshl_add_u64 v[148:149], v[236:237], 0, s[6:7]
	s_mov_b32 m0, s39
	s_nop 0
	global_load_lds_dwordx4 v[148:149], off
	s_waitcnt vmcnt(8)
	s_waitcnt lgkmcnt(0)
	s_setprio 1
	s_barrier
	v_mfma_f32_16x16x32_bf16 v[62:65], v[166:169], v[202:205], v[62:65]
	v_mfma_f32_16x16x32_bf16 v[58:61], v[178:181], v[202:205], v[58:61]
	v_mfma_f32_16x16x32_bf16 v[46:49], v[166:169], v[210:213], v[46:49]
	v_mfma_f32_16x16x32_bf16 v[42:45], v[178:181], v[210:213], v[42:45]
	v_mfma_f32_16x16x32_bf16 v[30:33], v[166:169], v[218:221], v[30:33]
	v_mfma_f32_16x16x32_bf16 v[26:29], v[178:181], v[218:221], v[26:29]
	v_mfma_f32_16x16x32_bf16 v[14:17], v[166:169], v[226:229], v[14:17]
	v_mfma_f32_16x16x32_bf16 v[10:13], v[178:181], v[226:229], v[10:13]
	v_mfma_f32_16x16x32_bf16 v[62:65], v[170:173], v[206:209], v[62:65]
	v_mfma_f32_16x16x32_bf16 v[58:61], v[182:185], v[206:209], v[58:61]
	v_mfma_f32_16x16x32_bf16 v[46:49], v[170:173], v[214:217], v[46:49]
	v_mfma_f32_16x16x32_bf16 v[42:45], v[182:185], v[214:217], v[42:45]
	v_mfma_f32_16x16x32_bf16 v[30:33], v[170:173], v[222:225], v[30:33]
	v_mfma_f32_16x16x32_bf16 v[26:29], v[182:185], v[222:225], v[26:29]
	v_mfma_f32_16x16x32_bf16 v[14:17], v[170:173], v[230:233], v[14:17]
	v_mfma_f32_16x16x32_bf16 v[10:13], v[182:185], v[230:233], v[10:13]
	v_mfma_f32_16x16x32_bf16 v[54:57], v[186:189], v[202:205], v[54:57]
	v_mfma_f32_16x16x32_bf16 v[50:53], v[194:197], v[202:205], v[50:53]
	v_mfma_f32_16x16x32_bf16 v[38:41], v[186:189], v[210:213], v[38:41]
	v_mfma_f32_16x16x32_bf16 v[34:37], v[194:197], v[210:213], v[34:37]
	v_mfma_f32_16x16x32_bf16 v[22:25], v[186:189], v[218:221], v[22:25]
	v_mfma_f32_16x16x32_bf16 v[18:21], v[194:197], v[218:221], v[18:21]
	v_mfma_f32_16x16x32_bf16 v[6:9], v[186:189], v[226:229], v[6:9]
	v_mfma_f32_16x16x32_bf16 v[2:5], v[194:197], v[226:229], v[2:5]
	v_mfma_f32_16x16x32_bf16 v[54:57], v[190:193], v[206:209], v[54:57]
	v_mfma_f32_16x16x32_bf16 v[50:53], v[198:201], v[206:209], v[50:53]
	v_mfma_f32_16x16x32_bf16 v[38:41], v[190:193], v[214:217], v[38:41]
	v_mfma_f32_16x16x32_bf16 v[34:37], v[198:201], v[214:217], v[34:37]
	v_mfma_f32_16x16x32_bf16 v[22:25], v[190:193], v[222:225], v[22:25]
	v_mfma_f32_16x16x32_bf16 v[18:21], v[198:201], v[222:225], v[18:21]
	v_mfma_f32_16x16x32_bf16 v[6:9], v[190:193], v[230:233], v[6:9]
	v_mfma_f32_16x16x32_bf16 v[2:5], v[198:201], v[230:233], v[2:5]
	s_barrier
	s_setprio 0
	s_add_i32 s52, s52, 2
	s_add_u32 s26, s26, 0x100
	s_addc_u32 s27, s27, 0
	s_add_u32 s46, s46, 0x100
	s_addc_u32 s47, s47, 0
	s_cmp_gt_u32 s52, 13
	s_cbranch_scc0 .LBB0_354

.LBB0_437:
	ds_read_b128 v[160:163], v133
	ds_read_b128 v[164:167], v133 offset:1024
	ds_read_b128 v[168:171], v133 offset:2048
	ds_read_b128 v[172:175], v133 offset:3072
	ds_read_b128 v[178:181], v135
	ds_read_b128 v[182:185], v135 offset:1024
	ds_read_b128 v[186:189], v135 offset:2048
	ds_read_b128 v[190:193], v135 offset:3072
	s_cmp_lg_u32 s8, 0x160000
	s_cselect_b32 s13, s8, 0
	s_cselect_b32 s12, s9, 0
	s_add_u32 s2, s6, s13
	s_addc_u32 s3, s7, s12
	s_add_u32 s14, s0, s13
	s_addc_u32 s15, s1, s12
	s_add_u32 s12, s2, 0x8000
	s_addc_u32 s13, s3, 0
	v_lshl_add_u64 v[226:227], v[148:149], 0, s[8:9]
	s_mov_b32 m0, s27
	v_lshl_add_u64 v[226:227], v[226:227], 0, s[10:11]
	ds_read_b128 v[194:197], v137
	ds_read_b128 v[198:201], v137 offset:1024
	ds_read_b128 v[202:205], v137 offset:2048
	ds_read_b128 v[206:209], v137 offset:3072
	ds_read_b128 v[210:213], v137 offset:4096
	ds_read_b128 v[214:217], v137 offset:5120
	ds_read_b128 v[218:221], v137 offset:6144
	ds_read_b128 v[222:225], v137 offset:7168
	global_load_lds_dwordx4 v[226:227], off
	v_lshl_add_u64 v[226:227], v[150:151], 0, s[8:9]
	v_lshl_add_u64 v[226:227], v[226:227], 0, s[10:11]
	s_mov_b32 m0, s28
	s_nop 0
	global_load_lds_dwordx4 v[226:227], off
	s_waitcnt vmcnt(8)
	s_waitcnt lgkmcnt(0)
	s_setprio 1
	s_barrier
	v_mfma_f32_16x16x32_bf16 v[126:129], v[160:163], v[194:197], v[126:129]
	v_mfma_f32_16x16x32_bf16 v[122:125], v[168:171], v[194:197], v[122:125]
	v_mfma_f32_16x16x32_bf16 v[114:117], v[160:163], v[202:205], v[114:117]
	v_mfma_f32_16x16x32_bf16 v[106:109], v[168:171], v[202:205], v[106:109]
	v_mfma_f32_16x16x32_bf16 v[98:101], v[160:163], v[210:213], v[98:101]
	v_mfma_f32_16x16x32_bf16 v[90:93], v[168:171], v[210:213], v[90:93]
	v_mfma_f32_16x16x32_bf16 v[82:85], v[160:163], v[218:221], v[82:85]
	v_mfma_f32_16x16x32_bf16 v[74:77], v[168:171], v[218:221], v[74:77]
	v_mfma_f32_16x16x32_bf16 v[126:129], v[164:167], v[198:201], v[126:129]
	v_mfma_f32_16x16x32_bf16 v[122:125], v[172:175], v[198:201], v[122:125]
	v_mfma_f32_16x16x32_bf16 v[114:117], v[164:167], v[206:209], v[114:117]
	v_mfma_f32_16x16x32_bf16 v[106:109], v[172:175], v[206:209], v[106:109]
	v_mfma_f32_16x16x32_bf16 v[98:101], v[164:167], v[214:217], v[98:101]
	v_mfma_f32_16x16x32_bf16 v[90:93], v[172:175], v[214:217], v[90:93]
	v_mfma_f32_16x16x32_bf16 v[82:85], v[164:167], v[222:225], v[82:85]
	v_mfma_f32_16x16x32_bf16 v[74:77], v[172:175], v[222:225], v[74:77]
	v_mfma_f32_16x16x32_bf16 v[118:121], v[178:181], v[194:197], v[118:121]
	v_mfma_f32_16x16x32_bf16 v[110:113], v[186:189], v[194:197], v[110:113]
	v_mfma_f32_16x16x32_bf16 v[102:105], v[178:181], v[202:205], v[102:105]
	v_mfma_f32_16x16x32_bf16 v[94:97], v[186:189], v[202:205], v[94:97]
	v_mfma_f32_16x16x32_bf16 v[86:89], v[178:181], v[210:213], v[86:89]
	v_mfma_f32_16x16x32_bf16 v[78:81], v[186:189], v[210:213], v[78:81]
	v_mfma_f32_16x16x32_bf16 v[70:73], v[178:181], v[218:221], v[70:73]
	v_mfma_f32_16x16x32_bf16 v[66:69], v[186:189], v[218:221], v[66:69]
	v_mfma_f32_16x16x32_bf16 v[118:121], v[182:185], v[198:201], v[118:121]
	v_mfma_f32_16x16x32_bf16 v[110:113], v[190:193], v[198:201], v[110:113]
	v_mfma_f32_16x16x32_bf16 v[102:105], v[182:185], v[206:209], v[102:105]
	v_mfma_f32_16x16x32_bf16 v[94:97], v[190:193], v[206:209], v[94:97]
	v_mfma_f32_16x16x32_bf16 v[86:89], v[182:185], v[214:217], v[86:89]
	v_mfma_f32_16x16x32_bf16 v[78:81], v[190:193], v[214:217], v[78:81]
	v_mfma_f32_16x16x32_bf16 v[70:73], v[182:185], v[222:225], v[70:73]
	v_mfma_f32_16x16x32_bf16 v[66:69], v[190:193], v[222:225], v[66:69]
	s_barrier
	s_setprio 0
	s_mov_b32 m0, s29
	v_lshl_add_u64 v[226:227], s[14:15], 0, v[142:143]
	s_add_u32 s40, s14, 0x4000
	ds_read_b128 v[194:197], v137 offset:16384
	ds_read_b128 v[198:201], v137 offset:17408
	ds_read_b128 v[202:205], v137 offset:18432
	ds_read_b128 v[206:209], v137 offset:19456
	ds_read_b128 v[210:213], v137 offset:20480
	ds_read_b128 v[214:217], v137 offset:21504
	ds_read_b128 v[218:221], v137 offset:22528
	ds_read_b128 v[222:225], v137 offset:23552
	global_load_lds_dwordx4 v[226:227], off
	v_lshl_add_u64 v[226:227], s[14:15], 0, v[146:147]
	s_mov_b32 m0, s30
	s_addc_u32 s41, s15, 0
	global_load_lds_dwordx4 v[226:227], off
	v_lshl_add_u64 v[226:227], s[40:41], 0, v[142:143]
	s_mov_b32 m0, s31
	s_nop 0
	global_load_lds_dwordx4 v[226:227], off
	v_lshl_add_u64 v[226:227], s[40:41], 0, v[146:147]
	s_mov_b32 m0, s34
	s_nop 0
	global_load_lds_dwordx4 v[226:227], off
	v_lshl_add_u64 v[226:227], s[2:3], 0, v[140:141]
	s_mov_b32 m0, s19
	s_nop 0
	global_load_lds_dwordx4 v[226:227], off
	v_lshl_add_u64 v[226:227], s[2:3], 0, v[144:145]
	s_mov_b32 m0, s20
	s_nop 0
	global_load_lds_dwordx4 v[226:227], off
	s_waitcnt vmcnt(8)
	s_waitcnt lgkmcnt(0)
	s_setprio 1
	s_barrier
	v_mfma_f32_16x16x32_bf16 v[62:65], v[160:163], v[194:197], v[62:65]
	v_mfma_f32_16x16x32_bf16 v[58:61], v[168:171], v[194:197], v[58:61]
	v_mfma_f32_16x16x32_bf16 v[50:53], v[160:163], v[202:205], v[50:53]
	v_mfma_f32_16x16x32_bf16 v[42:45], v[168:171], v[202:205], v[42:45]
	v_mfma_f32_16x16x32_bf16 v[34:37], v[160:163], v[210:213], v[34:37]
	v_mfma_f32_16x16x32_bf16 v[26:29], v[168:171], v[210:213], v[26:29]
	v_mfma_f32_16x16x32_bf16 v[18:21], v[160:163], v[218:221], v[18:21]
	v_mfma_f32_16x16x32_bf16 v[10:13], v[168:171], v[218:221], v[10:13]
	v_mfma_f32_16x16x32_bf16 v[62:65], v[164:167], v[198:201], v[62:65]
	v_mfma_f32_16x16x32_bf16 v[58:61], v[172:175], v[198:201], v[58:61]
	v_mfma_f32_16x16x32_bf16 v[50:53], v[164:167], v[206:209], v[50:53]
	v_mfma_f32_16x16x32_bf16 v[42:45], v[172:175], v[206:209], v[42:45]
	v_mfma_f32_16x16x32_bf16 v[34:37], v[164:167], v[214:217], v[34:37]
	v_mfma_f32_16x16x32_bf16 v[26:29], v[172:175], v[214:217], v[26:29]
	v_mfma_f32_16x16x32_bf16 v[18:21], v[164:167], v[222:225], v[18:21]
	v_mfma_f32_16x16x32_bf16 v[10:13], v[172:175], v[222:225], v[10:13]
	v_mfma_f32_16x16x32_bf16 v[54:57], v[178:181], v[194:197], v[54:57]
	v_mfma_f32_16x16x32_bf16 v[46:49], v[186:189], v[194:197], v[46:49]
	v_mfma_f32_16x16x32_bf16 v[38:41], v[178:181], v[202:205], v[38:41]
	v_mfma_f32_16x16x32_bf16 v[30:33], v[186:189], v[202:205], v[30:33]
	v_mfma_f32_16x16x32_bf16 v[22:25], v[178:181], v[210:213], v[22:25]
	v_mfma_f32_16x16x32_bf16 v[14:17], v[186:189], v[210:213], v[14:17]
	v_mfma_f32_16x16x32_bf16 v[6:9], v[178:181], v[218:221], v[6:9]
	v_mfma_f32_16x16x32_bf16 v[2:5], v[186:189], v[218:221], v[2:5]
	v_mfma_f32_16x16x32_bf16 v[54:57], v[182:185], v[198:201], v[54:57]
	v_mfma_f32_16x16x32_bf16 v[46:49], v[190:193], v[198:201], v[46:49]
	v_mfma_f32_16x16x32_bf16 v[38:41], v[182:185], v[206:209], v[38:41]
	v_mfma_f32_16x16x32_bf16 v[30:33], v[190:193], v[206:209], v[30:33]
	v_mfma_f32_16x16x32_bf16 v[22:25], v[182:185], v[214:217], v[22:25]
	v_mfma_f32_16x16x32_bf16 v[14:17], v[190:193], v[214:217], v[14:17]
	v_mfma_f32_16x16x32_bf16 v[6:9], v[182:185], v[222:225], v[6:9]
	v_mfma_f32_16x16x32_bf16 v[2:5], v[190:193], v[222:225], v[2:5]
	s_barrier
	s_setprio 0
	ds_read_b128 v[160:163], v139
	ds_read_b128 v[164:167], v139 offset:1024
	ds_read_b128 v[168:171], v139 offset:2048
	ds_read_b128 v[172:175], v139 offset:3072
	ds_read_b128 v[178:181], v159
	ds_read_b128 v[182:185], v159 offset:1024
	ds_read_b128 v[186:189], v159 offset:2048
	ds_read_b128 v[190:193], v159 offset:3072
	s_add_u32 s2, s2, 0x4000
	s_addc_u32 s3, s3, 0
	s_mov_b32 m0, s21
	v_lshl_add_u64 v[226:227], s[2:3], 0, v[140:141]
	ds_read_b128 v[194:197], v137 offset:32768
	ds_read_b128 v[198:201], v137 offset:33792
	ds_read_b128 v[202:205], v137 offset:34816
	ds_read_b128 v[206:209], v137 offset:35840
	ds_read_b128 v[210:213], v137 offset:36864
	ds_read_b128 v[214:217], v137 offset:37888
	ds_read_b128 v[218:221], v137 offset:38912
	ds_read_b128 v[222:225], v137 offset:39936
	global_load_lds_dwordx4 v[226:227], off
	v_lshl_add_u64 v[226:227], s[2:3], 0, v[144:145]
	s_mov_b32 m0, s22
	s_nop 0
	global_load_lds_dwordx4 v[226:227], off
	s_waitcnt vmcnt(8)
	s_waitcnt lgkmcnt(0)
	s_setprio 1
	s_barrier
	v_mfma_f32_16x16x32_bf16 v[126:129], v[160:163], v[194:197], v[126:129]
	v_mfma_f32_16x16x32_bf16 v[122:125], v[168:171], v[194:197], v[122:125]
	v_mfma_f32_16x16x32_bf16 v[114:117], v[160:163], v[202:205], v[114:117]
	v_mfma_f32_16x16x32_bf16 v[106:109], v[168:171], v[202:205], v[106:109]
	v_mfma_f32_16x16x32_bf16 v[98:101], v[160:163], v[210:213], v[98:101]
	v_mfma_f32_16x16x32_bf16 v[90:93], v[168:171], v[210:213], v[90:93]
	v_mfma_f32_16x16x32_bf16 v[82:85], v[160:163], v[218:221], v[82:85]
	v_mfma_f32_16x16x32_bf16 v[74:77], v[168:171], v[218:221], v[74:77]
	v_mfma_f32_16x16x32_bf16 v[126:129], v[164:167], v[198:201], v[126:129]
	v_mfma_f32_16x16x32_bf16 v[122:125], v[172:175], v[198:201], v[122:125]
	v_mfma_f32_16x16x32_bf16 v[114:117], v[164:167], v[206:209], v[114:117]
	v_mfma_f32_16x16x32_bf16 v[106:109], v[172:175], v[206:209], v[106:109]
	v_mfma_f32_16x16x32_bf16 v[98:101], v[164:167], v[214:217], v[98:101]
	v_mfma_f32_16x16x32_bf16 v[90:93], v[172:175], v[214:217], v[90:93]
	v_mfma_f32_16x16x32_bf16 v[82:85], v[164:167], v[222:225], v[82:85]
	v_mfma_f32_16x16x32_bf16 v[74:77], v[172:175], v[222:225], v[74:77]
	v_mfma_f32_16x16x32_bf16 v[118:121], v[178:181], v[194:197], v[118:121]
	v_mfma_f32_16x16x32_bf16 v[110:113], v[186:189], v[194:197], v[110:113]
	v_mfma_f32_16x16x32_bf16 v[102:105], v[178:181], v[202:205], v[102:105]
	v_mfma_f32_16x16x32_bf16 v[94:97], v[186:189], v[202:205], v[94:97]
	v_mfma_f32_16x16x32_bf16 v[86:89], v[178:181], v[210:213], v[86:89]
	v_mfma_f32_16x16x32_bf16 v[78:81], v[186:189], v[210:213], v[78:81]
	v_mfma_f32_16x16x32_bf16 v[70:73], v[178:181], v[218:221], v[70:73]
	v_mfma_f32_16x16x32_bf16 v[66:69], v[186:189], v[218:221], v[66:69]
	v_mfma_f32_16x16x32_bf16 v[118:121], v[182:185], v[198:201], v[118:121]
	v_mfma_f32_16x16x32_bf16 v[110:113], v[190:193], v[198:201], v[110:113]
	v_mfma_f32_16x16x32_bf16 v[102:105], v[182:185], v[206:209], v[102:105]
	v_mfma_f32_16x16x32_bf16 v[94:97], v[190:193], v[206:209], v[94:97]
	v_mfma_f32_16x16x32_bf16 v[86:89], v[182:185], v[214:217], v[86:89]
	v_mfma_f32_16x16x32_bf16 v[78:81], v[190:193], v[214:217], v[78:81]
	v_mfma_f32_16x16x32_bf16 v[70:73], v[182:185], v[222:225], v[70:73]
	v_mfma_f32_16x16x32_bf16 v[66:69], v[190:193], v[222:225], v[66:69]
	s_barrier
	s_setprio 0
	s_add_u32 s2, s14, 0x8000
	s_addc_u32 s3, s15, 0
	s_mov_b32 m0, s35
	v_lshl_add_u64 v[226:227], s[2:3], 0, v[142:143]
	ds_read_b128 v[194:197], v137 offset:49152
	ds_read_b128 v[198:201], v137 offset:50176
	ds_read_b128 v[202:205], v137 offset:51200
	ds_read_b128 v[206:209], v137 offset:52224
	ds_read_b128 v[210:213], v137 offset:53248
	ds_read_b128 v[214:217], v137 offset:54272
	ds_read_b128 v[218:221], v137 offset:55296
	ds_read_b128 v[222:225], v137 offset:56320
	global_load_lds_dwordx4 v[226:227], off
	v_lshl_add_u64 v[226:227], s[2:3], 0, v[146:147]
	s_add_u32 s2, s14, 0xc000
	s_mov_b32 m0, s36
	s_addc_u32 s3, s15, 0
	global_load_lds_dwordx4 v[226:227], off
	v_lshl_add_u64 v[226:227], s[2:3], 0, v[142:143]
	s_mov_b32 m0, s37
	s_nop 0
	global_load_lds_dwordx4 v[226:227], off
	v_lshl_add_u64 v[226:227], s[2:3], 0, v[146:147]
	s_mov_b32 m0, s38
	s_nop 0
	global_load_lds_dwordx4 v[226:227], off
	v_lshl_add_u64 v[226:227], s[12:13], 0, v[140:141]
	s_mov_b32 m0, s24
	s_nop 0
	global_load_lds_dwordx4 v[226:227], off
	v_lshl_add_u64 v[226:227], s[12:13], 0, v[144:145]
	s_mov_b32 m0, s25
	s_nop 0
	global_load_lds_dwordx4 v[226:227], off
	s_waitcnt vmcnt(8)
	s_waitcnt lgkmcnt(0)
	s_setprio 1
	s_barrier
	v_mfma_f32_16x16x32_bf16 v[62:65], v[160:163], v[194:197], v[62:65]
	v_mfma_f32_16x16x32_bf16 v[58:61], v[168:171], v[194:197], v[58:61]
	v_mfma_f32_16x16x32_bf16 v[50:53], v[160:163], v[202:205], v[50:53]
	v_mfma_f32_16x16x32_bf16 v[42:45], v[168:171], v[202:205], v[42:45]
	v_mfma_f32_16x16x32_bf16 v[34:37], v[160:163], v[210:213], v[34:37]
	v_mfma_f32_16x16x32_bf16 v[26:29], v[168:171], v[210:213], v[26:29]
	v_mfma_f32_16x16x32_bf16 v[18:21], v[160:163], v[218:221], v[18:21]
	v_mfma_f32_16x16x32_bf16 v[10:13], v[168:171], v[218:221], v[10:13]
	v_mfma_f32_16x16x32_bf16 v[62:65], v[164:167], v[198:201], v[62:65]
	v_mfma_f32_16x16x32_bf16 v[58:61], v[172:175], v[198:201], v[58:61]
	v_mfma_f32_16x16x32_bf16 v[50:53], v[164:167], v[206:209], v[50:53]
	v_mfma_f32_16x16x32_bf16 v[42:45], v[172:175], v[206:209], v[42:45]
	v_mfma_f32_16x16x32_bf16 v[34:37], v[164:167], v[214:217], v[34:37]
	v_mfma_f32_16x16x32_bf16 v[26:29], v[172:175], v[214:217], v[26:29]
	v_mfma_f32_16x16x32_bf16 v[18:21], v[164:167], v[222:225], v[18:21]
	v_mfma_f32_16x16x32_bf16 v[10:13], v[172:175], v[222:225], v[10:13]
	v_mfma_f32_16x16x32_bf16 v[54:57], v[178:181], v[194:197], v[54:57]
	v_mfma_f32_16x16x32_bf16 v[46:49], v[186:189], v[194:197], v[46:49]
	v_mfma_f32_16x16x32_bf16 v[38:41], v[178:181], v[202:205], v[38:41]
	v_mfma_f32_16x16x32_bf16 v[30:33], v[186:189], v[202:205], v[30:33]
	v_mfma_f32_16x16x32_bf16 v[22:25], v[178:181], v[210:213], v[22:25]
	v_mfma_f32_16x16x32_bf16 v[14:17], v[186:189], v[210:213], v[14:17]
	v_mfma_f32_16x16x32_bf16 v[6:9], v[178:181], v[218:221], v[6:9]
	v_mfma_f32_16x16x32_bf16 v[2:5], v[186:189], v[218:221], v[2:5]
	v_mfma_f32_16x16x32_bf16 v[54:57], v[182:185], v[198:201], v[54:57]
	v_mfma_f32_16x16x32_bf16 v[46:49], v[190:193], v[198:201], v[46:49]
	v_mfma_f32_16x16x32_bf16 v[38:41], v[182:185], v[206:209], v[38:41]
	v_mfma_f32_16x16x32_bf16 v[30:33], v[190:193], v[206:209], v[30:33]
	v_mfma_f32_16x16x32_bf16 v[22:25], v[182:185], v[214:217], v[22:25]
	v_mfma_f32_16x16x32_bf16 v[14:17], v[190:193], v[214:217], v[14:17]
	v_mfma_f32_16x16x32_bf16 v[6:9], v[182:185], v[222:225], v[6:9]
	v_mfma_f32_16x16x32_bf16 v[2:5], v[190:193], v[222:225], v[2:5]
	s_barrier
	s_setprio 0
	s_add_i32 s26, s26, 2
	s_add_u32 s8, s8, 0x10000
	s_addc_u32 s9, s9, 0
	s_cmp_gt_u32 s26, 41
	s_cbranch_scc0 .LBB0_437
	s_cmpk_lt_u32 s16, 0x100
	s_cbranch_scc0 .LBB0_440
	s_barrier

.Lpk451_peel:
	ds_read_b128 v[152:155], v149
	ds_read_b128 v[156:159], v149 offset:1024
	ds_read_b128 v[160:163], v149 offset:2048
	ds_read_b128 v[164:167], v149 offset:3072
	ds_read_b128 v[168:171], v150
	ds_read_b128 v[172:175], v150 offset:1024
	ds_read_b128 v[178:181], v150 offset:2048
	ds_read_b128 v[182:185], v150 offset:3072
	s_add_u32 s2, s28, 0xfffc0080
	s_addc_u32 s3, s29, -1
	s_cmp_eq_u32 s52, 12
	s_cselect_b32 s3, s11, s3
	s_cselect_b32 s2, s13, s2
	s_cselect_b32 s31, s44, s47
	s_cselect_b32 s30, s45, s46
	v_lshl_add_u64 v[146:147], s[28:29], 0, v[140:141]
	s_add_i32 m0, s25, 0xc000
	ds_read_b128 v[186:189], v151
	ds_read_b128 v[190:193], v151 offset:1024
	ds_read_b128 v[194:197], v151 offset:2048
	ds_read_b128 v[198:201], v151 offset:3072
	ds_read_b128 v[202:205], v151 offset:4096
	ds_read_b128 v[206:209], v151 offset:5120
	ds_read_b128 v[210:213], v151 offset:6144
	ds_read_b128 v[214:217], v151 offset:7168
	global_load_lds_dwordx4 v[146:147], off
	v_lshl_add_u64 v[146:147], s[28:29], 0, v[142:143]
	s_add_i32 m0, s25, 0xe000
	s_nop 0
	global_load_lds_dwordx4 v[146:147], off
	s_waitcnt vmcnt(8)
	s_waitcnt lgkmcnt(0)
	s_setprio 1
	s_barrier
	v_mfma_f32_16x16x32_bf16 v[126:129], v[152:155], v[186:189], 0
	v_mfma_f32_16x16x32_bf16 v[122:125], v[160:163], v[186:189], 0
	v_mfma_f32_16x16x32_bf16 v[110:113], v[152:155], v[194:197], 0
	v_mfma_f32_16x16x32_bf16 v[106:109], v[160:163], v[194:197], 0
	v_mfma_f32_16x16x32_bf16 v[94:97], v[152:155], v[202:205], 0
	v_mfma_f32_16x16x32_bf16 v[90:93], v[160:163], v[202:205], 0
	v_mfma_f32_16x16x32_bf16 v[78:81], v[152:155], v[210:213], 0
	v_mfma_f32_16x16x32_bf16 v[74:77], v[160:163], v[210:213], 0
	v_mfma_f32_16x16x32_bf16 v[126:129], v[156:159], v[190:193], v[126:129]
	v_mfma_f32_16x16x32_bf16 v[122:125], v[164:167], v[190:193], v[122:125]
	v_mfma_f32_16x16x32_bf16 v[110:113], v[156:159], v[198:201], v[110:113]
	v_mfma_f32_16x16x32_bf16 v[106:109], v[164:167], v[198:201], v[106:109]
	v_mfma_f32_16x16x32_bf16 v[94:97], v[156:159], v[206:209], v[94:97]
	v_mfma_f32_16x16x32_bf16 v[90:93], v[164:167], v[206:209], v[90:93]
	v_mfma_f32_16x16x32_bf16 v[78:81], v[156:159], v[214:217], v[78:81]
	v_mfma_f32_16x16x32_bf16 v[74:77], v[164:167], v[214:217], v[74:77]
	v_mfma_f32_16x16x32_bf16 v[118:121], v[168:171], v[186:189], 0
	v_mfma_f32_16x16x32_bf16 v[114:117], v[178:181], v[186:189], 0
	v_mfma_f32_16x16x32_bf16 v[102:105], v[168:171], v[194:197], 0
	v_mfma_f32_16x16x32_bf16 v[98:101], v[178:181], v[194:197], 0
	v_mfma_f32_16x16x32_bf16 v[86:89], v[168:171], v[202:205], 0
	v_mfma_f32_16x16x32_bf16 v[82:85], v[178:181], v[202:205], 0
	v_mfma_f32_16x16x32_bf16 v[70:73], v[168:171], v[210:213], 0
	v_mfma_f32_16x16x32_bf16 v[66:69], v[178:181], v[210:213], 0
	v_mfma_f32_16x16x32_bf16 v[118:121], v[172:175], v[190:193], v[118:121]
	v_mfma_f32_16x16x32_bf16 v[114:117], v[182:185], v[190:193], v[114:117]
	v_mfma_f32_16x16x32_bf16 v[102:105], v[172:175], v[198:201], v[102:105]
	v_mfma_f32_16x16x32_bf16 v[98:101], v[182:185], v[198:201], v[98:101]
	v_mfma_f32_16x16x32_bf16 v[86:89], v[172:175], v[206:209], v[86:89]
	v_mfma_f32_16x16x32_bf16 v[82:85], v[182:185], v[206:209], v[82:85]
	v_mfma_f32_16x16x32_bf16 v[70:73], v[172:175], v[214:217], v[70:73]
	v_mfma_f32_16x16x32_bf16 v[66:69], v[182:185], v[214:217], v[66:69]
	s_barrier
	s_setprio 0
	s_add_i32 s53, s42, s34
	v_lshl_add_u64 v[146:147], s[30:31], 0, v[132:133]
	s_mov_b32 m0, s53
	ds_read_b128 v[186:189], v151 offset:16384
	ds_read_b128 v[190:193], v151 offset:17408
	ds_read_b128 v[194:197], v151 offset:18432
	ds_read_b128 v[198:201], v151 offset:19456
	ds_read_b128 v[202:205], v151 offset:20480
	ds_read_b128 v[206:209], v151 offset:21504
	ds_read_b128 v[210:213], v151 offset:22528
	ds_read_b128 v[214:217], v151 offset:23552
	global_load_lds_dwordx4 v[146:147], off
	s_add_i32 m0, s53, 0x2000
	s_add_u32 s54, s30, 0x40000
	v_lshl_add_u64 v[218:219], s[30:31], 0, v[136:137]
	s_addc_u32 s55, s31, 0
	s_add_i32 s53, s43, s34
	global_load_lds_dwordx4 v[218:219], off
	v_lshl_add_u64 v[220:221], s[54:55], 0, v[132:133]
	s_mov_b32 m0, s53
	v_lshl_add_u64 v[222:223], s[2:3], 0, v[134:135]
	global_load_lds_dwordx4 v[220:221], off
	v_lshl_add_u64 v[220:221], s[54:55], 0, v[136:137]
	s_add_i32 m0, s53, 0x2000
	s_nop 0
	global_load_lds_dwordx4 v[220:221], off
	v_lshl_add_u64 v[220:221], s[2:3], 0, v[130:131]
	s_mov_b32 m0, s25
	s_nop 0
	global_load_lds_dwordx4 v[220:221], off
	s_mov_b32 m0, s27
	s_nop 0
	global_load_lds_dwordx4 v[222:223], off
	s_waitcnt vmcnt(8)
	s_waitcnt lgkmcnt(0)
	s_setprio 1
	s_barrier
	v_mfma_f32_16x16x32_bf16 v[62:65], v[152:155], v[186:189], 0
	v_mfma_f32_16x16x32_bf16 v[58:61], v[160:163], v[186:189], 0
	v_mfma_f32_16x16x32_bf16 v[46:49], v[152:155], v[194:197], 0
	v_mfma_f32_16x16x32_bf16 v[42:45], v[160:163], v[194:197], 0
	v_mfma_f32_16x16x32_bf16 v[30:33], v[152:155], v[202:205], 0
	v_mfma_f32_16x16x32_bf16 v[26:29], v[160:163], v[202:205], 0
	v_mfma_f32_16x16x32_bf16 v[14:17], v[152:155], v[210:213], 0
	v_mfma_f32_16x16x32_bf16 v[10:13], v[160:163], v[210:213], 0
	v_mfma_f32_16x16x32_bf16 v[62:65], v[156:159], v[190:193], v[62:65]
	v_mfma_f32_16x16x32_bf16 v[58:61], v[164:167], v[190:193], v[58:61]
	v_mfma_f32_16x16x32_bf16 v[46:49], v[156:159], v[198:201], v[46:49]
	v_mfma_f32_16x16x32_bf16 v[42:45], v[164:167], v[198:201], v[42:45]
	v_mfma_f32_16x16x32_bf16 v[30:33], v[156:159], v[206:209], v[30:33]
	v_mfma_f32_16x16x32_bf16 v[26:29], v[164:167], v[206:209], v[26:29]
	v_mfma_f32_16x16x32_bf16 v[14:17], v[156:159], v[214:217], v[14:17]
	v_mfma_f32_16x16x32_bf16 v[10:13], v[164:167], v[214:217], v[10:13]
	v_mfma_f32_16x16x32_bf16 v[54:57], v[168:171], v[186:189], 0
	v_mfma_f32_16x16x32_bf16 v[50:53], v[178:181], v[186:189], 0
	v_mfma_f32_16x16x32_bf16 v[38:41], v[168:171], v[194:197], 0
	v_mfma_f32_16x16x32_bf16 v[34:37], v[178:181], v[194:197], 0
	v_mfma_f32_16x16x32_bf16 v[22:25], v[168:171], v[202:205], 0
	v_mfma_f32_16x16x32_bf16 v[18:21], v[178:181], v[202:205], 0
	v_mfma_f32_16x16x32_bf16 v[6:9], v[168:171], v[210:213], 0
	v_mfma_f32_16x16x32_bf16 v[2:5], v[178:181], v[210:213], 0
	v_mfma_f32_16x16x32_bf16 v[54:57], v[172:175], v[190:193], v[54:57]
	v_mfma_f32_16x16x32_bf16 v[50:53], v[182:185], v[190:193], v[50:53]
	v_mfma_f32_16x16x32_bf16 v[38:41], v[172:175], v[198:201], v[38:41]
	v_mfma_f32_16x16x32_bf16 v[34:37], v[182:185], v[198:201], v[34:37]
	v_mfma_f32_16x16x32_bf16 v[22:25], v[172:175], v[206:209], v[22:25]
	v_mfma_f32_16x16x32_bf16 v[18:21], v[182:185], v[206:209], v[18:21]
	v_mfma_f32_16x16x32_bf16 v[6:9], v[172:175], v[214:217], v[6:9]
	v_mfma_f32_16x16x32_bf16 v[2:5], v[182:185], v[214:217], v[2:5]
	s_barrier
	s_setprio 0
	s_add_i32 s53, 0, 0x18000
	s_add_i32 s54, 0, 0x1c000
	v_add_u32_e32 v164, s53, v148
	v_add_u32_e32 v176, s54, v148
	ds_read_b128 v[152:155], v164
	ds_read_b128 v[156:159], v164 offset:1024
	ds_read_b128 v[160:163], v164 offset:2048
	ds_read_b128 v[164:167], v164 offset:3072
	ds_read_b128 v[168:171], v176
	ds_read_b128 v[172:175], v176 offset:1024
	ds_read_b128 v[178:181], v176 offset:2048
	ds_read_b128 v[182:185], v176 offset:3072
	s_add_u32 s2, s2, 0x40000
	s_addc_u32 s3, s3, 0
	s_mov_b32 m0, s36
	v_lshl_add_u64 v[224:225], s[2:3], 0, v[130:131]
	ds_read_b128 v[186:189], v151 offset:32768
	ds_read_b128 v[190:193], v151 offset:33792
	ds_read_b128 v[194:197], v151 offset:34816
	ds_read_b128 v[198:201], v151 offset:35840
	ds_read_b128 v[202:205], v151 offset:36864
	ds_read_b128 v[206:209], v151 offset:37888
	ds_read_b128 v[210:213], v151 offset:38912
	ds_read_b128 v[214:217], v151 offset:39936
	global_load_lds_dwordx4 v[224:225], off
	v_lshl_add_u64 v[224:225], s[2:3], 0, v[134:135]
	s_mov_b32 m0, s37
	s_nop 0
	global_load_lds_dwordx4 v[224:225], off
	s_waitcnt vmcnt(8)
	s_waitcnt lgkmcnt(0)
	s_setprio 1
	s_barrier
	v_mfma_f32_16x16x32_bf16 v[126:129], v[152:155], v[186:189], v[126:129]
	v_mfma_f32_16x16x32_bf16 v[122:125], v[160:163], v[186:189], v[122:125]
	v_mfma_f32_16x16x32_bf16 v[110:113], v[152:155], v[194:197], v[110:113]
	v_mfma_f32_16x16x32_bf16 v[106:109], v[160:163], v[194:197], v[106:109]
	v_mfma_f32_16x16x32_bf16 v[94:97], v[152:155], v[202:205], v[94:97]
	v_mfma_f32_16x16x32_bf16 v[90:93], v[160:163], v[202:205], v[90:93]
	v_mfma_f32_16x16x32_bf16 v[78:81], v[152:155], v[210:213], v[78:81]
	v_mfma_f32_16x16x32_bf16 v[74:77], v[160:163], v[210:213], v[74:77]
	v_mfma_f32_16x16x32_bf16 v[126:129], v[156:159], v[190:193], v[126:129]
	v_mfma_f32_16x16x32_bf16 v[122:125], v[164:167], v[190:193], v[122:125]
	v_mfma_f32_16x16x32_bf16 v[110:113], v[156:159], v[198:201], v[110:113]
	v_mfma_f32_16x16x32_bf16 v[106:109], v[164:167], v[198:201], v[106:109]
	v_mfma_f32_16x16x32_bf16 v[94:97], v[156:159], v[206:209], v[94:97]
	v_mfma_f32_16x16x32_bf16 v[90:93], v[164:167], v[206:209], v[90:93]
	v_mfma_f32_16x16x32_bf16 v[78:81], v[156:159], v[214:217], v[78:81]
	v_mfma_f32_16x16x32_bf16 v[74:77], v[164:167], v[214:217], v[74:77]
	v_mfma_f32_16x16x32_bf16 v[118:121], v[168:171], v[186:189], v[118:121]
	v_mfma_f32_16x16x32_bf16 v[114:117], v[178:181], v[186:189], v[114:117]
	v_mfma_f32_16x16x32_bf16 v[102:105], v[168:171], v[194:197], v[102:105]
	v_mfma_f32_16x16x32_bf16 v[98:101], v[178:181], v[194:197], v[98:101]
	v_mfma_f32_16x16x32_bf16 v[86:89], v[168:171], v[202:205], v[86:89]
	v_mfma_f32_16x16x32_bf16 v[82:85], v[178:181], v[202:205], v[82:85]
	v_mfma_f32_16x16x32_bf16 v[70:73], v[168:171], v[210:213], v[70:73]
	v_mfma_f32_16x16x32_bf16 v[66:69], v[178:181], v[210:213], v[66:69]
	v_mfma_f32_16x16x32_bf16 v[118:121], v[172:175], v[190:193], v[118:121]
	v_mfma_f32_16x16x32_bf16 v[114:117], v[182:185], v[190:193], v[114:117]
	v_mfma_f32_16x16x32_bf16 v[102:105], v[172:175], v[198:201], v[102:105]
	v_mfma_f32_16x16x32_bf16 v[98:101], v[182:185], v[198:201], v[98:101]
	v_mfma_f32_16x16x32_bf16 v[86:89], v[172:175], v[206:209], v[86:89]
	v_mfma_f32_16x16x32_bf16 v[82:85], v[182:185], v[206:209], v[82:85]
	v_mfma_f32_16x16x32_bf16 v[70:73], v[172:175], v[214:217], v[70:73]
	v_mfma_f32_16x16x32_bf16 v[66:69], v[182:185], v[214:217], v[66:69]
	s_barrier
	s_setprio 0
	s_add_i32 s2, s53, s34
	v_lshl_add_u64 v[146:147], v[146:147], 0, s[6:7]
	s_mov_b32 m0, s2
	ds_read_b128 v[186:189], v151 offset:49152
	ds_read_b128 v[190:193], v151 offset:50176
	ds_read_b128 v[194:197], v151 offset:51200
	ds_read_b128 v[198:201], v151 offset:52224
	ds_read_b128 v[202:205], v151 offset:53248
	ds_read_b128 v[206:209], v151 offset:54272
	ds_read_b128 v[210:213], v151 offset:55296
	ds_read_b128 v[214:217], v151 offset:56320
	global_load_lds_dwordx4 v[146:147], off
	s_add_i32 m0, s2, 0x2000
	s_add_u32 s2, s30, 0x40080
	v_lshl_add_u64 v[146:147], v[218:219], 0, s[6:7]
	s_addc_u32 s3, s31, 0
	s_add_i32 s30, s54, s34
	global_load_lds_dwordx4 v[146:147], off
	v_lshl_add_u64 v[146:147], s[2:3], 0, v[132:133]
	s_mov_b32 m0, s30
	s_nop 0
	global_load_lds_dwordx4 v[146:147], off
	v_lshl_add_u64 v[146:147], s[2:3], 0, v[136:137]
	s_add_i32 m0, s30, 0x2000
	s_nop 0
	global_load_lds_dwordx4 v[146:147], off
	v_lshl_add_u64 v[146:147], v[220:221], 0, s[6:7]
	s_mov_b32 m0, s39
	s_nop 0
	global_load_lds_dwordx4 v[146:147], off
	v_lshl_add_u64 v[146:147], v[222:223], 0, s[6:7]
	s_mov_b32 m0, s40
	s_nop 0
	global_load_lds_dwordx4 v[146:147], off
	s_waitcnt vmcnt(8)
	s_waitcnt lgkmcnt(0)
	s_setprio 1
	s_barrier
	v_mfma_f32_16x16x32_bf16 v[62:65], v[152:155], v[186:189], v[62:65]
	v_mfma_f32_16x16x32_bf16 v[58:61], v[160:163], v[186:189], v[58:61]
	v_mfma_f32_16x16x32_bf16 v[46:49], v[152:155], v[194:197], v[46:49]
	v_mfma_f32_16x16x32_bf16 v[42:45], v[160:163], v[194:197], v[42:45]
	v_mfma_f32_16x16x32_bf16 v[30:33], v[152:155], v[202:205], v[30:33]
	v_mfma_f32_16x16x32_bf16 v[26:29], v[160:163], v[202:205], v[26:29]
	v_mfma_f32_16x16x32_bf16 v[14:17], v[152:155], v[210:213], v[14:17]
	v_mfma_f32_16x16x32_bf16 v[10:13], v[160:163], v[210:213], v[10:13]
	v_mfma_f32_16x16x32_bf16 v[62:65], v[156:159], v[190:193], v[62:65]
	v_mfma_f32_16x16x32_bf16 v[58:61], v[164:167], v[190:193], v[58:61]
	v_mfma_f32_16x16x32_bf16 v[46:49], v[156:159], v[198:201], v[46:49]
	v_mfma_f32_16x16x32_bf16 v[42:45], v[164:167], v[198:201], v[42:45]
	v_mfma_f32_16x16x32_bf16 v[30:33], v[156:159], v[206:209], v[30:33]
	v_mfma_f32_16x16x32_bf16 v[26:29], v[164:167], v[206:209], v[26:29]
	v_mfma_f32_16x16x32_bf16 v[14:17], v[156:159], v[214:217], v[14:17]
	v_mfma_f32_16x16x32_bf16 v[10:13], v[164:167], v[214:217], v[10:13]
	v_mfma_f32_16x16x32_bf16 v[54:57], v[168:171], v[186:189], v[54:57]
	v_mfma_f32_16x16x32_bf16 v[50:53], v[178:181], v[186:189], v[50:53]
	v_mfma_f32_16x16x32_bf16 v[38:41], v[168:171], v[194:197], v[38:41]
	v_mfma_f32_16x16x32_bf16 v[34:37], v[178:181], v[194:197], v[34:37]
	v_mfma_f32_16x16x32_bf16 v[22:25], v[168:171], v[202:205], v[22:25]
	v_mfma_f32_16x16x32_bf16 v[18:21], v[178:181], v[202:205], v[18:21]
	v_mfma_f32_16x16x32_bf16 v[6:9], v[168:171], v[210:213], v[6:9]
	v_mfma_f32_16x16x32_bf16 v[2:5], v[178:181], v[210:213], v[2:5]
	v_mfma_f32_16x16x32_bf16 v[54:57], v[172:175], v[190:193], v[54:57]
	v_mfma_f32_16x16x32_bf16 v[50:53], v[182:185], v[190:193], v[50:53]
	v_mfma_f32_16x16x32_bf16 v[38:41], v[172:175], v[198:201], v[38:41]
	v_mfma_f32_16x16x32_bf16 v[34:37], v[182:185], v[198:201], v[34:37]
	v_mfma_f32_16x16x32_bf16 v[22:25], v[172:175], v[206:209], v[22:25]
	v_mfma_f32_16x16x32_bf16 v[18:21], v[182:185], v[206:209], v[18:21]
	v_mfma_f32_16x16x32_bf16 v[6:9], v[172:175], v[214:217], v[6:9]
	v_mfma_f32_16x16x32_bf16 v[2:5], v[182:185], v[214:217], v[2:5]
	s_barrier
	s_setprio 0
	s_add_i32 s52, s52, 2
	s_add_u32 s28, s28, 0x100
	s_addc_u32 s29, s29, 0
	s_add_u32 s46, s46, 0x100
	s_addc_u32 s47, s47, 0
	s_cmp_gt_u32 s52, 13
	s_cbranch_scc0 .LBB0_451
	s_branch .Lpk451_exit
.LBB0_451:
	ds_read_b128 v[152:155], v149
	ds_read_b128 v[156:159], v149 offset:1024
	ds_read_b128 v[160:163], v149 offset:2048
	ds_read_b128 v[164:167], v149 offset:3072
	ds_read_b128 v[168:171], v150
	ds_read_b128 v[172:175], v150 offset:1024
	ds_read_b128 v[178:181], v150 offset:2048
	ds_read_b128 v[182:185], v150 offset:3072
	s_add_u32 s2, s28, 0xfffc0080
	s_addc_u32 s3, s29, -1
	s_cmp_eq_u32 s52, 12
	s_cselect_b32 s3, s11, s3
	s_cselect_b32 s2, s13, s2
	s_cselect_b32 s31, s44, s47
	s_cselect_b32 s30, s45, s46
	v_lshl_add_u64 v[146:147], s[28:29], 0, v[140:141]
	s_add_i32 m0, s25, 0xc000
	ds_read_b128 v[186:189], v151
	ds_read_b128 v[190:193], v151 offset:1024
	ds_read_b128 v[194:197], v151 offset:2048
	ds_read_b128 v[198:201], v151 offset:3072
	ds_read_b128 v[202:205], v151 offset:4096
	ds_read_b128 v[206:209], v151 offset:5120
	ds_read_b128 v[210:213], v151 offset:6144
	ds_read_b128 v[214:217], v151 offset:7168
	global_load_lds_dwordx4 v[146:147], off
	v_lshl_add_u64 v[146:147], s[28:29], 0, v[142:143]
	s_add_i32 m0, s25, 0xe000
	s_nop 0
	global_load_lds_dwordx4 v[146:147], off
	s_waitcnt vmcnt(8)
	s_waitcnt lgkmcnt(0)
	s_setprio 1
	s_barrier
	v_mfma_f32_16x16x32_bf16 v[126:129], v[152:155], v[186:189], v[126:129]
	v_mfma_f32_16x16x32_bf16 v[122:125], v[160:163], v[186:189], v[122:125]
	v_mfma_f32_16x16x32_bf16 v[110:113], v[152:155], v[194:197], v[110:113]
	v_mfma_f32_16x16x32_bf16 v[106:109], v[160:163], v[194:197], v[106:109]
	v_mfma_f32_16x16x32_bf16 v[94:97], v[152:155], v[202:205], v[94:97]
	v_mfma_f32_16x16x32_bf16 v[90:93], v[160:163], v[202:205], v[90:93]
	v_mfma_f32_16x16x32_bf16 v[78:81], v[152:155], v[210:213], v[78:81]
	v_mfma_f32_16x16x32_bf16 v[74:77], v[160:163], v[210:213], v[74:77]
	v_mfma_f32_16x16x32_bf16 v[126:129], v[156:159], v[190:193], v[126:129]
	v_mfma_f32_16x16x32_bf16 v[122:125], v[164:167], v[190:193], v[122:125]
	v_mfma_f32_16x16x32_bf16 v[110:113], v[156:159], v[198:201], v[110:113]
	v_mfma_f32_16x16x32_bf16 v[106:109], v[164:167], v[198:201], v[106:109]
	v_mfma_f32_16x16x32_bf16 v[94:97], v[156:159], v[206:209], v[94:97]
	v_mfma_f32_16x16x32_bf16 v[90:93], v[164:167], v[206:209], v[90:93]
	v_mfma_f32_16x16x32_bf16 v[78:81], v[156:159], v[214:217], v[78:81]
	v_mfma_f32_16x16x32_bf16 v[74:77], v[164:167], v[214:217], v[74:77]
	v_mfma_f32_16x16x32_bf16 v[118:121], v[168:171], v[186:189], v[118:121]
	v_mfma_f32_16x16x32_bf16 v[114:117], v[178:181], v[186:189], v[114:117]
	v_mfma_f32_16x16x32_bf16 v[102:105], v[168:171], v[194:197], v[102:105]
	v_mfma_f32_16x16x32_bf16 v[98:101], v[178:181], v[194:197], v[98:101]
	v_mfma_f32_16x16x32_bf16 v[86:89], v[168:171], v[202:205], v[86:89]
	v_mfma_f32_16x16x32_bf16 v[82:85], v[178:181], v[202:205], v[82:85]
	v_mfma_f32_16x16x32_bf16 v[70:73], v[168:171], v[210:213], v[70:73]
	v_mfma_f32_16x16x32_bf16 v[66:69], v[178:181], v[210:213], v[66:69]
	v_mfma_f32_16x16x32_bf16 v[118:121], v[172:175], v[190:193], v[118:121]
	v_mfma_f32_16x16x32_bf16 v[114:117], v[182:185], v[190:193], v[114:117]
	v_mfma_f32_16x16x32_bf16 v[102:105], v[172:175], v[198:201], v[102:105]
	v_mfma_f32_16x16x32_bf16 v[98:101], v[182:185], v[198:201], v[98:101]
	v_mfma_f32_16x16x32_bf16 v[86:89], v[172:175], v[206:209], v[86:89]
	v_mfma_f32_16x16x32_bf16 v[82:85], v[182:185], v[206:209], v[82:85]
	v_mfma_f32_16x16x32_bf16 v[70:73], v[172:175], v[214:217], v[70:73]
	v_mfma_f32_16x16x32_bf16 v[66:69], v[182:185], v[214:217], v[66:69]
	s_barrier
	s_setprio 0
	s_add_i32 s53, s42, s34
	v_lshl_add_u64 v[146:147], s[30:31], 0, v[132:133]
	s_mov_b32 m0, s53
	ds_read_b128 v[186:189], v151 offset:16384
	ds_read_b128 v[190:193], v151 offset:17408
	ds_read_b128 v[194:197], v151 offset:18432
	ds_read_b128 v[198:201], v151 offset:19456
	ds_read_b128 v[202:205], v151 offset:20480
	ds_read_b128 v[206:209], v151 offset:21504
	ds_read_b128 v[210:213], v151 offset:22528
	ds_read_b128 v[214:217], v151 offset:23552
	global_load_lds_dwordx4 v[146:147], off
	s_add_i32 m0, s53, 0x2000
	s_add_u32 s54, s30, 0x40000
	v_lshl_add_u64 v[218:219], s[30:31], 0, v[136:137]
	s_addc_u32 s55, s31, 0
	s_add_i32 s53, s43, s34
	global_load_lds_dwordx4 v[218:219], off
	v_lshl_add_u64 v[220:221], s[54:55], 0, v[132:133]
	s_mov_b32 m0, s53
	v_lshl_add_u64 v[222:223], s[2:3], 0, v[134:135]
	global_load_lds_dwordx4 v[220:221], off
	v_lshl_add_u64 v[220:221], s[54:55], 0, v[136:137]
	s_add_i32 m0, s53, 0x2000
	s_nop 0
	global_load_lds_dwordx4 v[220:221], off
	v_lshl_add_u64 v[220:221], s[2:3], 0, v[130:131]
	s_mov_b32 m0, s25
	s_nop 0
	global_load_lds_dwordx4 v[220:221], off
	s_mov_b32 m0, s27
	s_nop 0
	global_load_lds_dwordx4 v[222:223], off
	s_waitcnt vmcnt(8)
	s_waitcnt lgkmcnt(0)
	s_setprio 1
	s_barrier
	v_mfma_f32_16x16x32_bf16 v[62:65], v[152:155], v[186:189], v[62:65]
	v_mfma_f32_16x16x32_bf16 v[58:61], v[160:163], v[186:189], v[58:61]
	v_mfma_f32_16x16x32_bf16 v[46:49], v[152:155], v[194:197], v[46:49]
	v_mfma_f32_16x16x32_bf16 v[42:45], v[160:163], v[194:197], v[42:45]
	v_mfma_f32_16x16x32_bf16 v[30:33], v[152:155], v[202:205], v[30:33]
	v_mfma_f32_16x16x32_bf16 v[26:29], v[160:163], v[202:205], v[26:29]
	v_mfma_f32_16x16x32_bf16 v[14:17], v[152:155], v[210:213], v[14:17]
	v_mfma_f32_16x16x32_bf16 v[10:13], v[160:163], v[210:213], v[10:13]
	v_mfma_f32_16x16x32_bf16 v[62:65], v[156:159], v[190:193], v[62:65]
	v_mfma_f32_16x16x32_bf16 v[58:61], v[164:167], v[190:193], v[58:61]
	v_mfma_f32_16x16x32_bf16 v[46:49], v[156:159], v[198:201], v[46:49]
	v_mfma_f32_16x16x32_bf16 v[42:45], v[164:167], v[198:201], v[42:45]
	v_mfma_f32_16x16x32_bf16 v[30:33], v[156:159], v[206:209], v[30:33]
	v_mfma_f32_16x16x32_bf16 v[26:29], v[164:167], v[206:209], v[26:29]
	v_mfma_f32_16x16x32_bf16 v[14:17], v[156:159], v[214:217], v[14:17]
	v_mfma_f32_16x16x32_bf16 v[10:13], v[164:167], v[214:217], v[10:13]
	v_mfma_f32_16x16x32_bf16 v[54:57], v[168:171], v[186:189], v[54:57]
	v_mfma_f32_16x16x32_bf16 v[50:53], v[178:181], v[186:189], v[50:53]
	v_mfma_f32_16x16x32_bf16 v[38:41], v[168:171], v[194:197], v[38:41]
	v_mfma_f32_16x16x32_bf16 v[34:37], v[178:181], v[194:197], v[34:37]
	v_mfma_f32_16x16x32_bf16 v[22:25], v[168:171], v[202:205], v[22:25]
	v_mfma_f32_16x16x32_bf16 v[18:21], v[178:181], v[202:205], v[18:21]
	v_mfma_f32_16x16x32_bf16 v[6:9], v[168:171], v[210:213], v[6:9]
	v_mfma_f32_16x16x32_bf16 v[2:5], v[178:181], v[210:213], v[2:5]
	v_mfma_f32_16x16x32_bf16 v[54:57], v[172:175], v[190:193], v[54:57]
	v_mfma_f32_16x16x32_bf16 v[50:53], v[182:185], v[190:193], v[50:53]
	v_mfma_f32_16x16x32_bf16 v[38:41], v[172:175], v[198:201], v[38:41]
	v_mfma_f32_16x16x32_bf16 v[34:37], v[182:185], v[198:201], v[34:37]
	v_mfma_f32_16x16x32_bf16 v[22:25], v[172:175], v[206:209], v[22:25]
	v_mfma_f32_16x16x32_bf16 v[18:21], v[182:185], v[206:209], v[18:21]
	v_mfma_f32_16x16x32_bf16 v[6:9], v[172:175], v[214:217], v[6:9]
	v_mfma_f32_16x16x32_bf16 v[2:5], v[182:185], v[214:217], v[2:5]
	s_barrier
	s_setprio 0
	s_add_i32 s53, 0, 0x18000
	s_add_i32 s54, 0, 0x1c000
	v_add_u32_e32 v164, s53, v148
	v_add_u32_e32 v176, s54, v148
	ds_read_b128 v[152:155], v164
	ds_read_b128 v[156:159], v164 offset:1024
	ds_read_b128 v[160:163], v164 offset:2048
	ds_read_b128 v[164:167], v164 offset:3072
	ds_read_b128 v[168:171], v176
	ds_read_b128 v[172:175], v176 offset:1024
	ds_read_b128 v[178:181], v176 offset:2048
	ds_read_b128 v[182:185], v176 offset:3072
	s_add_u32 s2, s2, 0x40000
	s_addc_u32 s3, s3, 0
	s_mov_b32 m0, s36
	v_lshl_add_u64 v[224:225], s[2:3], 0, v[130:131]
	ds_read_b128 v[186:189], v151 offset:32768
	ds_read_b128 v[190:193], v151 offset:33792
	ds_read_b128 v[194:197], v151 offset:34816
	ds_read_b128 v[198:201], v151 offset:35840
	ds_read_b128 v[202:205], v151 offset:36864
	ds_read_b128 v[206:209], v151 offset:37888
	ds_read_b128 v[210:213], v151 offset:38912
	ds_read_b128 v[214:217], v151 offset:39936
	global_load_lds_dwordx4 v[224:225], off
	v_lshl_add_u64 v[224:225], s[2:3], 0, v[134:135]
	s_mov_b32 m0, s37
	s_nop 0
	global_load_lds_dwordx4 v[224:225], off
	s_waitcnt vmcnt(8)
	s_waitcnt lgkmcnt(0)
	s_setprio 1
	s_barrier
	v_mfma_f32_16x16x32_bf16 v[126:129], v[152:155], v[186:189], v[126:129]
	v_mfma_f32_16x16x32_bf16 v[122:125], v[160:163], v[186:189], v[122:125]
	v_mfma_f32_16x16x32_bf16 v[110:113], v[152:155], v[194:197], v[110:113]
	v_mfma_f32_16x16x32_bf16 v[106:109], v[160:163], v[194:197], v[106:109]
	v_mfma_f32_16x16x32_bf16 v[94:97], v[152:155], v[202:205], v[94:97]
	v_mfma_f32_16x16x32_bf16 v[90:93], v[160:163], v[202:205], v[90:93]
	v_mfma_f32_16x16x32_bf16 v[78:81], v[152:155], v[210:213], v[78:81]
	v_mfma_f32_16x16x32_bf16 v[74:77], v[160:163], v[210:213], v[74:77]
	v_mfma_f32_16x16x32_bf16 v[126:129], v[156:159], v[190:193], v[126:129]
	v_mfma_f32_16x16x32_bf16 v[122:125], v[164:167], v[190:193], v[122:125]
	v_mfma_f32_16x16x32_bf16 v[110:113], v[156:159], v[198:201], v[110:113]
	v_mfma_f32_16x16x32_bf16 v[106:109], v[164:167], v[198:201], v[106:109]
	v_mfma_f32_16x16x32_bf16 v[94:97], v[156:159], v[206:209], v[94:97]
	v_mfma_f32_16x16x32_bf16 v[90:93], v[164:167], v[206:209], v[90:93]
	v_mfma_f32_16x16x32_bf16 v[78:81], v[156:159], v[214:217], v[78:81]
	v_mfma_f32_16x16x32_bf16 v[74:77], v[164:167], v[214:217], v[74:77]
	v_mfma_f32_16x16x32_bf16 v[118:121], v[168:171], v[186:189], v[118:121]
	v_mfma_f32_16x16x32_bf16 v[114:117], v[178:181], v[186:189], v[114:117]
	v_mfma_f32_16x16x32_bf16 v[102:105], v[168:171], v[194:197], v[102:105]
	v_mfma_f32_16x16x32_bf16 v[98:101], v[178:181], v[194:197], v[98:101]
	v_mfma_f32_16x16x32_bf16 v[86:89], v[168:171], v[202:205], v[86:89]
	v_mfma_f32_16x16x32_bf16 v[82:85], v[178:181], v[202:205], v[82:85]
	v_mfma_f32_16x16x32_bf16 v[70:73], v[168:171], v[210:213], v[70:73]
	v_mfma_f32_16x16x32_bf16 v[66:69], v[178:181], v[210:213], v[66:69]
	v_mfma_f32_16x16x32_bf16 v[118:121], v[172:175], v[190:193], v[118:121]
	v_mfma_f32_16x16x32_bf16 v[114:117], v[182:185], v[190:193], v[114:117]
	v_mfma_f32_16x16x32_bf16 v[102:105], v[172:175], v[198:201], v[102:105]
	v_mfma_f32_16x16x32_bf16 v[98:101], v[182:185], v[198:201], v[98:101]
	v_mfma_f32_16x16x32_bf16 v[86:89], v[172:175], v[206:209], v[86:89]
	v_mfma_f32_16x16x32_bf16 v[82:85], v[182:185], v[206:209], v[82:85]
	v_mfma_f32_16x16x32_bf16 v[70:73], v[172:175], v[214:217], v[70:73]
	v_mfma_f32_16x16x32_bf16 v[66:69], v[182:185], v[214:217], v[66:69]
	s_barrier
	s_setprio 0
	s_add_i32 s2, s53, s34
	v_lshl_add_u64 v[146:147], v[146:147], 0, s[6:7]
	s_mov_b32 m0, s2
	ds_read_b128 v[186:189], v151 offset:49152
	ds_read_b128 v[190:193], v151 offset:50176
	ds_read_b128 v[194:197], v151 offset:51200
	ds_read_b128 v[198:201], v151 offset:52224
	ds_read_b128 v[202:205], v151 offset:53248
	ds_read_b128 v[206:209], v151 offset:54272
	ds_read_b128 v[210:213], v151 offset:55296
	ds_read_b128 v[214:217], v151 offset:56320
	global_load_lds_dwordx4 v[146:147], off
	s_add_i32 m0, s2, 0x2000
	s_add_u32 s2, s30, 0x40080
	v_lshl_add_u64 v[146:147], v[218:219], 0, s[6:7]
	s_addc_u32 s3, s31, 0
	s_add_i32 s30, s54, s34
	global_load_lds_dwordx4 v[146:147], off
	v_lshl_add_u64 v[146:147], s[2:3], 0, v[132:133]
	s_mov_b32 m0, s30
	s_nop 0
	global_load_lds_dwordx4 v[146:147], off
	v_lshl_add_u64 v[146:147], s[2:3], 0, v[136:137]
	s_add_i32 m0, s30, 0x2000
	s_nop 0
	global_load_lds_dwordx4 v[146:147], off
	v_lshl_add_u64 v[146:147], v[220:221], 0, s[6:7]
	s_mov_b32 m0, s39
	s_nop 0
	global_load_lds_dwordx4 v[146:147], off
	v_lshl_add_u64 v[146:147], v[222:223], 0, s[6:7]
	s_mov_b32 m0, s40
	s_nop 0
	global_load_lds_dwordx4 v[146:147], off
	s_waitcnt vmcnt(8)
	s_waitcnt lgkmcnt(0)
	s_setprio 1
	s_barrier
	v_mfma_f32_16x16x32_bf16 v[62:65], v[152:155], v[186:189], v[62:65]
	v_mfma_f32_16x16x32_bf16 v[58:61], v[160:163], v[186:189], v[58:61]
	v_mfma_f32_16x16x32_bf16 v[46:49], v[152:155], v[194:197], v[46:49]
	v_mfma_f32_16x16x32_bf16 v[42:45], v[160:163], v[194:197], v[42:45]
	v_mfma_f32_16x16x32_bf16 v[30:33], v[152:155], v[202:205], v[30:33]
	v_mfma_f32_16x16x32_bf16 v[26:29], v[160:163], v[202:205], v[26:29]
	v_mfma_f32_16x16x32_bf16 v[14:17], v[152:155], v[210:213], v[14:17]
	v_mfma_f32_16x16x32_bf16 v[10:13], v[160:163], v[210:213], v[10:13]
	v_mfma_f32_16x16x32_bf16 v[62:65], v[156:159], v[190:193], v[62:65]
	v_mfma_f32_16x16x32_bf16 v[58:61], v[164:167], v[190:193], v[58:61]
	v_mfma_f32_16x16x32_bf16 v[46:49], v[156:159], v[198:201], v[46:49]
	v_mfma_f32_16x16x32_bf16 v[42:45], v[164:167], v[198:201], v[42:45]
	v_mfma_f32_16x16x32_bf16 v[30:33], v[156:159], v[206:209], v[30:33]
	v_mfma_f32_16x16x32_bf16 v[26:29], v[164:167], v[206:209], v[26:29]
	v_mfma_f32_16x16x32_bf16 v[14:17], v[156:159], v[214:217], v[14:17]
	v_mfma_f32_16x16x32_bf16 v[10:13], v[164:167], v[214:217], v[10:13]
	v_mfma_f32_16x16x32_bf16 v[54:57], v[168:171], v[186:189], v[54:57]
	v_mfma_f32_16x16x32_bf16 v[50:53], v[178:181], v[186:189], v[50:53]
	v_mfma_f32_16x16x32_bf16 v[38:41], v[168:171], v[194:197], v[38:41]
	v_mfma_f32_16x16x32_bf16 v[34:37], v[178:181], v[194:197], v[34:37]
	v_mfma_f32_16x16x32_bf16 v[22:25], v[168:171], v[202:205], v[22:25]
	v_mfma_f32_16x16x32_bf16 v[18:21], v[178:181], v[202:205], v[18:21]
	v_mfma_f32_16x16x32_bf16 v[6:9], v[168:171], v[210:213], v[6:9]
	v_mfma_f32_16x16x32_bf16 v[2:5], v[178:181], v[210:213], v[2:5]
	v_mfma_f32_16x16x32_bf16 v[54:57], v[172:175], v[190:193], v[54:57]
	v_mfma_f32_16x16x32_bf16 v[50:53], v[182:185], v[190:193], v[50:53]
	v_mfma_f32_16x16x32_bf16 v[38:41], v[172:175], v[198:201], v[38:41]
	v_mfma_f32_16x16x32_bf16 v[34:37], v[182:185], v[198:201], v[34:37]
	v_mfma_f32_16x16x32_bf16 v[22:25], v[172:175], v[206:209], v[22:25]
	v_mfma_f32_16x16x32_bf16 v[18:21], v[182:185], v[206:209], v[18:21]
	v_mfma_f32_16x16x32_bf16 v[6:9], v[172:175], v[214:217], v[6:9]
	v_mfma_f32_16x16x32_bf16 v[2:5], v[182:185], v[214:217], v[2:5]
	s_barrier
	s_setprio 0
	s_add_i32 s52, s52, 2
	s_add_u32 s28, s28, 0x100
	s_addc_u32 s29, s29, 0
	s_add_u32 s46, s46, 0x100
	s_addc_u32 s47, s47, 0
	s_cmp_gt_u32 s52, 13
	s_cbranch_scc0 .LBB0_451

.Lpk495_peel:
	ds_read_b128 v[152:155], v149
	ds_read_b128 v[156:159], v149 offset:1024
	ds_read_b128 v[160:163], v149 offset:2048
	ds_read_b128 v[164:167], v149 offset:3072
	ds_read_b128 v[168:171], v150
	ds_read_b128 v[172:175], v150 offset:1024
	ds_read_b128 v[178:181], v150 offset:2048
	ds_read_b128 v[182:185], v150 offset:3072
	s_add_u32 s2, s18, 0x4000
	s_addc_u32 s3, s19, 0
	s_cmp_eq_u32 s50, 40
	s_cselect_b32 s2, s45, s2
	s_cselect_b32 s3, s44, s3
	s_cselect_b32 s23, s46, s49
	s_cselect_b32 s22, s47, s48
	s_add_u32 s20, s2, 0x8000
	s_addc_u32 s21, s3, 0
	v_lshl_add_u64 v[144:145], s[18:19], 0, v[138:139]
	s_add_i32 m0, s29, 0xc000
	ds_read_b128 v[186:189], v151
	ds_read_b128 v[190:193], v151 offset:1024
	ds_read_b128 v[194:197], v151 offset:2048
	ds_read_b128 v[198:201], v151 offset:3072
	ds_read_b128 v[202:205], v151 offset:4096
	ds_read_b128 v[206:209], v151 offset:5120
	ds_read_b128 v[210:213], v151 offset:6144
	ds_read_b128 v[214:217], v151 offset:7168
	global_load_lds_dwordx4 v[144:145], off
	v_lshl_add_u64 v[144:145], s[18:19], 0, v[140:141]
	s_add_i32 m0, s29, 0xe000
	s_nop 0
	global_load_lds_dwordx4 v[144:145], off
	s_waitcnt vmcnt(8)
	s_waitcnt lgkmcnt(0)
	s_setprio 1
	s_barrier
	v_mfma_f32_16x16x32_bf16 v[126:129], v[152:155], v[186:189], 0
	v_mfma_f32_16x16x32_bf16 v[122:125], v[160:163], v[186:189], 0
	v_mfma_f32_16x16x32_bf16 v[114:117], v[152:155], v[194:197], 0
	v_mfma_f32_16x16x32_bf16 v[106:109], v[160:163], v[194:197], 0
	v_mfma_f32_16x16x32_bf16 v[98:101], v[152:155], v[202:205], 0
	v_mfma_f32_16x16x32_bf16 v[90:93], v[160:163], v[202:205], 0
	v_mfma_f32_16x16x32_bf16 v[82:85], v[152:155], v[210:213], 0
	v_mfma_f32_16x16x32_bf16 v[74:77], v[160:163], v[210:213], 0
	v_mfma_f32_16x16x32_bf16 v[126:129], v[156:159], v[190:193], v[126:129]
	v_mfma_f32_16x16x32_bf16 v[122:125], v[164:167], v[190:193], v[122:125]
	v_mfma_f32_16x16x32_bf16 v[114:117], v[156:159], v[198:201], v[114:117]
	v_mfma_f32_16x16x32_bf16 v[106:109], v[164:167], v[198:201], v[106:109]
	v_mfma_f32_16x16x32_bf16 v[98:101], v[156:159], v[206:209], v[98:101]
	v_mfma_f32_16x16x32_bf16 v[90:93], v[164:167], v[206:209], v[90:93]
	v_mfma_f32_16x16x32_bf16 v[82:85], v[156:159], v[214:217], v[82:85]
	v_mfma_f32_16x16x32_bf16 v[74:77], v[164:167], v[214:217], v[74:77]
	v_mfma_f32_16x16x32_bf16 v[118:121], v[168:171], v[186:189], 0
	v_mfma_f32_16x16x32_bf16 v[110:113], v[178:181], v[186:189], 0
	v_mfma_f32_16x16x32_bf16 v[102:105], v[168:171], v[194:197], 0
	v_mfma_f32_16x16x32_bf16 v[94:97], v[178:181], v[194:197], 0
	v_mfma_f32_16x16x32_bf16 v[86:89], v[168:171], v[202:205], 0
	v_mfma_f32_16x16x32_bf16 v[78:81], v[178:181], v[202:205], 0
	v_mfma_f32_16x16x32_bf16 v[70:73], v[168:171], v[210:213], 0
	v_mfma_f32_16x16x32_bf16 v[66:69], v[178:181], v[210:213], 0
	v_mfma_f32_16x16x32_bf16 v[118:121], v[172:175], v[190:193], v[118:121]
	v_mfma_f32_16x16x32_bf16 v[110:113], v[182:185], v[190:193], v[110:113]
	v_mfma_f32_16x16x32_bf16 v[102:105], v[172:175], v[198:201], v[102:105]
	v_mfma_f32_16x16x32_bf16 v[94:97], v[182:185], v[198:201], v[94:97]
	v_mfma_f32_16x16x32_bf16 v[86:89], v[172:175], v[206:209], v[86:89]
	v_mfma_f32_16x16x32_bf16 v[78:81], v[182:185], v[206:209], v[78:81]
	v_mfma_f32_16x16x32_bf16 v[70:73], v[172:175], v[214:217], v[70:73]
	v_mfma_f32_16x16x32_bf16 v[66:69], v[182:185], v[214:217], v[66:69]
	s_barrier
	s_setprio 0
	s_add_i32 s51, s38, s28
	v_lshl_add_u64 v[144:145], s[22:23], 0, v[132:133]
	s_mov_b32 m0, s51
	ds_read_b128 v[186:189], v151 offset:16384
	ds_read_b128 v[190:193], v151 offset:17408
	ds_read_b128 v[194:197], v151 offset:18432
	ds_read_b128 v[198:201], v151 offset:19456
	ds_read_b128 v[202:205], v151 offset:20480
	ds_read_b128 v[206:209], v151 offset:21504
	ds_read_b128 v[210:213], v151 offset:22528
	ds_read_b128 v[214:217], v151 offset:23552
	global_load_lds_dwordx4 v[144:145], off
	s_add_i32 m0, s51, 0x2000
	s_add_u32 s52, s22, 0x4000
	v_lshl_add_u64 v[144:145], s[22:23], 0, v[136:137]
	s_addc_u32 s53, s23, 0
	s_add_i32 s51, s39, s28
	global_load_lds_dwordx4 v[144:145], off
	v_lshl_add_u64 v[144:145], s[52:53], 0, v[132:133]
	s_mov_b32 m0, s51
	s_nop 0
	global_load_lds_dwordx4 v[144:145], off
	v_lshl_add_u64 v[144:145], s[52:53], 0, v[136:137]
	s_add_i32 m0, s51, 0x2000
	s_nop 0
	global_load_lds_dwordx4 v[144:145], off
	v_lshl_add_u64 v[144:145], s[2:3], 0, v[130:131]
	s_mov_b32 m0, s29
	s_nop 0
	global_load_lds_dwordx4 v[144:145], off
	v_lshl_add_u64 v[144:145], s[2:3], 0, v[134:135]
	s_mov_b32 m0, s30
	s_nop 0
	global_load_lds_dwordx4 v[144:145], off
	s_waitcnt vmcnt(8)
	s_waitcnt lgkmcnt(0)
	s_setprio 1
	s_barrier
	v_mfma_f32_16x16x32_bf16 v[62:65], v[152:155], v[186:189], 0
	v_mfma_f32_16x16x32_bf16 v[58:61], v[160:163], v[186:189], 0
	v_mfma_f32_16x16x32_bf16 v[50:53], v[152:155], v[194:197], 0
	v_mfma_f32_16x16x32_bf16 v[42:45], v[160:163], v[194:197], 0
	v_mfma_f32_16x16x32_bf16 v[34:37], v[152:155], v[202:205], 0
	v_mfma_f32_16x16x32_bf16 v[26:29], v[160:163], v[202:205], 0
	v_mfma_f32_16x16x32_bf16 v[18:21], v[152:155], v[210:213], 0
	v_mfma_f32_16x16x32_bf16 v[10:13], v[160:163], v[210:213], 0
	v_mfma_f32_16x16x32_bf16 v[62:65], v[156:159], v[190:193], v[62:65]
	v_mfma_f32_16x16x32_bf16 v[58:61], v[164:167], v[190:193], v[58:61]
	v_mfma_f32_16x16x32_bf16 v[50:53], v[156:159], v[198:201], v[50:53]
	v_mfma_f32_16x16x32_bf16 v[42:45], v[164:167], v[198:201], v[42:45]
	v_mfma_f32_16x16x32_bf16 v[34:37], v[156:159], v[206:209], v[34:37]
	v_mfma_f32_16x16x32_bf16 v[26:29], v[164:167], v[206:209], v[26:29]
	v_mfma_f32_16x16x32_bf16 v[18:21], v[156:159], v[214:217], v[18:21]
	v_mfma_f32_16x16x32_bf16 v[10:13], v[164:167], v[214:217], v[10:13]
	v_mfma_f32_16x16x32_bf16 v[54:57], v[168:171], v[186:189], 0
	v_mfma_f32_16x16x32_bf16 v[46:49], v[178:181], v[186:189], 0
	v_mfma_f32_16x16x32_bf16 v[38:41], v[168:171], v[194:197], 0
	v_mfma_f32_16x16x32_bf16 v[30:33], v[178:181], v[194:197], 0
	v_mfma_f32_16x16x32_bf16 v[22:25], v[168:171], v[202:205], 0
	v_mfma_f32_16x16x32_bf16 v[14:17], v[178:181], v[202:205], 0
	v_mfma_f32_16x16x32_bf16 v[6:9], v[168:171], v[210:213], 0
	v_mfma_f32_16x16x32_bf16 v[2:5], v[178:181], v[210:213], 0
	v_mfma_f32_16x16x32_bf16 v[54:57], v[172:175], v[190:193], v[54:57]
	v_mfma_f32_16x16x32_bf16 v[46:49], v[182:185], v[190:193], v[46:49]
	v_mfma_f32_16x16x32_bf16 v[38:41], v[172:175], v[198:201], v[38:41]
	v_mfma_f32_16x16x32_bf16 v[30:33], v[182:185], v[198:201], v[30:33]
	v_mfma_f32_16x16x32_bf16 v[22:25], v[172:175], v[206:209], v[22:25]
	v_mfma_f32_16x16x32_bf16 v[14:17], v[182:185], v[206:209], v[14:17]
	v_mfma_f32_16x16x32_bf16 v[6:9], v[172:175], v[214:217], v[6:9]
	v_mfma_f32_16x16x32_bf16 v[2:5], v[182:185], v[214:217], v[2:5]
	s_barrier
	s_setprio 0
	s_add_i32 s51, 0, 0x18000
	v_add_u32_e32 v144, s51, v147
	s_add_i32 s52, 0, 0x1c000
	ds_read_b128 v[152:155], v144
	ds_read_b128 v[156:159], v144 offset:1024
	ds_read_b128 v[160:163], v144 offset:2048
	ds_read_b128 v[164:167], v144 offset:3072
	v_add_u32_e32 v144, s52, v147
	ds_read_b128 v[168:171], v144
	ds_read_b128 v[172:175], v144 offset:1024
	ds_read_b128 v[178:181], v144 offset:2048
	ds_read_b128 v[182:185], v144 offset:3072
	s_add_u32 s2, s2, 0x4000
	s_addc_u32 s3, s3, 0
	s_mov_b32 m0, s31
	v_lshl_add_u64 v[144:145], s[2:3], 0, v[130:131]
	ds_read_b128 v[186:189], v151 offset:32768
	ds_read_b128 v[190:193], v151 offset:33792
	ds_read_b128 v[194:197], v151 offset:34816
	ds_read_b128 v[198:201], v151 offset:35840
	ds_read_b128 v[202:205], v151 offset:36864
	ds_read_b128 v[206:209], v151 offset:37888
	ds_read_b128 v[210:213], v151 offset:38912
	ds_read_b128 v[214:217], v151 offset:39936
	global_load_lds_dwordx4 v[144:145], off
	v_lshl_add_u64 v[144:145], s[2:3], 0, v[134:135]
	s_mov_b32 m0, s34
	s_nop 0
	global_load_lds_dwordx4 v[144:145], off
	s_waitcnt vmcnt(8)
	s_waitcnt lgkmcnt(0)
	s_setprio 1
	s_barrier
	v_mfma_f32_16x16x32_bf16 v[126:129], v[152:155], v[186:189], v[126:129]
	v_mfma_f32_16x16x32_bf16 v[122:125], v[160:163], v[186:189], v[122:125]
	v_mfma_f32_16x16x32_bf16 v[114:117], v[152:155], v[194:197], v[114:117]
	v_mfma_f32_16x16x32_bf16 v[106:109], v[160:163], v[194:197], v[106:109]
	v_mfma_f32_16x16x32_bf16 v[98:101], v[152:155], v[202:205], v[98:101]
	v_mfma_f32_16x16x32_bf16 v[90:93], v[160:163], v[202:205], v[90:93]
	v_mfma_f32_16x16x32_bf16 v[82:85], v[152:155], v[210:213], v[82:85]
	v_mfma_f32_16x16x32_bf16 v[74:77], v[160:163], v[210:213], v[74:77]
	v_mfma_f32_16x16x32_bf16 v[126:129], v[156:159], v[190:193], v[126:129]
	v_mfma_f32_16x16x32_bf16 v[122:125], v[164:167], v[190:193], v[122:125]
	v_mfma_f32_16x16x32_bf16 v[114:117], v[156:159], v[198:201], v[114:117]
	v_mfma_f32_16x16x32_bf16 v[106:109], v[164:167], v[198:201], v[106:109]
	v_mfma_f32_16x16x32_bf16 v[98:101], v[156:159], v[206:209], v[98:101]
	v_mfma_f32_16x16x32_bf16 v[90:93], v[164:167], v[206:209], v[90:93]
	v_mfma_f32_16x16x32_bf16 v[82:85], v[156:159], v[214:217], v[82:85]
	v_mfma_f32_16x16x32_bf16 v[74:77], v[164:167], v[214:217], v[74:77]
	v_mfma_f32_16x16x32_bf16 v[118:121], v[168:171], v[186:189], v[118:121]
	v_mfma_f32_16x16x32_bf16 v[110:113], v[178:181], v[186:189], v[110:113]
	v_mfma_f32_16x16x32_bf16 v[102:105], v[168:171], v[194:197], v[102:105]
	v_mfma_f32_16x16x32_bf16 v[94:97], v[178:181], v[194:197], v[94:97]
	v_mfma_f32_16x16x32_bf16 v[86:89], v[168:171], v[202:205], v[86:89]
	v_mfma_f32_16x16x32_bf16 v[78:81], v[178:181], v[202:205], v[78:81]
	v_mfma_f32_16x16x32_bf16 v[70:73], v[168:171], v[210:213], v[70:73]
	v_mfma_f32_16x16x32_bf16 v[66:69], v[178:181], v[210:213], v[66:69]
	v_mfma_f32_16x16x32_bf16 v[118:121], v[172:175], v[190:193], v[118:121]
	v_mfma_f32_16x16x32_bf16 v[110:113], v[182:185], v[190:193], v[110:113]
	v_mfma_f32_16x16x32_bf16 v[102:105], v[172:175], v[198:201], v[102:105]
	v_mfma_f32_16x16x32_bf16 v[94:97], v[182:185], v[198:201], v[94:97]
	v_mfma_f32_16x16x32_bf16 v[86:89], v[172:175], v[206:209], v[86:89]
	v_mfma_f32_16x16x32_bf16 v[78:81], v[182:185], v[206:209], v[78:81]
	v_mfma_f32_16x16x32_bf16 v[70:73], v[172:175], v[214:217], v[70:73]
	v_mfma_f32_16x16x32_bf16 v[66:69], v[182:185], v[214:217], v[66:69]
	s_barrier
	s_setprio 0
	s_add_u32 s2, s22, 0x8000
	s_addc_u32 s3, s23, 0
	s_add_i32 s51, s51, s28
	v_lshl_add_u64 v[144:145], s[2:3], 0, v[132:133]
	s_mov_b32 m0, s51
	ds_read_b128 v[186:189], v151 offset:49152
	ds_read_b128 v[190:193], v151 offset:50176
	ds_read_b128 v[194:197], v151 offset:51200
	ds_read_b128 v[198:201], v151 offset:52224
	ds_read_b128 v[202:205], v151 offset:53248
	ds_read_b128 v[206:209], v151 offset:54272
	ds_read_b128 v[210:213], v151 offset:55296
	ds_read_b128 v[214:217], v151 offset:56320
	global_load_lds_dwordx4 v[144:145], off
	s_add_i32 m0, s51, 0x2000
	v_lshl_add_u64 v[144:145], s[2:3], 0, v[136:137]
	s_add_u32 s2, s22, 0xc000
	s_addc_u32 s3, s23, 0
	s_add_i32 s22, s52, s28
	global_load_lds_dwordx4 v[144:145], off
	v_lshl_add_u64 v[144:145], s[2:3], 0, v[132:133]
	s_mov_b32 m0, s22
	s_nop 0
	global_load_lds_dwordx4 v[144:145], off
	v_lshl_add_u64 v[144:145], s[2:3], 0, v[136:137]
	s_add_i32 m0, s22, 0x2000
	s_nop 0
	global_load_lds_dwordx4 v[144:145], off
	v_lshl_add_u64 v[144:145], s[20:21], 0, v[130:131]
	s_mov_b32 m0, s36
	s_nop 0
	global_load_lds_dwordx4 v[144:145], off
	v_lshl_add_u64 v[144:145], s[20:21], 0, v[134:135]
	s_mov_b32 m0, s37
	s_nop 0
	global_load_lds_dwordx4 v[144:145], off
	s_waitcnt vmcnt(8)
	s_waitcnt lgkmcnt(0)
	s_setprio 1
	s_barrier
	v_mfma_f32_16x16x32_bf16 v[62:65], v[152:155], v[186:189], v[62:65]
	v_mfma_f32_16x16x32_bf16 v[58:61], v[160:163], v[186:189], v[58:61]
	v_mfma_f32_16x16x32_bf16 v[50:53], v[152:155], v[194:197], v[50:53]
	v_mfma_f32_16x16x32_bf16 v[42:45], v[160:163], v[194:197], v[42:45]
	v_mfma_f32_16x16x32_bf16 v[34:37], v[152:155], v[202:205], v[34:37]
	v_mfma_f32_16x16x32_bf16 v[26:29], v[160:163], v[202:205], v[26:29]
	v_mfma_f32_16x16x32_bf16 v[18:21], v[152:155], v[210:213], v[18:21]
	v_mfma_f32_16x16x32_bf16 v[10:13], v[160:163], v[210:213], v[10:13]
	v_mfma_f32_16x16x32_bf16 v[62:65], v[156:159], v[190:193], v[62:65]
	v_mfma_f32_16x16x32_bf16 v[58:61], v[164:167], v[190:193], v[58:61]
	v_mfma_f32_16x16x32_bf16 v[50:53], v[156:159], v[198:201], v[50:53]
	v_mfma_f32_16x16x32_bf16 v[42:45], v[164:167], v[198:201], v[42:45]
	v_mfma_f32_16x16x32_bf16 v[34:37], v[156:159], v[206:209], v[34:37]
	v_mfma_f32_16x16x32_bf16 v[26:29], v[164:167], v[206:209], v[26:29]
	v_mfma_f32_16x16x32_bf16 v[18:21], v[156:159], v[214:217], v[18:21]
	v_mfma_f32_16x16x32_bf16 v[10:13], v[164:167], v[214:217], v[10:13]
	v_mfma_f32_16x16x32_bf16 v[54:57], v[168:171], v[186:189], v[54:57]
	v_mfma_f32_16x16x32_bf16 v[46:49], v[178:181], v[186:189], v[46:49]
	v_mfma_f32_16x16x32_bf16 v[38:41], v[168:171], v[194:197], v[38:41]
	v_mfma_f32_16x16x32_bf16 v[30:33], v[178:181], v[194:197], v[30:33]
	v_mfma_f32_16x16x32_bf16 v[22:25], v[168:171], v[202:205], v[22:25]
	v_mfma_f32_16x16x32_bf16 v[14:17], v[178:181], v[202:205], v[14:17]
	v_mfma_f32_16x16x32_bf16 v[6:9], v[168:171], v[210:213], v[6:9]
	v_mfma_f32_16x16x32_bf16 v[2:5], v[178:181], v[210:213], v[2:5]
	v_mfma_f32_16x16x32_bf16 v[54:57], v[172:175], v[190:193], v[54:57]
	v_mfma_f32_16x16x32_bf16 v[46:49], v[182:185], v[190:193], v[46:49]
	v_mfma_f32_16x16x32_bf16 v[38:41], v[172:175], v[198:201], v[38:41]
	v_mfma_f32_16x16x32_bf16 v[30:33], v[182:185], v[198:201], v[30:33]
	v_mfma_f32_16x16x32_bf16 v[22:25], v[172:175], v[206:209], v[22:25]
	v_mfma_f32_16x16x32_bf16 v[14:17], v[182:185], v[206:209], v[14:17]
	v_mfma_f32_16x16x32_bf16 v[6:9], v[172:175], v[214:217], v[6:9]
	v_mfma_f32_16x16x32_bf16 v[2:5], v[182:185], v[214:217], v[2:5]
	s_barrier
	s_setprio 0
	s_add_i32 s50, s50, 2
	s_add_u32 s18, s18, 0x10000
	s_addc_u32 s19, s19, 0
	s_add_u32 s48, s48, 0x10000
	s_addc_u32 s49, s49, 0
	s_cmp_gt_u32 s50, 41
	s_cbranch_scc0 .LBB0_495
	s_branch .Lpk495_exit
.LBB0_495:
	ds_read_b128 v[152:155], v149
	ds_read_b128 v[156:159], v149 offset:1024
	ds_read_b128 v[160:163], v149 offset:2048
	ds_read_b128 v[164:167], v149 offset:3072
	ds_read_b128 v[168:171], v150
	ds_read_b128 v[172:175], v150 offset:1024
	ds_read_b128 v[178:181], v150 offset:2048
	ds_read_b128 v[182:185], v150 offset:3072
	s_add_u32 s2, s18, 0x4000
	s_addc_u32 s3, s19, 0
	s_cmp_eq_u32 s50, 40
	s_cselect_b32 s2, s45, s2
	s_cselect_b32 s3, s44, s3
	s_cselect_b32 s23, s46, s49
	s_cselect_b32 s22, s47, s48
	s_add_u32 s20, s2, 0x8000
	s_addc_u32 s21, s3, 0
	v_lshl_add_u64 v[144:145], s[18:19], 0, v[138:139]
	s_add_i32 m0, s29, 0xc000
	ds_read_b128 v[186:189], v151
	ds_read_b128 v[190:193], v151 offset:1024
	ds_read_b128 v[194:197], v151 offset:2048
	ds_read_b128 v[198:201], v151 offset:3072
	ds_read_b128 v[202:205], v151 offset:4096
	ds_read_b128 v[206:209], v151 offset:5120
	ds_read_b128 v[210:213], v151 offset:6144
	ds_read_b128 v[214:217], v151 offset:7168
	global_load_lds_dwordx4 v[144:145], off
	v_lshl_add_u64 v[144:145], s[18:19], 0, v[140:141]
	s_add_i32 m0, s29, 0xe000
	s_nop 0
	global_load_lds_dwordx4 v[144:145], off
	s_waitcnt vmcnt(8)
	s_waitcnt lgkmcnt(0)
	s_setprio 1
	s_barrier
	v_mfma_f32_16x16x32_bf16 v[126:129], v[152:155], v[186:189], v[126:129]
	v_mfma_f32_16x16x32_bf16 v[122:125], v[160:163], v[186:189], v[122:125]
	v_mfma_f32_16x16x32_bf16 v[114:117], v[152:155], v[194:197], v[114:117]
	v_mfma_f32_16x16x32_bf16 v[106:109], v[160:163], v[194:197], v[106:109]
	v_mfma_f32_16x16x32_bf16 v[98:101], v[152:155], v[202:205], v[98:101]
	v_mfma_f32_16x16x32_bf16 v[90:93], v[160:163], v[202:205], v[90:93]
	v_mfma_f32_16x16x32_bf16 v[82:85], v[152:155], v[210:213], v[82:85]
	v_mfma_f32_16x16x32_bf16 v[74:77], v[160:163], v[210:213], v[74:77]
	v_mfma_f32_16x16x32_bf16 v[126:129], v[156:159], v[190:193], v[126:129]
	v_mfma_f32_16x16x32_bf16 v[122:125], v[164:167], v[190:193], v[122:125]
	v_mfma_f32_16x16x32_bf16 v[114:117], v[156:159], v[198:201], v[114:117]
	v_mfma_f32_16x16x32_bf16 v[106:109], v[164:167], v[198:201], v[106:109]
	v_mfma_f32_16x16x32_bf16 v[98:101], v[156:159], v[206:209], v[98:101]
	v_mfma_f32_16x16x32_bf16 v[90:93], v[164:167], v[206:209], v[90:93]
	v_mfma_f32_16x16x32_bf16 v[82:85], v[156:159], v[214:217], v[82:85]
	v_mfma_f32_16x16x32_bf16 v[74:77], v[164:167], v[214:217], v[74:77]
	v_mfma_f32_16x16x32_bf16 v[118:121], v[168:171], v[186:189], v[118:121]
	v_mfma_f32_16x16x32_bf16 v[110:113], v[178:181], v[186:189], v[110:113]
	v_mfma_f32_16x16x32_bf16 v[102:105], v[168:171], v[194:197], v[102:105]
	v_mfma_f32_16x16x32_bf16 v[94:97], v[178:181], v[194:197], v[94:97]
	v_mfma_f32_16x16x32_bf16 v[86:89], v[168:171], v[202:205], v[86:89]
	v_mfma_f32_16x16x32_bf16 v[78:81], v[178:181], v[202:205], v[78:81]
	v_mfma_f32_16x16x32_bf16 v[70:73], v[168:171], v[210:213], v[70:73]
	v_mfma_f32_16x16x32_bf16 v[66:69], v[178:181], v[210:213], v[66:69]
	v_mfma_f32_16x16x32_bf16 v[118:121], v[172:175], v[190:193], v[118:121]
	v_mfma_f32_16x16x32_bf16 v[110:113], v[182:185], v[190:193], v[110:113]
	v_mfma_f32_16x16x32_bf16 v[102:105], v[172:175], v[198:201], v[102:105]
	v_mfma_f32_16x16x32_bf16 v[94:97], v[182:185], v[198:201], v[94:97]
	v_mfma_f32_16x16x32_bf16 v[86:89], v[172:175], v[206:209], v[86:89]
	v_mfma_f32_16x16x32_bf16 v[78:81], v[182:185], v[206:209], v[78:81]
	v_mfma_f32_16x16x32_bf16 v[70:73], v[172:175], v[214:217], v[70:73]
	v_mfma_f32_16x16x32_bf16 v[66:69], v[182:185], v[214:217], v[66:69]
	s_barrier
	s_setprio 0
	s_add_i32 s51, s38, s28
	v_lshl_add_u64 v[144:145], s[22:23], 0, v[132:133]
	s_mov_b32 m0, s51
	ds_read_b128 v[186:189], v151 offset:16384
	ds_read_b128 v[190:193], v151 offset:17408
	ds_read_b128 v[194:197], v151 offset:18432
	ds_read_b128 v[198:201], v151 offset:19456
	ds_read_b128 v[202:205], v151 offset:20480
	ds_read_b128 v[206:209], v151 offset:21504
	ds_read_b128 v[210:213], v151 offset:22528
	ds_read_b128 v[214:217], v151 offset:23552
	global_load_lds_dwordx4 v[144:145], off
	s_add_i32 m0, s51, 0x2000
	s_add_u32 s52, s22, 0x4000
	v_lshl_add_u64 v[144:145], s[22:23], 0, v[136:137]
	s_addc_u32 s53, s23, 0
	s_add_i32 s51, s39, s28
	global_load_lds_dwordx4 v[144:145], off
	v_lshl_add_u64 v[144:145], s[52:53], 0, v[132:133]
	s_mov_b32 m0, s51
	s_nop 0
	global_load_lds_dwordx4 v[144:145], off
	v_lshl_add_u64 v[144:145], s[52:53], 0, v[136:137]
	s_add_i32 m0, s51, 0x2000
	s_nop 0
	global_load_lds_dwordx4 v[144:145], off
	v_lshl_add_u64 v[144:145], s[2:3], 0, v[130:131]
	s_mov_b32 m0, s29
	s_nop 0
	global_load_lds_dwordx4 v[144:145], off
	v_lshl_add_u64 v[144:145], s[2:3], 0, v[134:135]
	s_mov_b32 m0, s30
	s_nop 0
	global_load_lds_dwordx4 v[144:145], off
	s_waitcnt vmcnt(8)
	s_waitcnt lgkmcnt(0)
	s_setprio 1
	s_barrier
	v_mfma_f32_16x16x32_bf16 v[62:65], v[152:155], v[186:189], v[62:65]
	v_mfma_f32_16x16x32_bf16 v[58:61], v[160:163], v[186:189], v[58:61]
	v_mfma_f32_16x16x32_bf16 v[50:53], v[152:155], v[194:197], v[50:53]
	v_mfma_f32_16x16x32_bf16 v[42:45], v[160:163], v[194:197], v[42:45]
	v_mfma_f32_16x16x32_bf16 v[34:37], v[152:155], v[202:205], v[34:37]
	v_mfma_f32_16x16x32_bf16 v[26:29], v[160:163], v[202:205], v[26:29]
	v_mfma_f32_16x16x32_bf16 v[18:21], v[152:155], v[210:213], v[18:21]
	v_mfma_f32_16x16x32_bf16 v[10:13], v[160:163], v[210:213], v[10:13]
	v_mfma_f32_16x16x32_bf16 v[62:65], v[156:159], v[190:193], v[62:65]
	v_mfma_f32_16x16x32_bf16 v[58:61], v[164:167], v[190:193], v[58:61]
	v_mfma_f32_16x16x32_bf16 v[50:53], v[156:159], v[198:201], v[50:53]
	v_mfma_f32_16x16x32_bf16 v[42:45], v[164:167], v[198:201], v[42:45]
	v_mfma_f32_16x16x32_bf16 v[34:37], v[156:159], v[206:209], v[34:37]
	v_mfma_f32_16x16x32_bf16 v[26:29], v[164:167], v[206:209], v[26:29]
	v_mfma_f32_16x16x32_bf16 v[18:21], v[156:159], v[214:217], v[18:21]
	v_mfma_f32_16x16x32_bf16 v[10:13], v[164:167], v[214:217], v[10:13]
	v_mfma_f32_16x16x32_bf16 v[54:57], v[168:171], v[186:189], v[54:57]
	v_mfma_f32_16x16x32_bf16 v[46:49], v[178:181], v[186:189], v[46:49]
	v_mfma_f32_16x16x32_bf16 v[38:41], v[168:171], v[194:197], v[38:41]
	v_mfma_f32_16x16x32_bf16 v[30:33], v[178:181], v[194:197], v[30:33]
	v_mfma_f32_16x16x32_bf16 v[22:25], v[168:171], v[202:205], v[22:25]
	v_mfma_f32_16x16x32_bf16 v[14:17], v[178:181], v[202:205], v[14:17]
	v_mfma_f32_16x16x32_bf16 v[6:9], v[168:171], v[210:213], v[6:9]
	v_mfma_f32_16x16x32_bf16 v[2:5], v[178:181], v[210:213], v[2:5]
	v_mfma_f32_16x16x32_bf16 v[54:57], v[172:175], v[190:193], v[54:57]
	v_mfma_f32_16x16x32_bf16 v[46:49], v[182:185], v[190:193], v[46:49]
	v_mfma_f32_16x16x32_bf16 v[38:41], v[172:175], v[198:201], v[38:41]
	v_mfma_f32_16x16x32_bf16 v[30:33], v[182:185], v[198:201], v[30:33]
	v_mfma_f32_16x16x32_bf16 v[22:25], v[172:175], v[206:209], v[22:25]
	v_mfma_f32_16x16x32_bf16 v[14:17], v[182:185], v[206:209], v[14:17]
	v_mfma_f32_16x16x32_bf16 v[6:9], v[172:175], v[214:217], v[6:9]
	v_mfma_f32_16x16x32_bf16 v[2:5], v[182:185], v[214:217], v[2:5]
	s_barrier
	s_setprio 0
	s_add_i32 s51, 0, 0x18000
	v_add_u32_e32 v144, s51, v147
	s_add_i32 s52, 0, 0x1c000
	ds_read_b128 v[152:155], v144
	ds_read_b128 v[156:159], v144 offset:1024
	ds_read_b128 v[160:163], v144 offset:2048
	ds_read_b128 v[164:167], v144 offset:3072
	v_add_u32_e32 v144, s52, v147
	ds_read_b128 v[168:171], v144
	ds_read_b128 v[172:175], v144 offset:1024
	ds_read_b128 v[178:181], v144 offset:2048
	ds_read_b128 v[182:185], v144 offset:3072
	s_add_u32 s2, s2, 0x4000
	s_addc_u32 s3, s3, 0
	s_mov_b32 m0, s31
	v_lshl_add_u64 v[144:145], s[2:3], 0, v[130:131]
	ds_read_b128 v[186:189], v151 offset:32768
	ds_read_b128 v[190:193], v151 offset:33792
	ds_read_b128 v[194:197], v151 offset:34816
	ds_read_b128 v[198:201], v151 offset:35840
	ds_read_b128 v[202:205], v151 offset:36864
	ds_read_b128 v[206:209], v151 offset:37888
	ds_read_b128 v[210:213], v151 offset:38912
	ds_read_b128 v[214:217], v151 offset:39936
	global_load_lds_dwordx4 v[144:145], off
	v_lshl_add_u64 v[144:145], s[2:3], 0, v[134:135]
	s_mov_b32 m0, s34
	s_nop 0
	global_load_lds_dwordx4 v[144:145], off
	s_waitcnt vmcnt(8)
	s_waitcnt lgkmcnt(0)
	s_setprio 1
	s_barrier
	v_mfma_f32_16x16x32_bf16 v[126:129], v[152:155], v[186:189], v[126:129]
	v_mfma_f32_16x16x32_bf16 v[122:125], v[160:163], v[186:189], v[122:125]
	v_mfma_f32_16x16x32_bf16 v[114:117], v[152:155], v[194:197], v[114:117]
	v_mfma_f32_16x16x32_bf16 v[106:109], v[160:163], v[194:197], v[106:109]
	v_mfma_f32_16x16x32_bf16 v[98:101], v[152:155], v[202:205], v[98:101]
	v_mfma_f32_16x16x32_bf16 v[90:93], v[160:163], v[202:205], v[90:93]
	v_mfma_f32_16x16x32_bf16 v[82:85], v[152:155], v[210:213], v[82:85]
	v_mfma_f32_16x16x32_bf16 v[74:77], v[160:163], v[210:213], v[74:77]
	v_mfma_f32_16x16x32_bf16 v[126:129], v[156:159], v[190:193], v[126:129]
	v_mfma_f32_16x16x32_bf16 v[122:125], v[164:167], v[190:193], v[122:125]
	v_mfma_f32_16x16x32_bf16 v[114:117], v[156:159], v[198:201], v[114:117]
	v_mfma_f32_16x16x32_bf16 v[106:109], v[164:167], v[198:201], v[106:109]
	v_mfma_f32_16x16x32_bf16 v[98:101], v[156:159], v[206:209], v[98:101]
	v_mfma_f32_16x16x32_bf16 v[90:93], v[164:167], v[206:209], v[90:93]
	v_mfma_f32_16x16x32_bf16 v[82:85], v[156:159], v[214:217], v[82:85]
	v_mfma_f32_16x16x32_bf16 v[74:77], v[164:167], v[214:217], v[74:77]
	v_mfma_f32_16x16x32_bf16 v[118:121], v[168:171], v[186:189], v[118:121]
	v_mfma_f32_16x16x32_bf16 v[110:113], v[178:181], v[186:189], v[110:113]
	v_mfma_f32_16x16x32_bf16 v[102:105], v[168:171], v[194:197], v[102:105]
	v_mfma_f32_16x16x32_bf16 v[94:97], v[178:181], v[194:197], v[94:97]
	v_mfma_f32_16x16x32_bf16 v[86:89], v[168:171], v[202:205], v[86:89]
	v_mfma_f32_16x16x32_bf16 v[78:81], v[178:181], v[202:205], v[78:81]
	v_mfma_f32_16x16x32_bf16 v[70:73], v[168:171], v[210:213], v[70:73]
	v_mfma_f32_16x16x32_bf16 v[66:69], v[178:181], v[210:213], v[66:69]
	v_mfma_f32_16x16x32_bf16 v[118:121], v[172:175], v[190:193], v[118:121]
	v_mfma_f32_16x16x32_bf16 v[110:113], v[182:185], v[190:193], v[110:113]
	v_mfma_f32_16x16x32_bf16 v[102:105], v[172:175], v[198:201], v[102:105]
	v_mfma_f32_16x16x32_bf16 v[94:97], v[182:185], v[198:201], v[94:97]
	v_mfma_f32_16x16x32_bf16 v[86:89], v[172:175], v[206:209], v[86:89]
	v_mfma_f32_16x16x32_bf16 v[78:81], v[182:185], v[206:209], v[78:81]
	v_mfma_f32_16x16x32_bf16 v[70:73], v[172:175], v[214:217], v[70:73]
	v_mfma_f32_16x16x32_bf16 v[66:69], v[182:185], v[214:217], v[66:69]
	s_barrier
	s_setprio 0
	s_add_u32 s2, s22, 0x8000
	s_addc_u32 s3, s23, 0
	s_add_i32 s51, s51, s28
	v_lshl_add_u64 v[144:145], s[2:3], 0, v[132:133]
	s_mov_b32 m0, s51
	ds_read_b128 v[186:189], v151 offset:49152
	ds_read_b128 v[190:193], v151 offset:50176
	ds_read_b128 v[194:197], v151 offset:51200
	ds_read_b128 v[198:201], v151 offset:52224
	ds_read_b128 v[202:205], v151 offset:53248
	ds_read_b128 v[206:209], v151 offset:54272
	ds_read_b128 v[210:213], v151 offset:55296
	ds_read_b128 v[214:217], v151 offset:56320
	global_load_lds_dwordx4 v[144:145], off
	s_add_i32 m0, s51, 0x2000
	v_lshl_add_u64 v[144:145], s[2:3], 0, v[136:137]
	s_add_u32 s2, s22, 0xc000
	s_addc_u32 s3, s23, 0
	s_add_i32 s22, s52, s28
	global_load_lds_dwordx4 v[144:145], off
	v_lshl_add_u64 v[144:145], s[2:3], 0, v[132:133]
	s_mov_b32 m0, s22
	s_nop 0
	global_load_lds_dwordx4 v[144:145], off
	v_lshl_add_u64 v[144:145], s[2:3], 0, v[136:137]
	s_add_i32 m0, s22, 0x2000
	s_nop 0
	global_load_lds_dwordx4 v[144:145], off
	v_lshl_add_u64 v[144:145], s[20:21], 0, v[130:131]
	s_mov_b32 m0, s36
	s_nop 0
	global_load_lds_dwordx4 v[144:145], off
	v_lshl_add_u64 v[144:145], s[20:21], 0, v[134:135]
	s_mov_b32 m0, s37
	s_nop 0
	global_load_lds_dwordx4 v[144:145], off
	s_waitcnt vmcnt(8)
	s_waitcnt lgkmcnt(0)
	s_setprio 1
	s_barrier
	v_mfma_f32_16x16x32_bf16 v[62:65], v[152:155], v[186:189], v[62:65]
	v_mfma_f32_16x16x32_bf16 v[58:61], v[160:163], v[186:189], v[58:61]
	v_mfma_f32_16x16x32_bf16 v[50:53], v[152:155], v[194:197], v[50:53]
	v_mfma_f32_16x16x32_bf16 v[42:45], v[160:163], v[194:197], v[42:45]
	v_mfma_f32_16x16x32_bf16 v[34:37], v[152:155], v[202:205], v[34:37]
	v_mfma_f32_16x16x32_bf16 v[26:29], v[160:163], v[202:205], v[26:29]
	v_mfma_f32_16x16x32_bf16 v[18:21], v[152:155], v[210:213], v[18:21]
	v_mfma_f32_16x16x32_bf16 v[10:13], v[160:163], v[210:213], v[10:13]
	v_mfma_f32_16x16x32_bf16 v[62:65], v[156:159], v[190:193], v[62:65]
	v_mfma_f32_16x16x32_bf16 v[58:61], v[164:167], v[190:193], v[58:61]
	v_mfma_f32_16x16x32_bf16 v[50:53], v[156:159], v[198:201], v[50:53]
	v_mfma_f32_16x16x32_bf16 v[42:45], v[164:167], v[198:201], v[42:45]
	v_mfma_f32_16x16x32_bf16 v[34:37], v[156:159], v[206:209], v[34:37]
	v_mfma_f32_16x16x32_bf16 v[26:29], v[164:167], v[206:209], v[26:29]
	v_mfma_f32_16x16x32_bf16 v[18:21], v[156:159], v[214:217], v[18:21]
	v_mfma_f32_16x16x32_bf16 v[10:13], v[164:167], v[214:217], v[10:13]
	v_mfma_f32_16x16x32_bf16 v[54:57], v[168:171], v[186:189], v[54:57]
	v_mfma_f32_16x16x32_bf16 v[46:49], v[178:181], v[186:189], v[46:49]
	v_mfma_f32_16x16x32_bf16 v[38:41], v[168:171], v[194:197], v[38:41]
	v_mfma_f32_16x16x32_bf16 v[30:33], v[178:181], v[194:197], v[30:33]
	v_mfma_f32_16x16x32_bf16 v[22:25], v[168:171], v[202:205], v[22:25]
	v_mfma_f32_16x16x32_bf16 v[14:17], v[178:181], v[202:205], v[14:17]
	v_mfma_f32_16x16x32_bf16 v[6:9], v[168:171], v[210:213], v[6:9]
	v_mfma_f32_16x16x32_bf16 v[2:5], v[178:181], v[210:213], v[2:5]
	v_mfma_f32_16x16x32_bf16 v[54:57], v[172:175], v[190:193], v[54:57]
	v_mfma_f32_16x16x32_bf16 v[46:49], v[182:185], v[190:193], v[46:49]
	v_mfma_f32_16x16x32_bf16 v[38:41], v[172:175], v[198:201], v[38:41]
	v_mfma_f32_16x16x32_bf16 v[30:33], v[182:185], v[198:201], v[30:33]
	v_mfma_f32_16x16x32_bf16 v[22:25], v[172:175], v[206:209], v[22:25]
	v_mfma_f32_16x16x32_bf16 v[14:17], v[182:185], v[206:209], v[14:17]
	v_mfma_f32_16x16x32_bf16 v[6:9], v[172:175], v[214:217], v[6:9]
	v_mfma_f32_16x16x32_bf16 v[2:5], v[182:185], v[214:217], v[2:5]
	s_barrier
	s_setprio 0
	s_add_i32 s50, s50, 2
	s_add_u32 s18, s18, 0x10000
	s_addc_u32 s19, s19, 0
	s_add_u32 s48, s48, 0x10000
	s_addc_u32 s49, s49, 0
	s_cmp_gt_u32 s50, 41
	s_cbranch_scc0 .LBB0_495

.Lpk555_peel:
	ds_read_b128 v[154:157], v151
	ds_read_b128 v[158:161], v151 offset:1024
	ds_read_b128 v[162:165], v151 offset:2048
	ds_read_b128 v[166:169], v151 offset:3072
	ds_read_b128 v[170:173], v152
	ds_read_b128 v[178:181], v152 offset:1024
	ds_read_b128 v[182:185], v152 offset:2048
	ds_read_b128 v[186:189], v152 offset:3072
	s_add_u32 s2, s26, 0xfffc0080
	s_addc_u32 s3, s27, -1
	s_cmp_eq_u32 s52, 12
	s_cselect_b32 s3, s11, s3
	s_cselect_b32 s2, s13, s2
	s_cselect_b32 s29, s48, s51
	s_cselect_b32 s28, s49, s50
	v_lshl_add_u64 v[144:145], s[26:27], 0, v[138:139]
	s_add_i32 m0, s37, 0xc000
	ds_read_b128 v[190:193], v153
	ds_read_b128 v[194:197], v153 offset:1024
	ds_read_b128 v[198:201], v153 offset:2048
	ds_read_b128 v[202:205], v153 offset:3072
	ds_read_b128 v[206:209], v153 offset:4096
	ds_read_b128 v[210:213], v153 offset:5120
	ds_read_b128 v[214:217], v153 offset:6144
	ds_read_b128 v[218:221], v153 offset:7168
	global_load_lds_dwordx4 v[144:145], off
	v_lshl_add_u64 v[144:145], s[26:27], 0, v[140:141]
	s_add_i32 m0, s37, 0xe000
	s_nop 0
	global_load_lds_dwordx4 v[144:145], off
	s_waitcnt vmcnt(8)
	s_waitcnt lgkmcnt(0)
	s_setprio 1
	s_barrier
	v_mfma_f32_16x16x32_bf16 v[126:129], v[154:157], v[190:193], 0
	v_mfma_f32_16x16x32_bf16 v[122:125], v[162:165], v[190:193], 0
	v_mfma_f32_16x16x32_bf16 v[114:117], v[154:157], v[198:201], 0
	v_mfma_f32_16x16x32_bf16 v[106:109], v[162:165], v[198:201], 0
	v_mfma_f32_16x16x32_bf16 v[98:101], v[154:157], v[206:209], 0
	v_mfma_f32_16x16x32_bf16 v[90:93], v[162:165], v[206:209], 0
	v_mfma_f32_16x16x32_bf16 v[82:85], v[154:157], v[214:217], 0
	v_mfma_f32_16x16x32_bf16 v[74:77], v[162:165], v[214:217], 0
	v_mfma_f32_16x16x32_bf16 v[126:129], v[158:161], v[194:197], v[126:129]
	v_mfma_f32_16x16x32_bf16 v[122:125], v[166:169], v[194:197], v[122:125]
	v_mfma_f32_16x16x32_bf16 v[114:117], v[158:161], v[202:205], v[114:117]
	v_mfma_f32_16x16x32_bf16 v[106:109], v[166:169], v[202:205], v[106:109]
	v_mfma_f32_16x16x32_bf16 v[98:101], v[158:161], v[210:213], v[98:101]
	v_mfma_f32_16x16x32_bf16 v[90:93], v[166:169], v[210:213], v[90:93]
	v_mfma_f32_16x16x32_bf16 v[82:85], v[158:161], v[218:221], v[82:85]
	v_mfma_f32_16x16x32_bf16 v[74:77], v[166:169], v[218:221], v[74:77]
	v_mfma_f32_16x16x32_bf16 v[118:121], v[170:173], v[190:193], 0
	v_mfma_f32_16x16x32_bf16 v[110:113], v[182:185], v[190:193], 0
	v_mfma_f32_16x16x32_bf16 v[102:105], v[170:173], v[198:201], 0
	v_mfma_f32_16x16x32_bf16 v[94:97], v[182:185], v[198:201], 0
	v_mfma_f32_16x16x32_bf16 v[86:89], v[170:173], v[206:209], 0
	v_mfma_f32_16x16x32_bf16 v[78:81], v[182:185], v[206:209], 0
	v_mfma_f32_16x16x32_bf16 v[70:73], v[170:173], v[214:217], 0
	v_mfma_f32_16x16x32_bf16 v[66:69], v[182:185], v[214:217], 0
	v_mfma_f32_16x16x32_bf16 v[118:121], v[178:181], v[194:197], v[118:121]
	v_mfma_f32_16x16x32_bf16 v[110:113], v[186:189], v[194:197], v[110:113]
	v_mfma_f32_16x16x32_bf16 v[102:105], v[178:181], v[202:205], v[102:105]
	v_mfma_f32_16x16x32_bf16 v[94:97], v[186:189], v[202:205], v[94:97]
	v_mfma_f32_16x16x32_bf16 v[86:89], v[178:181], v[210:213], v[86:89]
	v_mfma_f32_16x16x32_bf16 v[78:81], v[186:189], v[210:213], v[78:81]
	v_mfma_f32_16x16x32_bf16 v[70:73], v[178:181], v[218:221], v[70:73]
	v_mfma_f32_16x16x32_bf16 v[66:69], v[186:189], v[218:221], v[66:69]
	s_barrier
	s_setprio 0
	s_add_i32 s53, s44, s34
	v_lshl_add_u64 v[144:145], s[28:29], 0, v[134:135]
	s_mov_b32 m0, s53
	ds_read_b128 v[190:193], v153 offset:16384
	ds_read_b128 v[194:197], v153 offset:17408
	ds_read_b128 v[198:201], v153 offset:18432
	ds_read_b128 v[202:205], v153 offset:19456
	ds_read_b128 v[206:209], v153 offset:20480
	ds_read_b128 v[210:213], v153 offset:21504
	ds_read_b128 v[214:217], v153 offset:22528
	ds_read_b128 v[218:221], v153 offset:23552
	global_load_lds_dwordx4 v[144:145], off
	s_add_i32 m0, s53, 0x2000
	s_add_u32 s54, s28, 0x40000
	v_lshl_add_u64 v[174:175], s[28:29], 0, v[130:131]
	s_addc_u32 s55, s29, 0
	s_add_i32 s53, s45, s34
	global_load_lds_dwordx4 v[174:175], off
	v_lshl_add_u64 v[222:223], s[54:55], 0, v[134:135]
	s_mov_b32 m0, s53
	v_lshl_add_u64 v[224:225], s[2:3], 0, v[132:133]
	global_load_lds_dwordx4 v[222:223], off
	v_lshl_add_u64 v[222:223], s[54:55], 0, v[130:131]
	s_add_i32 m0, s53, 0x2000
	s_nop 0
	global_load_lds_dwordx4 v[222:223], off
	v_lshl_add_u64 v[222:223], s[2:3], 0, v[136:137]
	s_mov_b32 m0, s37
	s_nop 0
	global_load_lds_dwordx4 v[222:223], off
	s_mov_b32 m0, s25
	s_nop 0
	global_load_lds_dwordx4 v[224:225], off
	s_waitcnt vmcnt(8)
	s_waitcnt lgkmcnt(0)
	s_setprio 1
	s_barrier
	v_mfma_f32_16x16x32_bf16 v[62:65], v[154:157], v[190:193], 0
	v_mfma_f32_16x16x32_bf16 v[58:61], v[162:165], v[190:193], 0
	v_mfma_f32_16x16x32_bf16 v[50:53], v[154:157], v[198:201], 0
	v_mfma_f32_16x16x32_bf16 v[42:45], v[162:165], v[198:201], 0
	v_mfma_f32_16x16x32_bf16 v[34:37], v[154:157], v[206:209], 0
	v_mfma_f32_16x16x32_bf16 v[26:29], v[162:165], v[206:209], 0
	v_mfma_f32_16x16x32_bf16 v[18:21], v[154:157], v[214:217], 0
	v_mfma_f32_16x16x32_bf16 v[10:13], v[162:165], v[214:217], 0
	v_mfma_f32_16x16x32_bf16 v[62:65], v[158:161], v[194:197], v[62:65]
	v_mfma_f32_16x16x32_bf16 v[58:61], v[166:169], v[194:197], v[58:61]
	v_mfma_f32_16x16x32_bf16 v[50:53], v[158:161], v[202:205], v[50:53]
	v_mfma_f32_16x16x32_bf16 v[42:45], v[166:169], v[202:205], v[42:45]
	v_mfma_f32_16x16x32_bf16 v[34:37], v[158:161], v[210:213], v[34:37]
	v_mfma_f32_16x16x32_bf16 v[26:29], v[166:169], v[210:213], v[26:29]
	v_mfma_f32_16x16x32_bf16 v[18:21], v[158:161], v[218:221], v[18:21]
	v_mfma_f32_16x16x32_bf16 v[10:13], v[166:169], v[218:221], v[10:13]
	v_mfma_f32_16x16x32_bf16 v[54:57], v[170:173], v[190:193], 0
	v_mfma_f32_16x16x32_bf16 v[46:49], v[182:185], v[190:193], 0
	v_mfma_f32_16x16x32_bf16 v[38:41], v[170:173], v[198:201], 0
	v_mfma_f32_16x16x32_bf16 v[30:33], v[182:185], v[198:201], 0
	v_mfma_f32_16x16x32_bf16 v[22:25], v[170:173], v[206:209], 0
	v_mfma_f32_16x16x32_bf16 v[14:17], v[182:185], v[206:209], 0
	v_mfma_f32_16x16x32_bf16 v[6:9], v[170:173], v[214:217], 0
	v_mfma_f32_16x16x32_bf16 v[2:5], v[182:185], v[214:217], 0
	v_mfma_f32_16x16x32_bf16 v[54:57], v[178:181], v[194:197], v[54:57]
	v_mfma_f32_16x16x32_bf16 v[46:49], v[186:189], v[194:197], v[46:49]
	v_mfma_f32_16x16x32_bf16 v[38:41], v[178:181], v[202:205], v[38:41]
	v_mfma_f32_16x16x32_bf16 v[30:33], v[186:189], v[202:205], v[30:33]
	v_mfma_f32_16x16x32_bf16 v[22:25], v[178:181], v[210:213], v[22:25]
	v_mfma_f32_16x16x32_bf16 v[14:17], v[186:189], v[210:213], v[14:17]
	v_mfma_f32_16x16x32_bf16 v[6:9], v[178:181], v[218:221], v[6:9]
	v_mfma_f32_16x16x32_bf16 v[2:5], v[186:189], v[218:221], v[2:5]
	s_barrier
	s_setprio 0
	s_add_i32 s53, 0, 0x18000
	s_add_i32 s54, 0, 0x1c000
	v_add_u32_e32 v166, s53, v149
	v_add_u32_e32 v176, s54, v149
	ds_read_b128 v[154:157], v166
	ds_read_b128 v[158:161], v166 offset:1024
	ds_read_b128 v[162:165], v166 offset:2048
	ds_read_b128 v[166:169], v166 offset:3072
	ds_read_b128 v[170:173], v176
	ds_read_b128 v[178:181], v176 offset:1024
	ds_read_b128 v[182:185], v176 offset:2048
	ds_read_b128 v[186:189], v176 offset:3072
	s_add_u32 s2, s2, 0x40000
	s_addc_u32 s3, s3, 0
	s_mov_b32 m0, s38
	v_lshl_add_u64 v[226:227], s[2:3], 0, v[136:137]
	ds_read_b128 v[190:193], v153 offset:32768
	ds_read_b128 v[194:197], v153 offset:33792
	ds_read_b128 v[198:201], v153 offset:34816
	ds_read_b128 v[202:205], v153 offset:35840
	ds_read_b128 v[206:209], v153 offset:36864
	ds_read_b128 v[210:213], v153 offset:37888
	ds_read_b128 v[214:217], v153 offset:38912
	ds_read_b128 v[218:221], v153 offset:39936
	global_load_lds_dwordx4 v[226:227], off
	v_lshl_add_u64 v[226:227], s[2:3], 0, v[132:133]
	s_mov_b32 m0, s39
	s_nop 0
	global_load_lds_dwordx4 v[226:227], off
	s_waitcnt vmcnt(8)
	s_waitcnt lgkmcnt(0)
	s_setprio 1
	s_barrier
	v_mfma_f32_16x16x32_bf16 v[126:129], v[154:157], v[190:193], v[126:129]
	v_mfma_f32_16x16x32_bf16 v[122:125], v[162:165], v[190:193], v[122:125]
	v_mfma_f32_16x16x32_bf16 v[114:117], v[154:157], v[198:201], v[114:117]
	v_mfma_f32_16x16x32_bf16 v[106:109], v[162:165], v[198:201], v[106:109]
	v_mfma_f32_16x16x32_bf16 v[98:101], v[154:157], v[206:209], v[98:101]
	v_mfma_f32_16x16x32_bf16 v[90:93], v[162:165], v[206:209], v[90:93]
	v_mfma_f32_16x16x32_bf16 v[82:85], v[154:157], v[214:217], v[82:85]
	v_mfma_f32_16x16x32_bf16 v[74:77], v[162:165], v[214:217], v[74:77]
	v_mfma_f32_16x16x32_bf16 v[126:129], v[158:161], v[194:197], v[126:129]
	v_mfma_f32_16x16x32_bf16 v[122:125], v[166:169], v[194:197], v[122:125]
	v_mfma_f32_16x16x32_bf16 v[114:117], v[158:161], v[202:205], v[114:117]
	v_mfma_f32_16x16x32_bf16 v[106:109], v[166:169], v[202:205], v[106:109]
	v_mfma_f32_16x16x32_bf16 v[98:101], v[158:161], v[210:213], v[98:101]
	v_mfma_f32_16x16x32_bf16 v[90:93], v[166:169], v[210:213], v[90:93]
	v_mfma_f32_16x16x32_bf16 v[82:85], v[158:161], v[218:221], v[82:85]
	v_mfma_f32_16x16x32_bf16 v[74:77], v[166:169], v[218:221], v[74:77]
	v_mfma_f32_16x16x32_bf16 v[118:121], v[170:173], v[190:193], v[118:121]
	v_mfma_f32_16x16x32_bf16 v[110:113], v[182:185], v[190:193], v[110:113]
	v_mfma_f32_16x16x32_bf16 v[102:105], v[170:173], v[198:201], v[102:105]
	v_mfma_f32_16x16x32_bf16 v[94:97], v[182:185], v[198:201], v[94:97]
	v_mfma_f32_16x16x32_bf16 v[86:89], v[170:173], v[206:209], v[86:89]
	v_mfma_f32_16x16x32_bf16 v[78:81], v[182:185], v[206:209], v[78:81]
	v_mfma_f32_16x16x32_bf16 v[70:73], v[170:173], v[214:217], v[70:73]
	v_mfma_f32_16x16x32_bf16 v[66:69], v[182:185], v[214:217], v[66:69]
	v_mfma_f32_16x16x32_bf16 v[118:121], v[178:181], v[194:197], v[118:121]
	v_mfma_f32_16x16x32_bf16 v[110:113], v[186:189], v[194:197], v[110:113]
	v_mfma_f32_16x16x32_bf16 v[102:105], v[178:181], v[202:205], v[102:105]
	v_mfma_f32_16x16x32_bf16 v[94:97], v[186:189], v[202:205], v[94:97]
	v_mfma_f32_16x16x32_bf16 v[86:89], v[178:181], v[210:213], v[86:89]
	v_mfma_f32_16x16x32_bf16 v[78:81], v[186:189], v[210:213], v[78:81]
	v_mfma_f32_16x16x32_bf16 v[70:73], v[178:181], v[218:221], v[70:73]
	v_mfma_f32_16x16x32_bf16 v[66:69], v[186:189], v[218:221], v[66:69]
	s_barrier
	s_setprio 0
	s_add_i32 s2, s53, s34
	v_lshl_add_u64 v[144:145], v[144:145], 0, s[6:7]
	s_mov_b32 m0, s2
	ds_read_b128 v[190:193], v153 offset:49152
	ds_read_b128 v[194:197], v153 offset:50176
	ds_read_b128 v[198:201], v153 offset:51200
	ds_read_b128 v[202:205], v153 offset:52224
	ds_read_b128 v[206:209], v153 offset:53248
	ds_read_b128 v[210:213], v153 offset:54272
	ds_read_b128 v[214:217], v153 offset:55296
	ds_read_b128 v[218:221], v153 offset:56320
	global_load_lds_dwordx4 v[144:145], off
	s_add_i32 m0, s2, 0x2000
	s_add_u32 s2, s28, 0x40080
	v_lshl_add_u64 v[144:145], v[174:175], 0, s[6:7]
	s_addc_u32 s3, s29, 0
	s_add_i32 s28, s54, s34
	global_load_lds_dwordx4 v[144:145], off
	v_lshl_add_u64 v[144:145], s[2:3], 0, v[134:135]
	s_mov_b32 m0, s28
	s_nop 0
	global_load_lds_dwordx4 v[144:145], off
	v_lshl_add_u64 v[144:145], s[2:3], 0, v[130:131]
	s_add_i32 m0, s28, 0x2000
	s_nop 0
	global_load_lds_dwordx4 v[144:145], off
	v_lshl_add_u64 v[144:145], v[222:223], 0, s[6:7]
	s_mov_b32 m0, s41
	s_nop 0
	global_load_lds_dwordx4 v[144:145], off
	v_lshl_add_u64 v[144:145], v[224:225], 0, s[6:7]
	s_mov_b32 m0, s42
	s_nop 0
	global_load_lds_dwordx4 v[144:145], off
	s_waitcnt vmcnt(8)
	s_waitcnt lgkmcnt(0)
	s_setprio 1
	s_barrier
	v_mfma_f32_16x16x32_bf16 v[62:65], v[154:157], v[190:193], v[62:65]
	v_mfma_f32_16x16x32_bf16 v[58:61], v[162:165], v[190:193], v[58:61]
	v_mfma_f32_16x16x32_bf16 v[50:53], v[154:157], v[198:201], v[50:53]
	v_mfma_f32_16x16x32_bf16 v[42:45], v[162:165], v[198:201], v[42:45]
	v_mfma_f32_16x16x32_bf16 v[34:37], v[154:157], v[206:209], v[34:37]
	v_mfma_f32_16x16x32_bf16 v[26:29], v[162:165], v[206:209], v[26:29]
	v_mfma_f32_16x16x32_bf16 v[18:21], v[154:157], v[214:217], v[18:21]
	v_mfma_f32_16x16x32_bf16 v[10:13], v[162:165], v[214:217], v[10:13]
	v_mfma_f32_16x16x32_bf16 v[62:65], v[158:161], v[194:197], v[62:65]
	v_mfma_f32_16x16x32_bf16 v[58:61], v[166:169], v[194:197], v[58:61]
	v_mfma_f32_16x16x32_bf16 v[50:53], v[158:161], v[202:205], v[50:53]
	v_mfma_f32_16x16x32_bf16 v[42:45], v[166:169], v[202:205], v[42:45]
	v_mfma_f32_16x16x32_bf16 v[34:37], v[158:161], v[210:213], v[34:37]
	v_mfma_f32_16x16x32_bf16 v[26:29], v[166:169], v[210:213], v[26:29]
	v_mfma_f32_16x16x32_bf16 v[18:21], v[158:161], v[218:221], v[18:21]
	v_mfma_f32_16x16x32_bf16 v[10:13], v[166:169], v[218:221], v[10:13]
	v_mfma_f32_16x16x32_bf16 v[54:57], v[170:173], v[190:193], v[54:57]
	v_mfma_f32_16x16x32_bf16 v[46:49], v[182:185], v[190:193], v[46:49]
	v_mfma_f32_16x16x32_bf16 v[38:41], v[170:173], v[198:201], v[38:41]
	v_mfma_f32_16x16x32_bf16 v[30:33], v[182:185], v[198:201], v[30:33]
	v_mfma_f32_16x16x32_bf16 v[22:25], v[170:173], v[206:209], v[22:25]
	v_mfma_f32_16x16x32_bf16 v[14:17], v[182:185], v[206:209], v[14:17]
	v_mfma_f32_16x16x32_bf16 v[6:9], v[170:173], v[214:217], v[6:9]
	v_mfma_f32_16x16x32_bf16 v[2:5], v[182:185], v[214:217], v[2:5]
	v_mfma_f32_16x16x32_bf16 v[54:57], v[178:181], v[194:197], v[54:57]
	v_mfma_f32_16x16x32_bf16 v[46:49], v[186:189], v[194:197], v[46:49]
	v_mfma_f32_16x16x32_bf16 v[38:41], v[178:181], v[202:205], v[38:41]
	v_mfma_f32_16x16x32_bf16 v[30:33], v[186:189], v[202:205], v[30:33]
	v_mfma_f32_16x16x32_bf16 v[22:25], v[178:181], v[210:213], v[22:25]
	v_mfma_f32_16x16x32_bf16 v[14:17], v[186:189], v[210:213], v[14:17]
	v_mfma_f32_16x16x32_bf16 v[6:9], v[178:181], v[218:221], v[6:9]
	v_mfma_f32_16x16x32_bf16 v[2:5], v[186:189], v[218:221], v[2:5]
	s_barrier
	s_setprio 0
	s_add_i32 s52, s52, 2
	s_add_u32 s26, s26, 0x100
	s_addc_u32 s27, s27, 0
	s_add_u32 s50, s50, 0x100
	s_addc_u32 s51, s51, 0
	s_cmp_gt_u32 s52, 13
	s_cbranch_scc0 .LBB0_555
	s_branch .Lpk555_exit
.LBB0_555:
	ds_read_b128 v[154:157], v151
	ds_read_b128 v[158:161], v151 offset:1024
	ds_read_b128 v[162:165], v151 offset:2048
	ds_read_b128 v[166:169], v151 offset:3072
	ds_read_b128 v[170:173], v152
	ds_read_b128 v[178:181], v152 offset:1024
	ds_read_b128 v[182:185], v152 offset:2048
	ds_read_b128 v[186:189], v152 offset:3072
	s_add_u32 s2, s26, 0xfffc0080
	s_addc_u32 s3, s27, -1
	s_cmp_eq_u32 s52, 12
	s_cselect_b32 s3, s11, s3
	s_cselect_b32 s2, s13, s2
	s_cselect_b32 s29, s48, s51
	s_cselect_b32 s28, s49, s50
	v_lshl_add_u64 v[144:145], s[26:27], 0, v[138:139]
	s_add_i32 m0, s37, 0xc000
	ds_read_b128 v[190:193], v153
	ds_read_b128 v[194:197], v153 offset:1024
	ds_read_b128 v[198:201], v153 offset:2048
	ds_read_b128 v[202:205], v153 offset:3072
	ds_read_b128 v[206:209], v153 offset:4096
	ds_read_b128 v[210:213], v153 offset:5120
	ds_read_b128 v[214:217], v153 offset:6144
	ds_read_b128 v[218:221], v153 offset:7168
	global_load_lds_dwordx4 v[144:145], off
	v_lshl_add_u64 v[144:145], s[26:27], 0, v[140:141]
	s_add_i32 m0, s37, 0xe000
	s_nop 0
	global_load_lds_dwordx4 v[144:145], off
	s_waitcnt vmcnt(8)
	s_waitcnt lgkmcnt(0)
	s_setprio 1
	s_barrier
	v_mfma_f32_16x16x32_bf16 v[126:129], v[154:157], v[190:193], v[126:129]
	v_mfma_f32_16x16x32_bf16 v[122:125], v[162:165], v[190:193], v[122:125]
	v_mfma_f32_16x16x32_bf16 v[114:117], v[154:157], v[198:201], v[114:117]
	v_mfma_f32_16x16x32_bf16 v[106:109], v[162:165], v[198:201], v[106:109]
	v_mfma_f32_16x16x32_bf16 v[98:101], v[154:157], v[206:209], v[98:101]
	v_mfma_f32_16x16x32_bf16 v[90:93], v[162:165], v[206:209], v[90:93]
	v_mfma_f32_16x16x32_bf16 v[82:85], v[154:157], v[214:217], v[82:85]
	v_mfma_f32_16x16x32_bf16 v[74:77], v[162:165], v[214:217], v[74:77]
	v_mfma_f32_16x16x32_bf16 v[126:129], v[158:161], v[194:197], v[126:129]
	v_mfma_f32_16x16x32_bf16 v[122:125], v[166:169], v[194:197], v[122:125]
	v_mfma_f32_16x16x32_bf16 v[114:117], v[158:161], v[202:205], v[114:117]
	v_mfma_f32_16x16x32_bf16 v[106:109], v[166:169], v[202:205], v[106:109]
	v_mfma_f32_16x16x32_bf16 v[98:101], v[158:161], v[210:213], v[98:101]
	v_mfma_f32_16x16x32_bf16 v[90:93], v[166:169], v[210:213], v[90:93]
	v_mfma_f32_16x16x32_bf16 v[82:85], v[158:161], v[218:221], v[82:85]
	v_mfma_f32_16x16x32_bf16 v[74:77], v[166:169], v[218:221], v[74:77]
	v_mfma_f32_16x16x32_bf16 v[118:121], v[170:173], v[190:193], v[118:121]
	v_mfma_f32_16x16x32_bf16 v[110:113], v[182:185], v[190:193], v[110:113]
	v_mfma_f32_16x16x32_bf16 v[102:105], v[170:173], v[198:201], v[102:105]
	v_mfma_f32_16x16x32_bf16 v[94:97], v[182:185], v[198:201], v[94:97]
	v_mfma_f32_16x16x32_bf16 v[86:89], v[170:173], v[206:209], v[86:89]
	v_mfma_f32_16x16x32_bf16 v[78:81], v[182:185], v[206:209], v[78:81]
	v_mfma_f32_16x16x32_bf16 v[70:73], v[170:173], v[214:217], v[70:73]
	v_mfma_f32_16x16x32_bf16 v[66:69], v[182:185], v[214:217], v[66:69]
	v_mfma_f32_16x16x32_bf16 v[118:121], v[178:181], v[194:197], v[118:121]
	v_mfma_f32_16x16x32_bf16 v[110:113], v[186:189], v[194:197], v[110:113]
	v_mfma_f32_16x16x32_bf16 v[102:105], v[178:181], v[202:205], v[102:105]
	v_mfma_f32_16x16x32_bf16 v[94:97], v[186:189], v[202:205], v[94:97]
	v_mfma_f32_16x16x32_bf16 v[86:89], v[178:181], v[210:213], v[86:89]
	v_mfma_f32_16x16x32_bf16 v[78:81], v[186:189], v[210:213], v[78:81]
	v_mfma_f32_16x16x32_bf16 v[70:73], v[178:181], v[218:221], v[70:73]
	v_mfma_f32_16x16x32_bf16 v[66:69], v[186:189], v[218:221], v[66:69]
	s_barrier
	s_setprio 0
	s_add_i32 s53, s44, s34
	v_lshl_add_u64 v[144:145], s[28:29], 0, v[134:135]
	s_mov_b32 m0, s53
	ds_read_b128 v[190:193], v153 offset:16384
	ds_read_b128 v[194:197], v153 offset:17408
	ds_read_b128 v[198:201], v153 offset:18432
	ds_read_b128 v[202:205], v153 offset:19456
	ds_read_b128 v[206:209], v153 offset:20480
	ds_read_b128 v[210:213], v153 offset:21504
	ds_read_b128 v[214:217], v153 offset:22528
	ds_read_b128 v[218:221], v153 offset:23552
	global_load_lds_dwordx4 v[144:145], off
	s_add_i32 m0, s53, 0x2000
	s_add_u32 s54, s28, 0x40000
	v_lshl_add_u64 v[174:175], s[28:29], 0, v[130:131]
	s_addc_u32 s55, s29, 0
	s_add_i32 s53, s45, s34
	global_load_lds_dwordx4 v[174:175], off
	v_lshl_add_u64 v[222:223], s[54:55], 0, v[134:135]
	s_mov_b32 m0, s53
	v_lshl_add_u64 v[224:225], s[2:3], 0, v[132:133]
	global_load_lds_dwordx4 v[222:223], off
	v_lshl_add_u64 v[222:223], s[54:55], 0, v[130:131]
	s_add_i32 m0, s53, 0x2000
	s_nop 0
	global_load_lds_dwordx4 v[222:223], off
	v_lshl_add_u64 v[222:223], s[2:3], 0, v[136:137]
	s_mov_b32 m0, s37
	s_nop 0
	global_load_lds_dwordx4 v[222:223], off
	s_mov_b32 m0, s25
	s_nop 0
	global_load_lds_dwordx4 v[224:225], off
	s_waitcnt vmcnt(8)
	s_waitcnt lgkmcnt(0)
	s_setprio 1
	s_barrier
	v_mfma_f32_16x16x32_bf16 v[62:65], v[154:157], v[190:193], v[62:65]
	v_mfma_f32_16x16x32_bf16 v[58:61], v[162:165], v[190:193], v[58:61]
	v_mfma_f32_16x16x32_bf16 v[50:53], v[154:157], v[198:201], v[50:53]
	v_mfma_f32_16x16x32_bf16 v[42:45], v[162:165], v[198:201], v[42:45]
	v_mfma_f32_16x16x32_bf16 v[34:37], v[154:157], v[206:209], v[34:37]
	v_mfma_f32_16x16x32_bf16 v[26:29], v[162:165], v[206:209], v[26:29]
	v_mfma_f32_16x16x32_bf16 v[18:21], v[154:157], v[214:217], v[18:21]
	v_mfma_f32_16x16x32_bf16 v[10:13], v[162:165], v[214:217], v[10:13]
	v_mfma_f32_16x16x32_bf16 v[62:65], v[158:161], v[194:197], v[62:65]
	v_mfma_f32_16x16x32_bf16 v[58:61], v[166:169], v[194:197], v[58:61]
	v_mfma_f32_16x16x32_bf16 v[50:53], v[158:161], v[202:205], v[50:53]
	v_mfma_f32_16x16x32_bf16 v[42:45], v[166:169], v[202:205], v[42:45]
	v_mfma_f32_16x16x32_bf16 v[34:37], v[158:161], v[210:213], v[34:37]
	v_mfma_f32_16x16x32_bf16 v[26:29], v[166:169], v[210:213], v[26:29]
	v_mfma_f32_16x16x32_bf16 v[18:21], v[158:161], v[218:221], v[18:21]
	v_mfma_f32_16x16x32_bf16 v[10:13], v[166:169], v[218:221], v[10:13]
	v_mfma_f32_16x16x32_bf16 v[54:57], v[170:173], v[190:193], v[54:57]
	v_mfma_f32_16x16x32_bf16 v[46:49], v[182:185], v[190:193], v[46:49]
	v_mfma_f32_16x16x32_bf16 v[38:41], v[170:173], v[198:201], v[38:41]
	v_mfma_f32_16x16x32_bf16 v[30:33], v[182:185], v[198:201], v[30:33]
	v_mfma_f32_16x16x32_bf16 v[22:25], v[170:173], v[206:209], v[22:25]
	v_mfma_f32_16x16x32_bf16 v[14:17], v[182:185], v[206:209], v[14:17]
	v_mfma_f32_16x16x32_bf16 v[6:9], v[170:173], v[214:217], v[6:9]
	v_mfma_f32_16x16x32_bf16 v[2:5], v[182:185], v[214:217], v[2:5]
	v_mfma_f32_16x16x32_bf16 v[54:57], v[178:181], v[194:197], v[54:57]
	v_mfma_f32_16x16x32_bf16 v[46:49], v[186:189], v[194:197], v[46:49]
	v_mfma_f32_16x16x32_bf16 v[38:41], v[178:181], v[202:205], v[38:41]
	v_mfma_f32_16x16x32_bf16 v[30:33], v[186:189], v[202:205], v[30:33]
	v_mfma_f32_16x16x32_bf16 v[22:25], v[178:181], v[210:213], v[22:25]
	v_mfma_f32_16x16x32_bf16 v[14:17], v[186:189], v[210:213], v[14:17]
	v_mfma_f32_16x16x32_bf16 v[6:9], v[178:181], v[218:221], v[6:9]
	v_mfma_f32_16x16x32_bf16 v[2:5], v[186:189], v[218:221], v[2:5]
	s_barrier
	s_setprio 0
	s_add_i32 s53, 0, 0x18000
	s_add_i32 s54, 0, 0x1c000
	v_add_u32_e32 v166, s53, v149
	v_add_u32_e32 v176, s54, v149
	ds_read_b128 v[154:157], v166
	ds_read_b128 v[158:161], v166 offset:1024
	ds_read_b128 v[162:165], v166 offset:2048
	ds_read_b128 v[166:169], v166 offset:3072
	ds_read_b128 v[170:173], v176
	ds_read_b128 v[178:181], v176 offset:1024
	ds_read_b128 v[182:185], v176 offset:2048
	ds_read_b128 v[186:189], v176 offset:3072
	s_add_u32 s2, s2, 0x40000
	s_addc_u32 s3, s3, 0
	s_mov_b32 m0, s38
	v_lshl_add_u64 v[226:227], s[2:3], 0, v[136:137]
	ds_read_b128 v[190:193], v153 offset:32768
	ds_read_b128 v[194:197], v153 offset:33792
	ds_read_b128 v[198:201], v153 offset:34816
	ds_read_b128 v[202:205], v153 offset:35840
	ds_read_b128 v[206:209], v153 offset:36864
	ds_read_b128 v[210:213], v153 offset:37888
	ds_read_b128 v[214:217], v153 offset:38912
	ds_read_b128 v[218:221], v153 offset:39936
	global_load_lds_dwordx4 v[226:227], off
	v_lshl_add_u64 v[226:227], s[2:3], 0, v[132:133]
	s_mov_b32 m0, s39
	s_nop 0
	global_load_lds_dwordx4 v[226:227], off
	s_waitcnt vmcnt(8)
	s_waitcnt lgkmcnt(0)
	s_setprio 1
	s_barrier
	v_mfma_f32_16x16x32_bf16 v[126:129], v[154:157], v[190:193], v[126:129]
	v_mfma_f32_16x16x32_bf16 v[122:125], v[162:165], v[190:193], v[122:125]
	v_mfma_f32_16x16x32_bf16 v[114:117], v[154:157], v[198:201], v[114:117]
	v_mfma_f32_16x16x32_bf16 v[106:109], v[162:165], v[198:201], v[106:109]
	v_mfma_f32_16x16x32_bf16 v[98:101], v[154:157], v[206:209], v[98:101]
	v_mfma_f32_16x16x32_bf16 v[90:93], v[162:165], v[206:209], v[90:93]
	v_mfma_f32_16x16x32_bf16 v[82:85], v[154:157], v[214:217], v[82:85]
	v_mfma_f32_16x16x32_bf16 v[74:77], v[162:165], v[214:217], v[74:77]
	v_mfma_f32_16x16x32_bf16 v[126:129], v[158:161], v[194:197], v[126:129]
	v_mfma_f32_16x16x32_bf16 v[122:125], v[166:169], v[194:197], v[122:125]
	v_mfma_f32_16x16x32_bf16 v[114:117], v[158:161], v[202:205], v[114:117]
	v_mfma_f32_16x16x32_bf16 v[106:109], v[166:169], v[202:205], v[106:109]
	v_mfma_f32_16x16x32_bf16 v[98:101], v[158:161], v[210:213], v[98:101]
	v_mfma_f32_16x16x32_bf16 v[90:93], v[166:169], v[210:213], v[90:93]
	v_mfma_f32_16x16x32_bf16 v[82:85], v[158:161], v[218:221], v[82:85]
	v_mfma_f32_16x16x32_bf16 v[74:77], v[166:169], v[218:221], v[74:77]
	v_mfma_f32_16x16x32_bf16 v[118:121], v[170:173], v[190:193], v[118:121]
	v_mfma_f32_16x16x32_bf16 v[110:113], v[182:185], v[190:193], v[110:113]
	v_mfma_f32_16x16x32_bf16 v[102:105], v[170:173], v[198:201], v[102:105]
	v_mfma_f32_16x16x32_bf16 v[94:97], v[182:185], v[198:201], v[94:97]
	v_mfma_f32_16x16x32_bf16 v[86:89], v[170:173], v[206:209], v[86:89]
	v_mfma_f32_16x16x32_bf16 v[78:81], v[182:185], v[206:209], v[78:81]
	v_mfma_f32_16x16x32_bf16 v[70:73], v[170:173], v[214:217], v[70:73]
	v_mfma_f32_16x16x32_bf16 v[66:69], v[182:185], v[214:217], v[66:69]
	v_mfma_f32_16x16x32_bf16 v[118:121], v[178:181], v[194:197], v[118:121]
	v_mfma_f32_16x16x32_bf16 v[110:113], v[186:189], v[194:197], v[110:113]
	v_mfma_f32_16x16x32_bf16 v[102:105], v[178:181], v[202:205], v[102:105]
	v_mfma_f32_16x16x32_bf16 v[94:97], v[186:189], v[202:205], v[94:97]
	v_mfma_f32_16x16x32_bf16 v[86:89], v[178:181], v[210:213], v[86:89]
	v_mfma_f32_16x16x32_bf16 v[78:81], v[186:189], v[210:213], v[78:81]
	v_mfma_f32_16x16x32_bf16 v[70:73], v[178:181], v[218:221], v[70:73]
	v_mfma_f32_16x16x32_bf16 v[66:69], v[186:189], v[218:221], v[66:69]
	s_barrier
	s_setprio 0
	s_add_i32 s2, s53, s34
	v_lshl_add_u64 v[144:145], v[144:145], 0, s[6:7]
	s_mov_b32 m0, s2
	ds_read_b128 v[190:193], v153 offset:49152
	ds_read_b128 v[194:197], v153 offset:50176
	ds_read_b128 v[198:201], v153 offset:51200
	ds_read_b128 v[202:205], v153 offset:52224
	ds_read_b128 v[206:209], v153 offset:53248
	ds_read_b128 v[210:213], v153 offset:54272
	ds_read_b128 v[214:217], v153 offset:55296
	ds_read_b128 v[218:221], v153 offset:56320
	global_load_lds_dwordx4 v[144:145], off
	s_add_i32 m0, s2, 0x2000
	s_add_u32 s2, s28, 0x40080
	v_lshl_add_u64 v[144:145], v[174:175], 0, s[6:7]
	s_addc_u32 s3, s29, 0
	s_add_i32 s28, s54, s34
	global_load_lds_dwordx4 v[144:145], off
	v_lshl_add_u64 v[144:145], s[2:3], 0, v[134:135]
	s_mov_b32 m0, s28
	s_nop 0
	global_load_lds_dwordx4 v[144:145], off
	v_lshl_add_u64 v[144:145], s[2:3], 0, v[130:131]
	s_add_i32 m0, s28, 0x2000
	s_nop 0
	global_load_lds_dwordx4 v[144:145], off
	v_lshl_add_u64 v[144:145], v[222:223], 0, s[6:7]
	s_mov_b32 m0, s41
	s_nop 0
	global_load_lds_dwordx4 v[144:145], off
	v_lshl_add_u64 v[144:145], v[224:225], 0, s[6:7]
	s_mov_b32 m0, s42
	s_nop 0
	global_load_lds_dwordx4 v[144:145], off
	s_waitcnt vmcnt(8)
	s_waitcnt lgkmcnt(0)
	s_setprio 1
	s_barrier
	v_mfma_f32_16x16x32_bf16 v[62:65], v[154:157], v[190:193], v[62:65]
	v_mfma_f32_16x16x32_bf16 v[58:61], v[162:165], v[190:193], v[58:61]
	v_mfma_f32_16x16x32_bf16 v[50:53], v[154:157], v[198:201], v[50:53]
	v_mfma_f32_16x16x32_bf16 v[42:45], v[162:165], v[198:201], v[42:45]
	v_mfma_f32_16x16x32_bf16 v[34:37], v[154:157], v[206:209], v[34:37]
	v_mfma_f32_16x16x32_bf16 v[26:29], v[162:165], v[206:209], v[26:29]
	v_mfma_f32_16x16x32_bf16 v[18:21], v[154:157], v[214:217], v[18:21]
	v_mfma_f32_16x16x32_bf16 v[10:13], v[162:165], v[214:217], v[10:13]
	v_mfma_f32_16x16x32_bf16 v[62:65], v[158:161], v[194:197], v[62:65]
	v_mfma_f32_16x16x32_bf16 v[58:61], v[166:169], v[194:197], v[58:61]
	v_mfma_f32_16x16x32_bf16 v[50:53], v[158:161], v[202:205], v[50:53]
	v_mfma_f32_16x16x32_bf16 v[42:45], v[166:169], v[202:205], v[42:45]
	v_mfma_f32_16x16x32_bf16 v[34:37], v[158:161], v[210:213], v[34:37]
	v_mfma_f32_16x16x32_bf16 v[26:29], v[166:169], v[210:213], v[26:29]
	v_mfma_f32_16x16x32_bf16 v[18:21], v[158:161], v[218:221], v[18:21]
	v_mfma_f32_16x16x32_bf16 v[10:13], v[166:169], v[218:221], v[10:13]
	v_mfma_f32_16x16x32_bf16 v[54:57], v[170:173], v[190:193], v[54:57]
	v_mfma_f32_16x16x32_bf16 v[46:49], v[182:185], v[190:193], v[46:49]
	v_mfma_f32_16x16x32_bf16 v[38:41], v[170:173], v[198:201], v[38:41]
	v_mfma_f32_16x16x32_bf16 v[30:33], v[182:185], v[198:201], v[30:33]
	v_mfma_f32_16x16x32_bf16 v[22:25], v[170:173], v[206:209], v[22:25]
	v_mfma_f32_16x16x32_bf16 v[14:17], v[182:185], v[206:209], v[14:17]
	v_mfma_f32_16x16x32_bf16 v[6:9], v[170:173], v[214:217], v[6:9]
	v_mfma_f32_16x16x32_bf16 v[2:5], v[182:185], v[214:217], v[2:5]
	v_mfma_f32_16x16x32_bf16 v[54:57], v[178:181], v[194:197], v[54:57]
	v_mfma_f32_16x16x32_bf16 v[46:49], v[186:189], v[194:197], v[46:49]
	v_mfma_f32_16x16x32_bf16 v[38:41], v[178:181], v[202:205], v[38:41]
	v_mfma_f32_16x16x32_bf16 v[30:33], v[186:189], v[202:205], v[30:33]
	v_mfma_f32_16x16x32_bf16 v[22:25], v[178:181], v[210:213], v[22:25]
	v_mfma_f32_16x16x32_bf16 v[14:17], v[186:189], v[210:213], v[14:17]
	v_mfma_f32_16x16x32_bf16 v[6:9], v[178:181], v[218:221], v[6:9]
	v_mfma_f32_16x16x32_bf16 v[2:5], v[186:189], v[218:221], v[2:5]
	s_barrier
	s_setprio 0
	s_add_i32 s52, s52, 2
	s_add_u32 s26, s26, 0x100
	s_addc_u32 s27, s27, 0
	s_add_u32 s50, s50, 0x100
	s_addc_u32 s51, s51, 0
	s_cmp_gt_u32 s52, 13
	s_cbranch_scc0 .LBB0_555

.LBB0_646:
	ds_read_b128 v[152:155], v146
	ds_read_b128 v[156:159], v146 offset:1024
	ds_read_b128 v[160:163], v146 offset:2048
	ds_read_b128 v[164:167], v146 offset:3072
	ds_read_b128 v[168:171], v147
	ds_read_b128 v[172:175], v147 offset:1024
	ds_read_b128 v[178:181], v147 offset:2048
	ds_read_b128 v[182:185], v147 offset:3072
	s_add_u32 s2, s10, s12
	s_addc_u32 s3, s11, s13
	s_add_u32 s2, s2, 0x3400100
	s_addc_u32 s3, s3, 0
	s_add_u32 s14, s24, s12
	s_addc_u32 s15, s25, s13
	s_cmpk_eq_i32 s12, 0x700
	s_cselect_b32 s3, s7, s3
	s_cselect_b32 s2, s6, s2
	s_cselect_b32 s15, s5, s15
	s_cselect_b32 s14, s4, s14
	s_mov_b32 m0, s27
	v_lshl_add_u64 v[218:219], v[138:139], 0, s[12:13]
	ds_read_b128 v[186:189], v148
	ds_read_b128 v[190:193], v148 offset:1024
	ds_read_b128 v[194:197], v148 offset:2048
	ds_read_b128 v[198:201], v148 offset:3072
	ds_read_b128 v[202:205], v148 offset:4096
	ds_read_b128 v[206:209], v148 offset:5120
	ds_read_b128 v[210:213], v148 offset:6144
	ds_read_b128 v[214:217], v148 offset:7168
	global_load_lds_dwordx4 v[218:219], off
	v_lshl_add_u64 v[218:219], v[140:141], 0, s[12:13]
	s_mov_b32 m0, s28
	s_nop 0
	global_load_lds_dwordx4 v[218:219], off
	s_waitcnt vmcnt(8)
	s_waitcnt lgkmcnt(0)
	s_setprio 1
	s_barrier
	v_mfma_f32_16x16x32_bf16 v[126:129], v[152:155], v[186:189], v[126:129]
	v_mfma_f32_16x16x32_bf16 v[122:125], v[160:163], v[186:189], v[122:125]
	v_mfma_f32_16x16x32_bf16 v[114:117], v[152:155], v[194:197], v[114:117]
	v_mfma_f32_16x16x32_bf16 v[106:109], v[160:163], v[194:197], v[106:109]
	v_mfma_f32_16x16x32_bf16 v[98:101], v[152:155], v[202:205], v[98:101]
	v_mfma_f32_16x16x32_bf16 v[90:93], v[160:163], v[202:205], v[90:93]
	v_mfma_f32_16x16x32_bf16 v[82:85], v[152:155], v[210:213], v[82:85]
	v_mfma_f32_16x16x32_bf16 v[74:77], v[160:163], v[210:213], v[74:77]
	v_mfma_f32_16x16x32_bf16 v[126:129], v[156:159], v[190:193], v[126:129]
	v_mfma_f32_16x16x32_bf16 v[122:125], v[164:167], v[190:193], v[122:125]
	v_mfma_f32_16x16x32_bf16 v[114:117], v[156:159], v[198:201], v[114:117]
	v_mfma_f32_16x16x32_bf16 v[106:109], v[164:167], v[198:201], v[106:109]
	v_mfma_f32_16x16x32_bf16 v[98:101], v[156:159], v[206:209], v[98:101]
	v_mfma_f32_16x16x32_bf16 v[90:93], v[164:167], v[206:209], v[90:93]
	v_mfma_f32_16x16x32_bf16 v[82:85], v[156:159], v[214:217], v[82:85]
	v_mfma_f32_16x16x32_bf16 v[74:77], v[164:167], v[214:217], v[74:77]
	v_mfma_f32_16x16x32_bf16 v[118:121], v[168:171], v[186:189], v[118:121]
	v_mfma_f32_16x16x32_bf16 v[110:113], v[178:181], v[186:189], v[110:113]
	v_mfma_f32_16x16x32_bf16 v[102:105], v[168:171], v[194:197], v[102:105]
	v_mfma_f32_16x16x32_bf16 v[94:97], v[178:181], v[194:197], v[94:97]
	v_mfma_f32_16x16x32_bf16 v[86:89], v[168:171], v[202:205], v[86:89]
	v_mfma_f32_16x16x32_bf16 v[78:81], v[178:181], v[202:205], v[78:81]
	v_mfma_f32_16x16x32_bf16 v[70:73], v[168:171], v[210:213], v[70:73]
	v_mfma_f32_16x16x32_bf16 v[66:69], v[178:181], v[210:213], v[66:69]
	v_mfma_f32_16x16x32_bf16 v[118:121], v[172:175], v[190:193], v[118:121]
	v_mfma_f32_16x16x32_bf16 v[110:113], v[182:185], v[190:193], v[110:113]
	v_mfma_f32_16x16x32_bf16 v[102:105], v[172:175], v[198:201], v[102:105]
	v_mfma_f32_16x16x32_bf16 v[94:97], v[182:185], v[198:201], v[94:97]
	v_mfma_f32_16x16x32_bf16 v[86:89], v[172:175], v[206:209], v[86:89]
	v_mfma_f32_16x16x32_bf16 v[78:81], v[182:185], v[206:209], v[78:81]
	v_mfma_f32_16x16x32_bf16 v[70:73], v[172:175], v[214:217], v[70:73]
	v_mfma_f32_16x16x32_bf16 v[66:69], v[182:185], v[214:217], v[66:69]
	s_barrier
	s_setprio 0
	s_mov_b32 m0, s29
	v_lshl_add_u64 v[218:219], s[14:15], 0, v[134:135]
	s_add_u32 s40, s14, 0x40000
	ds_read_b128 v[186:189], v148 offset:16384
	ds_read_b128 v[190:193], v148 offset:17408
	ds_read_b128 v[194:197], v148 offset:18432
	ds_read_b128 v[198:201], v148 offset:19456
	ds_read_b128 v[202:205], v148 offset:20480
	ds_read_b128 v[206:209], v148 offset:21504
	ds_read_b128 v[210:213], v148 offset:22528
	ds_read_b128 v[214:217], v148 offset:23552
	global_load_lds_dwordx4 v[218:219], off
	v_lshl_add_u64 v[220:221], s[14:15], 0, v[130:131]
	s_mov_b32 m0, s30
	s_addc_u32 s41, s15, 0
	global_load_lds_dwordx4 v[220:221], off
	v_lshl_add_u64 v[222:223], s[40:41], 0, v[134:135]
	s_mov_b32 m0, s31
	v_lshl_add_u64 v[224:225], s[2:3], 0, v[132:133]
	global_load_lds_dwordx4 v[222:223], off
	v_lshl_add_u64 v[222:223], s[40:41], 0, v[130:131]
	s_mov_b32 m0, s34
	s_nop 0
	global_load_lds_dwordx4 v[222:223], off
	v_lshl_add_u64 v[222:223], s[2:3], 0, v[136:137]
	s_mov_b32 m0, s18
	s_nop 0
	global_load_lds_dwordx4 v[222:223], off
	s_mov_b32 m0, s1
	s_nop 0
	global_load_lds_dwordx4 v[224:225], off
	s_waitcnt vmcnt(8)
	s_waitcnt lgkmcnt(0)
	s_setprio 1
	s_barrier
	v_mfma_f32_16x16x32_bf16 v[62:65], v[152:155], v[186:189], v[62:65]
	v_mfma_f32_16x16x32_bf16 v[58:61], v[160:163], v[186:189], v[58:61]
	v_mfma_f32_16x16x32_bf16 v[50:53], v[152:155], v[194:197], v[50:53]
	v_mfma_f32_16x16x32_bf16 v[42:45], v[160:163], v[194:197], v[42:45]
	v_mfma_f32_16x16x32_bf16 v[34:37], v[152:155], v[202:205], v[34:37]
	v_mfma_f32_16x16x32_bf16 v[26:29], v[160:163], v[202:205], v[26:29]
	v_mfma_f32_16x16x32_bf16 v[18:21], v[152:155], v[210:213], v[18:21]
	v_mfma_f32_16x16x32_bf16 v[10:13], v[160:163], v[210:213], v[10:13]
	v_mfma_f32_16x16x32_bf16 v[62:65], v[156:159], v[190:193], v[62:65]
	v_mfma_f32_16x16x32_bf16 v[58:61], v[164:167], v[190:193], v[58:61]
	v_mfma_f32_16x16x32_bf16 v[50:53], v[156:159], v[198:201], v[50:53]
	v_mfma_f32_16x16x32_bf16 v[42:45], v[164:167], v[198:201], v[42:45]
	v_mfma_f32_16x16x32_bf16 v[34:37], v[156:159], v[206:209], v[34:37]
	v_mfma_f32_16x16x32_bf16 v[26:29], v[164:167], v[206:209], v[26:29]
	v_mfma_f32_16x16x32_bf16 v[18:21], v[156:159], v[214:217], v[18:21]
	v_mfma_f32_16x16x32_bf16 v[10:13], v[164:167], v[214:217], v[10:13]
	v_mfma_f32_16x16x32_bf16 v[54:57], v[168:171], v[186:189], v[54:57]
	v_mfma_f32_16x16x32_bf16 v[46:49], v[178:181], v[186:189], v[46:49]
	v_mfma_f32_16x16x32_bf16 v[38:41], v[168:171], v[194:197], v[38:41]
	v_mfma_f32_16x16x32_bf16 v[30:33], v[178:181], v[194:197], v[30:33]
	v_mfma_f32_16x16x32_bf16 v[22:25], v[168:171], v[202:205], v[22:25]
	v_mfma_f32_16x16x32_bf16 v[14:17], v[178:181], v[202:205], v[14:17]
	v_mfma_f32_16x16x32_bf16 v[6:9], v[168:171], v[210:213], v[6:9]
	v_mfma_f32_16x16x32_bf16 v[2:5], v[178:181], v[210:213], v[2:5]
	v_mfma_f32_16x16x32_bf16 v[54:57], v[172:175], v[190:193], v[54:57]
	v_mfma_f32_16x16x32_bf16 v[46:49], v[182:185], v[190:193], v[46:49]
	v_mfma_f32_16x16x32_bf16 v[38:41], v[172:175], v[198:201], v[38:41]
	v_mfma_f32_16x16x32_bf16 v[30:33], v[182:185], v[198:201], v[30:33]
	v_mfma_f32_16x16x32_bf16 v[22:25], v[172:175], v[206:209], v[22:25]
	v_mfma_f32_16x16x32_bf16 v[14:17], v[182:185], v[206:209], v[14:17]
	v_mfma_f32_16x16x32_bf16 v[6:9], v[172:175], v[214:217], v[6:9]
	v_mfma_f32_16x16x32_bf16 v[2:5], v[182:185], v[214:217], v[2:5]
	s_barrier
	s_setprio 0
	ds_read_b128 v[152:155], v149
	ds_read_b128 v[156:159], v149 offset:1024
	ds_read_b128 v[160:163], v149 offset:2048
	ds_read_b128 v[164:167], v149 offset:3072
	ds_read_b128 v[168:171], v150
	ds_read_b128 v[172:175], v150 offset:1024
	ds_read_b128 v[178:181], v150 offset:2048
	ds_read_b128 v[182:185], v150 offset:3072
	s_add_u32 s2, s2, 0x40000
	s_addc_u32 s3, s3, 0
	s_mov_b32 m0, s19
	v_lshl_add_u64 v[226:227], s[2:3], 0, v[136:137]
	ds_read_b128 v[186:189], v148 offset:32768
	ds_read_b128 v[190:193], v148 offset:33792
	ds_read_b128 v[194:197], v148 offset:34816
	ds_read_b128 v[198:201], v148 offset:35840
	ds_read_b128 v[202:205], v148 offset:36864
	ds_read_b128 v[206:209], v148 offset:37888
	ds_read_b128 v[210:213], v148 offset:38912
	ds_read_b128 v[214:217], v148 offset:39936
	global_load_lds_dwordx4 v[226:227], off
	v_lshl_add_u64 v[226:227], s[2:3], 0, v[132:133]
	s_mov_b32 m0, s20
	s_nop 0
	global_load_lds_dwordx4 v[226:227], off
	s_waitcnt vmcnt(8)
	s_waitcnt lgkmcnt(0)
	s_setprio 1
	s_barrier
	v_mfma_f32_16x16x32_bf16 v[126:129], v[152:155], v[186:189], v[126:129]
	v_mfma_f32_16x16x32_bf16 v[122:125], v[160:163], v[186:189], v[122:125]
	v_mfma_f32_16x16x32_bf16 v[114:117], v[152:155], v[194:197], v[114:117]
	v_mfma_f32_16x16x32_bf16 v[106:109], v[160:163], v[194:197], v[106:109]
	v_mfma_f32_16x16x32_bf16 v[98:101], v[152:155], v[202:205], v[98:101]
	v_mfma_f32_16x16x32_bf16 v[90:93], v[160:163], v[202:205], v[90:93]
	v_mfma_f32_16x16x32_bf16 v[82:85], v[152:155], v[210:213], v[82:85]
	v_mfma_f32_16x16x32_bf16 v[74:77], v[160:163], v[210:213], v[74:77]
	v_mfma_f32_16x16x32_bf16 v[126:129], v[156:159], v[190:193], v[126:129]
	v_mfma_f32_16x16x32_bf16 v[122:125], v[164:167], v[190:193], v[122:125]
	v_mfma_f32_16x16x32_bf16 v[114:117], v[156:159], v[198:201], v[114:117]
	v_mfma_f32_16x16x32_bf16 v[106:109], v[164:167], v[198:201], v[106:109]
	v_mfma_f32_16x16x32_bf16 v[98:101], v[156:159], v[206:209], v[98:101]
	v_mfma_f32_16x16x32_bf16 v[90:93], v[164:167], v[206:209], v[90:93]
	v_mfma_f32_16x16x32_bf16 v[82:85], v[156:159], v[214:217], v[82:85]
	v_mfma_f32_16x16x32_bf16 v[74:77], v[164:167], v[214:217], v[74:77]
	v_mfma_f32_16x16x32_bf16 v[118:121], v[168:171], v[186:189], v[118:121]
	v_mfma_f32_16x16x32_bf16 v[110:113], v[178:181], v[186:189], v[110:113]
	v_mfma_f32_16x16x32_bf16 v[102:105], v[168:171], v[194:197], v[102:105]
	v_mfma_f32_16x16x32_bf16 v[94:97], v[178:181], v[194:197], v[94:97]
	v_mfma_f32_16x16x32_bf16 v[86:89], v[168:171], v[202:205], v[86:89]
	v_mfma_f32_16x16x32_bf16 v[78:81], v[178:181], v[202:205], v[78:81]
	v_mfma_f32_16x16x32_bf16 v[70:73], v[168:171], v[210:213], v[70:73]
	v_mfma_f32_16x16x32_bf16 v[66:69], v[178:181], v[210:213], v[66:69]
	v_mfma_f32_16x16x32_bf16 v[118:121], v[172:175], v[190:193], v[118:121]
	v_mfma_f32_16x16x32_bf16 v[110:113], v[182:185], v[190:193], v[110:113]
	v_mfma_f32_16x16x32_bf16 v[102:105], v[172:175], v[198:201], v[102:105]
	v_mfma_f32_16x16x32_bf16 v[94:97], v[182:185], v[198:201], v[94:97]
	v_mfma_f32_16x16x32_bf16 v[86:89], v[172:175], v[206:209], v[86:89]
	v_mfma_f32_16x16x32_bf16 v[78:81], v[182:185], v[206:209], v[78:81]
	v_mfma_f32_16x16x32_bf16 v[70:73], v[172:175], v[214:217], v[70:73]
	v_mfma_f32_16x16x32_bf16 v[66:69], v[182:185], v[214:217], v[66:69]
	s_barrier
	s_setprio 0
	s_mov_b32 m0, s35
	v_lshl_add_u64 v[218:219], v[218:219], 0, s[8:9]
	s_add_u32 s2, s14, 0x40080
	ds_read_b128 v[186:189], v148 offset:49152
	ds_read_b128 v[190:193], v148 offset:50176
	ds_read_b128 v[194:197], v148 offset:51200
	ds_read_b128 v[198:201], v148 offset:52224
	ds_read_b128 v[202:205], v148 offset:53248
	ds_read_b128 v[206:209], v148 offset:54272
	ds_read_b128 v[210:213], v148 offset:55296
	ds_read_b128 v[214:217], v148 offset:56320
	global_load_lds_dwordx4 v[218:219], off
	v_lshl_add_u64 v[218:219], v[220:221], 0, s[8:9]
	s_mov_b32 m0, s36
	s_addc_u32 s3, s15, 0
	global_load_lds_dwordx4 v[218:219], off
	v_lshl_add_u64 v[218:219], s[2:3], 0, v[134:135]
	s_mov_b32 m0, s37
	s_nop 0
	global_load_lds_dwordx4 v[218:219], off
	v_lshl_add_u64 v[218:219], s[2:3], 0, v[130:131]
	s_mov_b32 m0, s38
	s_nop 0
	global_load_lds_dwordx4 v[218:219], off
	v_lshl_add_u64 v[218:219], v[222:223], 0, s[8:9]
	s_mov_b32 m0, s22
	s_nop 0
	global_load_lds_dwordx4 v[218:219], off
	v_lshl_add_u64 v[218:219], v[224:225], 0, s[8:9]
	s_mov_b32 m0, s23
	s_nop 0
	global_load_lds_dwordx4 v[218:219], off
	s_waitcnt vmcnt(8)
	s_waitcnt lgkmcnt(0)
	s_setprio 1
	s_barrier
	v_mfma_f32_16x16x32_bf16 v[62:65], v[152:155], v[186:189], v[62:65]
	v_mfma_f32_16x16x32_bf16 v[58:61], v[160:163], v[186:189], v[58:61]
	v_mfma_f32_16x16x32_bf16 v[50:53], v[152:155], v[194:197], v[50:53]
	v_mfma_f32_16x16x32_bf16 v[42:45], v[160:163], v[194:197], v[42:45]
	v_mfma_f32_16x16x32_bf16 v[34:37], v[152:155], v[202:205], v[34:37]
	v_mfma_f32_16x16x32_bf16 v[26:29], v[160:163], v[202:205], v[26:29]
	v_mfma_f32_16x16x32_bf16 v[18:21], v[152:155], v[210:213], v[18:21]
	v_mfma_f32_16x16x32_bf16 v[10:13], v[160:163], v[210:213], v[10:13]
	v_mfma_f32_16x16x32_bf16 v[62:65], v[156:159], v[190:193], v[62:65]
	v_mfma_f32_16x16x32_bf16 v[58:61], v[164:167], v[190:193], v[58:61]
	v_mfma_f32_16x16x32_bf16 v[50:53], v[156:159], v[198:201], v[50:53]
	v_mfma_f32_16x16x32_bf16 v[42:45], v[164:167], v[198:201], v[42:45]
	v_mfma_f32_16x16x32_bf16 v[34:37], v[156:159], v[206:209], v[34:37]
	v_mfma_f32_16x16x32_bf16 v[26:29], v[164:167], v[206:209], v[26:29]
	v_mfma_f32_16x16x32_bf16 v[18:21], v[156:159], v[214:217], v[18:21]
	v_mfma_f32_16x16x32_bf16 v[10:13], v[164:167], v[214:217], v[10:13]
	v_mfma_f32_16x16x32_bf16 v[54:57], v[168:171], v[186:189], v[54:57]
	v_mfma_f32_16x16x32_bf16 v[46:49], v[178:181], v[186:189], v[46:49]
	v_mfma_f32_16x16x32_bf16 v[38:41], v[168:171], v[194:197], v[38:41]
	v_mfma_f32_16x16x32_bf16 v[30:33], v[178:181], v[194:197], v[30:33]
	v_mfma_f32_16x16x32_bf16 v[22:25], v[168:171], v[202:205], v[22:25]
	v_mfma_f32_16x16x32_bf16 v[14:17], v[178:181], v[202:205], v[14:17]
	v_mfma_f32_16x16x32_bf16 v[6:9], v[168:171], v[210:213], v[6:9]
	v_mfma_f32_16x16x32_bf16 v[2:5], v[178:181], v[210:213], v[2:5]
	v_mfma_f32_16x16x32_bf16 v[54:57], v[172:175], v[190:193], v[54:57]
	v_mfma_f32_16x16x32_bf16 v[46:49], v[182:185], v[190:193], v[46:49]
	v_mfma_f32_16x16x32_bf16 v[38:41], v[172:175], v[198:201], v[38:41]
	v_mfma_f32_16x16x32_bf16 v[30:33], v[182:185], v[198:201], v[30:33]
	v_mfma_f32_16x16x32_bf16 v[22:25], v[172:175], v[206:209], v[22:25]
	v_mfma_f32_16x16x32_bf16 v[14:17], v[182:185], v[206:209], v[14:17]
	v_mfma_f32_16x16x32_bf16 v[6:9], v[172:175], v[214:217], v[6:9]
	v_mfma_f32_16x16x32_bf16 v[2:5], v[182:185], v[214:217], v[2:5]
	s_barrier
	s_setprio 0
	s_add_i32 s26, s26, 2
	s_add_u32 s12, s12, 0x100
	s_addc_u32 s13, s13, 0
	s_cmp_gt_u32 s26, 13
	s_cbranch_scc0 .LBB0_646
	s_cmpk_lt_u32 s16, 0x100
	s_mov_b32 s28, s33
	v_readlane_b32 s30, v253, 58
	s_cbranch_scc0 .LBB0_649
	s_barrier

.Lpk1098_peel:
	ds_read_b128 v[152:155], v148
	ds_read_b128 v[156:159], v148 offset:1024
	ds_read_b128 v[160:163], v148 offset:2048
	ds_read_b128 v[164:167], v148 offset:3072
	ds_read_b128 v[168:171], v149
	ds_read_b128 v[172:175], v149 offset:1024
	ds_read_b128 v[178:181], v149 offset:2048
	ds_read_b128 v[182:185], v149 offset:3072
	s_add_u32 s2, s30, 0xfffc0080
	s_addc_u32 s3, s31, -1
	s_cmp_eq_u32 s56, 12
	s_cselect_b32 s3, s15, s3
	s_cselect_b32 s2, s17, s2
	s_cselect_b32 s35, s52, s55
	s_cselect_b32 s34, s53, s54
	v_lshl_add_u64 v[144:145], s[30:31], 0, v[138:139]
	s_add_i32 m0, s40, 0xc000
	ds_read_b128 v[186:189], v150
	ds_read_b128 v[190:193], v150 offset:1024
	ds_read_b128 v[194:197], v150 offset:2048
	ds_read_b128 v[198:201], v150 offset:3072
	ds_read_b128 v[202:205], v150 offset:4096
	ds_read_b128 v[206:209], v150 offset:5120
	ds_read_b128 v[210:213], v150 offset:6144
	ds_read_b128 v[214:217], v150 offset:7168
	global_load_lds_dwordx4 v[144:145], off
	v_lshl_add_u64 v[144:145], s[30:31], 0, v[140:141]
	s_add_i32 m0, s40, 0xe000
	s_nop 0
	global_load_lds_dwordx4 v[144:145], off
	s_waitcnt vmcnt(8)
	s_waitcnt lgkmcnt(0)
	s_setprio 1
	s_barrier
	v_mfma_f32_16x16x32_bf16 v[126:129], v[152:155], v[186:189], 0
	v_mfma_f32_16x16x32_bf16 v[122:125], v[160:163], v[186:189], 0
	v_mfma_f32_16x16x32_bf16 v[114:117], v[152:155], v[194:197], 0
	v_mfma_f32_16x16x32_bf16 v[106:109], v[160:163], v[194:197], 0
	v_mfma_f32_16x16x32_bf16 v[98:101], v[152:155], v[202:205], 0
	v_mfma_f32_16x16x32_bf16 v[90:93], v[160:163], v[202:205], 0
	v_mfma_f32_16x16x32_bf16 v[82:85], v[152:155], v[210:213], 0
	v_mfma_f32_16x16x32_bf16 v[74:77], v[160:163], v[210:213], 0
	v_mfma_f32_16x16x32_bf16 v[126:129], v[156:159], v[190:193], v[126:129]
	v_mfma_f32_16x16x32_bf16 v[122:125], v[164:167], v[190:193], v[122:125]
	v_mfma_f32_16x16x32_bf16 v[114:117], v[156:159], v[198:201], v[114:117]
	v_mfma_f32_16x16x32_bf16 v[106:109], v[164:167], v[198:201], v[106:109]
	v_mfma_f32_16x16x32_bf16 v[98:101], v[156:159], v[206:209], v[98:101]
	v_mfma_f32_16x16x32_bf16 v[90:93], v[164:167], v[206:209], v[90:93]
	v_mfma_f32_16x16x32_bf16 v[82:85], v[156:159], v[214:217], v[82:85]
	v_mfma_f32_16x16x32_bf16 v[74:77], v[164:167], v[214:217], v[74:77]
	v_mfma_f32_16x16x32_bf16 v[118:121], v[168:171], v[186:189], 0
	v_mfma_f32_16x16x32_bf16 v[110:113], v[178:181], v[186:189], 0
	v_mfma_f32_16x16x32_bf16 v[102:105], v[168:171], v[194:197], 0
	v_mfma_f32_16x16x32_bf16 v[94:97], v[178:181], v[194:197], 0
	v_mfma_f32_16x16x32_bf16 v[86:89], v[168:171], v[202:205], 0
	v_mfma_f32_16x16x32_bf16 v[78:81], v[178:181], v[202:205], 0
	v_mfma_f32_16x16x32_bf16 v[70:73], v[168:171], v[210:213], 0
	v_mfma_f32_16x16x32_bf16 v[66:69], v[178:181], v[210:213], 0
	v_mfma_f32_16x16x32_bf16 v[118:121], v[172:175], v[190:193], v[118:121]
	v_mfma_f32_16x16x32_bf16 v[110:113], v[182:185], v[190:193], v[110:113]
	v_mfma_f32_16x16x32_bf16 v[102:105], v[172:175], v[198:201], v[102:105]
	v_mfma_f32_16x16x32_bf16 v[94:97], v[182:185], v[198:201], v[94:97]
	v_mfma_f32_16x16x32_bf16 v[86:89], v[172:175], v[206:209], v[86:89]
	v_mfma_f32_16x16x32_bf16 v[78:81], v[182:185], v[206:209], v[78:81]
	v_mfma_f32_16x16x32_bf16 v[70:73], v[172:175], v[214:217], v[70:73]
	v_mfma_f32_16x16x32_bf16 v[66:69], v[182:185], v[214:217], v[66:69]
	s_barrier
	s_setprio 0
	s_add_i32 s57, s47, s39
	v_lshl_add_u64 v[144:145], s[34:35], 0, v[132:133]
	s_mov_b32 m0, s57
	ds_read_b128 v[186:189], v150 offset:16384
	ds_read_b128 v[190:193], v150 offset:17408
	ds_read_b128 v[194:197], v150 offset:18432
	ds_read_b128 v[198:201], v150 offset:19456
	ds_read_b128 v[202:205], v150 offset:20480
	ds_read_b128 v[206:209], v150 offset:21504
	ds_read_b128 v[210:213], v150 offset:22528
	ds_read_b128 v[214:217], v150 offset:23552
	global_load_lds_dwordx4 v[144:145], off
	s_add_i32 m0, s57, 0x2000
	s_add_u32 s58, s34, 0x40000
	v_lshl_add_u64 v[218:219], s[34:35], 0, v[136:137]
	s_addc_u32 s59, s35, 0
	s_add_i32 s57, s48, s39
	global_load_lds_dwordx4 v[218:219], off
	v_lshl_add_u64 v[220:221], s[58:59], 0, v[132:133]
	s_mov_b32 m0, s57
	v_lshl_add_u64 v[222:223], s[2:3], 0, v[134:135]
	global_load_lds_dwordx4 v[220:221], off
	v_lshl_add_u64 v[220:221], s[58:59], 0, v[136:137]
	s_add_i32 m0, s57, 0x2000
	s_nop 0
	global_load_lds_dwordx4 v[220:221], off
	v_lshl_add_u64 v[220:221], s[2:3], 0, v[130:131]
	s_mov_b32 m0, s40
	s_nop 0
	global_load_lds_dwordx4 v[220:221], off
	s_mov_b32 m0, s29
	s_nop 0
	global_load_lds_dwordx4 v[222:223], off
	s_waitcnt vmcnt(8)
	s_waitcnt lgkmcnt(0)
	s_setprio 1
	s_barrier
	v_mfma_f32_16x16x32_bf16 v[62:65], v[152:155], v[186:189], 0
	v_mfma_f32_16x16x32_bf16 v[58:61], v[160:163], v[186:189], 0
	v_mfma_f32_16x16x32_bf16 v[50:53], v[152:155], v[194:197], 0
	v_mfma_f32_16x16x32_bf16 v[42:45], v[160:163], v[194:197], 0
	v_mfma_f32_16x16x32_bf16 v[34:37], v[152:155], v[202:205], 0
	v_mfma_f32_16x16x32_bf16 v[26:29], v[160:163], v[202:205], 0
	v_mfma_f32_16x16x32_bf16 v[18:21], v[152:155], v[210:213], 0
	v_mfma_f32_16x16x32_bf16 v[10:13], v[160:163], v[210:213], 0
	v_mfma_f32_16x16x32_bf16 v[62:65], v[156:159], v[190:193], v[62:65]
	v_mfma_f32_16x16x32_bf16 v[58:61], v[164:167], v[190:193], v[58:61]
	v_mfma_f32_16x16x32_bf16 v[50:53], v[156:159], v[198:201], v[50:53]
	v_mfma_f32_16x16x32_bf16 v[42:45], v[164:167], v[198:201], v[42:45]
	v_mfma_f32_16x16x32_bf16 v[34:37], v[156:159], v[206:209], v[34:37]
	v_mfma_f32_16x16x32_bf16 v[26:29], v[164:167], v[206:209], v[26:29]
	v_mfma_f32_16x16x32_bf16 v[18:21], v[156:159], v[214:217], v[18:21]
	v_mfma_f32_16x16x32_bf16 v[10:13], v[164:167], v[214:217], v[10:13]
	v_mfma_f32_16x16x32_bf16 v[54:57], v[168:171], v[186:189], 0
	v_mfma_f32_16x16x32_bf16 v[46:49], v[178:181], v[186:189], 0
	v_mfma_f32_16x16x32_bf16 v[38:41], v[168:171], v[194:197], 0
	v_mfma_f32_16x16x32_bf16 v[30:33], v[178:181], v[194:197], 0
	v_mfma_f32_16x16x32_bf16 v[22:25], v[168:171], v[202:205], 0
	v_mfma_f32_16x16x32_bf16 v[14:17], v[178:181], v[202:205], 0
	v_mfma_f32_16x16x32_bf16 v[6:9], v[168:171], v[210:213], 0
	v_mfma_f32_16x16x32_bf16 v[2:5], v[178:181], v[210:213], 0
	v_mfma_f32_16x16x32_bf16 v[54:57], v[172:175], v[190:193], v[54:57]
	v_mfma_f32_16x16x32_bf16 v[46:49], v[182:185], v[190:193], v[46:49]
	v_mfma_f32_16x16x32_bf16 v[38:41], v[172:175], v[198:201], v[38:41]
	v_mfma_f32_16x16x32_bf16 v[30:33], v[182:185], v[198:201], v[30:33]
	v_mfma_f32_16x16x32_bf16 v[22:25], v[172:175], v[206:209], v[22:25]
	v_mfma_f32_16x16x32_bf16 v[14:17], v[182:185], v[206:209], v[14:17]
	v_mfma_f32_16x16x32_bf16 v[6:9], v[172:175], v[214:217], v[6:9]
	v_mfma_f32_16x16x32_bf16 v[2:5], v[182:185], v[214:217], v[2:5]
	s_barrier
	s_setprio 0
	s_add_i32 s57, 0, 0x18000
	v_add_u32_e32 v151, s57, v146
	s_add_i32 s58, 0, 0x1c000
	ds_read_b128 v[152:155], v151
	ds_read_b128 v[156:159], v151 offset:1024
	ds_read_b128 v[160:163], v151 offset:2048
	ds_read_b128 v[164:167], v151 offset:3072
	v_add_u32_e32 v151, s58, v146
	ds_read_b128 v[168:171], v151
	ds_read_b128 v[172:175], v151 offset:1024
	ds_read_b128 v[178:181], v151 offset:2048
	ds_read_b128 v[182:185], v151 offset:3072
	s_add_u32 s2, s2, 0x40000
	s_addc_u32 s3, s3, 0
	s_mov_b32 m0, s41
	v_lshl_add_u64 v[224:225], s[2:3], 0, v[130:131]
	ds_read_b128 v[186:189], v150 offset:32768
	ds_read_b128 v[190:193], v150 offset:33792
	ds_read_b128 v[194:197], v150 offset:34816
	ds_read_b128 v[198:201], v150 offset:35840
	ds_read_b128 v[202:205], v150 offset:36864
	ds_read_b128 v[206:209], v150 offset:37888
	ds_read_b128 v[210:213], v150 offset:38912
	ds_read_b128 v[214:217], v150 offset:39936
	global_load_lds_dwordx4 v[224:225], off
	v_lshl_add_u64 v[224:225], s[2:3], 0, v[134:135]
	s_mov_b32 m0, s42
	s_nop 0
	global_load_lds_dwordx4 v[224:225], off
	s_waitcnt vmcnt(8)
	s_waitcnt lgkmcnt(0)
	s_setprio 1
	s_barrier
	v_mfma_f32_16x16x32_bf16 v[126:129], v[152:155], v[186:189], v[126:129]
	v_mfma_f32_16x16x32_bf16 v[122:125], v[160:163], v[186:189], v[122:125]
	v_mfma_f32_16x16x32_bf16 v[114:117], v[152:155], v[194:197], v[114:117]
	v_mfma_f32_16x16x32_bf16 v[106:109], v[160:163], v[194:197], v[106:109]
	v_mfma_f32_16x16x32_bf16 v[98:101], v[152:155], v[202:205], v[98:101]
	v_mfma_f32_16x16x32_bf16 v[90:93], v[160:163], v[202:205], v[90:93]
	v_mfma_f32_16x16x32_bf16 v[82:85], v[152:155], v[210:213], v[82:85]
	v_mfma_f32_16x16x32_bf16 v[74:77], v[160:163], v[210:213], v[74:77]
	v_mfma_f32_16x16x32_bf16 v[126:129], v[156:159], v[190:193], v[126:129]
	v_mfma_f32_16x16x32_bf16 v[122:125], v[164:167], v[190:193], v[122:125]
	v_mfma_f32_16x16x32_bf16 v[114:117], v[156:159], v[198:201], v[114:117]
	v_mfma_f32_16x16x32_bf16 v[106:109], v[164:167], v[198:201], v[106:109]
	v_mfma_f32_16x16x32_bf16 v[98:101], v[156:159], v[206:209], v[98:101]
	v_mfma_f32_16x16x32_bf16 v[90:93], v[164:167], v[206:209], v[90:93]
	v_mfma_f32_16x16x32_bf16 v[82:85], v[156:159], v[214:217], v[82:85]
	v_mfma_f32_16x16x32_bf16 v[74:77], v[164:167], v[214:217], v[74:77]
	v_mfma_f32_16x16x32_bf16 v[118:121], v[168:171], v[186:189], v[118:121]
	v_mfma_f32_16x16x32_bf16 v[110:113], v[178:181], v[186:189], v[110:113]
	v_mfma_f32_16x16x32_bf16 v[102:105], v[168:171], v[194:197], v[102:105]
	v_mfma_f32_16x16x32_bf16 v[94:97], v[178:181], v[194:197], v[94:97]
	v_mfma_f32_16x16x32_bf16 v[86:89], v[168:171], v[202:205], v[86:89]
	v_mfma_f32_16x16x32_bf16 v[78:81], v[178:181], v[202:205], v[78:81]
	v_mfma_f32_16x16x32_bf16 v[70:73], v[168:171], v[210:213], v[70:73]
	v_mfma_f32_16x16x32_bf16 v[66:69], v[178:181], v[210:213], v[66:69]
	v_mfma_f32_16x16x32_bf16 v[118:121], v[172:175], v[190:193], v[118:121]
	v_mfma_f32_16x16x32_bf16 v[110:113], v[182:185], v[190:193], v[110:113]
	v_mfma_f32_16x16x32_bf16 v[102:105], v[172:175], v[198:201], v[102:105]
	v_mfma_f32_16x16x32_bf16 v[94:97], v[182:185], v[198:201], v[94:97]
	v_mfma_f32_16x16x32_bf16 v[86:89], v[172:175], v[206:209], v[86:89]
	v_mfma_f32_16x16x32_bf16 v[78:81], v[182:185], v[206:209], v[78:81]
	v_mfma_f32_16x16x32_bf16 v[70:73], v[172:175], v[214:217], v[70:73]
	v_mfma_f32_16x16x32_bf16 v[66:69], v[182:185], v[214:217], v[66:69]
	s_barrier
	s_setprio 0
	s_add_i32 s2, s57, s39
	v_lshl_add_u64 v[144:145], v[144:145], 0, s[6:7]
	s_mov_b32 m0, s2
	ds_read_b128 v[186:189], v150 offset:49152
	ds_read_b128 v[190:193], v150 offset:50176
	ds_read_b128 v[194:197], v150 offset:51200
	ds_read_b128 v[198:201], v150 offset:52224
	ds_read_b128 v[202:205], v150 offset:53248
	ds_read_b128 v[206:209], v150 offset:54272
	ds_read_b128 v[210:213], v150 offset:55296
	ds_read_b128 v[214:217], v150 offset:56320
	global_load_lds_dwordx4 v[144:145], off
	s_add_i32 m0, s2, 0x2000
	s_add_u32 s2, s34, 0x40080
	v_lshl_add_u64 v[144:145], v[218:219], 0, s[6:7]
	s_addc_u32 s3, s35, 0
	s_add_i32 s34, s58, s39
	global_load_lds_dwordx4 v[144:145], off
	v_lshl_add_u64 v[144:145], s[2:3], 0, v[132:133]
	s_mov_b32 m0, s34
	s_nop 0
	global_load_lds_dwordx4 v[144:145], off
	v_lshl_add_u64 v[144:145], s[2:3], 0, v[136:137]
	s_add_i32 m0, s34, 0x2000
	s_nop 0
	global_load_lds_dwordx4 v[144:145], off
	v_lshl_add_u64 v[144:145], v[220:221], 0, s[6:7]
	s_mov_b32 m0, s44
	s_nop 0
	global_load_lds_dwordx4 v[144:145], off
	v_lshl_add_u64 v[144:145], v[222:223], 0, s[6:7]
	s_mov_b32 m0, s45
	s_nop 0
	global_load_lds_dwordx4 v[144:145], off
	s_waitcnt vmcnt(8)
	s_waitcnt lgkmcnt(0)
	s_setprio 1
	s_barrier
	v_mfma_f32_16x16x32_bf16 v[62:65], v[152:155], v[186:189], v[62:65]
	v_mfma_f32_16x16x32_bf16 v[58:61], v[160:163], v[186:189], v[58:61]
	v_mfma_f32_16x16x32_bf16 v[50:53], v[152:155], v[194:197], v[50:53]
	v_mfma_f32_16x16x32_bf16 v[42:45], v[160:163], v[194:197], v[42:45]
	v_mfma_f32_16x16x32_bf16 v[34:37], v[152:155], v[202:205], v[34:37]
	v_mfma_f32_16x16x32_bf16 v[26:29], v[160:163], v[202:205], v[26:29]
	v_mfma_f32_16x16x32_bf16 v[18:21], v[152:155], v[210:213], v[18:21]
	v_mfma_f32_16x16x32_bf16 v[10:13], v[160:163], v[210:213], v[10:13]
	v_mfma_f32_16x16x32_bf16 v[62:65], v[156:159], v[190:193], v[62:65]
	v_mfma_f32_16x16x32_bf16 v[58:61], v[164:167], v[190:193], v[58:61]
	v_mfma_f32_16x16x32_bf16 v[50:53], v[156:159], v[198:201], v[50:53]
	v_mfma_f32_16x16x32_bf16 v[42:45], v[164:167], v[198:201], v[42:45]
	v_mfma_f32_16x16x32_bf16 v[34:37], v[156:159], v[206:209], v[34:37]
	v_mfma_f32_16x16x32_bf16 v[26:29], v[164:167], v[206:209], v[26:29]
	v_mfma_f32_16x16x32_bf16 v[18:21], v[156:159], v[214:217], v[18:21]
	v_mfma_f32_16x16x32_bf16 v[10:13], v[164:167], v[214:217], v[10:13]
	v_mfma_f32_16x16x32_bf16 v[54:57], v[168:171], v[186:189], v[54:57]
	v_mfma_f32_16x16x32_bf16 v[46:49], v[178:181], v[186:189], v[46:49]
	v_mfma_f32_16x16x32_bf16 v[38:41], v[168:171], v[194:197], v[38:41]
	v_mfma_f32_16x16x32_bf16 v[30:33], v[178:181], v[194:197], v[30:33]
	v_mfma_f32_16x16x32_bf16 v[22:25], v[168:171], v[202:205], v[22:25]
	v_mfma_f32_16x16x32_bf16 v[14:17], v[178:181], v[202:205], v[14:17]
	v_mfma_f32_16x16x32_bf16 v[6:9], v[168:171], v[210:213], v[6:9]
	v_mfma_f32_16x16x32_bf16 v[2:5], v[178:181], v[210:213], v[2:5]
	v_mfma_f32_16x16x32_bf16 v[54:57], v[172:175], v[190:193], v[54:57]
	v_mfma_f32_16x16x32_bf16 v[46:49], v[182:185], v[190:193], v[46:49]
	v_mfma_f32_16x16x32_bf16 v[38:41], v[172:175], v[198:201], v[38:41]
	v_mfma_f32_16x16x32_bf16 v[30:33], v[182:185], v[198:201], v[30:33]
	v_mfma_f32_16x16x32_bf16 v[22:25], v[172:175], v[206:209], v[22:25]
	v_mfma_f32_16x16x32_bf16 v[14:17], v[182:185], v[206:209], v[14:17]
	v_mfma_f32_16x16x32_bf16 v[6:9], v[172:175], v[214:217], v[6:9]
	v_mfma_f32_16x16x32_bf16 v[2:5], v[182:185], v[214:217], v[2:5]
	s_barrier
	s_setprio 0
	s_add_i32 s56, s56, 2
	s_add_u32 s30, s30, 0x100
	s_addc_u32 s31, s31, 0
	s_add_u32 s54, s54, 0x100
	s_addc_u32 s55, s55, 0
	s_cmp_gt_u32 s56, 13
	s_cbranch_scc0 .LBB0_1098
	s_branch .Lpk1098_exit
.LBB0_1098:
	ds_read_b128 v[152:155], v148
	ds_read_b128 v[156:159], v148 offset:1024
	ds_read_b128 v[160:163], v148 offset:2048
	ds_read_b128 v[164:167], v148 offset:3072
	ds_read_b128 v[168:171], v149
	ds_read_b128 v[172:175], v149 offset:1024
	ds_read_b128 v[178:181], v149 offset:2048
	ds_read_b128 v[182:185], v149 offset:3072
	s_add_u32 s2, s30, 0xfffc0080
	s_addc_u32 s3, s31, -1
	s_cmp_eq_u32 s56, 12
	s_cselect_b32 s3, s15, s3
	s_cselect_b32 s2, s17, s2
	s_cselect_b32 s35, s52, s55
	s_cselect_b32 s34, s53, s54
	v_lshl_add_u64 v[144:145], s[30:31], 0, v[138:139]
	s_add_i32 m0, s40, 0xc000
	ds_read_b128 v[186:189], v150
	ds_read_b128 v[190:193], v150 offset:1024
	ds_read_b128 v[194:197], v150 offset:2048
	ds_read_b128 v[198:201], v150 offset:3072
	ds_read_b128 v[202:205], v150 offset:4096
	ds_read_b128 v[206:209], v150 offset:5120
	ds_read_b128 v[210:213], v150 offset:6144
	ds_read_b128 v[214:217], v150 offset:7168
	global_load_lds_dwordx4 v[144:145], off
	v_lshl_add_u64 v[144:145], s[30:31], 0, v[140:141]
	s_add_i32 m0, s40, 0xe000
	s_nop 0
	global_load_lds_dwordx4 v[144:145], off
	s_waitcnt vmcnt(8)
	s_waitcnt lgkmcnt(0)
	s_setprio 1
	s_barrier
	v_mfma_f32_16x16x32_bf16 v[126:129], v[152:155], v[186:189], v[126:129]
	v_mfma_f32_16x16x32_bf16 v[122:125], v[160:163], v[186:189], v[122:125]
	v_mfma_f32_16x16x32_bf16 v[114:117], v[152:155], v[194:197], v[114:117]
	v_mfma_f32_16x16x32_bf16 v[106:109], v[160:163], v[194:197], v[106:109]
	v_mfma_f32_16x16x32_bf16 v[98:101], v[152:155], v[202:205], v[98:101]
	v_mfma_f32_16x16x32_bf16 v[90:93], v[160:163], v[202:205], v[90:93]
	v_mfma_f32_16x16x32_bf16 v[82:85], v[152:155], v[210:213], v[82:85]
	v_mfma_f32_16x16x32_bf16 v[74:77], v[160:163], v[210:213], v[74:77]
	v_mfma_f32_16x16x32_bf16 v[126:129], v[156:159], v[190:193], v[126:129]
	v_mfma_f32_16x16x32_bf16 v[122:125], v[164:167], v[190:193], v[122:125]
	v_mfma_f32_16x16x32_bf16 v[114:117], v[156:159], v[198:201], v[114:117]
	v_mfma_f32_16x16x32_bf16 v[106:109], v[164:167], v[198:201], v[106:109]
	v_mfma_f32_16x16x32_bf16 v[98:101], v[156:159], v[206:209], v[98:101]
	v_mfma_f32_16x16x32_bf16 v[90:93], v[164:167], v[206:209], v[90:93]
	v_mfma_f32_16x16x32_bf16 v[82:85], v[156:159], v[214:217], v[82:85]
	v_mfma_f32_16x16x32_bf16 v[74:77], v[164:167], v[214:217], v[74:77]
	v_mfma_f32_16x16x32_bf16 v[118:121], v[168:171], v[186:189], v[118:121]
	v_mfma_f32_16x16x32_bf16 v[110:113], v[178:181], v[186:189], v[110:113]
	v_mfma_f32_16x16x32_bf16 v[102:105], v[168:171], v[194:197], v[102:105]
	v_mfma_f32_16x16x32_bf16 v[94:97], v[178:181], v[194:197], v[94:97]
	v_mfma_f32_16x16x32_bf16 v[86:89], v[168:171], v[202:205], v[86:89]
	v_mfma_f32_16x16x32_bf16 v[78:81], v[178:181], v[202:205], v[78:81]
	v_mfma_f32_16x16x32_bf16 v[70:73], v[168:171], v[210:213], v[70:73]
	v_mfma_f32_16x16x32_bf16 v[66:69], v[178:181], v[210:213], v[66:69]
	v_mfma_f32_16x16x32_bf16 v[118:121], v[172:175], v[190:193], v[118:121]
	v_mfma_f32_16x16x32_bf16 v[110:113], v[182:185], v[190:193], v[110:113]
	v_mfma_f32_16x16x32_bf16 v[102:105], v[172:175], v[198:201], v[102:105]
	v_mfma_f32_16x16x32_bf16 v[94:97], v[182:185], v[198:201], v[94:97]
	v_mfma_f32_16x16x32_bf16 v[86:89], v[172:175], v[206:209], v[86:89]
	v_mfma_f32_16x16x32_bf16 v[78:81], v[182:185], v[206:209], v[78:81]
	v_mfma_f32_16x16x32_bf16 v[70:73], v[172:175], v[214:217], v[70:73]
	v_mfma_f32_16x16x32_bf16 v[66:69], v[182:185], v[214:217], v[66:69]
	s_barrier
	s_setprio 0
	s_add_i32 s57, s47, s39
	v_lshl_add_u64 v[144:145], s[34:35], 0, v[132:133]
	s_mov_b32 m0, s57
	ds_read_b128 v[186:189], v150 offset:16384
	ds_read_b128 v[190:193], v150 offset:17408
	ds_read_b128 v[194:197], v150 offset:18432
	ds_read_b128 v[198:201], v150 offset:19456
	ds_read_b128 v[202:205], v150 offset:20480
	ds_read_b128 v[206:209], v150 offset:21504
	ds_read_b128 v[210:213], v150 offset:22528
	ds_read_b128 v[214:217], v150 offset:23552
	global_load_lds_dwordx4 v[144:145], off
	s_add_i32 m0, s57, 0x2000
	s_add_u32 s58, s34, 0x40000
	v_lshl_add_u64 v[218:219], s[34:35], 0, v[136:137]
	s_addc_u32 s59, s35, 0
	s_add_i32 s57, s48, s39
	global_load_lds_dwordx4 v[218:219], off
	v_lshl_add_u64 v[220:221], s[58:59], 0, v[132:133]
	s_mov_b32 m0, s57
	v_lshl_add_u64 v[222:223], s[2:3], 0, v[134:135]
	global_load_lds_dwordx4 v[220:221], off
	v_lshl_add_u64 v[220:221], s[58:59], 0, v[136:137]
	s_add_i32 m0, s57, 0x2000
	s_nop 0
	global_load_lds_dwordx4 v[220:221], off
	v_lshl_add_u64 v[220:221], s[2:3], 0, v[130:131]
	s_mov_b32 m0, s40
	s_nop 0
	global_load_lds_dwordx4 v[220:221], off
	s_mov_b32 m0, s29
	s_nop 0
	global_load_lds_dwordx4 v[222:223], off
	s_waitcnt vmcnt(8)
	s_waitcnt lgkmcnt(0)
	s_setprio 1
	s_barrier
	v_mfma_f32_16x16x32_bf16 v[62:65], v[152:155], v[186:189], v[62:65]
	v_mfma_f32_16x16x32_bf16 v[58:61], v[160:163], v[186:189], v[58:61]
	v_mfma_f32_16x16x32_bf16 v[50:53], v[152:155], v[194:197], v[50:53]
	v_mfma_f32_16x16x32_bf16 v[42:45], v[160:163], v[194:197], v[42:45]
	v_mfma_f32_16x16x32_bf16 v[34:37], v[152:155], v[202:205], v[34:37]
	v_mfma_f32_16x16x32_bf16 v[26:29], v[160:163], v[202:205], v[26:29]
	v_mfma_f32_16x16x32_bf16 v[18:21], v[152:155], v[210:213], v[18:21]
	v_mfma_f32_16x16x32_bf16 v[10:13], v[160:163], v[210:213], v[10:13]
	v_mfma_f32_16x16x32_bf16 v[62:65], v[156:159], v[190:193], v[62:65]
	v_mfma_f32_16x16x32_bf16 v[58:61], v[164:167], v[190:193], v[58:61]
	v_mfma_f32_16x16x32_bf16 v[50:53], v[156:159], v[198:201], v[50:53]
	v_mfma_f32_16x16x32_bf16 v[42:45], v[164:167], v[198:201], v[42:45]
	v_mfma_f32_16x16x32_bf16 v[34:37], v[156:159], v[206:209], v[34:37]
	v_mfma_f32_16x16x32_bf16 v[26:29], v[164:167], v[206:209], v[26:29]
	v_mfma_f32_16x16x32_bf16 v[18:21], v[156:159], v[214:217], v[18:21]
	v_mfma_f32_16x16x32_bf16 v[10:13], v[164:167], v[214:217], v[10:13]
	v_mfma_f32_16x16x32_bf16 v[54:57], v[168:171], v[186:189], v[54:57]
	v_mfma_f32_16x16x32_bf16 v[46:49], v[178:181], v[186:189], v[46:49]
	v_mfma_f32_16x16x32_bf16 v[38:41], v[168:171], v[194:197], v[38:41]
	v_mfma_f32_16x16x32_bf16 v[30:33], v[178:181], v[194:197], v[30:33]
	v_mfma_f32_16x16x32_bf16 v[22:25], v[168:171], v[202:205], v[22:25]
	v_mfma_f32_16x16x32_bf16 v[14:17], v[178:181], v[202:205], v[14:17]
	v_mfma_f32_16x16x32_bf16 v[6:9], v[168:171], v[210:213], v[6:9]
	v_mfma_f32_16x16x32_bf16 v[2:5], v[178:181], v[210:213], v[2:5]
	v_mfma_f32_16x16x32_bf16 v[54:57], v[172:175], v[190:193], v[54:57]
	v_mfma_f32_16x16x32_bf16 v[46:49], v[182:185], v[190:193], v[46:49]
	v_mfma_f32_16x16x32_bf16 v[38:41], v[172:175], v[198:201], v[38:41]
	v_mfma_f32_16x16x32_bf16 v[30:33], v[182:185], v[198:201], v[30:33]
	v_mfma_f32_16x16x32_bf16 v[22:25], v[172:175], v[206:209], v[22:25]
	v_mfma_f32_16x16x32_bf16 v[14:17], v[182:185], v[206:209], v[14:17]
	v_mfma_f32_16x16x32_bf16 v[6:9], v[172:175], v[214:217], v[6:9]
	v_mfma_f32_16x16x32_bf16 v[2:5], v[182:185], v[214:217], v[2:5]
	s_barrier
	s_setprio 0
	s_add_i32 s57, 0, 0x18000
	v_add_u32_e32 v151, s57, v146
	s_add_i32 s58, 0, 0x1c000
	ds_read_b128 v[152:155], v151
	ds_read_b128 v[156:159], v151 offset:1024
	ds_read_b128 v[160:163], v151 offset:2048
	ds_read_b128 v[164:167], v151 offset:3072
	v_add_u32_e32 v151, s58, v146
	ds_read_b128 v[168:171], v151
	ds_read_b128 v[172:175], v151 offset:1024
	ds_read_b128 v[178:181], v151 offset:2048
	ds_read_b128 v[182:185], v151 offset:3072
	s_add_u32 s2, s2, 0x40000
	s_addc_u32 s3, s3, 0
	s_mov_b32 m0, s41
	v_lshl_add_u64 v[224:225], s[2:3], 0, v[130:131]
	ds_read_b128 v[186:189], v150 offset:32768
	ds_read_b128 v[190:193], v150 offset:33792
	ds_read_b128 v[194:197], v150 offset:34816
	ds_read_b128 v[198:201], v150 offset:35840
	ds_read_b128 v[202:205], v150 offset:36864
	ds_read_b128 v[206:209], v150 offset:37888
	ds_read_b128 v[210:213], v150 offset:38912
	ds_read_b128 v[214:217], v150 offset:39936
	global_load_lds_dwordx4 v[224:225], off
	v_lshl_add_u64 v[224:225], s[2:3], 0, v[134:135]
	s_mov_b32 m0, s42
	s_nop 0
	global_load_lds_dwordx4 v[224:225], off
	s_waitcnt vmcnt(8)
	s_waitcnt lgkmcnt(0)
	s_setprio 1
	s_barrier
	v_mfma_f32_16x16x32_bf16 v[126:129], v[152:155], v[186:189], v[126:129]
	v_mfma_f32_16x16x32_bf16 v[122:125], v[160:163], v[186:189], v[122:125]
	v_mfma_f32_16x16x32_bf16 v[114:117], v[152:155], v[194:197], v[114:117]
	v_mfma_f32_16x16x32_bf16 v[106:109], v[160:163], v[194:197], v[106:109]
	v_mfma_f32_16x16x32_bf16 v[98:101], v[152:155], v[202:205], v[98:101]
	v_mfma_f32_16x16x32_bf16 v[90:93], v[160:163], v[202:205], v[90:93]
	v_mfma_f32_16x16x32_bf16 v[82:85], v[152:155], v[210:213], v[82:85]
	v_mfma_f32_16x16x32_bf16 v[74:77], v[160:163], v[210:213], v[74:77]
	v_mfma_f32_16x16x32_bf16 v[126:129], v[156:159], v[190:193], v[126:129]
	v_mfma_f32_16x16x32_bf16 v[122:125], v[164:167], v[190:193], v[122:125]
	v_mfma_f32_16x16x32_bf16 v[114:117], v[156:159], v[198:201], v[114:117]
	v_mfma_f32_16x16x32_bf16 v[106:109], v[164:167], v[198:201], v[106:109]
	v_mfma_f32_16x16x32_bf16 v[98:101], v[156:159], v[206:209], v[98:101]
	v_mfma_f32_16x16x32_bf16 v[90:93], v[164:167], v[206:209], v[90:93]
	v_mfma_f32_16x16x32_bf16 v[82:85], v[156:159], v[214:217], v[82:85]
	v_mfma_f32_16x16x32_bf16 v[74:77], v[164:167], v[214:217], v[74:77]
	v_mfma_f32_16x16x32_bf16 v[118:121], v[168:171], v[186:189], v[118:121]
	v_mfma_f32_16x16x32_bf16 v[110:113], v[178:181], v[186:189], v[110:113]
	v_mfma_f32_16x16x32_bf16 v[102:105], v[168:171], v[194:197], v[102:105]
	v_mfma_f32_16x16x32_bf16 v[94:97], v[178:181], v[194:197], v[94:97]
	v_mfma_f32_16x16x32_bf16 v[86:89], v[168:171], v[202:205], v[86:89]
	v_mfma_f32_16x16x32_bf16 v[78:81], v[178:181], v[202:205], v[78:81]
	v_mfma_f32_16x16x32_bf16 v[70:73], v[168:171], v[210:213], v[70:73]
	v_mfma_f32_16x16x32_bf16 v[66:69], v[178:181], v[210:213], v[66:69]
	v_mfma_f32_16x16x32_bf16 v[118:121], v[172:175], v[190:193], v[118:121]
	v_mfma_f32_16x16x32_bf16 v[110:113], v[182:185], v[190:193], v[110:113]
	v_mfma_f32_16x16x32_bf16 v[102:105], v[172:175], v[198:201], v[102:105]
	v_mfma_f32_16x16x32_bf16 v[94:97], v[182:185], v[198:201], v[94:97]
	v_mfma_f32_16x16x32_bf16 v[86:89], v[172:175], v[206:209], v[86:89]
	v_mfma_f32_16x16x32_bf16 v[78:81], v[182:185], v[206:209], v[78:81]
	v_mfma_f32_16x16x32_bf16 v[70:73], v[172:175], v[214:217], v[70:73]
	v_mfma_f32_16x16x32_bf16 v[66:69], v[182:185], v[214:217], v[66:69]
	s_barrier
	s_setprio 0
	s_add_i32 s2, s57, s39
	v_lshl_add_u64 v[144:145], v[144:145], 0, s[6:7]
	s_mov_b32 m0, s2
	ds_read_b128 v[186:189], v150 offset:49152
	ds_read_b128 v[190:193], v150 offset:50176
	ds_read_b128 v[194:197], v150 offset:51200
	ds_read_b128 v[198:201], v150 offset:52224
	ds_read_b128 v[202:205], v150 offset:53248
	ds_read_b128 v[206:209], v150 offset:54272
	ds_read_b128 v[210:213], v150 offset:55296
	ds_read_b128 v[214:217], v150 offset:56320
	global_load_lds_dwordx4 v[144:145], off
	s_add_i32 m0, s2, 0x2000
	s_add_u32 s2, s34, 0x40080
	v_lshl_add_u64 v[144:145], v[218:219], 0, s[6:7]
	s_addc_u32 s3, s35, 0
	s_add_i32 s34, s58, s39
	global_load_lds_dwordx4 v[144:145], off
	v_lshl_add_u64 v[144:145], s[2:3], 0, v[132:133]
	s_mov_b32 m0, s34
	s_nop 0
	global_load_lds_dwordx4 v[144:145], off
	v_lshl_add_u64 v[144:145], s[2:3], 0, v[136:137]
	s_add_i32 m0, s34, 0x2000
	s_nop 0
	global_load_lds_dwordx4 v[144:145], off
	v_lshl_add_u64 v[144:145], v[220:221], 0, s[6:7]
	s_mov_b32 m0, s44
	s_nop 0
	global_load_lds_dwordx4 v[144:145], off
	v_lshl_add_u64 v[144:145], v[222:223], 0, s[6:7]
	s_mov_b32 m0, s45
	s_nop 0
	global_load_lds_dwordx4 v[144:145], off
	s_waitcnt vmcnt(8)
	s_waitcnt lgkmcnt(0)
	s_setprio 1
	s_barrier
	v_mfma_f32_16x16x32_bf16 v[62:65], v[152:155], v[186:189], v[62:65]
	v_mfma_f32_16x16x32_bf16 v[58:61], v[160:163], v[186:189], v[58:61]
	v_mfma_f32_16x16x32_bf16 v[50:53], v[152:155], v[194:197], v[50:53]
	v_mfma_f32_16x16x32_bf16 v[42:45], v[160:163], v[194:197], v[42:45]
	v_mfma_f32_16x16x32_bf16 v[34:37], v[152:155], v[202:205], v[34:37]
	v_mfma_f32_16x16x32_bf16 v[26:29], v[160:163], v[202:205], v[26:29]
	v_mfma_f32_16x16x32_bf16 v[18:21], v[152:155], v[210:213], v[18:21]
	v_mfma_f32_16x16x32_bf16 v[10:13], v[160:163], v[210:213], v[10:13]
	v_mfma_f32_16x16x32_bf16 v[62:65], v[156:159], v[190:193], v[62:65]
	v_mfma_f32_16x16x32_bf16 v[58:61], v[164:167], v[190:193], v[58:61]
	v_mfma_f32_16x16x32_bf16 v[50:53], v[156:159], v[198:201], v[50:53]
	v_mfma_f32_16x16x32_bf16 v[42:45], v[164:167], v[198:201], v[42:45]
	v_mfma_f32_16x16x32_bf16 v[34:37], v[156:159], v[206:209], v[34:37]
	v_mfma_f32_16x16x32_bf16 v[26:29], v[164:167], v[206:209], v[26:29]
	v_mfma_f32_16x16x32_bf16 v[18:21], v[156:159], v[214:217], v[18:21]
	v_mfma_f32_16x16x32_bf16 v[10:13], v[164:167], v[214:217], v[10:13]
	v_mfma_f32_16x16x32_bf16 v[54:57], v[168:171], v[186:189], v[54:57]
	v_mfma_f32_16x16x32_bf16 v[46:49], v[178:181], v[186:189], v[46:49]
	v_mfma_f32_16x16x32_bf16 v[38:41], v[168:171], v[194:197], v[38:41]
	v_mfma_f32_16x16x32_bf16 v[30:33], v[178:181], v[194:197], v[30:33]
	v_mfma_f32_16x16x32_bf16 v[22:25], v[168:171], v[202:205], v[22:25]
	v_mfma_f32_16x16x32_bf16 v[14:17], v[178:181], v[202:205], v[14:17]
	v_mfma_f32_16x16x32_bf16 v[6:9], v[168:171], v[210:213], v[6:9]
	v_mfma_f32_16x16x32_bf16 v[2:5], v[178:181], v[210:213], v[2:5]
	v_mfma_f32_16x16x32_bf16 v[54:57], v[172:175], v[190:193], v[54:57]
	v_mfma_f32_16x16x32_bf16 v[46:49], v[182:185], v[190:193], v[46:49]
	v_mfma_f32_16x16x32_bf16 v[38:41], v[172:175], v[198:201], v[38:41]
	v_mfma_f32_16x16x32_bf16 v[30:33], v[182:185], v[198:201], v[30:33]
	v_mfma_f32_16x16x32_bf16 v[22:25], v[172:175], v[206:209], v[22:25]
	v_mfma_f32_16x16x32_bf16 v[14:17], v[182:185], v[206:209], v[14:17]
	v_mfma_f32_16x16x32_bf16 v[6:9], v[172:175], v[214:217], v[6:9]
	v_mfma_f32_16x16x32_bf16 v[2:5], v[182:185], v[214:217], v[2:5]
	s_barrier
	s_setprio 0
	s_add_i32 s56, s56, 2
	s_add_u32 s30, s30, 0x100
	s_addc_u32 s31, s31, 0
	s_add_u32 s54, s54, 0x100
	s_addc_u32 s55, s55, 0
	s_cmp_gt_u32 s56, 13
	s_cbranch_scc0 .LBB0_1098

.LBB0_1137:
	s_add_i32 s26, 0, 0x18000
	s_add_i32 s3, s26, s18
	s_mov_b64 s[24:25], 0x80
	v_lshl_add_u64 v[4:5], v[26:27], 0, s[24:25]
	s_mov_b32 m0, s3
	s_add_i32 s5, s3, 0x2000
	s_waitcnt vmcnt(2)
	s_barrier
	global_load_lds_dwordx4 v[4:5], off
	v_lshl_add_u64 v[6:7], v[28:29], 0, s[24:25]
	s_mov_b32 m0, s5
	s_add_i32 s4, s15, 0x8000
	global_load_lds_dwordx4 v[6:7], off
	v_lshl_add_u64 v[2:3], v[20:21], 0, s[24:25]
	s_mov_b32 m0, s4
	s_add_i32 s9, s15, 0xa000
	s_add_i32 s27, 0, 0x1c000
	global_load_lds_dwordx4 v[2:3], off
	v_lshl_add_u64 v[8:9], v[22:23], 0, s[24:25]
	s_mov_b32 m0, s9
	s_add_i32 s13, s27, s18
	global_load_lds_dwordx4 v[8:9], off
	v_lshl_add_u64 v[10:11], v[24:25], 0, s[24:25]
	s_mov_b32 m0, s13
	s_add_i32 s14, s13, 0x2000
	global_load_lds_dwordx4 v[10:11], off
	v_lshl_add_u64 v[12:13], v[18:19], 0, s[24:25]
	s_mov_b32 m0, s14
	v_and_b32_e32 v30, 15, v0
	global_load_lds_dwordx4 v[12:13], off
	v_lshlrev_b32_e32 v31, 1, v1
	v_lshlrev_b32_e32 v32, 2, v0
	v_lshl_or_b32 v130, s17, 6, v30
	v_lshl_or_b32 v30, v30, 6, v31
	s_lshl_b32 s2, s17, 13
	v_and_b32_e32 v32, 32, v32
	v_bitop3_b32 v62, v30, s2, v32 bitop3:0xde
	s_lshl_b32 s2, s19, 5
	s_and_b32 s2, s2, 0x60
	v_lshlrev_b32_e32 v30, 6, v0
	s_movk_i32 s17, 0x3c0
	v_and_or_b32 v30, v30, s17, v31
	s_lshl_b32 s17, s2, 7
	v_bitop3_b32 v63, s17, v30, v32 bitop3:0xf6
	s_add_i32 s29, 0, 0x10000
	s_add_i32 s28, 0, 0x14000
	v_add_u32_e32 v176, s29, v63
	s_waitcnt vmcnt(6)
	s_barrier
	v_add_u32_e32 v131, s28, v63
	ds_read_b128 v[30:33], v176
	ds_read_b128 v[34:37], v176 offset:1024
	ds_read_b128 v[38:41], v176 offset:2048
	ds_read_b128 v[42:45], v176 offset:3072
	ds_read_b128 v[46:49], v131
	ds_read_b128 v[50:53], v131 offset:1024
	ds_read_b128 v[54:57], v131 offset:2048
	ds_read_b128 v[58:61], v131 offset:3072
	s_add_i32 s20, s29, s18
	s_add_i32 s18, s28, s18
	s_add_i32 s22, s15, 0xc000
	s_add_i32 s21, s15, 0xe000
	s_add_i32 s19, s20, 0x2000
	s_add_i32 s17, s18, 0x2000
	s_cmpk_gt_u32 s23, 0xff
	v_add_u32_e32 v242, 0, v62
	v_add_u32_e32 v238, s27, v63
	v_add_u32_e32 v239, s26, v63
	s_mov_b32 m0, s22
	v_lshl_add_u64 v[94:95], v[14:15], 0, s[24:25]
	ds_read_b128 v[62:65], v242
	ds_read_b128 v[66:69], v242 offset:1024
	ds_read_b128 v[70:73], v242 offset:2048
	ds_read_b128 v[74:77], v242 offset:3072
	ds_read_b128 v[78:81], v242 offset:4096
	ds_read_b128 v[82:85], v242 offset:5120
	ds_read_b128 v[86:89], v242 offset:6144
	ds_read_b128 v[90:93], v242 offset:7168
	global_load_lds_dwordx4 v[94:95], off
	v_lshl_add_u64 v[94:95], v[16:17], 0, s[24:25]
	s_mov_b32 m0, s21
	s_nop 0
	global_load_lds_dwordx4 v[94:95], off
	s_waitcnt vmcnt(8)
	s_waitcnt lgkmcnt(0)
	s_setprio 1
	s_barrier
	v_mfma_f32_16x16x32_bf16 v[94:97], v[30:33], v[62:65], 0
	v_mfma_f32_16x16x32_bf16 v[98:101], v[38:41], v[62:65], 0
	v_mfma_f32_16x16x32_bf16 v[102:105], v[30:33], v[70:73], 0
	v_mfma_f32_16x16x32_bf16 v[106:109], v[38:41], v[70:73], 0
	v_mfma_f32_16x16x32_bf16 v[110:113], v[30:33], v[78:81], 0
	v_mfma_f32_16x16x32_bf16 v[114:117], v[38:41], v[78:81], 0
	v_mfma_f32_16x16x32_bf16 v[118:121], v[30:33], v[86:89], 0
	v_mfma_f32_16x16x32_bf16 v[122:125], v[38:41], v[86:89], 0
	v_mfma_f32_16x16x32_bf16 v[94:97], v[34:37], v[66:69], v[94:97]
	v_mfma_f32_16x16x32_bf16 v[98:101], v[42:45], v[66:69], v[98:101]
	v_mfma_f32_16x16x32_bf16 v[102:105], v[34:37], v[74:77], v[102:105]
	v_mfma_f32_16x16x32_bf16 v[106:109], v[42:45], v[74:77], v[106:109]
	v_mfma_f32_16x16x32_bf16 v[110:113], v[34:37], v[82:85], v[110:113]
	v_mfma_f32_16x16x32_bf16 v[114:117], v[42:45], v[82:85], v[114:117]
	v_mfma_f32_16x16x32_bf16 v[118:121], v[34:37], v[90:93], v[118:121]
	v_mfma_f32_16x16x32_bf16 v[122:125], v[42:45], v[90:93], v[122:125]
	v_mfma_f32_16x16x32_bf16 v[126:129], v[46:49], v[62:65], 0
	v_mfma_f32_16x16x32_bf16 v[62:65], v[54:57], v[62:65], 0
	v_mfma_f32_16x16x32_bf16 v[126:129], v[50:53], v[66:69], v[126:129]
	v_mfma_f32_16x16x32_bf16 v[62:65], v[58:61], v[66:69], v[62:65]
	v_mfma_f32_16x16x32_bf16 v[66:69], v[46:49], v[70:73], 0
	v_mfma_f32_16x16x32_bf16 v[70:73], v[54:57], v[70:73], 0
	v_mfma_f32_16x16x32_bf16 v[66:69], v[50:53], v[74:77], v[66:69]
	v_mfma_f32_16x16x32_bf16 v[70:73], v[58:61], v[74:77], v[70:73]
	v_mfma_f32_16x16x32_bf16 v[74:77], v[46:49], v[78:81], 0
	v_mfma_f32_16x16x32_bf16 v[78:81], v[54:57], v[78:81], 0
	v_mfma_f32_16x16x32_bf16 v[74:77], v[50:53], v[82:85], v[74:77]
	v_mfma_f32_16x16x32_bf16 v[78:81], v[58:61], v[82:85], v[78:81]
	v_mfma_f32_16x16x32_bf16 v[82:85], v[46:49], v[86:89], 0
	v_mfma_f32_16x16x32_bf16 v[86:89], v[54:57], v[86:89], 0
	v_mfma_f32_16x16x32_bf16 v[82:85], v[50:53], v[90:93], v[82:85]
	v_mfma_f32_16x16x32_bf16 v[86:89], v[58:61], v[90:93], v[86:89]
	s_barrier
	s_setprio 0
	s_mov_b64 s[24:25], 0x100
	s_mov_b32 m0, s20
	v_lshl_add_u64 v[160:161], v[26:27], 0, s[24:25]
	ds_read_b128 v[90:93], v242 offset:16384
	ds_read_b128 v[132:135], v242 offset:17408
	ds_read_b128 v[136:139], v242 offset:18432
	ds_read_b128 v[140:143], v242 offset:19456
	ds_read_b128 v[144:147], v242 offset:20480
	ds_read_b128 v[148:151], v242 offset:21504
	ds_read_b128 v[152:155], v242 offset:22528
	ds_read_b128 v[156:159], v242 offset:23552
	global_load_lds_dwordx4 v[160:161], off
	v_lshl_add_u64 v[160:161], v[28:29], 0, s[24:25]
	s_mov_b32 m0, s19
	s_nop 0
	global_load_lds_dwordx4 v[160:161], off
	v_lshl_add_u64 v[160:161], v[24:25], 0, s[24:25]
	s_mov_b32 m0, s18
	s_nop 0
	global_load_lds_dwordx4 v[160:161], off
	v_lshl_add_u64 v[160:161], v[18:19], 0, s[24:25]
	s_mov_b32 m0, s17
	s_nop 0
	global_load_lds_dwordx4 v[160:161], off
	v_lshl_add_u64 v[160:161], v[20:21], 0, s[24:25]
	s_mov_b32 m0, s15
	s_nop 0
	global_load_lds_dwordx4 v[160:161], off
	v_lshl_add_u64 v[160:161], v[22:23], 0, s[24:25]
	s_mov_b32 m0, s16
	s_nop 0
	global_load_lds_dwordx4 v[160:161], off
	s_waitcnt vmcnt(8)
	s_waitcnt lgkmcnt(0)
	s_setprio 1
	s_barrier
	v_mfma_f32_16x16x32_bf16 v[160:163], v[30:33], v[90:93], 0
	v_mfma_f32_16x16x32_bf16 v[168:171], v[30:33], v[136:139], 0
	v_mfma_f32_16x16x32_bf16 v[178:181], v[30:33], v[144:147], 0
	v_mfma_f32_16x16x32_bf16 v[30:33], v[30:33], v[152:155], 0
	v_mfma_f32_16x16x32_bf16 v[160:163], v[34:37], v[132:135], v[160:163]
	v_mfma_f32_16x16x32_bf16 v[168:171], v[34:37], v[140:143], v[168:171]
	v_mfma_f32_16x16x32_bf16 v[178:181], v[34:37], v[148:151], v[178:181]
	v_mfma_f32_16x16x32_bf16 v[30:33], v[34:37], v[156:159], v[30:33]
	v_mfma_f32_16x16x32_bf16 v[34:37], v[38:41], v[152:155], 0
	v_mfma_f32_16x16x32_bf16 v[164:167], v[38:41], v[90:93], 0
	v_mfma_f32_16x16x32_bf16 v[172:175], v[38:41], v[136:139], 0
	v_mfma_f32_16x16x32_bf16 v[182:185], v[38:41], v[144:147], 0
	v_mfma_f32_16x16x32_bf16 v[34:37], v[42:45], v[156:159], v[34:37]
	v_mfma_f32_16x16x32_bf16 v[164:167], v[42:45], v[132:135], v[164:167]
	v_mfma_f32_16x16x32_bf16 v[172:175], v[42:45], v[140:143], v[172:175]
	v_mfma_f32_16x16x32_bf16 v[182:185], v[42:45], v[148:151], v[182:185]
	v_mfma_f32_16x16x32_bf16 v[38:41], v[46:49], v[90:93], 0
	v_mfma_f32_16x16x32_bf16 v[42:45], v[54:57], v[90:93], 0
	v_mfma_f32_16x16x32_bf16 v[38:41], v[50:53], v[132:135], v[38:41]
	v_mfma_f32_16x16x32_bf16 v[42:45], v[58:61], v[132:135], v[42:45]
	v_mfma_f32_16x16x32_bf16 v[90:93], v[46:49], v[136:139], 0
	v_mfma_f32_16x16x32_bf16 v[132:135], v[54:57], v[136:139], 0
	v_mfma_f32_16x16x32_bf16 v[136:139], v[46:49], v[144:147], 0
	v_mfma_f32_16x16x32_bf16 v[46:49], v[46:49], v[152:155], 0
	v_mfma_f32_16x16x32_bf16 v[90:93], v[50:53], v[140:143], v[90:93]
	v_mfma_f32_16x16x32_bf16 v[136:139], v[50:53], v[148:151], v[136:139]
	v_mfma_f32_16x16x32_bf16 v[46:49], v[50:53], v[156:159], v[46:49]
	v_mfma_f32_16x16x32_bf16 v[50:53], v[54:57], v[152:155], 0
	v_mfma_f32_16x16x32_bf16 v[132:135], v[58:61], v[140:143], v[132:135]
	v_mfma_f32_16x16x32_bf16 v[140:143], v[54:57], v[144:147], 0
	v_mfma_f32_16x16x32_bf16 v[50:53], v[58:61], v[156:159], v[50:53]
	v_mfma_f32_16x16x32_bf16 v[140:143], v[58:61], v[148:151], v[140:143]
	s_barrier
	s_setprio 0
	ds_read_b128 v[54:57], v239
	ds_read_b128 v[58:61], v239 offset:1024
	ds_read_b128 v[144:147], v239 offset:2048
	ds_read_b128 v[148:151], v239 offset:3072
	ds_read_b128 v[152:155], v238
	ds_read_b128 v[156:159], v238 offset:1024
	ds_read_b128 v[186:189], v238 offset:2048
	ds_read_b128 v[190:193], v238 offset:3072
	s_mov_b32 m0, s11
	v_lshl_add_u64 v[226:227], v[14:15], 0, s[24:25]
	ds_read_b128 v[194:197], v242 offset:32768
	ds_read_b128 v[198:201], v242 offset:33792
	ds_read_b128 v[202:205], v242 offset:34816
	ds_read_b128 v[206:209], v242 offset:35840
	ds_read_b128 v[210:213], v242 offset:36864
	ds_read_b128 v[214:217], v242 offset:37888
	ds_read_b128 v[218:221], v242 offset:38912
	ds_read_b128 v[222:225], v242 offset:39936
	global_load_lds_dwordx4 v[226:227], off
	v_lshl_add_u64 v[226:227], v[16:17], 0, s[24:25]
	s_mov_b32 m0, s12
	s_nop 0
	global_load_lds_dwordx4 v[226:227], off
	s_waitcnt vmcnt(8)
	s_waitcnt lgkmcnt(0)
	s_setprio 1
	s_barrier
	v_mfma_f32_16x16x32_bf16 v[94:97], v[54:57], v[194:197], v[94:97]
	v_mfma_f32_16x16x32_bf16 v[98:101], v[144:147], v[194:197], v[98:101]
	v_mfma_f32_16x16x32_bf16 v[102:105], v[54:57], v[202:205], v[102:105]
	v_mfma_f32_16x16x32_bf16 v[106:109], v[144:147], v[202:205], v[106:109]
	v_mfma_f32_16x16x32_bf16 v[110:113], v[54:57], v[210:213], v[110:113]
	v_mfma_f32_16x16x32_bf16 v[114:117], v[144:147], v[210:213], v[114:117]
	v_mfma_f32_16x16x32_bf16 v[118:121], v[54:57], v[218:221], v[118:121]
	v_mfma_f32_16x16x32_bf16 v[122:125], v[144:147], v[218:221], v[122:125]
	v_mfma_f32_16x16x32_bf16 v[94:97], v[58:61], v[198:201], v[94:97]
	v_mfma_f32_16x16x32_bf16 v[98:101], v[148:151], v[198:201], v[98:101]
	v_mfma_f32_16x16x32_bf16 v[102:105], v[58:61], v[206:209], v[102:105]
	v_mfma_f32_16x16x32_bf16 v[106:109], v[148:151], v[206:209], v[106:109]
	v_mfma_f32_16x16x32_bf16 v[110:113], v[58:61], v[214:217], v[110:113]
	v_mfma_f32_16x16x32_bf16 v[114:117], v[148:151], v[214:217], v[114:117]
	v_mfma_f32_16x16x32_bf16 v[118:121], v[58:61], v[222:225], v[118:121]
	v_mfma_f32_16x16x32_bf16 v[122:125], v[148:151], v[222:225], v[122:125]
	v_mfma_f32_16x16x32_bf16 v[126:129], v[152:155], v[194:197], v[126:129]
	v_mfma_f32_16x16x32_bf16 v[62:65], v[186:189], v[194:197], v[62:65]
	v_mfma_f32_16x16x32_bf16 v[66:69], v[152:155], v[202:205], v[66:69]
	v_mfma_f32_16x16x32_bf16 v[70:73], v[186:189], v[202:205], v[70:73]
	v_mfma_f32_16x16x32_bf16 v[74:77], v[152:155], v[210:213], v[74:77]
	v_mfma_f32_16x16x32_bf16 v[78:81], v[186:189], v[210:213], v[78:81]
	v_mfma_f32_16x16x32_bf16 v[82:85], v[152:155], v[218:221], v[82:85]
	v_mfma_f32_16x16x32_bf16 v[86:89], v[186:189], v[218:221], v[86:89]
	v_mfma_f32_16x16x32_bf16 v[126:129], v[156:159], v[198:201], v[126:129]
	v_mfma_f32_16x16x32_bf16 v[62:65], v[190:193], v[198:201], v[62:65]
	v_mfma_f32_16x16x32_bf16 v[66:69], v[156:159], v[206:209], v[66:69]
	v_mfma_f32_16x16x32_bf16 v[70:73], v[190:193], v[206:209], v[70:73]
	v_mfma_f32_16x16x32_bf16 v[74:77], v[156:159], v[214:217], v[74:77]
	v_mfma_f32_16x16x32_bf16 v[78:81], v[190:193], v[214:217], v[78:81]
	v_mfma_f32_16x16x32_bf16 v[82:85], v[156:159], v[222:225], v[82:85]
	v_mfma_f32_16x16x32_bf16 v[86:89], v[190:193], v[222:225], v[86:89]
	s_barrier
	s_setprio 0
	s_mov_b64 s[24:25], 0x180
	s_mov_b32 m0, s3
	v_lshl_add_u64 v[226:227], v[26:27], 0, s[24:25]
	ds_read_b128 v[194:197], v242 offset:49152
	ds_read_b128 v[198:201], v242 offset:50176
	ds_read_b128 v[202:205], v242 offset:51200
	ds_read_b128 v[206:209], v242 offset:52224
	ds_read_b128 v[210:213], v242 offset:53248
	ds_read_b128 v[214:217], v242 offset:54272
	ds_read_b128 v[218:221], v242 offset:55296
	ds_read_b128 v[222:225], v242 offset:56320
	global_load_lds_dwordx4 v[226:227], off
	v_lshl_add_u64 v[226:227], v[28:29], 0, s[24:25]
	s_mov_b32 m0, s5
	s_nop 0
	global_load_lds_dwordx4 v[226:227], off
	v_lshl_add_u64 v[226:227], v[24:25], 0, s[24:25]
	s_mov_b32 m0, s13
	s_nop 0
	global_load_lds_dwordx4 v[226:227], off
	v_lshl_add_u64 v[226:227], v[18:19], 0, s[24:25]
	s_mov_b32 m0, s14
	s_nop 0
	global_load_lds_dwordx4 v[226:227], off
	v_lshl_add_u64 v[226:227], v[20:21], 0, s[24:25]
	s_mov_b32 m0, s4
	s_nop 0
	global_load_lds_dwordx4 v[226:227], off
	v_lshl_add_u64 v[226:227], v[22:23], 0, s[24:25]
	s_mov_b32 m0, s9
	s_nop 0
	global_load_lds_dwordx4 v[226:227], off
	s_waitcnt vmcnt(8)
	s_waitcnt lgkmcnt(0)
	s_setprio 1
	s_barrier
	v_mfma_f32_16x16x32_bf16 v[30:33], v[54:57], v[218:221], v[30:33]
	v_mfma_f32_16x16x32_bf16 v[34:37], v[144:147], v[218:221], v[34:37]
	v_mfma_f32_16x16x32_bf16 v[160:163], v[54:57], v[194:197], v[160:163]
	v_mfma_f32_16x16x32_bf16 v[164:167], v[144:147], v[194:197], v[164:167]
	v_mfma_f32_16x16x32_bf16 v[168:171], v[54:57], v[202:205], v[168:171]
	v_mfma_f32_16x16x32_bf16 v[172:175], v[144:147], v[202:205], v[172:175]
	v_mfma_f32_16x16x32_bf16 v[178:181], v[54:57], v[210:213], v[178:181]
	v_mfma_f32_16x16x32_bf16 v[182:185], v[144:147], v[210:213], v[182:185]
	v_mfma_f32_16x16x32_bf16 v[30:33], v[58:61], v[222:225], v[30:33]
	v_mfma_f32_16x16x32_bf16 v[34:37], v[148:151], v[222:225], v[34:37]
	v_mfma_f32_16x16x32_bf16 v[160:163], v[58:61], v[198:201], v[160:163]
	v_mfma_f32_16x16x32_bf16 v[164:167], v[148:151], v[198:201], v[164:167]
	v_mfma_f32_16x16x32_bf16 v[168:171], v[58:61], v[206:209], v[168:171]
	v_mfma_f32_16x16x32_bf16 v[172:175], v[148:151], v[206:209], v[172:175]
	v_mfma_f32_16x16x32_bf16 v[178:181], v[58:61], v[214:217], v[178:181]
	v_mfma_f32_16x16x32_bf16 v[182:185], v[148:151], v[214:217], v[182:185]
	v_mfma_f32_16x16x32_bf16 v[38:41], v[152:155], v[194:197], v[38:41]
	v_mfma_f32_16x16x32_bf16 v[42:45], v[186:189], v[194:197], v[42:45]
	v_mfma_f32_16x16x32_bf16 v[54:57], v[152:155], v[202:205], v[90:93]
	v_mfma_f32_16x16x32_bf16 v[58:61], v[186:189], v[202:205], v[132:135]
	v_mfma_f32_16x16x32_bf16 v[90:93], v[152:155], v[210:213], v[136:139]
	v_mfma_f32_16x16x32_bf16 v[46:49], v[152:155], v[218:221], v[46:49]
	v_mfma_f32_16x16x32_bf16 v[50:53], v[186:189], v[218:221], v[50:53]
	v_mfma_f32_16x16x32_bf16 v[38:41], v[156:159], v[198:201], v[38:41]
	v_mfma_f32_16x16x32_bf16 v[42:45], v[190:193], v[198:201], v[42:45]
	v_mfma_f32_16x16x32_bf16 v[54:57], v[156:159], v[206:209], v[54:57]
	v_mfma_f32_16x16x32_bf16 v[58:61], v[190:193], v[206:209], v[58:61]
	v_mfma_f32_16x16x32_bf16 v[90:93], v[156:159], v[214:217], v[90:93]
	v_mfma_f32_16x16x32_bf16 v[132:135], v[186:189], v[210:213], v[140:143]
	v_mfma_f32_16x16x32_bf16 v[46:49], v[156:159], v[222:225], v[46:49]
	v_mfma_f32_16x16x32_bf16 v[50:53], v[190:193], v[222:225], v[50:53]
	v_mfma_f32_16x16x32_bf16 v[132:135], v[190:193], v[214:217], v[132:135]
	s_barrier
	s_setprio 0
	ds_read_b128 v[136:139], v176
	ds_read_b128 v[140:143], v176 offset:1024
	ds_read_b128 v[144:147], v176 offset:2048
	ds_read_b128 v[148:151], v176 offset:3072
	ds_read_b128 v[152:155], v131
	ds_read_b128 v[156:159], v131 offset:1024
	ds_read_b128 v[186:189], v131 offset:2048
	ds_read_b128 v[190:193], v131 offset:3072
	s_mov_b32 m0, s22
	v_lshl_add_u64 v[226:227], v[14:15], 0, s[24:25]
	ds_read_b128 v[194:197], v242
	ds_read_b128 v[198:201], v242 offset:1024
	ds_read_b128 v[202:205], v242 offset:2048
	ds_read_b128 v[206:209], v242 offset:3072
	ds_read_b128 v[210:213], v242 offset:4096
	ds_read_b128 v[214:217], v242 offset:5120
	ds_read_b128 v[218:221], v242 offset:6144
	ds_read_b128 v[222:225], v242 offset:7168
	global_load_lds_dwordx4 v[226:227], off
	v_lshl_add_u64 v[226:227], v[16:17], 0, s[24:25]
	s_mov_b32 m0, s21
	s_nop 0
	global_load_lds_dwordx4 v[226:227], off
	s_waitcnt vmcnt(8)
	s_waitcnt lgkmcnt(0)
	s_setprio 1
	s_barrier
	v_mfma_f32_16x16x32_bf16 v[110:113], v[136:139], v[210:213], v[110:113]
	v_mfma_f32_16x16x32_bf16 v[226:229], v[140:143], v[214:217], v[110:113]
	v_mfma_f32_16x16x32_bf16 v[110:113], v[144:147], v[210:213], v[114:117]
	v_mfma_f32_16x16x32_bf16 v[94:97], v[136:139], v[194:197], v[94:97]
	v_mfma_f32_16x16x32_bf16 v[98:101], v[144:147], v[194:197], v[98:101]
	v_mfma_f32_16x16x32_bf16 v[102:105], v[136:139], v[202:205], v[102:105]
	v_mfma_f32_16x16x32_bf16 v[106:109], v[144:147], v[202:205], v[106:109]
	v_mfma_f32_16x16x32_bf16 v[114:117], v[148:151], v[214:217], v[110:113]
	v_mfma_f32_16x16x32_bf16 v[110:113], v[136:139], v[218:221], v[118:121]
	v_mfma_f32_16x16x32_bf16 v[94:97], v[140:143], v[198:201], v[94:97]
	v_mfma_f32_16x16x32_bf16 v[98:101], v[148:151], v[198:201], v[98:101]
	v_mfma_f32_16x16x32_bf16 v[102:105], v[140:143], v[206:209], v[102:105]
	v_mfma_f32_16x16x32_bf16 v[106:109], v[148:151], v[206:209], v[106:109]
	v_mfma_f32_16x16x32_bf16 v[118:121], v[140:143], v[222:225], v[110:113]
	v_mfma_f32_16x16x32_bf16 v[110:113], v[144:147], v[218:221], v[122:125]
	v_mfma_f32_16x16x32_bf16 v[230:233], v[148:151], v[222:225], v[110:113]
	v_mfma_f32_16x16x32_bf16 v[74:77], v[152:155], v[210:213], v[74:77]
	v_mfma_f32_16x16x32_bf16 v[110:113], v[152:155], v[194:197], v[126:129]
	v_mfma_f32_16x16x32_bf16 v[62:65], v[186:189], v[194:197], v[62:65]
	v_mfma_f32_16x16x32_bf16 v[194:197], v[156:159], v[214:217], v[74:77]
	v_mfma_f32_16x16x32_bf16 v[74:77], v[186:189], v[210:213], v[78:81]
	v_mfma_f32_16x16x32_bf16 v[234:237], v[156:159], v[198:201], v[110:113]
	v_mfma_f32_16x16x32_bf16 v[62:65], v[190:193], v[198:201], v[62:65]
	v_mfma_f32_16x16x32_bf16 v[66:69], v[152:155], v[202:205], v[66:69]
	v_mfma_f32_16x16x32_bf16 v[70:73], v[186:189], v[202:205], v[70:73]
	v_mfma_f32_16x16x32_bf16 v[198:201], v[190:193], v[214:217], v[74:77]
	v_mfma_f32_16x16x32_bf16 v[74:77], v[152:155], v[218:221], v[82:85]
	v_mfma_f32_16x16x32_bf16 v[66:69], v[156:159], v[206:209], v[66:69]
	v_mfma_f32_16x16x32_bf16 v[70:73], v[190:193], v[206:209], v[70:73]
	v_mfma_f32_16x16x32_bf16 v[202:205], v[156:159], v[222:225], v[74:77]
	v_mfma_f32_16x16x32_bf16 v[74:77], v[186:189], v[218:221], v[86:89]
	v_mfma_f32_16x16x32_bf16 v[206:209], v[190:193], v[222:225], v[74:77]
	s_barrier
	s_setprio 0
	s_mov_b32 m0, s20
	s_nop 3
	ds_read_b128 v[74:77], v242 offset:16384
	ds_read_b128 v[78:81], v242 offset:17408
	ds_read_b128 v[82:85], v242 offset:18432
	ds_read_b128 v[86:89], v242 offset:19456
	ds_read_b128 v[110:113], v242 offset:20480
	ds_read_b128 v[122:125], v242 offset:21504
	ds_read_b128 v[126:129], v242 offset:22528
	ds_read_b128 v[210:213], v242 offset:23552
	global_load_lds_dwordx4 v[26:27], off
	s_mov_b32 m0, s19
	s_nop 0
	global_load_lds_dwordx4 v[28:29], off
	s_mov_b32 m0, s18
	s_nop 0
	global_load_lds_dwordx4 v[24:25], off
	s_mov_b32 m0, s17
	s_nop 0
	global_load_lds_dwordx4 v[18:19], off
	s_mov_b32 m0, s15
	s_nop 0
	global_load_lds_dwordx4 v[20:21], off
	s_mov_b32 m0, s16
	s_nop 0
	global_load_lds_dwordx4 v[22:23], off
	s_waitcnt vmcnt(8)
	s_waitcnt lgkmcnt(0)
	s_setprio 1
	s_barrier
	v_mfma_f32_16x16x32_bf16 v[30:33], v[136:139], v[126:129], v[30:33]
	v_mfma_f32_16x16x32_bf16 v[18:21], v[136:139], v[74:77], v[160:163]
	v_mfma_f32_16x16x32_bf16 v[22:25], v[144:147], v[74:77], v[164:167]
	v_mfma_f32_16x16x32_bf16 v[26:29], v[136:139], v[82:85], v[168:171]
	v_mfma_f32_16x16x32_bf16 v[164:167], v[136:139], v[110:113], v[178:181]
	v_mfma_f32_16x16x32_bf16 v[136:139], v[140:143], v[210:213], v[30:33]
	v_mfma_f32_16x16x32_bf16 v[30:33], v[144:147], v[126:129], v[34:37]
	v_mfma_f32_16x16x32_bf16 v[18:21], v[140:143], v[78:81], v[18:21]
	v_mfma_f32_16x16x32_bf16 v[22:25], v[148:151], v[78:81], v[22:25]
	v_mfma_f32_16x16x32_bf16 v[26:29], v[140:143], v[86:89], v[26:29]
	v_mfma_f32_16x16x32_bf16 v[160:163], v[144:147], v[82:85], v[172:175]
	v_mfma_f32_16x16x32_bf16 v[168:171], v[144:147], v[110:113], v[182:185]
	v_mfma_f32_16x16x32_bf16 v[34:37], v[148:151], v[210:213], v[30:33]
	v_mfma_f32_16x16x32_bf16 v[160:163], v[148:151], v[86:89], v[160:163]
	v_mfma_f32_16x16x32_bf16 v[164:167], v[140:143], v[122:125], v[164:167]
	v_mfma_f32_16x16x32_bf16 v[168:171], v[148:151], v[122:125], v[168:171]
	v_mfma_f32_16x16x32_bf16 v[30:33], v[152:155], v[74:77], v[38:41]
	v_mfma_f32_16x16x32_bf16 v[38:41], v[156:159], v[78:81], v[30:33]
	v_mfma_f32_16x16x32_bf16 v[30:33], v[186:189], v[74:77], v[42:45]
	v_mfma_f32_16x16x32_bf16 v[140:143], v[190:193], v[78:81], v[30:33]
	v_mfma_f32_16x16x32_bf16 v[30:33], v[152:155], v[82:85], v[54:57]
	v_mfma_f32_16x16x32_bf16 v[144:147], v[156:159], v[86:89], v[30:33]
	v_mfma_f32_16x16x32_bf16 v[30:33], v[186:189], v[82:85], v[58:61]
	v_mfma_f32_16x16x32_bf16 v[148:151], v[190:193], v[86:89], v[30:33]
	v_mfma_f32_16x16x32_bf16 v[30:33], v[152:155], v[110:113], v[90:93]
	v_mfma_f32_16x16x32_bf16 v[172:175], v[156:159], v[122:125], v[30:33]
	v_mfma_f32_16x16x32_bf16 v[30:33], v[186:189], v[110:113], v[132:135]
	v_mfma_f32_16x16x32_bf16 v[132:135], v[190:193], v[122:125], v[30:33]
	v_mfma_f32_16x16x32_bf16 v[30:33], v[152:155], v[126:129], v[46:49]
	v_mfma_f32_16x16x32_bf16 v[152:155], v[156:159], v[210:213], v[30:33]
	v_mfma_f32_16x16x32_bf16 v[30:33], v[186:189], v[126:129], v[50:53]
	v_mfma_f32_16x16x32_bf16 v[156:159], v[190:193], v[210:213], v[30:33]
	s_barrier
	s_setprio 0
	ds_read_b128 v[50:53], v239
	ds_read_b128 v[54:57], v239 offset:1024
	ds_read_b128 v[178:181], v239 offset:2048
	ds_read_b128 v[182:185], v239 offset:3072
	ds_read_b128 v[186:189], v238
	ds_read_b128 v[190:193], v238 offset:1024
	ds_read_b128 v[210:213], v238 offset:2048
	ds_read_b128 v[214:217], v238 offset:3072
	s_mov_b32 m0, s11
	ds_read_b128 v[30:33], v242 offset:32768
	ds_read_b128 v[42:45], v242 offset:33792
	ds_read_b128 v[46:49], v242 offset:34816
	ds_read_b128 v[58:61], v242 offset:35840
	ds_read_b128 v[82:85], v242 offset:36864
	ds_read_b128 v[218:221], v242 offset:37888
	ds_read_b128 v[222:225], v242 offset:38912
	ds_read_b128 v[238:241], v242 offset:39936
	global_load_lds_dwordx4 v[14:15], off
	s_mov_b32 m0, s12
	s_nop 0
	global_load_lds_dwordx4 v[16:17], off
	s_waitcnt vmcnt(8)
	s_waitcnt lgkmcnt(0)
	s_setprio 1
	s_barrier
	v_mfma_f32_16x16x32_bf16 v[14:17], v[50:53], v[30:33], v[94:97]
	v_mfma_f32_16x16x32_bf16 v[126:129], v[54:57], v[42:45], v[14:17]
	v_mfma_f32_16x16x32_bf16 v[14:17], v[178:181], v[30:33], v[98:101]
	v_mfma_f32_16x16x32_bf16 v[122:125], v[182:185], v[42:45], v[14:17]
	v_mfma_f32_16x16x32_bf16 v[14:17], v[50:53], v[46:49], v[102:105]
	v_mfma_f32_16x16x32_bf16 v[110:113], v[54:57], v[58:61], v[14:17]
	v_mfma_f32_16x16x32_bf16 v[14:17], v[178:181], v[46:49], v[106:109]
	v_mfma_f32_16x16x32_bf16 v[106:109], v[182:185], v[58:61], v[14:17]
	v_mfma_f32_16x16x32_bf16 v[14:17], v[50:53], v[82:85], v[226:229]
	v_mfma_f32_16x16x32_bf16 v[94:97], v[54:57], v[218:221], v[14:17]
	v_mfma_f32_16x16x32_bf16 v[14:17], v[178:181], v[82:85], v[114:117]
	v_mfma_f32_16x16x32_bf16 v[90:93], v[182:185], v[218:221], v[14:17]
	v_mfma_f32_16x16x32_bf16 v[14:17], v[50:53], v[222:225], v[118:121]
	v_mfma_f32_16x16x32_bf16 v[78:81], v[54:57], v[238:241], v[14:17]
	v_mfma_f32_16x16x32_bf16 v[14:17], v[178:181], v[222:225], v[230:233]
	v_mfma_f32_16x16x32_bf16 v[74:77], v[182:185], v[238:241], v[14:17]
	v_mfma_f32_16x16x32_bf16 v[14:17], v[186:189], v[30:33], v[234:237]
	v_mfma_f32_16x16x32_bf16 v[118:121], v[190:193], v[42:45], v[14:17]
	v_mfma_f32_16x16x32_bf16 v[14:17], v[210:213], v[30:33], v[62:65]
	v_mfma_f32_16x16x32_bf16 v[114:117], v[214:217], v[42:45], v[14:17]
	v_mfma_f32_16x16x32_bf16 v[14:17], v[186:189], v[46:49], v[66:69]
	v_mfma_f32_16x16x32_bf16 v[102:105], v[190:193], v[58:61], v[14:17]
	v_mfma_f32_16x16x32_bf16 v[14:17], v[210:213], v[46:49], v[70:73]
	v_mfma_f32_16x16x32_bf16 v[98:101], v[214:217], v[58:61], v[14:17]
	v_mfma_f32_16x16x32_bf16 v[14:17], v[186:189], v[82:85], v[194:197]
	v_mfma_f32_16x16x32_bf16 v[86:89], v[190:193], v[218:221], v[14:17]
	v_mfma_f32_16x16x32_bf16 v[14:17], v[210:213], v[82:85], v[198:201]
	v_mfma_f32_16x16x32_bf16 v[82:85], v[214:217], v[218:221], v[14:17]
	v_mfma_f32_16x16x32_bf16 v[14:17], v[186:189], v[222:225], v[202:205]
	v_mfma_f32_16x16x32_bf16 v[66:69], v[190:193], v[238:241], v[14:17]
	v_mfma_f32_16x16x32_bf16 v[14:17], v[210:213], v[222:225], v[206:209]
	v_mfma_f32_16x16x32_bf16 v[58:61], v[214:217], v[238:241], v[14:17]
	s_barrier
	s_setprio 0
	s_mov_b32 m0, s3
	ds_read_b128 v[194:197], v242 offset:49152
	ds_read_b128 v[198:201], v242 offset:50176
	ds_read_b128 v[202:205], v242 offset:51200
	ds_read_b128 v[206:209], v242 offset:52224
	ds_read_b128 v[218:221], v242 offset:53248
	ds_read_b128 v[222:225], v242 offset:54272
	ds_read_b128 v[226:229], v242 offset:55296
	ds_read_b128 v[230:233], v242 offset:56320
	global_load_lds_dwordx4 v[4:5], off
	s_mov_b32 m0, s5
	s_nop 0
	global_load_lds_dwordx4 v[6:7], off
	s_mov_b32 m0, s13
	s_nop 0
	global_load_lds_dwordx4 v[10:11], off
	s_mov_b32 m0, s14
	s_nop 0
	global_load_lds_dwordx4 v[12:13], off
	s_mov_b32 m0, s4
	s_nop 0
	global_load_lds_dwordx4 v[2:3], off
	s_mov_b32 m0, s9
	s_nop 0
	global_load_lds_dwordx4 v[8:9], off
	s_waitcnt vmcnt(8)
	s_waitcnt lgkmcnt(0)
	s_setprio 1
	s_barrier
	v_mfma_f32_16x16x32_bf16 v[2:5], v[50:53], v[194:197], v[18:21]
	v_mfma_f32_16x16x32_bf16 v[70:73], v[54:57], v[198:201], v[2:5]
	v_mfma_f32_16x16x32_bf16 v[2:5], v[178:181], v[194:197], v[22:25]
	v_mfma_f32_16x16x32_bf16 v[62:65], v[182:185], v[198:201], v[2:5]
	v_mfma_f32_16x16x32_bf16 v[2:5], v[50:53], v[202:205], v[26:29]
	v_mfma_f32_16x16x32_bf16 v[46:49], v[54:57], v[206:209], v[2:5]
	v_mfma_f32_16x16x32_bf16 v[2:5], v[178:181], v[202:205], v[160:163]
	v_mfma_f32_16x16x32_bf16 v[42:45], v[182:185], v[206:209], v[2:5]
	v_mfma_f32_16x16x32_bf16 v[2:5], v[50:53], v[218:221], v[164:167]
	v_mfma_f32_16x16x32_bf16 v[30:33], v[54:57], v[222:225], v[2:5]
	v_mfma_f32_16x16x32_bf16 v[2:5], v[178:181], v[218:221], v[168:171]
	v_mfma_f32_16x16x32_bf16 v[26:29], v[182:185], v[222:225], v[2:5]
	v_mfma_f32_16x16x32_bf16 v[2:5], v[50:53], v[226:229], v[136:139]
	v_mfma_f32_16x16x32_bf16 v[14:17], v[54:57], v[230:233], v[2:5]
	v_mfma_f32_16x16x32_bf16 v[2:5], v[178:181], v[226:229], v[34:37]
	v_mfma_f32_16x16x32_bf16 v[10:13], v[182:185], v[230:233], v[2:5]
	v_mfma_f32_16x16x32_bf16 v[2:5], v[186:189], v[194:197], v[38:41]
	v_mfma_f32_16x16x32_bf16 v[54:57], v[190:193], v[198:201], v[2:5]
	v_mfma_f32_16x16x32_bf16 v[2:5], v[210:213], v[194:197], v[140:143]
	v_mfma_f32_16x16x32_bf16 v[50:53], v[214:217], v[198:201], v[2:5]
	v_mfma_f32_16x16x32_bf16 v[2:5], v[186:189], v[202:205], v[144:147]
	v_mfma_f32_16x16x32_bf16 v[38:41], v[190:193], v[206:209], v[2:5]
	v_mfma_f32_16x16x32_bf16 v[2:5], v[210:213], v[202:205], v[148:151]
	v_mfma_f32_16x16x32_bf16 v[34:37], v[214:217], v[206:209], v[2:5]
	v_mfma_f32_16x16x32_bf16 v[2:5], v[186:189], v[218:221], v[172:175]
	v_mfma_f32_16x16x32_bf16 v[22:25], v[190:193], v[222:225], v[2:5]
	v_mfma_f32_16x16x32_bf16 v[2:5], v[210:213], v[218:221], v[132:135]
	v_mfma_f32_16x16x32_bf16 v[18:21], v[214:217], v[222:225], v[2:5]
	v_mfma_f32_16x16x32_bf16 v[2:5], v[186:189], v[226:229], v[152:155]
	v_mfma_f32_16x16x32_bf16 v[6:9], v[190:193], v[230:233], v[2:5]
	v_mfma_f32_16x16x32_bf16 v[2:5], v[210:213], v[226:229], v[156:159]
	v_mfma_f32_16x16x32_bf16 v[2:5], v[214:217], v[230:233], v[2:5]
	s_barrier
	s_setprio 0
	s_cbranch_scc1 .LBB0_1139
	s_barrier

.Lpk1179_peel:
	ds_read_b128 v[144:147], v158
	ds_read_b128 v[164:167], v158 offset:1024
	ds_read_b128 v[168:171], v158 offset:2048
	ds_read_b128 v[172:175], v158 offset:3072
	ds_read_b128 v[178:181], v159
	ds_read_b128 v[182:185], v159 offset:1024
	ds_read_b128 v[186:189], v159 offset:2048
	ds_read_b128 v[190:193], v159 offset:3072
	s_add_u32 s2, s36, 0xfffc0080
	s_addc_u32 s3, s37, -1
	s_cmp_eq_u32 s61, 12
	s_cselect_b32 s3, s19, s3
	s_cselect_b32 s2, s21, s2
	s_cselect_b32 s39, s57, s60
	s_cselect_b32 s38, s58, s59
	v_lshl_add_u64 v[226:227], s[36:37], 0, v[138:139]
	s_add_i32 m0, s42, 0xc000
	ds_read_b128 v[194:197], v160
	ds_read_b128 v[198:201], v160 offset:1024
	ds_read_b128 v[202:205], v160 offset:2048
	ds_read_b128 v[206:209], v160 offset:3072
	ds_read_b128 v[210:213], v160 offset:4096
	ds_read_b128 v[214:217], v160 offset:5120
	ds_read_b128 v[218:221], v160 offset:6144
	ds_read_b128 v[222:225], v160 offset:7168
	global_load_lds_dwordx4 v[226:227], off
	v_lshl_add_u64 v[226:227], s[36:37], 0, v[140:141]
	s_add_i32 m0, s42, 0xe000
	s_nop 0
	global_load_lds_dwordx4 v[226:227], off
	s_waitcnt vmcnt(8)
	s_waitcnt lgkmcnt(0)
	s_setprio 1
	s_barrier
	v_mfma_f32_16x16x32_bf16 v[126:129], v[144:147], v[194:197], 0
	v_mfma_f32_16x16x32_bf16 v[122:125], v[168:171], v[194:197], 0
	v_mfma_f32_16x16x32_bf16 v[114:117], v[144:147], v[202:205], 0
	v_mfma_f32_16x16x32_bf16 v[106:109], v[168:171], v[202:205], 0
	v_mfma_f32_16x16x32_bf16 v[98:101], v[144:147], v[210:213], 0
	v_mfma_f32_16x16x32_bf16 v[90:93], v[168:171], v[210:213], 0
	v_mfma_f32_16x16x32_bf16 v[82:85], v[144:147], v[218:221], 0
	v_mfma_f32_16x16x32_bf16 v[74:77], v[168:171], v[218:221], 0
	v_mfma_f32_16x16x32_bf16 v[126:129], v[164:167], v[198:201], v[126:129]
	v_mfma_f32_16x16x32_bf16 v[122:125], v[172:175], v[198:201], v[122:125]
	v_mfma_f32_16x16x32_bf16 v[114:117], v[164:167], v[206:209], v[114:117]
	v_mfma_f32_16x16x32_bf16 v[106:109], v[172:175], v[206:209], v[106:109]
	v_mfma_f32_16x16x32_bf16 v[98:101], v[164:167], v[214:217], v[98:101]
	v_mfma_f32_16x16x32_bf16 v[90:93], v[172:175], v[214:217], v[90:93]
	v_mfma_f32_16x16x32_bf16 v[82:85], v[164:167], v[222:225], v[82:85]
	v_mfma_f32_16x16x32_bf16 v[74:77], v[172:175], v[222:225], v[74:77]
	v_mfma_f32_16x16x32_bf16 v[118:121], v[178:181], v[194:197], 0
	v_mfma_f32_16x16x32_bf16 v[110:113], v[186:189], v[194:197], 0
	v_mfma_f32_16x16x32_bf16 v[102:105], v[178:181], v[202:205], 0
	v_mfma_f32_16x16x32_bf16 v[94:97], v[186:189], v[202:205], 0
	v_mfma_f32_16x16x32_bf16 v[86:89], v[178:181], v[210:213], 0
	v_mfma_f32_16x16x32_bf16 v[78:81], v[186:189], v[210:213], 0
	v_mfma_f32_16x16x32_bf16 v[70:73], v[178:181], v[218:221], 0
	v_mfma_f32_16x16x32_bf16 v[66:69], v[186:189], v[218:221], 0
	v_mfma_f32_16x16x32_bf16 v[118:121], v[182:185], v[198:201], v[118:121]
	v_mfma_f32_16x16x32_bf16 v[110:113], v[190:193], v[198:201], v[110:113]
	v_mfma_f32_16x16x32_bf16 v[102:105], v[182:185], v[206:209], v[102:105]
	v_mfma_f32_16x16x32_bf16 v[94:97], v[190:193], v[206:209], v[94:97]
	v_mfma_f32_16x16x32_bf16 v[86:89], v[182:185], v[214:217], v[86:89]
	v_mfma_f32_16x16x32_bf16 v[78:81], v[190:193], v[214:217], v[78:81]
	v_mfma_f32_16x16x32_bf16 v[70:73], v[182:185], v[222:225], v[70:73]
	v_mfma_f32_16x16x32_bf16 v[66:69], v[190:193], v[222:225], v[66:69]
	s_barrier
	s_setprio 0
	s_add_i32 s62, s51, s41
	v_lshl_add_u64 v[226:227], s[38:39], 0, v[132:133]
	s_mov_b32 m0, s62
	ds_read_b128 v[194:197], v160 offset:16384
	ds_read_b128 v[198:201], v160 offset:17408
	ds_read_b128 v[202:205], v160 offset:18432
	ds_read_b128 v[206:209], v160 offset:19456
	ds_read_b128 v[210:213], v160 offset:20480
	ds_read_b128 v[214:217], v160 offset:21504
	ds_read_b128 v[218:221], v160 offset:22528
	ds_read_b128 v[222:225], v160 offset:23552
	global_load_lds_dwordx4 v[226:227], off
	s_add_i32 m0, s62, 0x2000
	s_add_u32 s62, s38, 0x40000
	v_lshl_add_u64 v[228:229], s[38:39], 0, v[136:137]
	s_addc_u32 s63, s39, 0
	s_add_i32 s64, s52, s41
	global_load_lds_dwordx4 v[228:229], off
	v_lshl_add_u64 v[230:231], s[62:63], 0, v[132:133]
	s_mov_b32 m0, s64
	v_lshl_add_u64 v[232:233], s[2:3], 0, v[134:135]
	global_load_lds_dwordx4 v[230:231], off
	v_lshl_add_u64 v[230:231], s[62:63], 0, v[136:137]
	s_add_i32 m0, s64, 0x2000
	s_nop 0
	global_load_lds_dwordx4 v[230:231], off
	v_lshl_add_u64 v[230:231], s[2:3], 0, v[130:131]
	s_mov_b32 m0, s42
	s_nop 0
	global_load_lds_dwordx4 v[230:231], off
	s_mov_b32 m0, s43
	s_nop 0
	global_load_lds_dwordx4 v[232:233], off
	s_waitcnt vmcnt(8)
	s_waitcnt lgkmcnt(0)
	s_setprio 1
	s_barrier
	v_mfma_f32_16x16x32_bf16 v[62:65], v[144:147], v[194:197], 0
	v_mfma_f32_16x16x32_bf16 v[58:61], v[168:171], v[194:197], 0
	v_mfma_f32_16x16x32_bf16 v[50:53], v[144:147], v[202:205], 0
	v_mfma_f32_16x16x32_bf16 v[42:45], v[168:171], v[202:205], 0
	v_mfma_f32_16x16x32_bf16 v[34:37], v[144:147], v[210:213], 0
	v_mfma_f32_16x16x32_bf16 v[26:29], v[168:171], v[210:213], 0
	v_mfma_f32_16x16x32_bf16 v[18:21], v[144:147], v[218:221], 0
	v_mfma_f32_16x16x32_bf16 v[10:13], v[168:171], v[218:221], 0
	v_mfma_f32_16x16x32_bf16 v[62:65], v[164:167], v[198:201], v[62:65]
	v_mfma_f32_16x16x32_bf16 v[58:61], v[172:175], v[198:201], v[58:61]
	v_mfma_f32_16x16x32_bf16 v[50:53], v[164:167], v[206:209], v[50:53]
	v_mfma_f32_16x16x32_bf16 v[42:45], v[172:175], v[206:209], v[42:45]
	v_mfma_f32_16x16x32_bf16 v[34:37], v[164:167], v[214:217], v[34:37]
	v_mfma_f32_16x16x32_bf16 v[26:29], v[172:175], v[214:217], v[26:29]
	v_mfma_f32_16x16x32_bf16 v[18:21], v[164:167], v[222:225], v[18:21]
	v_mfma_f32_16x16x32_bf16 v[10:13], v[172:175], v[222:225], v[10:13]
	v_mfma_f32_16x16x32_bf16 v[54:57], v[178:181], v[194:197], 0
	v_mfma_f32_16x16x32_bf16 v[46:49], v[186:189], v[194:197], 0
	v_mfma_f32_16x16x32_bf16 v[38:41], v[178:181], v[202:205], 0
	v_mfma_f32_16x16x32_bf16 v[30:33], v[186:189], v[202:205], 0
	v_mfma_f32_16x16x32_bf16 v[22:25], v[178:181], v[210:213], 0
	v_mfma_f32_16x16x32_bf16 v[14:17], v[186:189], v[210:213], 0
	v_mfma_f32_16x16x32_bf16 v[6:9], v[178:181], v[218:221], 0
	v_mfma_f32_16x16x32_bf16 v[2:5], v[186:189], v[218:221], 0
	v_mfma_f32_16x16x32_bf16 v[54:57], v[182:185], v[198:201], v[54:57]
	v_mfma_f32_16x16x32_bf16 v[46:49], v[190:193], v[198:201], v[46:49]
	v_mfma_f32_16x16x32_bf16 v[38:41], v[182:185], v[206:209], v[38:41]
	v_mfma_f32_16x16x32_bf16 v[30:33], v[190:193], v[206:209], v[30:33]
	v_mfma_f32_16x16x32_bf16 v[22:25], v[182:185], v[214:217], v[22:25]
	v_mfma_f32_16x16x32_bf16 v[14:17], v[190:193], v[214:217], v[14:17]
	v_mfma_f32_16x16x32_bf16 v[6:9], v[182:185], v[222:225], v[6:9]
	v_mfma_f32_16x16x32_bf16 v[2:5], v[190:193], v[222:225], v[2:5]
	s_barrier
	s_setprio 0
	s_add_i32 s62, 0, 0x18000
	v_add_u32_e32 v163, s62, v148
	s_add_i32 s63, 0, 0x1c000
	ds_read_b128 v[144:147], v163
	ds_read_b128 v[164:167], v163 offset:1024
	ds_read_b128 v[168:171], v163 offset:2048
	ds_read_b128 v[172:175], v163 offset:3072
	v_add_u32_e32 v163, s63, v148
	ds_read_b128 v[178:181], v163
	ds_read_b128 v[182:185], v163 offset:1024
	ds_read_b128 v[186:189], v163 offset:2048
	ds_read_b128 v[190:193], v163 offset:3072
	s_add_u32 s2, s2, 0x40000
	s_addc_u32 s3, s3, 0
	s_mov_b32 m0, s44
	v_lshl_add_u64 v[234:235], s[2:3], 0, v[130:131]
	ds_read_b128 v[194:197], v160 offset:32768
	ds_read_b128 v[198:201], v160 offset:33792
	ds_read_b128 v[202:205], v160 offset:34816
	ds_read_b128 v[206:209], v160 offset:35840
	ds_read_b128 v[210:213], v160 offset:36864
	ds_read_b128 v[214:217], v160 offset:37888
	ds_read_b128 v[218:221], v160 offset:38912
	ds_read_b128 v[222:225], v160 offset:39936
	global_load_lds_dwordx4 v[234:235], off
	v_lshl_add_u64 v[234:235], s[2:3], 0, v[134:135]
	s_mov_b32 m0, s45
	s_nop 0
	global_load_lds_dwordx4 v[234:235], off
	s_waitcnt vmcnt(8)
	s_waitcnt lgkmcnt(0)
	s_setprio 1
	s_barrier
	v_mfma_f32_16x16x32_bf16 v[126:129], v[144:147], v[194:197], v[126:129]
	v_mfma_f32_16x16x32_bf16 v[122:125], v[168:171], v[194:197], v[122:125]
	v_mfma_f32_16x16x32_bf16 v[114:117], v[144:147], v[202:205], v[114:117]
	v_mfma_f32_16x16x32_bf16 v[106:109], v[168:171], v[202:205], v[106:109]
	v_mfma_f32_16x16x32_bf16 v[98:101], v[144:147], v[210:213], v[98:101]
	v_mfma_f32_16x16x32_bf16 v[90:93], v[168:171], v[210:213], v[90:93]
	v_mfma_f32_16x16x32_bf16 v[82:85], v[144:147], v[218:221], v[82:85]
	v_mfma_f32_16x16x32_bf16 v[74:77], v[168:171], v[218:221], v[74:77]
	v_mfma_f32_16x16x32_bf16 v[126:129], v[164:167], v[198:201], v[126:129]
	v_mfma_f32_16x16x32_bf16 v[122:125], v[172:175], v[198:201], v[122:125]
	v_mfma_f32_16x16x32_bf16 v[114:117], v[164:167], v[206:209], v[114:117]
	v_mfma_f32_16x16x32_bf16 v[106:109], v[172:175], v[206:209], v[106:109]
	v_mfma_f32_16x16x32_bf16 v[98:101], v[164:167], v[214:217], v[98:101]
	v_mfma_f32_16x16x32_bf16 v[90:93], v[172:175], v[214:217], v[90:93]
	v_mfma_f32_16x16x32_bf16 v[82:85], v[164:167], v[222:225], v[82:85]
	v_mfma_f32_16x16x32_bf16 v[74:77], v[172:175], v[222:225], v[74:77]
	v_mfma_f32_16x16x32_bf16 v[118:121], v[178:181], v[194:197], v[118:121]
	v_mfma_f32_16x16x32_bf16 v[110:113], v[186:189], v[194:197], v[110:113]
	v_mfma_f32_16x16x32_bf16 v[102:105], v[178:181], v[202:205], v[102:105]
	v_mfma_f32_16x16x32_bf16 v[94:97], v[186:189], v[202:205], v[94:97]
	v_mfma_f32_16x16x32_bf16 v[86:89], v[178:181], v[210:213], v[86:89]
	v_mfma_f32_16x16x32_bf16 v[78:81], v[186:189], v[210:213], v[78:81]
	v_mfma_f32_16x16x32_bf16 v[70:73], v[178:181], v[218:221], v[70:73]
	v_mfma_f32_16x16x32_bf16 v[66:69], v[186:189], v[218:221], v[66:69]
	v_mfma_f32_16x16x32_bf16 v[118:121], v[182:185], v[198:201], v[118:121]
	v_mfma_f32_16x16x32_bf16 v[110:113], v[190:193], v[198:201], v[110:113]
	v_mfma_f32_16x16x32_bf16 v[102:105], v[182:185], v[206:209], v[102:105]
	v_mfma_f32_16x16x32_bf16 v[94:97], v[190:193], v[206:209], v[94:97]
	v_mfma_f32_16x16x32_bf16 v[86:89], v[182:185], v[214:217], v[86:89]
	v_mfma_f32_16x16x32_bf16 v[78:81], v[190:193], v[214:217], v[78:81]
	v_mfma_f32_16x16x32_bf16 v[70:73], v[182:185], v[222:225], v[70:73]
	v_mfma_f32_16x16x32_bf16 v[66:69], v[190:193], v[222:225], v[66:69]
	s_barrier
	s_setprio 0
	s_add_i32 s2, s62, s41
	v_lshl_add_u64 v[226:227], v[226:227], 0, s[10:11]
	s_mov_b32 m0, s2
	ds_read_b128 v[194:197], v160 offset:49152
	ds_read_b128 v[198:201], v160 offset:50176
	ds_read_b128 v[202:205], v160 offset:51200
	ds_read_b128 v[206:209], v160 offset:52224
	ds_read_b128 v[210:213], v160 offset:53248
	ds_read_b128 v[214:217], v160 offset:54272
	ds_read_b128 v[218:221], v160 offset:55296
	ds_read_b128 v[222:225], v160 offset:56320
	global_load_lds_dwordx4 v[226:227], off
	s_add_i32 m0, s2, 0x2000
	s_add_u32 s2, s38, 0x40080
	v_lshl_add_u64 v[226:227], v[228:229], 0, s[10:11]
	s_addc_u32 s3, s39, 0
	s_add_i32 s38, s63, s41
	global_load_lds_dwordx4 v[226:227], off
	v_lshl_add_u64 v[226:227], s[2:3], 0, v[132:133]
	s_mov_b32 m0, s38
	s_nop 0
	global_load_lds_dwordx4 v[226:227], off
	v_lshl_add_u64 v[226:227], s[2:3], 0, v[136:137]
	s_add_i32 m0, s38, 0x2000
	s_nop 0
	global_load_lds_dwordx4 v[226:227], off
	v_lshl_add_u64 v[226:227], v[230:231], 0, s[10:11]
	s_mov_b32 m0, s47
	s_nop 0
	global_load_lds_dwordx4 v[226:227], off
	v_lshl_add_u64 v[226:227], v[232:233], 0, s[10:11]
	s_mov_b32 m0, s48
	s_nop 0
	global_load_lds_dwordx4 v[226:227], off
	s_waitcnt vmcnt(8)
	s_waitcnt lgkmcnt(0)
	s_setprio 1
	s_barrier
	v_mfma_f32_16x16x32_bf16 v[62:65], v[144:147], v[194:197], v[62:65]
	v_mfma_f32_16x16x32_bf16 v[58:61], v[168:171], v[194:197], v[58:61]
	v_mfma_f32_16x16x32_bf16 v[50:53], v[144:147], v[202:205], v[50:53]
	v_mfma_f32_16x16x32_bf16 v[42:45], v[168:171], v[202:205], v[42:45]
	v_mfma_f32_16x16x32_bf16 v[34:37], v[144:147], v[210:213], v[34:37]
	v_mfma_f32_16x16x32_bf16 v[26:29], v[168:171], v[210:213], v[26:29]
	v_mfma_f32_16x16x32_bf16 v[18:21], v[144:147], v[218:221], v[18:21]
	v_mfma_f32_16x16x32_bf16 v[10:13], v[168:171], v[218:221], v[10:13]
	v_mfma_f32_16x16x32_bf16 v[62:65], v[164:167], v[198:201], v[62:65]
	v_mfma_f32_16x16x32_bf16 v[58:61], v[172:175], v[198:201], v[58:61]
	v_mfma_f32_16x16x32_bf16 v[50:53], v[164:167], v[206:209], v[50:53]
	v_mfma_f32_16x16x32_bf16 v[42:45], v[172:175], v[206:209], v[42:45]
	v_mfma_f32_16x16x32_bf16 v[34:37], v[164:167], v[214:217], v[34:37]
	v_mfma_f32_16x16x32_bf16 v[26:29], v[172:175], v[214:217], v[26:29]
	v_mfma_f32_16x16x32_bf16 v[18:21], v[164:167], v[222:225], v[18:21]
	v_mfma_f32_16x16x32_bf16 v[10:13], v[172:175], v[222:225], v[10:13]
	v_mfma_f32_16x16x32_bf16 v[54:57], v[178:181], v[194:197], v[54:57]
	v_mfma_f32_16x16x32_bf16 v[46:49], v[186:189], v[194:197], v[46:49]
	v_mfma_f32_16x16x32_bf16 v[38:41], v[178:181], v[202:205], v[38:41]
	v_mfma_f32_16x16x32_bf16 v[30:33], v[186:189], v[202:205], v[30:33]
	v_mfma_f32_16x16x32_bf16 v[22:25], v[178:181], v[210:213], v[22:25]
	v_mfma_f32_16x16x32_bf16 v[14:17], v[186:189], v[210:213], v[14:17]
	v_mfma_f32_16x16x32_bf16 v[6:9], v[178:181], v[218:221], v[6:9]
	v_mfma_f32_16x16x32_bf16 v[2:5], v[186:189], v[218:221], v[2:5]
	v_mfma_f32_16x16x32_bf16 v[54:57], v[182:185], v[198:201], v[54:57]
	v_mfma_f32_16x16x32_bf16 v[46:49], v[190:193], v[198:201], v[46:49]
	v_mfma_f32_16x16x32_bf16 v[38:41], v[182:185], v[206:209], v[38:41]
	v_mfma_f32_16x16x32_bf16 v[30:33], v[190:193], v[206:209], v[30:33]
	v_mfma_f32_16x16x32_bf16 v[22:25], v[182:185], v[214:217], v[22:25]
	v_mfma_f32_16x16x32_bf16 v[14:17], v[190:193], v[214:217], v[14:17]
	v_mfma_f32_16x16x32_bf16 v[6:9], v[182:185], v[222:225], v[6:9]
	v_mfma_f32_16x16x32_bf16 v[2:5], v[190:193], v[222:225], v[2:5]
	s_barrier
	s_setprio 0
	s_add_i32 s61, s61, 2
	s_add_u32 s36, s36, 0x100
	s_addc_u32 s37, s37, 0
	s_add_u32 s59, s59, 0x100
	s_addc_u32 s60, s60, 0
	s_cmp_gt_u32 s61, 13
	s_cbranch_scc0 .LBB0_1179
	s_branch .Lpk1179_exit
.LBB0_1179:
	ds_read_b128 v[144:147], v158
	ds_read_b128 v[164:167], v158 offset:1024
	ds_read_b128 v[168:171], v158 offset:2048
	ds_read_b128 v[172:175], v158 offset:3072
	ds_read_b128 v[178:181], v159
	ds_read_b128 v[182:185], v159 offset:1024
	ds_read_b128 v[186:189], v159 offset:2048
	ds_read_b128 v[190:193], v159 offset:3072
	s_add_u32 s2, s36, 0xfffc0080
	s_addc_u32 s3, s37, -1
	s_cmp_eq_u32 s61, 12
	s_cselect_b32 s3, s19, s3
	s_cselect_b32 s2, s21, s2
	s_cselect_b32 s39, s57, s60
	s_cselect_b32 s38, s58, s59
	v_lshl_add_u64 v[226:227], s[36:37], 0, v[138:139]
	s_add_i32 m0, s42, 0xc000
	ds_read_b128 v[194:197], v160
	ds_read_b128 v[198:201], v160 offset:1024
	ds_read_b128 v[202:205], v160 offset:2048
	ds_read_b128 v[206:209], v160 offset:3072
	ds_read_b128 v[210:213], v160 offset:4096
	ds_read_b128 v[214:217], v160 offset:5120
	ds_read_b128 v[218:221], v160 offset:6144
	ds_read_b128 v[222:225], v160 offset:7168
	global_load_lds_dwordx4 v[226:227], off
	v_lshl_add_u64 v[226:227], s[36:37], 0, v[140:141]
	s_add_i32 m0, s42, 0xe000
	s_nop 0
	global_load_lds_dwordx4 v[226:227], off
	s_waitcnt vmcnt(8)
	s_waitcnt lgkmcnt(0)
	s_setprio 1
	s_barrier
	v_mfma_f32_16x16x32_bf16 v[126:129], v[144:147], v[194:197], v[126:129]
	v_mfma_f32_16x16x32_bf16 v[122:125], v[168:171], v[194:197], v[122:125]
	v_mfma_f32_16x16x32_bf16 v[114:117], v[144:147], v[202:205], v[114:117]
	v_mfma_f32_16x16x32_bf16 v[106:109], v[168:171], v[202:205], v[106:109]
	v_mfma_f32_16x16x32_bf16 v[98:101], v[144:147], v[210:213], v[98:101]
	v_mfma_f32_16x16x32_bf16 v[90:93], v[168:171], v[210:213], v[90:93]
	v_mfma_f32_16x16x32_bf16 v[82:85], v[144:147], v[218:221], v[82:85]
	v_mfma_f32_16x16x32_bf16 v[74:77], v[168:171], v[218:221], v[74:77]
	v_mfma_f32_16x16x32_bf16 v[126:129], v[164:167], v[198:201], v[126:129]
	v_mfma_f32_16x16x32_bf16 v[122:125], v[172:175], v[198:201], v[122:125]
	v_mfma_f32_16x16x32_bf16 v[114:117], v[164:167], v[206:209], v[114:117]
	v_mfma_f32_16x16x32_bf16 v[106:109], v[172:175], v[206:209], v[106:109]
	v_mfma_f32_16x16x32_bf16 v[98:101], v[164:167], v[214:217], v[98:101]
	v_mfma_f32_16x16x32_bf16 v[90:93], v[172:175], v[214:217], v[90:93]
	v_mfma_f32_16x16x32_bf16 v[82:85], v[164:167], v[222:225], v[82:85]
	v_mfma_f32_16x16x32_bf16 v[74:77], v[172:175], v[222:225], v[74:77]
	v_mfma_f32_16x16x32_bf16 v[118:121], v[178:181], v[194:197], v[118:121]
	v_mfma_f32_16x16x32_bf16 v[110:113], v[186:189], v[194:197], v[110:113]
	v_mfma_f32_16x16x32_bf16 v[102:105], v[178:181], v[202:205], v[102:105]
	v_mfma_f32_16x16x32_bf16 v[94:97], v[186:189], v[202:205], v[94:97]
	v_mfma_f32_16x16x32_bf16 v[86:89], v[178:181], v[210:213], v[86:89]
	v_mfma_f32_16x16x32_bf16 v[78:81], v[186:189], v[210:213], v[78:81]
	v_mfma_f32_16x16x32_bf16 v[70:73], v[178:181], v[218:221], v[70:73]
	v_mfma_f32_16x16x32_bf16 v[66:69], v[186:189], v[218:221], v[66:69]
	v_mfma_f32_16x16x32_bf16 v[118:121], v[182:185], v[198:201], v[118:121]
	v_mfma_f32_16x16x32_bf16 v[110:113], v[190:193], v[198:201], v[110:113]
	v_mfma_f32_16x16x32_bf16 v[102:105], v[182:185], v[206:209], v[102:105]
	v_mfma_f32_16x16x32_bf16 v[94:97], v[190:193], v[206:209], v[94:97]
	v_mfma_f32_16x16x32_bf16 v[86:89], v[182:185], v[214:217], v[86:89]
	v_mfma_f32_16x16x32_bf16 v[78:81], v[190:193], v[214:217], v[78:81]
	v_mfma_f32_16x16x32_bf16 v[70:73], v[182:185], v[222:225], v[70:73]
	v_mfma_f32_16x16x32_bf16 v[66:69], v[190:193], v[222:225], v[66:69]
	s_barrier
	s_setprio 0
	s_add_i32 s62, s51, s41
	v_lshl_add_u64 v[226:227], s[38:39], 0, v[132:133]
	s_mov_b32 m0, s62
	ds_read_b128 v[194:197], v160 offset:16384
	ds_read_b128 v[198:201], v160 offset:17408
	ds_read_b128 v[202:205], v160 offset:18432
	ds_read_b128 v[206:209], v160 offset:19456
	ds_read_b128 v[210:213], v160 offset:20480
	ds_read_b128 v[214:217], v160 offset:21504
	ds_read_b128 v[218:221], v160 offset:22528
	ds_read_b128 v[222:225], v160 offset:23552
	global_load_lds_dwordx4 v[226:227], off
	s_add_i32 m0, s62, 0x2000
	s_add_u32 s62, s38, 0x40000
	v_lshl_add_u64 v[228:229], s[38:39], 0, v[136:137]
	s_addc_u32 s63, s39, 0
	s_add_i32 s64, s52, s41
	global_load_lds_dwordx4 v[228:229], off
	v_lshl_add_u64 v[230:231], s[62:63], 0, v[132:133]
	s_mov_b32 m0, s64
	v_lshl_add_u64 v[232:233], s[2:3], 0, v[134:135]
	global_load_lds_dwordx4 v[230:231], off
	v_lshl_add_u64 v[230:231], s[62:63], 0, v[136:137]
	s_add_i32 m0, s64, 0x2000
	s_nop 0
	global_load_lds_dwordx4 v[230:231], off
	v_lshl_add_u64 v[230:231], s[2:3], 0, v[130:131]
	s_mov_b32 m0, s42
	s_nop 0
	global_load_lds_dwordx4 v[230:231], off
	s_mov_b32 m0, s43
	s_nop 0
	global_load_lds_dwordx4 v[232:233], off
	s_waitcnt vmcnt(8)
	s_waitcnt lgkmcnt(0)
	s_setprio 1
	s_barrier
	v_mfma_f32_16x16x32_bf16 v[62:65], v[144:147], v[194:197], v[62:65]
	v_mfma_f32_16x16x32_bf16 v[58:61], v[168:171], v[194:197], v[58:61]
	v_mfma_f32_16x16x32_bf16 v[50:53], v[144:147], v[202:205], v[50:53]
	v_mfma_f32_16x16x32_bf16 v[42:45], v[168:171], v[202:205], v[42:45]
	v_mfma_f32_16x16x32_bf16 v[34:37], v[144:147], v[210:213], v[34:37]
	v_mfma_f32_16x16x32_bf16 v[26:29], v[168:171], v[210:213], v[26:29]
	v_mfma_f32_16x16x32_bf16 v[18:21], v[144:147], v[218:221], v[18:21]
	v_mfma_f32_16x16x32_bf16 v[10:13], v[168:171], v[218:221], v[10:13]
	v_mfma_f32_16x16x32_bf16 v[62:65], v[164:167], v[198:201], v[62:65]
	v_mfma_f32_16x16x32_bf16 v[58:61], v[172:175], v[198:201], v[58:61]
	v_mfma_f32_16x16x32_bf16 v[50:53], v[164:167], v[206:209], v[50:53]
	v_mfma_f32_16x16x32_bf16 v[42:45], v[172:175], v[206:209], v[42:45]
	v_mfma_f32_16x16x32_bf16 v[34:37], v[164:167], v[214:217], v[34:37]
	v_mfma_f32_16x16x32_bf16 v[26:29], v[172:175], v[214:217], v[26:29]
	v_mfma_f32_16x16x32_bf16 v[18:21], v[164:167], v[222:225], v[18:21]
	v_mfma_f32_16x16x32_bf16 v[10:13], v[172:175], v[222:225], v[10:13]
	v_mfma_f32_16x16x32_bf16 v[54:57], v[178:181], v[194:197], v[54:57]
	v_mfma_f32_16x16x32_bf16 v[46:49], v[186:189], v[194:197], v[46:49]
	v_mfma_f32_16x16x32_bf16 v[38:41], v[178:181], v[202:205], v[38:41]
	v_mfma_f32_16x16x32_bf16 v[30:33], v[186:189], v[202:205], v[30:33]
	v_mfma_f32_16x16x32_bf16 v[22:25], v[178:181], v[210:213], v[22:25]
	v_mfma_f32_16x16x32_bf16 v[14:17], v[186:189], v[210:213], v[14:17]
	v_mfma_f32_16x16x32_bf16 v[6:9], v[178:181], v[218:221], v[6:9]
	v_mfma_f32_16x16x32_bf16 v[2:5], v[186:189], v[218:221], v[2:5]
	v_mfma_f32_16x16x32_bf16 v[54:57], v[182:185], v[198:201], v[54:57]
	v_mfma_f32_16x16x32_bf16 v[46:49], v[190:193], v[198:201], v[46:49]
	v_mfma_f32_16x16x32_bf16 v[38:41], v[182:185], v[206:209], v[38:41]
	v_mfma_f32_16x16x32_bf16 v[30:33], v[190:193], v[206:209], v[30:33]
	v_mfma_f32_16x16x32_bf16 v[22:25], v[182:185], v[214:217], v[22:25]
	v_mfma_f32_16x16x32_bf16 v[14:17], v[190:193], v[214:217], v[14:17]
	v_mfma_f32_16x16x32_bf16 v[6:9], v[182:185], v[222:225], v[6:9]
	v_mfma_f32_16x16x32_bf16 v[2:5], v[190:193], v[222:225], v[2:5]
	s_barrier
	s_setprio 0
	s_add_i32 s62, 0, 0x18000
	v_add_u32_e32 v163, s62, v148
	s_add_i32 s63, 0, 0x1c000
	ds_read_b128 v[144:147], v163
	ds_read_b128 v[164:167], v163 offset:1024
	ds_read_b128 v[168:171], v163 offset:2048
	ds_read_b128 v[172:175], v163 offset:3072
	v_add_u32_e32 v163, s63, v148
	ds_read_b128 v[178:181], v163
	ds_read_b128 v[182:185], v163 offset:1024
	ds_read_b128 v[186:189], v163 offset:2048
	ds_read_b128 v[190:193], v163 offset:3072
	s_add_u32 s2, s2, 0x40000
	s_addc_u32 s3, s3, 0
	s_mov_b32 m0, s44
	v_lshl_add_u64 v[234:235], s[2:3], 0, v[130:131]
	ds_read_b128 v[194:197], v160 offset:32768
	ds_read_b128 v[198:201], v160 offset:33792
	ds_read_b128 v[202:205], v160 offset:34816
	ds_read_b128 v[206:209], v160 offset:35840
	ds_read_b128 v[210:213], v160 offset:36864
	ds_read_b128 v[214:217], v160 offset:37888
	ds_read_b128 v[218:221], v160 offset:38912
	ds_read_b128 v[222:225], v160 offset:39936
	global_load_lds_dwordx4 v[234:235], off
	v_lshl_add_u64 v[234:235], s[2:3], 0, v[134:135]
	s_mov_b32 m0, s45
	s_nop 0
	global_load_lds_dwordx4 v[234:235], off
	s_waitcnt vmcnt(8)
	s_waitcnt lgkmcnt(0)
	s_setprio 1
	s_barrier
	v_mfma_f32_16x16x32_bf16 v[126:129], v[144:147], v[194:197], v[126:129]
	v_mfma_f32_16x16x32_bf16 v[122:125], v[168:171], v[194:197], v[122:125]
	v_mfma_f32_16x16x32_bf16 v[114:117], v[144:147], v[202:205], v[114:117]
	v_mfma_f32_16x16x32_bf16 v[106:109], v[168:171], v[202:205], v[106:109]
	v_mfma_f32_16x16x32_bf16 v[98:101], v[144:147], v[210:213], v[98:101]
	v_mfma_f32_16x16x32_bf16 v[90:93], v[168:171], v[210:213], v[90:93]
	v_mfma_f32_16x16x32_bf16 v[82:85], v[144:147], v[218:221], v[82:85]
	v_mfma_f32_16x16x32_bf16 v[74:77], v[168:171], v[218:221], v[74:77]
	v_mfma_f32_16x16x32_bf16 v[126:129], v[164:167], v[198:201], v[126:129]
	v_mfma_f32_16x16x32_bf16 v[122:125], v[172:175], v[198:201], v[122:125]
	v_mfma_f32_16x16x32_bf16 v[114:117], v[164:167], v[206:209], v[114:117]
	v_mfma_f32_16x16x32_bf16 v[106:109], v[172:175], v[206:209], v[106:109]
	v_mfma_f32_16x16x32_bf16 v[98:101], v[164:167], v[214:217], v[98:101]
	v_mfma_f32_16x16x32_bf16 v[90:93], v[172:175], v[214:217], v[90:93]
	v_mfma_f32_16x16x32_bf16 v[82:85], v[164:167], v[222:225], v[82:85]
	v_mfma_f32_16x16x32_bf16 v[74:77], v[172:175], v[222:225], v[74:77]
	v_mfma_f32_16x16x32_bf16 v[118:121], v[178:181], v[194:197], v[118:121]
	v_mfma_f32_16x16x32_bf16 v[110:113], v[186:189], v[194:197], v[110:113]
	v_mfma_f32_16x16x32_bf16 v[102:105], v[178:181], v[202:205], v[102:105]
	v_mfma_f32_16x16x32_bf16 v[94:97], v[186:189], v[202:205], v[94:97]
	v_mfma_f32_16x16x32_bf16 v[86:89], v[178:181], v[210:213], v[86:89]
	v_mfma_f32_16x16x32_bf16 v[78:81], v[186:189], v[210:213], v[78:81]
	v_mfma_f32_16x16x32_bf16 v[70:73], v[178:181], v[218:221], v[70:73]
	v_mfma_f32_16x16x32_bf16 v[66:69], v[186:189], v[218:221], v[66:69]
	v_mfma_f32_16x16x32_bf16 v[118:121], v[182:185], v[198:201], v[118:121]
	v_mfma_f32_16x16x32_bf16 v[110:113], v[190:193], v[198:201], v[110:113]
	v_mfma_f32_16x16x32_bf16 v[102:105], v[182:185], v[206:209], v[102:105]
	v_mfma_f32_16x16x32_bf16 v[94:97], v[190:193], v[206:209], v[94:97]
	v_mfma_f32_16x16x32_bf16 v[86:89], v[182:185], v[214:217], v[86:89]
	v_mfma_f32_16x16x32_bf16 v[78:81], v[190:193], v[214:217], v[78:81]
	v_mfma_f32_16x16x32_bf16 v[70:73], v[182:185], v[222:225], v[70:73]
	v_mfma_f32_16x16x32_bf16 v[66:69], v[190:193], v[222:225], v[66:69]
	s_barrier
	s_setprio 0
	s_add_i32 s2, s62, s41
	v_lshl_add_u64 v[226:227], v[226:227], 0, s[10:11]
	s_mov_b32 m0, s2
	ds_read_b128 v[194:197], v160 offset:49152
	ds_read_b128 v[198:201], v160 offset:50176
	ds_read_b128 v[202:205], v160 offset:51200
	ds_read_b128 v[206:209], v160 offset:52224
	ds_read_b128 v[210:213], v160 offset:53248
	ds_read_b128 v[214:217], v160 offset:54272
	ds_read_b128 v[218:221], v160 offset:55296
	ds_read_b128 v[222:225], v160 offset:56320
	global_load_lds_dwordx4 v[226:227], off
	s_add_i32 m0, s2, 0x2000
	s_add_u32 s2, s38, 0x40080
	v_lshl_add_u64 v[226:227], v[228:229], 0, s[10:11]
	s_addc_u32 s3, s39, 0
	s_add_i32 s38, s63, s41
	global_load_lds_dwordx4 v[226:227], off
	v_lshl_add_u64 v[226:227], s[2:3], 0, v[132:133]
	s_mov_b32 m0, s38
	s_nop 0
	global_load_lds_dwordx4 v[226:227], off
	v_lshl_add_u64 v[226:227], s[2:3], 0, v[136:137]
	s_add_i32 m0, s38, 0x2000
	s_nop 0
	global_load_lds_dwordx4 v[226:227], off
	v_lshl_add_u64 v[226:227], v[230:231], 0, s[10:11]
	s_mov_b32 m0, s47
	s_nop 0
	global_load_lds_dwordx4 v[226:227], off
	v_lshl_add_u64 v[226:227], v[232:233], 0, s[10:11]
	s_mov_b32 m0, s48
	s_nop 0
	global_load_lds_dwordx4 v[226:227], off
	s_waitcnt vmcnt(8)
	s_waitcnt lgkmcnt(0)
	s_setprio 1
	s_barrier
	v_mfma_f32_16x16x32_bf16 v[62:65], v[144:147], v[194:197], v[62:65]
	v_mfma_f32_16x16x32_bf16 v[58:61], v[168:171], v[194:197], v[58:61]
	v_mfma_f32_16x16x32_bf16 v[50:53], v[144:147], v[202:205], v[50:53]
	v_mfma_f32_16x16x32_bf16 v[42:45], v[168:171], v[202:205], v[42:45]
	v_mfma_f32_16x16x32_bf16 v[34:37], v[144:147], v[210:213], v[34:37]
	v_mfma_f32_16x16x32_bf16 v[26:29], v[168:171], v[210:213], v[26:29]
	v_mfma_f32_16x16x32_bf16 v[18:21], v[144:147], v[218:221], v[18:21]
	v_mfma_f32_16x16x32_bf16 v[10:13], v[168:171], v[218:221], v[10:13]
	v_mfma_f32_16x16x32_bf16 v[62:65], v[164:167], v[198:201], v[62:65]
	v_mfma_f32_16x16x32_bf16 v[58:61], v[172:175], v[198:201], v[58:61]
	v_mfma_f32_16x16x32_bf16 v[50:53], v[164:167], v[206:209], v[50:53]
	v_mfma_f32_16x16x32_bf16 v[42:45], v[172:175], v[206:209], v[42:45]
	v_mfma_f32_16x16x32_bf16 v[34:37], v[164:167], v[214:217], v[34:37]
	v_mfma_f32_16x16x32_bf16 v[26:29], v[172:175], v[214:217], v[26:29]
	v_mfma_f32_16x16x32_bf16 v[18:21], v[164:167], v[222:225], v[18:21]
	v_mfma_f32_16x16x32_bf16 v[10:13], v[172:175], v[222:225], v[10:13]
	v_mfma_f32_16x16x32_bf16 v[54:57], v[178:181], v[194:197], v[54:57]
	v_mfma_f32_16x16x32_bf16 v[46:49], v[186:189], v[194:197], v[46:49]
	v_mfma_f32_16x16x32_bf16 v[38:41], v[178:181], v[202:205], v[38:41]
	v_mfma_f32_16x16x32_bf16 v[30:33], v[186:189], v[202:205], v[30:33]
	v_mfma_f32_16x16x32_bf16 v[22:25], v[178:181], v[210:213], v[22:25]
	v_mfma_f32_16x16x32_bf16 v[14:17], v[186:189], v[210:213], v[14:17]
	v_mfma_f32_16x16x32_bf16 v[6:9], v[178:181], v[218:221], v[6:9]
	v_mfma_f32_16x16x32_bf16 v[2:5], v[186:189], v[218:221], v[2:5]
	v_mfma_f32_16x16x32_bf16 v[54:57], v[182:185], v[198:201], v[54:57]
	v_mfma_f32_16x16x32_bf16 v[46:49], v[190:193], v[198:201], v[46:49]
	v_mfma_f32_16x16x32_bf16 v[38:41], v[182:185], v[206:209], v[38:41]
	v_mfma_f32_16x16x32_bf16 v[30:33], v[190:193], v[206:209], v[30:33]
	v_mfma_f32_16x16x32_bf16 v[22:25], v[182:185], v[214:217], v[22:25]
	v_mfma_f32_16x16x32_bf16 v[14:17], v[190:193], v[214:217], v[14:17]
	v_mfma_f32_16x16x32_bf16 v[6:9], v[182:185], v[222:225], v[6:9]
	v_mfma_f32_16x16x32_bf16 v[2:5], v[190:193], v[222:225], v[2:5]
	s_barrier
	s_setprio 0
	s_add_i32 s61, s61, 2
	s_add_u32 s36, s36, 0x100
	s_addc_u32 s37, s37, 0
	s_add_u32 s59, s59, 0x100
	s_addc_u32 s60, s60, 0
	s_cmp_gt_u32 s61, 13
	s_cbranch_scc0 .LBB0_1179

.Lpk1239_peel:
	ds_read_b128 v[152:155], v148
	ds_read_b128 v[156:159], v148 offset:1024
	ds_read_b128 v[160:163], v148 offset:2048
	ds_read_b128 v[164:167], v148 offset:3072
	ds_read_b128 v[168:171], v149
	ds_read_b128 v[172:175], v149 offset:1024
	ds_read_b128 v[178:181], v149 offset:2048
	ds_read_b128 v[182:185], v149 offset:3072
	s_add_u32 s2, s36, 0xfffc0080
	s_addc_u32 s3, s37, -1
	s_cmp_eq_u32 s62, 12
	s_cselect_b32 s3, s19, s3
	s_cselect_b32 s2, s21, s2
	s_cselect_b32 s39, s58, s61
	s_cselect_b32 s38, s59, s60
	v_lshl_add_u64 v[144:145], s[36:37], 0, v[138:139]
	s_add_i32 m0, s44, 0xc000
	ds_read_b128 v[186:189], v150
	ds_read_b128 v[190:193], v150 offset:1024
	ds_read_b128 v[194:197], v150 offset:2048
	ds_read_b128 v[198:201], v150 offset:3072
	ds_read_b128 v[202:205], v150 offset:4096
	ds_read_b128 v[206:209], v150 offset:5120
	ds_read_b128 v[210:213], v150 offset:6144
	ds_read_b128 v[214:217], v150 offset:7168
	global_load_lds_dwordx4 v[144:145], off
	v_lshl_add_u64 v[144:145], s[36:37], 0, v[140:141]
	s_add_i32 m0, s44, 0xe000
	s_nop 0
	global_load_lds_dwordx4 v[144:145], off
	s_waitcnt vmcnt(8)
	s_waitcnt lgkmcnt(0)
	s_setprio 1
	s_barrier
	v_mfma_f32_16x16x32_bf16 v[126:129], v[152:155], v[186:189], 0
	v_mfma_f32_16x16x32_bf16 v[122:125], v[160:163], v[186:189], 0
	v_mfma_f32_16x16x32_bf16 v[114:117], v[152:155], v[194:197], 0
	v_mfma_f32_16x16x32_bf16 v[106:109], v[160:163], v[194:197], 0
	v_mfma_f32_16x16x32_bf16 v[98:101], v[152:155], v[202:205], 0
	v_mfma_f32_16x16x32_bf16 v[90:93], v[160:163], v[202:205], 0
	v_mfma_f32_16x16x32_bf16 v[82:85], v[152:155], v[210:213], 0
	v_mfma_f32_16x16x32_bf16 v[74:77], v[160:163], v[210:213], 0
	v_mfma_f32_16x16x32_bf16 v[126:129], v[156:159], v[190:193], v[126:129]
	v_mfma_f32_16x16x32_bf16 v[122:125], v[164:167], v[190:193], v[122:125]
	v_mfma_f32_16x16x32_bf16 v[114:117], v[156:159], v[198:201], v[114:117]
	v_mfma_f32_16x16x32_bf16 v[106:109], v[164:167], v[198:201], v[106:109]
	v_mfma_f32_16x16x32_bf16 v[98:101], v[156:159], v[206:209], v[98:101]
	v_mfma_f32_16x16x32_bf16 v[90:93], v[164:167], v[206:209], v[90:93]
	v_mfma_f32_16x16x32_bf16 v[82:85], v[156:159], v[214:217], v[82:85]
	v_mfma_f32_16x16x32_bf16 v[74:77], v[164:167], v[214:217], v[74:77]
	v_mfma_f32_16x16x32_bf16 v[118:121], v[168:171], v[186:189], 0
	v_mfma_f32_16x16x32_bf16 v[110:113], v[178:181], v[186:189], 0
	v_mfma_f32_16x16x32_bf16 v[102:105], v[168:171], v[194:197], 0
	v_mfma_f32_16x16x32_bf16 v[94:97], v[178:181], v[194:197], 0
	v_mfma_f32_16x16x32_bf16 v[86:89], v[168:171], v[202:205], 0
	v_mfma_f32_16x16x32_bf16 v[78:81], v[178:181], v[202:205], 0
	v_mfma_f32_16x16x32_bf16 v[70:73], v[168:171], v[210:213], 0
	v_mfma_f32_16x16x32_bf16 v[66:69], v[178:181], v[210:213], 0
	v_mfma_f32_16x16x32_bf16 v[118:121], v[172:175], v[190:193], v[118:121]
	v_mfma_f32_16x16x32_bf16 v[110:113], v[182:185], v[190:193], v[110:113]
	v_mfma_f32_16x16x32_bf16 v[102:105], v[172:175], v[198:201], v[102:105]
	v_mfma_f32_16x16x32_bf16 v[94:97], v[182:185], v[198:201], v[94:97]
	v_mfma_f32_16x16x32_bf16 v[86:89], v[172:175], v[206:209], v[86:89]
	v_mfma_f32_16x16x32_bf16 v[78:81], v[182:185], v[206:209], v[78:81]
	v_mfma_f32_16x16x32_bf16 v[70:73], v[172:175], v[214:217], v[70:73]
	v_mfma_f32_16x16x32_bf16 v[66:69], v[182:185], v[214:217], v[66:69]
	s_barrier
	s_setprio 0
	s_add_i32 s63, s51, s43
	v_lshl_add_u64 v[144:145], s[38:39], 0, v[132:133]
	s_mov_b32 m0, s63
	ds_read_b128 v[186:189], v150 offset:16384
	ds_read_b128 v[190:193], v150 offset:17408
	ds_read_b128 v[194:197], v150 offset:18432
	ds_read_b128 v[198:201], v150 offset:19456
	ds_read_b128 v[202:205], v150 offset:20480
	ds_read_b128 v[206:209], v150 offset:21504
	ds_read_b128 v[210:213], v150 offset:22528
	ds_read_b128 v[214:217], v150 offset:23552
	global_load_lds_dwordx4 v[144:145], off
	s_add_i32 m0, s63, 0x2000
	s_add_u32 s64, s38, 0x40000
	v_lshl_add_u64 v[218:219], s[38:39], 0, v[136:137]
	s_addc_u32 s65, s39, 0
	s_add_i32 s63, s52, s43
	global_load_lds_dwordx4 v[218:219], off
	v_lshl_add_u64 v[220:221], s[64:65], 0, v[132:133]
	s_mov_b32 m0, s63
	v_lshl_add_u64 v[222:223], s[2:3], 0, v[134:135]
	global_load_lds_dwordx4 v[220:221], off
	v_lshl_add_u64 v[220:221], s[64:65], 0, v[136:137]
	s_add_i32 m0, s63, 0x2000
	s_nop 0
	global_load_lds_dwordx4 v[220:221], off
	v_lshl_add_u64 v[220:221], s[2:3], 0, v[130:131]
	s_mov_b32 m0, s44
	s_nop 0
	global_load_lds_dwordx4 v[220:221], off
	s_mov_b32 m0, s35
	s_nop 0
	global_load_lds_dwordx4 v[222:223], off
	s_waitcnt vmcnt(8)
	s_waitcnt lgkmcnt(0)
	s_setprio 1
	s_barrier
	v_mfma_f32_16x16x32_bf16 v[62:65], v[152:155], v[186:189], 0
	v_mfma_f32_16x16x32_bf16 v[58:61], v[160:163], v[186:189], 0
	v_mfma_f32_16x16x32_bf16 v[50:53], v[152:155], v[194:197], 0
	v_mfma_f32_16x16x32_bf16 v[42:45], v[160:163], v[194:197], 0
	v_mfma_f32_16x16x32_bf16 v[34:37], v[152:155], v[202:205], 0
	v_mfma_f32_16x16x32_bf16 v[26:29], v[160:163], v[202:205], 0
	v_mfma_f32_16x16x32_bf16 v[18:21], v[152:155], v[210:213], 0
	v_mfma_f32_16x16x32_bf16 v[10:13], v[160:163], v[210:213], 0
	v_mfma_f32_16x16x32_bf16 v[62:65], v[156:159], v[190:193], v[62:65]
	v_mfma_f32_16x16x32_bf16 v[58:61], v[164:167], v[190:193], v[58:61]
	v_mfma_f32_16x16x32_bf16 v[50:53], v[156:159], v[198:201], v[50:53]
	v_mfma_f32_16x16x32_bf16 v[42:45], v[164:167], v[198:201], v[42:45]
	v_mfma_f32_16x16x32_bf16 v[34:37], v[156:159], v[206:209], v[34:37]
	v_mfma_f32_16x16x32_bf16 v[26:29], v[164:167], v[206:209], v[26:29]
	v_mfma_f32_16x16x32_bf16 v[18:21], v[156:159], v[214:217], v[18:21]
	v_mfma_f32_16x16x32_bf16 v[10:13], v[164:167], v[214:217], v[10:13]
	v_mfma_f32_16x16x32_bf16 v[54:57], v[168:171], v[186:189], 0
	v_mfma_f32_16x16x32_bf16 v[46:49], v[178:181], v[186:189], 0
	v_mfma_f32_16x16x32_bf16 v[38:41], v[168:171], v[194:197], 0
	v_mfma_f32_16x16x32_bf16 v[30:33], v[178:181], v[194:197], 0
	v_mfma_f32_16x16x32_bf16 v[22:25], v[168:171], v[202:205], 0
	v_mfma_f32_16x16x32_bf16 v[14:17], v[178:181], v[202:205], 0
	v_mfma_f32_16x16x32_bf16 v[6:9], v[168:171], v[210:213], 0
	v_mfma_f32_16x16x32_bf16 v[2:5], v[178:181], v[210:213], 0
	v_mfma_f32_16x16x32_bf16 v[54:57], v[172:175], v[190:193], v[54:57]
	v_mfma_f32_16x16x32_bf16 v[46:49], v[182:185], v[190:193], v[46:49]
	v_mfma_f32_16x16x32_bf16 v[38:41], v[172:175], v[198:201], v[38:41]
	v_mfma_f32_16x16x32_bf16 v[30:33], v[182:185], v[198:201], v[30:33]
	v_mfma_f32_16x16x32_bf16 v[22:25], v[172:175], v[206:209], v[22:25]
	v_mfma_f32_16x16x32_bf16 v[14:17], v[182:185], v[206:209], v[14:17]
	v_mfma_f32_16x16x32_bf16 v[6:9], v[172:175], v[214:217], v[6:9]
	v_mfma_f32_16x16x32_bf16 v[2:5], v[182:185], v[214:217], v[2:5]
	s_barrier
	s_setprio 0
	s_add_i32 s63, 0, 0x18000
	v_add_u32_e32 v151, s63, v146
	s_add_i32 s64, 0, 0x1c000
	ds_read_b128 v[152:155], v151
	ds_read_b128 v[156:159], v151 offset:1024
	ds_read_b128 v[160:163], v151 offset:2048
	ds_read_b128 v[164:167], v151 offset:3072
	v_add_u32_e32 v151, s64, v146
	ds_read_b128 v[168:171], v151
	ds_read_b128 v[172:175], v151 offset:1024
	ds_read_b128 v[178:181], v151 offset:2048
	ds_read_b128 v[182:185], v151 offset:3072
	s_add_u32 s2, s2, 0x40000
	s_addc_u32 s3, s3, 0
	s_mov_b32 m0, s45
	v_lshl_add_u64 v[224:225], s[2:3], 0, v[130:131]
	ds_read_b128 v[186:189], v150 offset:32768
	ds_read_b128 v[190:193], v150 offset:33792
	ds_read_b128 v[194:197], v150 offset:34816
	ds_read_b128 v[198:201], v150 offset:35840
	ds_read_b128 v[202:205], v150 offset:36864
	ds_read_b128 v[206:209], v150 offset:37888
	ds_read_b128 v[210:213], v150 offset:38912
	ds_read_b128 v[214:217], v150 offset:39936
	global_load_lds_dwordx4 v[224:225], off
	v_lshl_add_u64 v[224:225], s[2:3], 0, v[134:135]
	s_mov_b32 m0, s46
	s_nop 0
	global_load_lds_dwordx4 v[224:225], off
	s_waitcnt vmcnt(8)
	s_waitcnt lgkmcnt(0)
	s_setprio 1
	s_barrier
	v_mfma_f32_16x16x32_bf16 v[126:129], v[152:155], v[186:189], v[126:129]
	v_mfma_f32_16x16x32_bf16 v[122:125], v[160:163], v[186:189], v[122:125]
	v_mfma_f32_16x16x32_bf16 v[114:117], v[152:155], v[194:197], v[114:117]
	v_mfma_f32_16x16x32_bf16 v[106:109], v[160:163], v[194:197], v[106:109]
	v_mfma_f32_16x16x32_bf16 v[98:101], v[152:155], v[202:205], v[98:101]
	v_mfma_f32_16x16x32_bf16 v[90:93], v[160:163], v[202:205], v[90:93]
	v_mfma_f32_16x16x32_bf16 v[82:85], v[152:155], v[210:213], v[82:85]
	v_mfma_f32_16x16x32_bf16 v[74:77], v[160:163], v[210:213], v[74:77]
	v_mfma_f32_16x16x32_bf16 v[126:129], v[156:159], v[190:193], v[126:129]
	v_mfma_f32_16x16x32_bf16 v[122:125], v[164:167], v[190:193], v[122:125]
	v_mfma_f32_16x16x32_bf16 v[114:117], v[156:159], v[198:201], v[114:117]
	v_mfma_f32_16x16x32_bf16 v[106:109], v[164:167], v[198:201], v[106:109]
	v_mfma_f32_16x16x32_bf16 v[98:101], v[156:159], v[206:209], v[98:101]
	v_mfma_f32_16x16x32_bf16 v[90:93], v[164:167], v[206:209], v[90:93]
	v_mfma_f32_16x16x32_bf16 v[82:85], v[156:159], v[214:217], v[82:85]
	v_mfma_f32_16x16x32_bf16 v[74:77], v[164:167], v[214:217], v[74:77]
	v_mfma_f32_16x16x32_bf16 v[118:121], v[168:171], v[186:189], v[118:121]
	v_mfma_f32_16x16x32_bf16 v[110:113], v[178:181], v[186:189], v[110:113]
	v_mfma_f32_16x16x32_bf16 v[102:105], v[168:171], v[194:197], v[102:105]
	v_mfma_f32_16x16x32_bf16 v[94:97], v[178:181], v[194:197], v[94:97]
	v_mfma_f32_16x16x32_bf16 v[86:89], v[168:171], v[202:205], v[86:89]
	v_mfma_f32_16x16x32_bf16 v[78:81], v[178:181], v[202:205], v[78:81]
	v_mfma_f32_16x16x32_bf16 v[70:73], v[168:171], v[210:213], v[70:73]
	v_mfma_f32_16x16x32_bf16 v[66:69], v[178:181], v[210:213], v[66:69]
	v_mfma_f32_16x16x32_bf16 v[118:121], v[172:175], v[190:193], v[118:121]
	v_mfma_f32_16x16x32_bf16 v[110:113], v[182:185], v[190:193], v[110:113]
	v_mfma_f32_16x16x32_bf16 v[102:105], v[172:175], v[198:201], v[102:105]
	v_mfma_f32_16x16x32_bf16 v[94:97], v[182:185], v[198:201], v[94:97]
	v_mfma_f32_16x16x32_bf16 v[86:89], v[172:175], v[206:209], v[86:89]
	v_mfma_f32_16x16x32_bf16 v[78:81], v[182:185], v[206:209], v[78:81]
	v_mfma_f32_16x16x32_bf16 v[70:73], v[172:175], v[214:217], v[70:73]
	v_mfma_f32_16x16x32_bf16 v[66:69], v[182:185], v[214:217], v[66:69]
	s_barrier
	s_setprio 0
	s_add_i32 s2, s63, s43
	v_lshl_add_u64 v[144:145], v[144:145], 0, s[8:9]
	s_mov_b32 m0, s2
	ds_read_b128 v[186:189], v150 offset:49152
	ds_read_b128 v[190:193], v150 offset:50176
	ds_read_b128 v[194:197], v150 offset:51200
	ds_read_b128 v[198:201], v150 offset:52224
	ds_read_b128 v[202:205], v150 offset:53248
	ds_read_b128 v[206:209], v150 offset:54272
	ds_read_b128 v[210:213], v150 offset:55296
	ds_read_b128 v[214:217], v150 offset:56320
	global_load_lds_dwordx4 v[144:145], off
	s_add_i32 m0, s2, 0x2000
	s_add_u32 s2, s38, 0x40080
	v_lshl_add_u64 v[144:145], v[218:219], 0, s[8:9]
	s_addc_u32 s3, s39, 0
	s_add_i32 s38, s64, s43
	global_load_lds_dwordx4 v[144:145], off
	v_lshl_add_u64 v[144:145], s[2:3], 0, v[132:133]
	s_mov_b32 m0, s38
	s_nop 0
	global_load_lds_dwordx4 v[144:145], off
	v_lshl_add_u64 v[144:145], s[2:3], 0, v[136:137]
	s_add_i32 m0, s38, 0x2000
	s_nop 0
	global_load_lds_dwordx4 v[144:145], off
	v_lshl_add_u64 v[144:145], v[220:221], 0, s[8:9]
	s_mov_b32 m0, s48
	s_nop 0
	global_load_lds_dwordx4 v[144:145], off
	v_lshl_add_u64 v[144:145], v[222:223], 0, s[8:9]
	s_mov_b32 m0, s49
	s_nop 0
	global_load_lds_dwordx4 v[144:145], off
	s_waitcnt vmcnt(8)
	s_waitcnt lgkmcnt(0)
	s_setprio 1
	s_barrier
	v_mfma_f32_16x16x32_bf16 v[62:65], v[152:155], v[186:189], v[62:65]
	v_mfma_f32_16x16x32_bf16 v[58:61], v[160:163], v[186:189], v[58:61]
	v_mfma_f32_16x16x32_bf16 v[50:53], v[152:155], v[194:197], v[50:53]
	v_mfma_f32_16x16x32_bf16 v[42:45], v[160:163], v[194:197], v[42:45]
	v_mfma_f32_16x16x32_bf16 v[34:37], v[152:155], v[202:205], v[34:37]
	v_mfma_f32_16x16x32_bf16 v[26:29], v[160:163], v[202:205], v[26:29]
	v_mfma_f32_16x16x32_bf16 v[18:21], v[152:155], v[210:213], v[18:21]
	v_mfma_f32_16x16x32_bf16 v[10:13], v[160:163], v[210:213], v[10:13]
	v_mfma_f32_16x16x32_bf16 v[62:65], v[156:159], v[190:193], v[62:65]
	v_mfma_f32_16x16x32_bf16 v[58:61], v[164:167], v[190:193], v[58:61]
	v_mfma_f32_16x16x32_bf16 v[50:53], v[156:159], v[198:201], v[50:53]
	v_mfma_f32_16x16x32_bf16 v[42:45], v[164:167], v[198:201], v[42:45]
	v_mfma_f32_16x16x32_bf16 v[34:37], v[156:159], v[206:209], v[34:37]
	v_mfma_f32_16x16x32_bf16 v[26:29], v[164:167], v[206:209], v[26:29]
	v_mfma_f32_16x16x32_bf16 v[18:21], v[156:159], v[214:217], v[18:21]
	v_mfma_f32_16x16x32_bf16 v[10:13], v[164:167], v[214:217], v[10:13]
	v_mfma_f32_16x16x32_bf16 v[54:57], v[168:171], v[186:189], v[54:57]
	v_mfma_f32_16x16x32_bf16 v[46:49], v[178:181], v[186:189], v[46:49]
	v_mfma_f32_16x16x32_bf16 v[38:41], v[168:171], v[194:197], v[38:41]
	v_mfma_f32_16x16x32_bf16 v[30:33], v[178:181], v[194:197], v[30:33]
	v_mfma_f32_16x16x32_bf16 v[22:25], v[168:171], v[202:205], v[22:25]
	v_mfma_f32_16x16x32_bf16 v[14:17], v[178:181], v[202:205], v[14:17]
	v_mfma_f32_16x16x32_bf16 v[6:9], v[168:171], v[210:213], v[6:9]
	v_mfma_f32_16x16x32_bf16 v[2:5], v[178:181], v[210:213], v[2:5]
	v_mfma_f32_16x16x32_bf16 v[54:57], v[172:175], v[190:193], v[54:57]
	v_mfma_f32_16x16x32_bf16 v[46:49], v[182:185], v[190:193], v[46:49]
	v_mfma_f32_16x16x32_bf16 v[38:41], v[172:175], v[198:201], v[38:41]
	v_mfma_f32_16x16x32_bf16 v[30:33], v[182:185], v[198:201], v[30:33]
	v_mfma_f32_16x16x32_bf16 v[22:25], v[172:175], v[206:209], v[22:25]
	v_mfma_f32_16x16x32_bf16 v[14:17], v[182:185], v[206:209], v[14:17]
	v_mfma_f32_16x16x32_bf16 v[6:9], v[172:175], v[214:217], v[6:9]
	v_mfma_f32_16x16x32_bf16 v[2:5], v[182:185], v[214:217], v[2:5]
	s_barrier
	s_setprio 0
	s_add_i32 s62, s62, 2
	s_add_u32 s36, s36, 0x100
	s_addc_u32 s37, s37, 0
	s_add_u32 s60, s60, 0x100
	s_addc_u32 s61, s61, 0
	s_cmp_gt_u32 s62, 13
	s_cbranch_scc0 .LBB0_1239
	s_branch .Lpk1239_exit
.LBB0_1239:
	ds_read_b128 v[152:155], v148
	ds_read_b128 v[156:159], v148 offset:1024
	ds_read_b128 v[160:163], v148 offset:2048
	ds_read_b128 v[164:167], v148 offset:3072
	ds_read_b128 v[168:171], v149
	ds_read_b128 v[172:175], v149 offset:1024
	ds_read_b128 v[178:181], v149 offset:2048
	ds_read_b128 v[182:185], v149 offset:3072
	s_add_u32 s2, s36, 0xfffc0080
	s_addc_u32 s3, s37, -1
	s_cmp_eq_u32 s62, 12
	s_cselect_b32 s3, s19, s3
	s_cselect_b32 s2, s21, s2
	s_cselect_b32 s39, s58, s61
	s_cselect_b32 s38, s59, s60
	v_lshl_add_u64 v[144:145], s[36:37], 0, v[138:139]
	s_add_i32 m0, s44, 0xc000
	ds_read_b128 v[186:189], v150
	ds_read_b128 v[190:193], v150 offset:1024
	ds_read_b128 v[194:197], v150 offset:2048
	ds_read_b128 v[198:201], v150 offset:3072
	ds_read_b128 v[202:205], v150 offset:4096
	ds_read_b128 v[206:209], v150 offset:5120
	ds_read_b128 v[210:213], v150 offset:6144
	ds_read_b128 v[214:217], v150 offset:7168
	global_load_lds_dwordx4 v[144:145], off
	v_lshl_add_u64 v[144:145], s[36:37], 0, v[140:141]
	s_add_i32 m0, s44, 0xe000
	s_nop 0
	global_load_lds_dwordx4 v[144:145], off
	s_waitcnt vmcnt(8)
	s_waitcnt lgkmcnt(0)
	s_setprio 1
	s_barrier
	v_mfma_f32_16x16x32_bf16 v[126:129], v[152:155], v[186:189], v[126:129]
	v_mfma_f32_16x16x32_bf16 v[122:125], v[160:163], v[186:189], v[122:125]
	v_mfma_f32_16x16x32_bf16 v[114:117], v[152:155], v[194:197], v[114:117]
	v_mfma_f32_16x16x32_bf16 v[106:109], v[160:163], v[194:197], v[106:109]
	v_mfma_f32_16x16x32_bf16 v[98:101], v[152:155], v[202:205], v[98:101]
	v_mfma_f32_16x16x32_bf16 v[90:93], v[160:163], v[202:205], v[90:93]
	v_mfma_f32_16x16x32_bf16 v[82:85], v[152:155], v[210:213], v[82:85]
	v_mfma_f32_16x16x32_bf16 v[74:77], v[160:163], v[210:213], v[74:77]
	v_mfma_f32_16x16x32_bf16 v[126:129], v[156:159], v[190:193], v[126:129]
	v_mfma_f32_16x16x32_bf16 v[122:125], v[164:167], v[190:193], v[122:125]
	v_mfma_f32_16x16x32_bf16 v[114:117], v[156:159], v[198:201], v[114:117]
	v_mfma_f32_16x16x32_bf16 v[106:109], v[164:167], v[198:201], v[106:109]
	v_mfma_f32_16x16x32_bf16 v[98:101], v[156:159], v[206:209], v[98:101]
	v_mfma_f32_16x16x32_bf16 v[90:93], v[164:167], v[206:209], v[90:93]
	v_mfma_f32_16x16x32_bf16 v[82:85], v[156:159], v[214:217], v[82:85]
	v_mfma_f32_16x16x32_bf16 v[74:77], v[164:167], v[214:217], v[74:77]
	v_mfma_f32_16x16x32_bf16 v[118:121], v[168:171], v[186:189], v[118:121]
	v_mfma_f32_16x16x32_bf16 v[110:113], v[178:181], v[186:189], v[110:113]
	v_mfma_f32_16x16x32_bf16 v[102:105], v[168:171], v[194:197], v[102:105]
	v_mfma_f32_16x16x32_bf16 v[94:97], v[178:181], v[194:197], v[94:97]
	v_mfma_f32_16x16x32_bf16 v[86:89], v[168:171], v[202:205], v[86:89]
	v_mfma_f32_16x16x32_bf16 v[78:81], v[178:181], v[202:205], v[78:81]
	v_mfma_f32_16x16x32_bf16 v[70:73], v[168:171], v[210:213], v[70:73]
	v_mfma_f32_16x16x32_bf16 v[66:69], v[178:181], v[210:213], v[66:69]
	v_mfma_f32_16x16x32_bf16 v[118:121], v[172:175], v[190:193], v[118:121]
	v_mfma_f32_16x16x32_bf16 v[110:113], v[182:185], v[190:193], v[110:113]
	v_mfma_f32_16x16x32_bf16 v[102:105], v[172:175], v[198:201], v[102:105]
	v_mfma_f32_16x16x32_bf16 v[94:97], v[182:185], v[198:201], v[94:97]
	v_mfma_f32_16x16x32_bf16 v[86:89], v[172:175], v[206:209], v[86:89]
	v_mfma_f32_16x16x32_bf16 v[78:81], v[182:185], v[206:209], v[78:81]
	v_mfma_f32_16x16x32_bf16 v[70:73], v[172:175], v[214:217], v[70:73]
	v_mfma_f32_16x16x32_bf16 v[66:69], v[182:185], v[214:217], v[66:69]
	s_barrier
	s_setprio 0
	s_add_i32 s63, s51, s43
	v_lshl_add_u64 v[144:145], s[38:39], 0, v[132:133]
	s_mov_b32 m0, s63
	ds_read_b128 v[186:189], v150 offset:16384
	ds_read_b128 v[190:193], v150 offset:17408
	ds_read_b128 v[194:197], v150 offset:18432
	ds_read_b128 v[198:201], v150 offset:19456
	ds_read_b128 v[202:205], v150 offset:20480
	ds_read_b128 v[206:209], v150 offset:21504
	ds_read_b128 v[210:213], v150 offset:22528
	ds_read_b128 v[214:217], v150 offset:23552
	global_load_lds_dwordx4 v[144:145], off
	s_add_i32 m0, s63, 0x2000
	s_add_u32 s64, s38, 0x40000
	v_lshl_add_u64 v[218:219], s[38:39], 0, v[136:137]
	s_addc_u32 s65, s39, 0
	s_add_i32 s63, s52, s43
	global_load_lds_dwordx4 v[218:219], off
	v_lshl_add_u64 v[220:221], s[64:65], 0, v[132:133]
	s_mov_b32 m0, s63
	v_lshl_add_u64 v[222:223], s[2:3], 0, v[134:135]
	global_load_lds_dwordx4 v[220:221], off
	v_lshl_add_u64 v[220:221], s[64:65], 0, v[136:137]
	s_add_i32 m0, s63, 0x2000
	s_nop 0
	global_load_lds_dwordx4 v[220:221], off
	v_lshl_add_u64 v[220:221], s[2:3], 0, v[130:131]
	s_mov_b32 m0, s44
	s_nop 0
	global_load_lds_dwordx4 v[220:221], off
	s_mov_b32 m0, s35
	s_nop 0
	global_load_lds_dwordx4 v[222:223], off
	s_waitcnt vmcnt(8)
	s_waitcnt lgkmcnt(0)
	s_setprio 1
	s_barrier
	v_mfma_f32_16x16x32_bf16 v[62:65], v[152:155], v[186:189], v[62:65]
	v_mfma_f32_16x16x32_bf16 v[58:61], v[160:163], v[186:189], v[58:61]
	v_mfma_f32_16x16x32_bf16 v[50:53], v[152:155], v[194:197], v[50:53]
	v_mfma_f32_16x16x32_bf16 v[42:45], v[160:163], v[194:197], v[42:45]
	v_mfma_f32_16x16x32_bf16 v[34:37], v[152:155], v[202:205], v[34:37]
	v_mfma_f32_16x16x32_bf16 v[26:29], v[160:163], v[202:205], v[26:29]
	v_mfma_f32_16x16x32_bf16 v[18:21], v[152:155], v[210:213], v[18:21]
	v_mfma_f32_16x16x32_bf16 v[10:13], v[160:163], v[210:213], v[10:13]
	v_mfma_f32_16x16x32_bf16 v[62:65], v[156:159], v[190:193], v[62:65]
	v_mfma_f32_16x16x32_bf16 v[58:61], v[164:167], v[190:193], v[58:61]
	v_mfma_f32_16x16x32_bf16 v[50:53], v[156:159], v[198:201], v[50:53]
	v_mfma_f32_16x16x32_bf16 v[42:45], v[164:167], v[198:201], v[42:45]
	v_mfma_f32_16x16x32_bf16 v[34:37], v[156:159], v[206:209], v[34:37]
	v_mfma_f32_16x16x32_bf16 v[26:29], v[164:167], v[206:209], v[26:29]
	v_mfma_f32_16x16x32_bf16 v[18:21], v[156:159], v[214:217], v[18:21]
	v_mfma_f32_16x16x32_bf16 v[10:13], v[164:167], v[214:217], v[10:13]
	v_mfma_f32_16x16x32_bf16 v[54:57], v[168:171], v[186:189], v[54:57]
	v_mfma_f32_16x16x32_bf16 v[46:49], v[178:181], v[186:189], v[46:49]
	v_mfma_f32_16x16x32_bf16 v[38:41], v[168:171], v[194:197], v[38:41]
	v_mfma_f32_16x16x32_bf16 v[30:33], v[178:181], v[194:197], v[30:33]
	v_mfma_f32_16x16x32_bf16 v[22:25], v[168:171], v[202:205], v[22:25]
	v_mfma_f32_16x16x32_bf16 v[14:17], v[178:181], v[202:205], v[14:17]
	v_mfma_f32_16x16x32_bf16 v[6:9], v[168:171], v[210:213], v[6:9]
	v_mfma_f32_16x16x32_bf16 v[2:5], v[178:181], v[210:213], v[2:5]
	v_mfma_f32_16x16x32_bf16 v[54:57], v[172:175], v[190:193], v[54:57]
	v_mfma_f32_16x16x32_bf16 v[46:49], v[182:185], v[190:193], v[46:49]
	v_mfma_f32_16x16x32_bf16 v[38:41], v[172:175], v[198:201], v[38:41]
	v_mfma_f32_16x16x32_bf16 v[30:33], v[182:185], v[198:201], v[30:33]
	v_mfma_f32_16x16x32_bf16 v[22:25], v[172:175], v[206:209], v[22:25]
	v_mfma_f32_16x16x32_bf16 v[14:17], v[182:185], v[206:209], v[14:17]
	v_mfma_f32_16x16x32_bf16 v[6:9], v[172:175], v[214:217], v[6:9]
	v_mfma_f32_16x16x32_bf16 v[2:5], v[182:185], v[214:217], v[2:5]
	s_barrier
	s_setprio 0
	s_add_i32 s63, 0, 0x18000
	v_add_u32_e32 v151, s63, v146
	s_add_i32 s64, 0, 0x1c000
	ds_read_b128 v[152:155], v151
	ds_read_b128 v[156:159], v151 offset:1024
	ds_read_b128 v[160:163], v151 offset:2048
	ds_read_b128 v[164:167], v151 offset:3072
	v_add_u32_e32 v151, s64, v146
	ds_read_b128 v[168:171], v151
	ds_read_b128 v[172:175], v151 offset:1024
	ds_read_b128 v[178:181], v151 offset:2048
	ds_read_b128 v[182:185], v151 offset:3072
	s_add_u32 s2, s2, 0x40000
	s_addc_u32 s3, s3, 0
	s_mov_b32 m0, s45
	v_lshl_add_u64 v[224:225], s[2:3], 0, v[130:131]
	ds_read_b128 v[186:189], v150 offset:32768
	ds_read_b128 v[190:193], v150 offset:33792
	ds_read_b128 v[194:197], v150 offset:34816
	ds_read_b128 v[198:201], v150 offset:35840
	ds_read_b128 v[202:205], v150 offset:36864
	ds_read_b128 v[206:209], v150 offset:37888
	ds_read_b128 v[210:213], v150 offset:38912
	ds_read_b128 v[214:217], v150 offset:39936
	global_load_lds_dwordx4 v[224:225], off
	v_lshl_add_u64 v[224:225], s[2:3], 0, v[134:135]
	s_mov_b32 m0, s46
	s_nop 0
	global_load_lds_dwordx4 v[224:225], off
	s_waitcnt vmcnt(8)
	s_waitcnt lgkmcnt(0)
	s_setprio 1
	s_barrier
	v_mfma_f32_16x16x32_bf16 v[126:129], v[152:155], v[186:189], v[126:129]
	v_mfma_f32_16x16x32_bf16 v[122:125], v[160:163], v[186:189], v[122:125]
	v_mfma_f32_16x16x32_bf16 v[114:117], v[152:155], v[194:197], v[114:117]
	v_mfma_f32_16x16x32_bf16 v[106:109], v[160:163], v[194:197], v[106:109]
	v_mfma_f32_16x16x32_bf16 v[98:101], v[152:155], v[202:205], v[98:101]
	v_mfma_f32_16x16x32_bf16 v[90:93], v[160:163], v[202:205], v[90:93]
	v_mfma_f32_16x16x32_bf16 v[82:85], v[152:155], v[210:213], v[82:85]
	v_mfma_f32_16x16x32_bf16 v[74:77], v[160:163], v[210:213], v[74:77]
	v_mfma_f32_16x16x32_bf16 v[126:129], v[156:159], v[190:193], v[126:129]
	v_mfma_f32_16x16x32_bf16 v[122:125], v[164:167], v[190:193], v[122:125]
	v_mfma_f32_16x16x32_bf16 v[114:117], v[156:159], v[198:201], v[114:117]
	v_mfma_f32_16x16x32_bf16 v[106:109], v[164:167], v[198:201], v[106:109]
	v_mfma_f32_16x16x32_bf16 v[98:101], v[156:159], v[206:209], v[98:101]
	v_mfma_f32_16x16x32_bf16 v[90:93], v[164:167], v[206:209], v[90:93]
	v_mfma_f32_16x16x32_bf16 v[82:85], v[156:159], v[214:217], v[82:85]
	v_mfma_f32_16x16x32_bf16 v[74:77], v[164:167], v[214:217], v[74:77]
	v_mfma_f32_16x16x32_bf16 v[118:121], v[168:171], v[186:189], v[118:121]
	v_mfma_f32_16x16x32_bf16 v[110:113], v[178:181], v[186:189], v[110:113]
	v_mfma_f32_16x16x32_bf16 v[102:105], v[168:171], v[194:197], v[102:105]
	v_mfma_f32_16x16x32_bf16 v[94:97], v[178:181], v[194:197], v[94:97]
	v_mfma_f32_16x16x32_bf16 v[86:89], v[168:171], v[202:205], v[86:89]
	v_mfma_f32_16x16x32_bf16 v[78:81], v[178:181], v[202:205], v[78:81]
	v_mfma_f32_16x16x32_bf16 v[70:73], v[168:171], v[210:213], v[70:73]
	v_mfma_f32_16x16x32_bf16 v[66:69], v[178:181], v[210:213], v[66:69]
	v_mfma_f32_16x16x32_bf16 v[118:121], v[172:175], v[190:193], v[118:121]
	v_mfma_f32_16x16x32_bf16 v[110:113], v[182:185], v[190:193], v[110:113]
	v_mfma_f32_16x16x32_bf16 v[102:105], v[172:175], v[198:201], v[102:105]
	v_mfma_f32_16x16x32_bf16 v[94:97], v[182:185], v[198:201], v[94:97]
	v_mfma_f32_16x16x32_bf16 v[86:89], v[172:175], v[206:209], v[86:89]
	v_mfma_f32_16x16x32_bf16 v[78:81], v[182:185], v[206:209], v[78:81]
	v_mfma_f32_16x16x32_bf16 v[70:73], v[172:175], v[214:217], v[70:73]
	v_mfma_f32_16x16x32_bf16 v[66:69], v[182:185], v[214:217], v[66:69]
	s_barrier
	s_setprio 0
	s_add_i32 s2, s63, s43
	v_lshl_add_u64 v[144:145], v[144:145], 0, s[8:9]
	s_mov_b32 m0, s2
	ds_read_b128 v[186:189], v150 offset:49152
	ds_read_b128 v[190:193], v150 offset:50176
	ds_read_b128 v[194:197], v150 offset:51200
	ds_read_b128 v[198:201], v150 offset:52224
	ds_read_b128 v[202:205], v150 offset:53248
	ds_read_b128 v[206:209], v150 offset:54272
	ds_read_b128 v[210:213], v150 offset:55296
	ds_read_b128 v[214:217], v150 offset:56320
	global_load_lds_dwordx4 v[144:145], off
	s_add_i32 m0, s2, 0x2000
	s_add_u32 s2, s38, 0x40080
	v_lshl_add_u64 v[144:145], v[218:219], 0, s[8:9]
	s_addc_u32 s3, s39, 0
	s_add_i32 s38, s64, s43
	global_load_lds_dwordx4 v[144:145], off
	v_lshl_add_u64 v[144:145], s[2:3], 0, v[132:133]
	s_mov_b32 m0, s38
	s_nop 0
	global_load_lds_dwordx4 v[144:145], off
	v_lshl_add_u64 v[144:145], s[2:3], 0, v[136:137]
	s_add_i32 m0, s38, 0x2000
	s_nop 0
	global_load_lds_dwordx4 v[144:145], off
	v_lshl_add_u64 v[144:145], v[220:221], 0, s[8:9]
	s_mov_b32 m0, s48
	s_nop 0
	global_load_lds_dwordx4 v[144:145], off
	v_lshl_add_u64 v[144:145], v[222:223], 0, s[8:9]
	s_mov_b32 m0, s49
	s_nop 0
	global_load_lds_dwordx4 v[144:145], off
	s_waitcnt vmcnt(8)
	s_waitcnt lgkmcnt(0)
	s_setprio 1
	s_barrier
	v_mfma_f32_16x16x32_bf16 v[62:65], v[152:155], v[186:189], v[62:65]
	v_mfma_f32_16x16x32_bf16 v[58:61], v[160:163], v[186:189], v[58:61]
	v_mfma_f32_16x16x32_bf16 v[50:53], v[152:155], v[194:197], v[50:53]
	v_mfma_f32_16x16x32_bf16 v[42:45], v[160:163], v[194:197], v[42:45]
	v_mfma_f32_16x16x32_bf16 v[34:37], v[152:155], v[202:205], v[34:37]
	v_mfma_f32_16x16x32_bf16 v[26:29], v[160:163], v[202:205], v[26:29]
	v_mfma_f32_16x16x32_bf16 v[18:21], v[152:155], v[210:213], v[18:21]
	v_mfma_f32_16x16x32_bf16 v[10:13], v[160:163], v[210:213], v[10:13]
	v_mfma_f32_16x16x32_bf16 v[62:65], v[156:159], v[190:193], v[62:65]
	v_mfma_f32_16x16x32_bf16 v[58:61], v[164:167], v[190:193], v[58:61]
	v_mfma_f32_16x16x32_bf16 v[50:53], v[156:159], v[198:201], v[50:53]
	v_mfma_f32_16x16x32_bf16 v[42:45], v[164:167], v[198:201], v[42:45]
	v_mfma_f32_16x16x32_bf16 v[34:37], v[156:159], v[206:209], v[34:37]
	v_mfma_f32_16x16x32_bf16 v[26:29], v[164:167], v[206:209], v[26:29]
	v_mfma_f32_16x16x32_bf16 v[18:21], v[156:159], v[214:217], v[18:21]
	v_mfma_f32_16x16x32_bf16 v[10:13], v[164:167], v[214:217], v[10:13]
	v_mfma_f32_16x16x32_bf16 v[54:57], v[168:171], v[186:189], v[54:57]
	v_mfma_f32_16x16x32_bf16 v[46:49], v[178:181], v[186:189], v[46:49]
	v_mfma_f32_16x16x32_bf16 v[38:41], v[168:171], v[194:197], v[38:41]
	v_mfma_f32_16x16x32_bf16 v[30:33], v[178:181], v[194:197], v[30:33]
	v_mfma_f32_16x16x32_bf16 v[22:25], v[168:171], v[202:205], v[22:25]
	v_mfma_f32_16x16x32_bf16 v[14:17], v[178:181], v[202:205], v[14:17]
	v_mfma_f32_16x16x32_bf16 v[6:9], v[168:171], v[210:213], v[6:9]
	v_mfma_f32_16x16x32_bf16 v[2:5], v[178:181], v[210:213], v[2:5]
	v_mfma_f32_16x16x32_bf16 v[54:57], v[172:175], v[190:193], v[54:57]
	v_mfma_f32_16x16x32_bf16 v[46:49], v[182:185], v[190:193], v[46:49]
	v_mfma_f32_16x16x32_bf16 v[38:41], v[172:175], v[198:201], v[38:41]
	v_mfma_f32_16x16x32_bf16 v[30:33], v[182:185], v[198:201], v[30:33]
	v_mfma_f32_16x16x32_bf16 v[22:25], v[172:175], v[206:209], v[22:25]
	v_mfma_f32_16x16x32_bf16 v[14:17], v[182:185], v[206:209], v[14:17]
	v_mfma_f32_16x16x32_bf16 v[6:9], v[172:175], v[214:217], v[6:9]
	v_mfma_f32_16x16x32_bf16 v[2:5], v[182:185], v[214:217], v[2:5]
	s_barrier
	s_setprio 0
	s_add_i32 s62, s62, 2
	s_add_u32 s36, s36, 0x100
	s_addc_u32 s37, s37, 0
	s_add_u32 s60, s60, 0x100
	s_addc_u32 s61, s61, 0
	s_cmp_gt_u32 s62, 13
	s_cbranch_scc0 .LBB0_1239

.Lpk1303_peel:
	ds_read_b128 v[166:169], v139
	ds_read_b128 v[170:173], v139 offset:1024
	ds_read_b128 v[178:181], v139 offset:2048
	ds_read_b128 v[182:185], v139 offset:3072
	ds_read_b128 v[186:189], v163
	ds_read_b128 v[190:193], v163 offset:1024
	ds_read_b128 v[194:197], v163 offset:2048
	ds_read_b128 v[198:201], v163 offset:3072
	s_add_u32 s2, s26, 0xfffc0080
	s_addc_u32 s3, s27, -1
	s_cmp_eq_u32 s55, 12
	s_cselect_b32 s3, s11, s3
	s_cselect_b32 s2, s13, s2
	s_cselect_b32 s29, s47, s54
	s_cselect_b32 s28, s52, s53
	v_lshl_add_u64 v[148:149], s[26:27], 0, v[142:143]
	s_add_i32 m0, s34, 0xc000
	ds_read_b128 v[202:205], v164
	ds_read_b128 v[206:209], v164 offset:1024
	ds_read_b128 v[210:213], v164 offset:2048
	ds_read_b128 v[214:217], v164 offset:3072
	ds_read_b128 v[218:221], v164 offset:4096
	ds_read_b128 v[222:225], v164 offset:5120
	ds_read_b128 v[226:229], v164 offset:6144
	ds_read_b128 v[230:233], v164 offset:7168
	global_load_lds_dwordx4 v[148:149], off
	v_lshl_add_u64 v[148:149], s[26:27], 0, v[144:145]
	s_add_i32 m0, s34, 0xe000
	s_nop 0
	global_load_lds_dwordx4 v[148:149], off
	s_waitcnt vmcnt(8)
	s_waitcnt lgkmcnt(0)
	s_setprio 1
	s_barrier
	v_mfma_f32_16x16x32_bf16 v[126:129], v[166:169], v[202:205], 0
	v_mfma_f32_16x16x32_bf16 v[122:125], v[178:181], v[202:205], 0
	v_mfma_f32_16x16x32_bf16 v[110:113], v[166:169], v[210:213], 0
	v_mfma_f32_16x16x32_bf16 v[106:109], v[178:181], v[210:213], 0
	v_mfma_f32_16x16x32_bf16 v[94:97], v[166:169], v[218:221], 0
	v_mfma_f32_16x16x32_bf16 v[90:93], v[178:181], v[218:221], 0
	v_mfma_f32_16x16x32_bf16 v[78:81], v[166:169], v[226:229], 0
	v_mfma_f32_16x16x32_bf16 v[74:77], v[178:181], v[226:229], 0
	v_mfma_f32_16x16x32_bf16 v[126:129], v[170:173], v[206:209], v[126:129]
	v_mfma_f32_16x16x32_bf16 v[122:125], v[182:185], v[206:209], v[122:125]
	v_mfma_f32_16x16x32_bf16 v[110:113], v[170:173], v[214:217], v[110:113]
	v_mfma_f32_16x16x32_bf16 v[106:109], v[182:185], v[214:217], v[106:109]
	v_mfma_f32_16x16x32_bf16 v[94:97], v[170:173], v[222:225], v[94:97]
	v_mfma_f32_16x16x32_bf16 v[90:93], v[182:185], v[222:225], v[90:93]
	v_mfma_f32_16x16x32_bf16 v[78:81], v[170:173], v[230:233], v[78:81]
	v_mfma_f32_16x16x32_bf16 v[74:77], v[182:185], v[230:233], v[74:77]
	v_mfma_f32_16x16x32_bf16 v[118:121], v[186:189], v[202:205], 0
	v_mfma_f32_16x16x32_bf16 v[114:117], v[194:197], v[202:205], 0
	v_mfma_f32_16x16x32_bf16 v[102:105], v[186:189], v[210:213], 0
	v_mfma_f32_16x16x32_bf16 v[98:101], v[194:197], v[210:213], 0
	v_mfma_f32_16x16x32_bf16 v[86:89], v[186:189], v[218:221], 0
	v_mfma_f32_16x16x32_bf16 v[82:85], v[194:197], v[218:221], 0
	v_mfma_f32_16x16x32_bf16 v[70:73], v[186:189], v[226:229], 0
	v_mfma_f32_16x16x32_bf16 v[66:69], v[194:197], v[226:229], 0
	v_mfma_f32_16x16x32_bf16 v[118:121], v[190:193], v[206:209], v[118:121]
	v_mfma_f32_16x16x32_bf16 v[114:117], v[198:201], v[206:209], v[114:117]
	v_mfma_f32_16x16x32_bf16 v[102:105], v[190:193], v[214:217], v[102:105]
	v_mfma_f32_16x16x32_bf16 v[98:101], v[198:201], v[214:217], v[98:101]
	v_mfma_f32_16x16x32_bf16 v[86:89], v[190:193], v[222:225], v[86:89]
	v_mfma_f32_16x16x32_bf16 v[82:85], v[198:201], v[222:225], v[82:85]
	v_mfma_f32_16x16x32_bf16 v[70:73], v[190:193], v[230:233], v[70:73]
	v_mfma_f32_16x16x32_bf16 v[66:69], v[198:201], v[230:233], v[66:69]
	s_barrier
	s_setprio 0
	s_add_i32 s56, s42, s30
	v_lshl_add_u64 v[148:149], s[28:29], 0, v[132:133]
	s_mov_b32 m0, s56
	ds_read_b128 v[202:205], v164 offset:16384
	ds_read_b128 v[206:209], v164 offset:17408
	ds_read_b128 v[210:213], v164 offset:18432
	ds_read_b128 v[214:217], v164 offset:19456
	ds_read_b128 v[218:221], v164 offset:20480
	ds_read_b128 v[222:225], v164 offset:21504
	ds_read_b128 v[226:229], v164 offset:22528
	ds_read_b128 v[230:233], v164 offset:23552
	global_load_lds_dwordx4 v[148:149], off
	s_add_i32 m0, s56, 0x2000
	s_add_u32 s56, s28, 0x40000
	v_lshl_add_u64 v[174:175], s[28:29], 0, v[136:137]
	s_addc_u32 s57, s29, 0
	s_add_i32 s58, s43, s30
	global_load_lds_dwordx4 v[174:175], off
	v_lshl_add_u64 v[234:235], s[56:57], 0, v[132:133]
	s_mov_b32 m0, s58
	v_lshl_add_u64 v[236:237], s[2:3], 0, v[134:135]
	global_load_lds_dwordx4 v[234:235], off
	v_lshl_add_u64 v[234:235], s[56:57], 0, v[136:137]
	s_add_i32 m0, s58, 0x2000
	s_nop 0
	global_load_lds_dwordx4 v[234:235], off
	v_lshl_add_u64 v[234:235], s[2:3], 0, v[130:131]
	s_mov_b32 m0, s34
	s_nop 0
	global_load_lds_dwordx4 v[234:235], off
	s_mov_b32 m0, s25
	s_nop 0
	global_load_lds_dwordx4 v[236:237], off
	s_waitcnt vmcnt(8)
	s_waitcnt lgkmcnt(0)
	s_setprio 1
	s_barrier
	v_mfma_f32_16x16x32_bf16 v[62:65], v[166:169], v[202:205], 0
	v_mfma_f32_16x16x32_bf16 v[58:61], v[178:181], v[202:205], 0
	v_mfma_f32_16x16x32_bf16 v[46:49], v[166:169], v[210:213], 0
	v_mfma_f32_16x16x32_bf16 v[42:45], v[178:181], v[210:213], 0
	v_mfma_f32_16x16x32_bf16 v[30:33], v[166:169], v[218:221], 0
	v_mfma_f32_16x16x32_bf16 v[26:29], v[178:181], v[218:221], 0
	v_mfma_f32_16x16x32_bf16 v[14:17], v[166:169], v[226:229], 0
	v_mfma_f32_16x16x32_bf16 v[10:13], v[178:181], v[226:229], 0
	v_mfma_f32_16x16x32_bf16 v[62:65], v[170:173], v[206:209], v[62:65]
	v_mfma_f32_16x16x32_bf16 v[58:61], v[182:185], v[206:209], v[58:61]
	v_mfma_f32_16x16x32_bf16 v[46:49], v[170:173], v[214:217], v[46:49]
	v_mfma_f32_16x16x32_bf16 v[42:45], v[182:185], v[214:217], v[42:45]
	v_mfma_f32_16x16x32_bf16 v[30:33], v[170:173], v[222:225], v[30:33]
	v_mfma_f32_16x16x32_bf16 v[26:29], v[182:185], v[222:225], v[26:29]
	v_mfma_f32_16x16x32_bf16 v[14:17], v[170:173], v[230:233], v[14:17]
	v_mfma_f32_16x16x32_bf16 v[10:13], v[182:185], v[230:233], v[10:13]
	v_mfma_f32_16x16x32_bf16 v[54:57], v[186:189], v[202:205], 0
	v_mfma_f32_16x16x32_bf16 v[50:53], v[194:197], v[202:205], 0
	v_mfma_f32_16x16x32_bf16 v[38:41], v[186:189], v[210:213], 0
	v_mfma_f32_16x16x32_bf16 v[34:37], v[194:197], v[210:213], 0
	v_mfma_f32_16x16x32_bf16 v[22:25], v[186:189], v[218:221], 0
	v_mfma_f32_16x16x32_bf16 v[18:21], v[194:197], v[218:221], 0
	v_mfma_f32_16x16x32_bf16 v[6:9], v[186:189], v[226:229], 0
	v_mfma_f32_16x16x32_bf16 v[2:5], v[194:197], v[226:229], 0
	v_mfma_f32_16x16x32_bf16 v[54:57], v[190:193], v[206:209], v[54:57]
	v_mfma_f32_16x16x32_bf16 v[50:53], v[198:201], v[206:209], v[50:53]
	v_mfma_f32_16x16x32_bf16 v[38:41], v[190:193], v[214:217], v[38:41]
	v_mfma_f32_16x16x32_bf16 v[34:37], v[198:201], v[214:217], v[34:37]
	v_mfma_f32_16x16x32_bf16 v[22:25], v[190:193], v[222:225], v[22:25]
	v_mfma_f32_16x16x32_bf16 v[18:21], v[198:201], v[222:225], v[18:21]
	v_mfma_f32_16x16x32_bf16 v[6:9], v[190:193], v[230:233], v[6:9]
	v_mfma_f32_16x16x32_bf16 v[2:5], v[198:201], v[230:233], v[2:5]
	s_barrier
	s_setprio 0
	s_add_i32 s56, 0, 0x18000
	v_add_u32_e32 v165, s56, v162
	s_add_i32 s57, 0, 0x1c000
	ds_read_b128 v[166:169], v165
	ds_read_b128 v[170:173], v165 offset:1024
	ds_read_b128 v[178:181], v165 offset:2048
	ds_read_b128 v[182:185], v165 offset:3072
	v_add_u32_e32 v165, s57, v162
	ds_read_b128 v[186:189], v165
	ds_read_b128 v[190:193], v165 offset:1024
	ds_read_b128 v[194:197], v165 offset:2048
	ds_read_b128 v[198:201], v165 offset:3072
	s_add_u32 s2, s2, 0x40000
	s_addc_u32 s3, s3, 0
	s_mov_b32 m0, s35
	v_lshl_add_u64 v[238:239], s[2:3], 0, v[130:131]
	ds_read_b128 v[202:205], v164 offset:32768
	ds_read_b128 v[206:209], v164 offset:33792
	ds_read_b128 v[210:213], v164 offset:34816
	ds_read_b128 v[214:217], v164 offset:35840
	ds_read_b128 v[218:221], v164 offset:36864
	ds_read_b128 v[222:225], v164 offset:37888
	ds_read_b128 v[226:229], v164 offset:38912
	ds_read_b128 v[230:233], v164 offset:39936
	global_load_lds_dwordx4 v[238:239], off
	v_lshl_add_u64 v[238:239], s[2:3], 0, v[134:135]
	s_mov_b32 m0, s36
	s_nop 0
	global_load_lds_dwordx4 v[238:239], off
	s_waitcnt vmcnt(8)
	s_waitcnt lgkmcnt(0)
	s_setprio 1
	s_barrier
	v_mfma_f32_16x16x32_bf16 v[126:129], v[166:169], v[202:205], v[126:129]
	v_mfma_f32_16x16x32_bf16 v[122:125], v[178:181], v[202:205], v[122:125]
	v_mfma_f32_16x16x32_bf16 v[110:113], v[166:169], v[210:213], v[110:113]
	v_mfma_f32_16x16x32_bf16 v[106:109], v[178:181], v[210:213], v[106:109]
	v_mfma_f32_16x16x32_bf16 v[94:97], v[166:169], v[218:221], v[94:97]
	v_mfma_f32_16x16x32_bf16 v[90:93], v[178:181], v[218:221], v[90:93]
	v_mfma_f32_16x16x32_bf16 v[78:81], v[166:169], v[226:229], v[78:81]
	v_mfma_f32_16x16x32_bf16 v[74:77], v[178:181], v[226:229], v[74:77]
	v_mfma_f32_16x16x32_bf16 v[126:129], v[170:173], v[206:209], v[126:129]
	v_mfma_f32_16x16x32_bf16 v[122:125], v[182:185], v[206:209], v[122:125]
	v_mfma_f32_16x16x32_bf16 v[110:113], v[170:173], v[214:217], v[110:113]
	v_mfma_f32_16x16x32_bf16 v[106:109], v[182:185], v[214:217], v[106:109]
	v_mfma_f32_16x16x32_bf16 v[94:97], v[170:173], v[222:225], v[94:97]
	v_mfma_f32_16x16x32_bf16 v[90:93], v[182:185], v[222:225], v[90:93]
	v_mfma_f32_16x16x32_bf16 v[78:81], v[170:173], v[230:233], v[78:81]
	v_mfma_f32_16x16x32_bf16 v[74:77], v[182:185], v[230:233], v[74:77]
	v_mfma_f32_16x16x32_bf16 v[118:121], v[186:189], v[202:205], v[118:121]
	v_mfma_f32_16x16x32_bf16 v[114:117], v[194:197], v[202:205], v[114:117]
	v_mfma_f32_16x16x32_bf16 v[102:105], v[186:189], v[210:213], v[102:105]
	v_mfma_f32_16x16x32_bf16 v[98:101], v[194:197], v[210:213], v[98:101]
	v_mfma_f32_16x16x32_bf16 v[86:89], v[186:189], v[218:221], v[86:89]
	v_mfma_f32_16x16x32_bf16 v[82:85], v[194:197], v[218:221], v[82:85]
	v_mfma_f32_16x16x32_bf16 v[70:73], v[186:189], v[226:229], v[70:73]
	v_mfma_f32_16x16x32_bf16 v[66:69], v[194:197], v[226:229], v[66:69]
	v_mfma_f32_16x16x32_bf16 v[118:121], v[190:193], v[206:209], v[118:121]
	v_mfma_f32_16x16x32_bf16 v[114:117], v[198:201], v[206:209], v[114:117]
	v_mfma_f32_16x16x32_bf16 v[102:105], v[190:193], v[214:217], v[102:105]
	v_mfma_f32_16x16x32_bf16 v[98:101], v[198:201], v[214:217], v[98:101]
	v_mfma_f32_16x16x32_bf16 v[86:89], v[190:193], v[222:225], v[86:89]
	v_mfma_f32_16x16x32_bf16 v[82:85], v[198:201], v[222:225], v[82:85]
	v_mfma_f32_16x16x32_bf16 v[70:73], v[190:193], v[230:233], v[70:73]
	v_mfma_f32_16x16x32_bf16 v[66:69], v[198:201], v[230:233], v[66:69]
	s_barrier
	s_setprio 0
	s_add_i32 s2, s56, s30
	v_lshl_add_u64 v[148:149], v[148:149], 0, s[6:7]
	s_mov_b32 m0, s2
	ds_read_b128 v[202:205], v164 offset:49152
	ds_read_b128 v[206:209], v164 offset:50176
	ds_read_b128 v[210:213], v164 offset:51200
	ds_read_b128 v[214:217], v164 offset:52224
	ds_read_b128 v[218:221], v164 offset:53248
	ds_read_b128 v[222:225], v164 offset:54272
	ds_read_b128 v[226:229], v164 offset:55296
	ds_read_b128 v[230:233], v164 offset:56320
	global_load_lds_dwordx4 v[148:149], off
	s_add_i32 m0, s2, 0x2000
	s_add_u32 s2, s28, 0x40080
	v_lshl_add_u64 v[148:149], v[174:175], 0, s[6:7]
	s_addc_u32 s3, s29, 0
	s_add_i32 s28, s57, s30
	global_load_lds_dwordx4 v[148:149], off
	v_lshl_add_u64 v[148:149], s[2:3], 0, v[132:133]
	s_mov_b32 m0, s28
	s_nop 0
	global_load_lds_dwordx4 v[148:149], off
	v_lshl_add_u64 v[148:149], s[2:3], 0, v[136:137]
	s_add_i32 m0, s28, 0x2000
	s_nop 0
	global_load_lds_dwordx4 v[148:149], off
	v_lshl_add_u64 v[148:149], v[234:235], 0, s[6:7]
	s_mov_b32 m0, s39
	s_nop 0
	global_load_lds_dwordx4 v[148:149], off
	v_lshl_add_u64 v[148:149], v[236:237], 0, s[6:7]
	s_mov_b32 m0, s40
	s_nop 0
	global_load_lds_dwordx4 v[148:149], off
	s_waitcnt vmcnt(8)
	s_waitcnt lgkmcnt(0)
	s_setprio 1
	s_barrier
	v_mfma_f32_16x16x32_bf16 v[62:65], v[166:169], v[202:205], v[62:65]
	v_mfma_f32_16x16x32_bf16 v[58:61], v[178:181], v[202:205], v[58:61]
	v_mfma_f32_16x16x32_bf16 v[46:49], v[166:169], v[210:213], v[46:49]
	v_mfma_f32_16x16x32_bf16 v[42:45], v[178:181], v[210:213], v[42:45]
	v_mfma_f32_16x16x32_bf16 v[30:33], v[166:169], v[218:221], v[30:33]
	v_mfma_f32_16x16x32_bf16 v[26:29], v[178:181], v[218:221], v[26:29]
	v_mfma_f32_16x16x32_bf16 v[14:17], v[166:169], v[226:229], v[14:17]
	v_mfma_f32_16x16x32_bf16 v[10:13], v[178:181], v[226:229], v[10:13]
	v_mfma_f32_16x16x32_bf16 v[62:65], v[170:173], v[206:209], v[62:65]
	v_mfma_f32_16x16x32_bf16 v[58:61], v[182:185], v[206:209], v[58:61]
	v_mfma_f32_16x16x32_bf16 v[46:49], v[170:173], v[214:217], v[46:49]
	v_mfma_f32_16x16x32_bf16 v[42:45], v[182:185], v[214:217], v[42:45]
	v_mfma_f32_16x16x32_bf16 v[30:33], v[170:173], v[222:225], v[30:33]
	v_mfma_f32_16x16x32_bf16 v[26:29], v[182:185], v[222:225], v[26:29]
	v_mfma_f32_16x16x32_bf16 v[14:17], v[170:173], v[230:233], v[14:17]
	v_mfma_f32_16x16x32_bf16 v[10:13], v[182:185], v[230:233], v[10:13]
	v_mfma_f32_16x16x32_bf16 v[54:57], v[186:189], v[202:205], v[54:57]
	v_mfma_f32_16x16x32_bf16 v[50:53], v[194:197], v[202:205], v[50:53]
	v_mfma_f32_16x16x32_bf16 v[38:41], v[186:189], v[210:213], v[38:41]
	v_mfma_f32_16x16x32_bf16 v[34:37], v[194:197], v[210:213], v[34:37]
	v_mfma_f32_16x16x32_bf16 v[22:25], v[186:189], v[218:221], v[22:25]
	v_mfma_f32_16x16x32_bf16 v[18:21], v[194:197], v[218:221], v[18:21]
	v_mfma_f32_16x16x32_bf16 v[6:9], v[186:189], v[226:229], v[6:9]
	v_mfma_f32_16x16x32_bf16 v[2:5], v[194:197], v[226:229], v[2:5]
	v_mfma_f32_16x16x32_bf16 v[54:57], v[190:193], v[206:209], v[54:57]
	v_mfma_f32_16x16x32_bf16 v[50:53], v[198:201], v[206:209], v[50:53]
	v_mfma_f32_16x16x32_bf16 v[38:41], v[190:193], v[214:217], v[38:41]
	v_mfma_f32_16x16x32_bf16 v[34:37], v[198:201], v[214:217], v[34:37]
	v_mfma_f32_16x16x32_bf16 v[22:25], v[190:193], v[222:225], v[22:25]
	v_mfma_f32_16x16x32_bf16 v[18:21], v[198:201], v[222:225], v[18:21]
	v_mfma_f32_16x16x32_bf16 v[6:9], v[190:193], v[230:233], v[6:9]
	v_mfma_f32_16x16x32_bf16 v[2:5], v[198:201], v[230:233], v[2:5]
	s_barrier
	s_setprio 0
	s_add_i32 s55, s55, 2
	s_add_u32 s26, s26, 0x100
	s_addc_u32 s27, s27, 0
	s_add_u32 s53, s53, 0x100
	s_addc_u32 s54, s54, 0
	s_cmp_gt_u32 s55, 13
	s_cbranch_scc0 .LBB0_1303
	s_branch .Lpk1303_exit
.LBB0_1303:
	ds_read_b128 v[166:169], v139
	ds_read_b128 v[170:173], v139 offset:1024
	ds_read_b128 v[178:181], v139 offset:2048
	ds_read_b128 v[182:185], v139 offset:3072
	ds_read_b128 v[186:189], v163
	ds_read_b128 v[190:193], v163 offset:1024
	ds_read_b128 v[194:197], v163 offset:2048
	ds_read_b128 v[198:201], v163 offset:3072
	s_add_u32 s2, s26, 0xfffc0080
	s_addc_u32 s3, s27, -1
	s_cmp_eq_u32 s55, 12
	s_cselect_b32 s3, s11, s3
	s_cselect_b32 s2, s13, s2
	s_cselect_b32 s29, s47, s54
	s_cselect_b32 s28, s52, s53
	v_lshl_add_u64 v[148:149], s[26:27], 0, v[142:143]
	s_add_i32 m0, s34, 0xc000
	ds_read_b128 v[202:205], v164
	ds_read_b128 v[206:209], v164 offset:1024
	ds_read_b128 v[210:213], v164 offset:2048
	ds_read_b128 v[214:217], v164 offset:3072
	ds_read_b128 v[218:221], v164 offset:4096
	ds_read_b128 v[222:225], v164 offset:5120
	ds_read_b128 v[226:229], v164 offset:6144
	ds_read_b128 v[230:233], v164 offset:7168
	global_load_lds_dwordx4 v[148:149], off
	v_lshl_add_u64 v[148:149], s[26:27], 0, v[144:145]
	s_add_i32 m0, s34, 0xe000
	s_nop 0
	global_load_lds_dwordx4 v[148:149], off
	s_waitcnt vmcnt(8)
	s_waitcnt lgkmcnt(0)
	s_setprio 1
	s_barrier
	v_mfma_f32_16x16x32_bf16 v[126:129], v[166:169], v[202:205], v[126:129]
	v_mfma_f32_16x16x32_bf16 v[122:125], v[178:181], v[202:205], v[122:125]
	v_mfma_f32_16x16x32_bf16 v[110:113], v[166:169], v[210:213], v[110:113]
	v_mfma_f32_16x16x32_bf16 v[106:109], v[178:181], v[210:213], v[106:109]
	v_mfma_f32_16x16x32_bf16 v[94:97], v[166:169], v[218:221], v[94:97]
	v_mfma_f32_16x16x32_bf16 v[90:93], v[178:181], v[218:221], v[90:93]
	v_mfma_f32_16x16x32_bf16 v[78:81], v[166:169], v[226:229], v[78:81]
	v_mfma_f32_16x16x32_bf16 v[74:77], v[178:181], v[226:229], v[74:77]
	v_mfma_f32_16x16x32_bf16 v[126:129], v[170:173], v[206:209], v[126:129]
	v_mfma_f32_16x16x32_bf16 v[122:125], v[182:185], v[206:209], v[122:125]
	v_mfma_f32_16x16x32_bf16 v[110:113], v[170:173], v[214:217], v[110:113]
	v_mfma_f32_16x16x32_bf16 v[106:109], v[182:185], v[214:217], v[106:109]
	v_mfma_f32_16x16x32_bf16 v[94:97], v[170:173], v[222:225], v[94:97]
	v_mfma_f32_16x16x32_bf16 v[90:93], v[182:185], v[222:225], v[90:93]
	v_mfma_f32_16x16x32_bf16 v[78:81], v[170:173], v[230:233], v[78:81]
	v_mfma_f32_16x16x32_bf16 v[74:77], v[182:185], v[230:233], v[74:77]
	v_mfma_f32_16x16x32_bf16 v[118:121], v[186:189], v[202:205], v[118:121]
	v_mfma_f32_16x16x32_bf16 v[114:117], v[194:197], v[202:205], v[114:117]
	v_mfma_f32_16x16x32_bf16 v[102:105], v[186:189], v[210:213], v[102:105]
	v_mfma_f32_16x16x32_bf16 v[98:101], v[194:197], v[210:213], v[98:101]
	v_mfma_f32_16x16x32_bf16 v[86:89], v[186:189], v[218:221], v[86:89]
	v_mfma_f32_16x16x32_bf16 v[82:85], v[194:197], v[218:221], v[82:85]
	v_mfma_f32_16x16x32_bf16 v[70:73], v[186:189], v[226:229], v[70:73]
	v_mfma_f32_16x16x32_bf16 v[66:69], v[194:197], v[226:229], v[66:69]
	v_mfma_f32_16x16x32_bf16 v[118:121], v[190:193], v[206:209], v[118:121]
	v_mfma_f32_16x16x32_bf16 v[114:117], v[198:201], v[206:209], v[114:117]
	v_mfma_f32_16x16x32_bf16 v[102:105], v[190:193], v[214:217], v[102:105]
	v_mfma_f32_16x16x32_bf16 v[98:101], v[198:201], v[214:217], v[98:101]
	v_mfma_f32_16x16x32_bf16 v[86:89], v[190:193], v[222:225], v[86:89]
	v_mfma_f32_16x16x32_bf16 v[82:85], v[198:201], v[222:225], v[82:85]
	v_mfma_f32_16x16x32_bf16 v[70:73], v[190:193], v[230:233], v[70:73]
	v_mfma_f32_16x16x32_bf16 v[66:69], v[198:201], v[230:233], v[66:69]
	s_barrier
	s_setprio 0
	s_add_i32 s56, s42, s30
	v_lshl_add_u64 v[148:149], s[28:29], 0, v[132:133]
	s_mov_b32 m0, s56
	ds_read_b128 v[202:205], v164 offset:16384
	ds_read_b128 v[206:209], v164 offset:17408
	ds_read_b128 v[210:213], v164 offset:18432
	ds_read_b128 v[214:217], v164 offset:19456
	ds_read_b128 v[218:221], v164 offset:20480
	ds_read_b128 v[222:225], v164 offset:21504
	ds_read_b128 v[226:229], v164 offset:22528
	ds_read_b128 v[230:233], v164 offset:23552
	global_load_lds_dwordx4 v[148:149], off
	s_add_i32 m0, s56, 0x2000
	s_add_u32 s56, s28, 0x40000
	v_lshl_add_u64 v[174:175], s[28:29], 0, v[136:137]
	s_addc_u32 s57, s29, 0
	s_add_i32 s58, s43, s30
	global_load_lds_dwordx4 v[174:175], off
	v_lshl_add_u64 v[234:235], s[56:57], 0, v[132:133]
	s_mov_b32 m0, s58
	v_lshl_add_u64 v[236:237], s[2:3], 0, v[134:135]
	global_load_lds_dwordx4 v[234:235], off
	v_lshl_add_u64 v[234:235], s[56:57], 0, v[136:137]
	s_add_i32 m0, s58, 0x2000
	s_nop 0
	global_load_lds_dwordx4 v[234:235], off
	v_lshl_add_u64 v[234:235], s[2:3], 0, v[130:131]
	s_mov_b32 m0, s34
	s_nop 0
	global_load_lds_dwordx4 v[234:235], off
	s_mov_b32 m0, s25
	s_nop 0
	global_load_lds_dwordx4 v[236:237], off
	s_waitcnt vmcnt(8)
	s_waitcnt lgkmcnt(0)
	s_setprio 1
	s_barrier
	v_mfma_f32_16x16x32_bf16 v[62:65], v[166:169], v[202:205], v[62:65]
	v_mfma_f32_16x16x32_bf16 v[58:61], v[178:181], v[202:205], v[58:61]
	v_mfma_f32_16x16x32_bf16 v[46:49], v[166:169], v[210:213], v[46:49]
	v_mfma_f32_16x16x32_bf16 v[42:45], v[178:181], v[210:213], v[42:45]
	v_mfma_f32_16x16x32_bf16 v[30:33], v[166:169], v[218:221], v[30:33]
	v_mfma_f32_16x16x32_bf16 v[26:29], v[178:181], v[218:221], v[26:29]
	v_mfma_f32_16x16x32_bf16 v[14:17], v[166:169], v[226:229], v[14:17]
	v_mfma_f32_16x16x32_bf16 v[10:13], v[178:181], v[226:229], v[10:13]
	v_mfma_f32_16x16x32_bf16 v[62:65], v[170:173], v[206:209], v[62:65]
	v_mfma_f32_16x16x32_bf16 v[58:61], v[182:185], v[206:209], v[58:61]
	v_mfma_f32_16x16x32_bf16 v[46:49], v[170:173], v[214:217], v[46:49]
	v_mfma_f32_16x16x32_bf16 v[42:45], v[182:185], v[214:217], v[42:45]
	v_mfma_f32_16x16x32_bf16 v[30:33], v[170:173], v[222:225], v[30:33]
	v_mfma_f32_16x16x32_bf16 v[26:29], v[182:185], v[222:225], v[26:29]
	v_mfma_f32_16x16x32_bf16 v[14:17], v[170:173], v[230:233], v[14:17]
	v_mfma_f32_16x16x32_bf16 v[10:13], v[182:185], v[230:233], v[10:13]
	v_mfma_f32_16x16x32_bf16 v[54:57], v[186:189], v[202:205], v[54:57]
	v_mfma_f32_16x16x32_bf16 v[50:53], v[194:197], v[202:205], v[50:53]
	v_mfma_f32_16x16x32_bf16 v[38:41], v[186:189], v[210:213], v[38:41]
	v_mfma_f32_16x16x32_bf16 v[34:37], v[194:197], v[210:213], v[34:37]
	v_mfma_f32_16x16x32_bf16 v[22:25], v[186:189], v[218:221], v[22:25]
	v_mfma_f32_16x16x32_bf16 v[18:21], v[194:197], v[218:221], v[18:21]
	v_mfma_f32_16x16x32_bf16 v[6:9], v[186:189], v[226:229], v[6:9]
	v_mfma_f32_16x16x32_bf16 v[2:5], v[194:197], v[226:229], v[2:5]
	v_mfma_f32_16x16x32_bf16 v[54:57], v[190:193], v[206:209], v[54:57]
	v_mfma_f32_16x16x32_bf16 v[50:53], v[198:201], v[206:209], v[50:53]
	v_mfma_f32_16x16x32_bf16 v[38:41], v[190:193], v[214:217], v[38:41]
	v_mfma_f32_16x16x32_bf16 v[34:37], v[198:201], v[214:217], v[34:37]
	v_mfma_f32_16x16x32_bf16 v[22:25], v[190:193], v[222:225], v[22:25]
	v_mfma_f32_16x16x32_bf16 v[18:21], v[198:201], v[222:225], v[18:21]
	v_mfma_f32_16x16x32_bf16 v[6:9], v[190:193], v[230:233], v[6:9]
	v_mfma_f32_16x16x32_bf16 v[2:5], v[198:201], v[230:233], v[2:5]
	s_barrier
	s_setprio 0
	s_add_i32 s56, 0, 0x18000
	v_add_u32_e32 v165, s56, v162
	s_add_i32 s57, 0, 0x1c000
	ds_read_b128 v[166:169], v165
	ds_read_b128 v[170:173], v165 offset:1024
	ds_read_b128 v[178:181], v165 offset:2048
	ds_read_b128 v[182:185], v165 offset:3072
	v_add_u32_e32 v165, s57, v162
	ds_read_b128 v[186:189], v165
	ds_read_b128 v[190:193], v165 offset:1024
	ds_read_b128 v[194:197], v165 offset:2048
	ds_read_b128 v[198:201], v165 offset:3072
	s_add_u32 s2, s2, 0x40000
	s_addc_u32 s3, s3, 0
	s_mov_b32 m0, s35
	v_lshl_add_u64 v[238:239], s[2:3], 0, v[130:131]
	ds_read_b128 v[202:205], v164 offset:32768
	ds_read_b128 v[206:209], v164 offset:33792
	ds_read_b128 v[210:213], v164 offset:34816
	ds_read_b128 v[214:217], v164 offset:35840
	ds_read_b128 v[218:221], v164 offset:36864
	ds_read_b128 v[222:225], v164 offset:37888
	ds_read_b128 v[226:229], v164 offset:38912
	ds_read_b128 v[230:233], v164 offset:39936
	global_load_lds_dwordx4 v[238:239], off
	v_lshl_add_u64 v[238:239], s[2:3], 0, v[134:135]
	s_mov_b32 m0, s36
	s_nop 0
	global_load_lds_dwordx4 v[238:239], off
	s_waitcnt vmcnt(8)
	s_waitcnt lgkmcnt(0)
	s_setprio 1
	s_barrier
	v_mfma_f32_16x16x32_bf16 v[126:129], v[166:169], v[202:205], v[126:129]
	v_mfma_f32_16x16x32_bf16 v[122:125], v[178:181], v[202:205], v[122:125]
	v_mfma_f32_16x16x32_bf16 v[110:113], v[166:169], v[210:213], v[110:113]
	v_mfma_f32_16x16x32_bf16 v[106:109], v[178:181], v[210:213], v[106:109]
	v_mfma_f32_16x16x32_bf16 v[94:97], v[166:169], v[218:221], v[94:97]
	v_mfma_f32_16x16x32_bf16 v[90:93], v[178:181], v[218:221], v[90:93]
	v_mfma_f32_16x16x32_bf16 v[78:81], v[166:169], v[226:229], v[78:81]
	v_mfma_f32_16x16x32_bf16 v[74:77], v[178:181], v[226:229], v[74:77]
	v_mfma_f32_16x16x32_bf16 v[126:129], v[170:173], v[206:209], v[126:129]
	v_mfma_f32_16x16x32_bf16 v[122:125], v[182:185], v[206:209], v[122:125]
	v_mfma_f32_16x16x32_bf16 v[110:113], v[170:173], v[214:217], v[110:113]
	v_mfma_f32_16x16x32_bf16 v[106:109], v[182:185], v[214:217], v[106:109]
	v_mfma_f32_16x16x32_bf16 v[94:97], v[170:173], v[222:225], v[94:97]
	v_mfma_f32_16x16x32_bf16 v[90:93], v[182:185], v[222:225], v[90:93]
	v_mfma_f32_16x16x32_bf16 v[78:81], v[170:173], v[230:233], v[78:81]
	v_mfma_f32_16x16x32_bf16 v[74:77], v[182:185], v[230:233], v[74:77]
	v_mfma_f32_16x16x32_bf16 v[118:121], v[186:189], v[202:205], v[118:121]
	v_mfma_f32_16x16x32_bf16 v[114:117], v[194:197], v[202:205], v[114:117]
	v_mfma_f32_16x16x32_bf16 v[102:105], v[186:189], v[210:213], v[102:105]
	v_mfma_f32_16x16x32_bf16 v[98:101], v[194:197], v[210:213], v[98:101]
	v_mfma_f32_16x16x32_bf16 v[86:89], v[186:189], v[218:221], v[86:89]
	v_mfma_f32_16x16x32_bf16 v[82:85], v[194:197], v[218:221], v[82:85]
	v_mfma_f32_16x16x32_bf16 v[70:73], v[186:189], v[226:229], v[70:73]
	v_mfma_f32_16x16x32_bf16 v[66:69], v[194:197], v[226:229], v[66:69]
	v_mfma_f32_16x16x32_bf16 v[118:121], v[190:193], v[206:209], v[118:121]
	v_mfma_f32_16x16x32_bf16 v[114:117], v[198:201], v[206:209], v[114:117]
	v_mfma_f32_16x16x32_bf16 v[102:105], v[190:193], v[214:217], v[102:105]
	v_mfma_f32_16x16x32_bf16 v[98:101], v[198:201], v[214:217], v[98:101]
	v_mfma_f32_16x16x32_bf16 v[86:89], v[190:193], v[222:225], v[86:89]
	v_mfma_f32_16x16x32_bf16 v[82:85], v[198:201], v[222:225], v[82:85]
	v_mfma_f32_16x16x32_bf16 v[70:73], v[190:193], v[230:233], v[70:73]
	v_mfma_f32_16x16x32_bf16 v[66:69], v[198:201], v[230:233], v[66:69]
	s_barrier
	s_setprio 0
	s_add_i32 s2, s56, s30
	v_lshl_add_u64 v[148:149], v[148:149], 0, s[6:7]
	s_mov_b32 m0, s2
	ds_read_b128 v[202:205], v164 offset:49152
	ds_read_b128 v[206:209], v164 offset:50176
	ds_read_b128 v[210:213], v164 offset:51200
	ds_read_b128 v[214:217], v164 offset:52224
	ds_read_b128 v[218:221], v164 offset:53248
	ds_read_b128 v[222:225], v164 offset:54272
	ds_read_b128 v[226:229], v164 offset:55296
	ds_read_b128 v[230:233], v164 offset:56320
	global_load_lds_dwordx4 v[148:149], off
	s_add_i32 m0, s2, 0x2000
	s_add_u32 s2, s28, 0x40080
	v_lshl_add_u64 v[148:149], v[174:175], 0, s[6:7]
	s_addc_u32 s3, s29, 0
	s_add_i32 s28, s57, s30
	global_load_lds_dwordx4 v[148:149], off
	v_lshl_add_u64 v[148:149], s[2:3], 0, v[132:133]
	s_mov_b32 m0, s28
	s_nop 0
	global_load_lds_dwordx4 v[148:149], off
	v_lshl_add_u64 v[148:149], s[2:3], 0, v[136:137]
	s_add_i32 m0, s28, 0x2000
	s_nop 0
	global_load_lds_dwordx4 v[148:149], off
	v_lshl_add_u64 v[148:149], v[234:235], 0, s[6:7]
	s_mov_b32 m0, s39
	s_nop 0
	global_load_lds_dwordx4 v[148:149], off
	v_lshl_add_u64 v[148:149], v[236:237], 0, s[6:7]
	s_mov_b32 m0, s40
	s_nop 0
	global_load_lds_dwordx4 v[148:149], off
	s_waitcnt vmcnt(8)
	s_waitcnt lgkmcnt(0)
	s_setprio 1
	s_barrier
	v_mfma_f32_16x16x32_bf16 v[62:65], v[166:169], v[202:205], v[62:65]
	v_mfma_f32_16x16x32_bf16 v[58:61], v[178:181], v[202:205], v[58:61]
	v_mfma_f32_16x16x32_bf16 v[46:49], v[166:169], v[210:213], v[46:49]
	v_mfma_f32_16x16x32_bf16 v[42:45], v[178:181], v[210:213], v[42:45]
	v_mfma_f32_16x16x32_bf16 v[30:33], v[166:169], v[218:221], v[30:33]
	v_mfma_f32_16x16x32_bf16 v[26:29], v[178:181], v[218:221], v[26:29]
	v_mfma_f32_16x16x32_bf16 v[14:17], v[166:169], v[226:229], v[14:17]
	v_mfma_f32_16x16x32_bf16 v[10:13], v[178:181], v[226:229], v[10:13]
	v_mfma_f32_16x16x32_bf16 v[62:65], v[170:173], v[206:209], v[62:65]
	v_mfma_f32_16x16x32_bf16 v[58:61], v[182:185], v[206:209], v[58:61]
	v_mfma_f32_16x16x32_bf16 v[46:49], v[170:173], v[214:217], v[46:49]
	v_mfma_f32_16x16x32_bf16 v[42:45], v[182:185], v[214:217], v[42:45]
	v_mfma_f32_16x16x32_bf16 v[30:33], v[170:173], v[222:225], v[30:33]
	v_mfma_f32_16x16x32_bf16 v[26:29], v[182:185], v[222:225], v[26:29]
	v_mfma_f32_16x16x32_bf16 v[14:17], v[170:173], v[230:233], v[14:17]
	v_mfma_f32_16x16x32_bf16 v[10:13], v[182:185], v[230:233], v[10:13]
	v_mfma_f32_16x16x32_bf16 v[54:57], v[186:189], v[202:205], v[54:57]
	v_mfma_f32_16x16x32_bf16 v[50:53], v[194:197], v[202:205], v[50:53]
	v_mfma_f32_16x16x32_bf16 v[38:41], v[186:189], v[210:213], v[38:41]
	v_mfma_f32_16x16x32_bf16 v[34:37], v[194:197], v[210:213], v[34:37]
	v_mfma_f32_16x16x32_bf16 v[22:25], v[186:189], v[218:221], v[22:25]
	v_mfma_f32_16x16x32_bf16 v[18:21], v[194:197], v[218:221], v[18:21]
	v_mfma_f32_16x16x32_bf16 v[6:9], v[186:189], v[226:229], v[6:9]
	v_mfma_f32_16x16x32_bf16 v[2:5], v[194:197], v[226:229], v[2:5]
	v_mfma_f32_16x16x32_bf16 v[54:57], v[190:193], v[206:209], v[54:57]
	v_mfma_f32_16x16x32_bf16 v[50:53], v[198:201], v[206:209], v[50:53]
	v_mfma_f32_16x16x32_bf16 v[38:41], v[190:193], v[214:217], v[38:41]
	v_mfma_f32_16x16x32_bf16 v[34:37], v[198:201], v[214:217], v[34:37]
	v_mfma_f32_16x16x32_bf16 v[22:25], v[190:193], v[222:225], v[22:25]
	v_mfma_f32_16x16x32_bf16 v[18:21], v[198:201], v[222:225], v[18:21]
	v_mfma_f32_16x16x32_bf16 v[6:9], v[190:193], v[230:233], v[6:9]
	v_mfma_f32_16x16x32_bf16 v[2:5], v[198:201], v[230:233], v[2:5]
	s_barrier
	s_setprio 0
	s_add_i32 s55, s55, 2
	s_add_u32 s26, s26, 0x100
	s_addc_u32 s27, s27, 0
	s_add_u32 s53, s53, 0x100
	s_addc_u32 s54, s54, 0
	s_cmp_gt_u32 s55, 13
	s_cbranch_scc0 .LBB0_1303

.LBB0_1386:
	ds_read_b128 v[160:163], v133
	ds_read_b128 v[164:167], v133 offset:1024
	ds_read_b128 v[168:171], v133 offset:2048
	ds_read_b128 v[172:175], v133 offset:3072
	ds_read_b128 v[178:181], v135
	ds_read_b128 v[182:185], v135 offset:1024
	ds_read_b128 v[186:189], v135 offset:2048
	ds_read_b128 v[190:193], v135 offset:3072
	s_cmp_lg_u32 s8, 0x160000
	s_cselect_b32 s13, s8, 0
	s_cselect_b32 s12, s9, 0
	s_add_u32 s2, s6, s13
	s_addc_u32 s3, s7, s12
	s_add_u32 s14, s0, s13
	s_addc_u32 s15, s1, s12
	s_add_u32 s12, s2, 0x8000
	s_addc_u32 s13, s3, 0
	v_lshl_add_u64 v[226:227], v[148:149], 0, s[8:9]
	s_mov_b32 m0, s27
	v_lshl_add_u64 v[226:227], v[226:227], 0, s[10:11]
	ds_read_b128 v[194:197], v137
	ds_read_b128 v[198:201], v137 offset:1024
	ds_read_b128 v[202:205], v137 offset:2048
	ds_read_b128 v[206:209], v137 offset:3072
	ds_read_b128 v[210:213], v137 offset:4096
	ds_read_b128 v[214:217], v137 offset:5120
	ds_read_b128 v[218:221], v137 offset:6144
	ds_read_b128 v[222:225], v137 offset:7168
	global_load_lds_dwordx4 v[226:227], off
	v_lshl_add_u64 v[226:227], v[150:151], 0, s[8:9]
	v_lshl_add_u64 v[226:227], v[226:227], 0, s[10:11]
	s_mov_b32 m0, s28
	s_nop 0
	global_load_lds_dwordx4 v[226:227], off
	s_waitcnt vmcnt(8)
	s_waitcnt lgkmcnt(0)
	s_setprio 1
	s_barrier
	v_mfma_f32_16x16x32_bf16 v[126:129], v[160:163], v[194:197], v[126:129]
	v_mfma_f32_16x16x32_bf16 v[122:125], v[168:171], v[194:197], v[122:125]
	v_mfma_f32_16x16x32_bf16 v[114:117], v[160:163], v[202:205], v[114:117]
	v_mfma_f32_16x16x32_bf16 v[106:109], v[168:171], v[202:205], v[106:109]
	v_mfma_f32_16x16x32_bf16 v[98:101], v[160:163], v[210:213], v[98:101]
	v_mfma_f32_16x16x32_bf16 v[90:93], v[168:171], v[210:213], v[90:93]
	v_mfma_f32_16x16x32_bf16 v[82:85], v[160:163], v[218:221], v[82:85]
	v_mfma_f32_16x16x32_bf16 v[74:77], v[168:171], v[218:221], v[74:77]
	v_mfma_f32_16x16x32_bf16 v[126:129], v[164:167], v[198:201], v[126:129]
	v_mfma_f32_16x16x32_bf16 v[122:125], v[172:175], v[198:201], v[122:125]
	v_mfma_f32_16x16x32_bf16 v[114:117], v[164:167], v[206:209], v[114:117]
	v_mfma_f32_16x16x32_bf16 v[106:109], v[172:175], v[206:209], v[106:109]
	v_mfma_f32_16x16x32_bf16 v[98:101], v[164:167], v[214:217], v[98:101]
	v_mfma_f32_16x16x32_bf16 v[90:93], v[172:175], v[214:217], v[90:93]
	v_mfma_f32_16x16x32_bf16 v[82:85], v[164:167], v[222:225], v[82:85]
	v_mfma_f32_16x16x32_bf16 v[74:77], v[172:175], v[222:225], v[74:77]
	v_mfma_f32_16x16x32_bf16 v[118:121], v[178:181], v[194:197], v[118:121]
	v_mfma_f32_16x16x32_bf16 v[110:113], v[186:189], v[194:197], v[110:113]
	v_mfma_f32_16x16x32_bf16 v[102:105], v[178:181], v[202:205], v[102:105]
	v_mfma_f32_16x16x32_bf16 v[94:97], v[186:189], v[202:205], v[94:97]
	v_mfma_f32_16x16x32_bf16 v[86:89], v[178:181], v[210:213], v[86:89]
	v_mfma_f32_16x16x32_bf16 v[78:81], v[186:189], v[210:213], v[78:81]
	v_mfma_f32_16x16x32_bf16 v[70:73], v[178:181], v[218:221], v[70:73]
	v_mfma_f32_16x16x32_bf16 v[66:69], v[186:189], v[218:221], v[66:69]
	v_mfma_f32_16x16x32_bf16 v[118:121], v[182:185], v[198:201], v[118:121]
	v_mfma_f32_16x16x32_bf16 v[110:113], v[190:193], v[198:201], v[110:113]
	v_mfma_f32_16x16x32_bf16 v[102:105], v[182:185], v[206:209], v[102:105]
	v_mfma_f32_16x16x32_bf16 v[94:97], v[190:193], v[206:209], v[94:97]
	v_mfma_f32_16x16x32_bf16 v[86:89], v[182:185], v[214:217], v[86:89]
	v_mfma_f32_16x16x32_bf16 v[78:81], v[190:193], v[214:217], v[78:81]
	v_mfma_f32_16x16x32_bf16 v[70:73], v[182:185], v[222:225], v[70:73]
	v_mfma_f32_16x16x32_bf16 v[66:69], v[190:193], v[222:225], v[66:69]
	s_barrier
	s_setprio 0
	s_mov_b32 m0, s29
	v_lshl_add_u64 v[226:227], s[14:15], 0, v[142:143]
	s_add_u32 s40, s14, 0x4000
	ds_read_b128 v[194:197], v137 offset:16384
	ds_read_b128 v[198:201], v137 offset:17408
	ds_read_b128 v[202:205], v137 offset:18432
	ds_read_b128 v[206:209], v137 offset:19456
	ds_read_b128 v[210:213], v137 offset:20480
	ds_read_b128 v[214:217], v137 offset:21504
	ds_read_b128 v[218:221], v137 offset:22528
	ds_read_b128 v[222:225], v137 offset:23552
	global_load_lds_dwordx4 v[226:227], off
	v_lshl_add_u64 v[226:227], s[14:15], 0, v[146:147]
	s_mov_b32 m0, s30
	s_addc_u32 s41, s15, 0
	global_load_lds_dwordx4 v[226:227], off
	v_lshl_add_u64 v[226:227], s[40:41], 0, v[142:143]
	s_mov_b32 m0, s31
	s_nop 0
	global_load_lds_dwordx4 v[226:227], off
	v_lshl_add_u64 v[226:227], s[40:41], 0, v[146:147]
	s_mov_b32 m0, s34
	s_nop 0
	global_load_lds_dwordx4 v[226:227], off
	v_lshl_add_u64 v[226:227], s[2:3], 0, v[140:141]
	s_mov_b32 m0, s19
	s_nop 0
	global_load_lds_dwordx4 v[226:227], off
	v_lshl_add_u64 v[226:227], s[2:3], 0, v[144:145]
	s_mov_b32 m0, s20
	s_nop 0
	global_load_lds_dwordx4 v[226:227], off
	s_waitcnt vmcnt(8)
	s_waitcnt lgkmcnt(0)
	s_setprio 1
	s_barrier
	v_mfma_f32_16x16x32_bf16 v[62:65], v[160:163], v[194:197], v[62:65]
	v_mfma_f32_16x16x32_bf16 v[58:61], v[168:171], v[194:197], v[58:61]
	v_mfma_f32_16x16x32_bf16 v[50:53], v[160:163], v[202:205], v[50:53]
	v_mfma_f32_16x16x32_bf16 v[42:45], v[168:171], v[202:205], v[42:45]
	v_mfma_f32_16x16x32_bf16 v[34:37], v[160:163], v[210:213], v[34:37]
	v_mfma_f32_16x16x32_bf16 v[26:29], v[168:171], v[210:213], v[26:29]
	v_mfma_f32_16x16x32_bf16 v[18:21], v[160:163], v[218:221], v[18:21]
	v_mfma_f32_16x16x32_bf16 v[10:13], v[168:171], v[218:221], v[10:13]
	v_mfma_f32_16x16x32_bf16 v[62:65], v[164:167], v[198:201], v[62:65]
	v_mfma_f32_16x16x32_bf16 v[58:61], v[172:175], v[198:201], v[58:61]
	v_mfma_f32_16x16x32_bf16 v[50:53], v[164:167], v[206:209], v[50:53]
	v_mfma_f32_16x16x32_bf16 v[42:45], v[172:175], v[206:209], v[42:45]
	v_mfma_f32_16x16x32_bf16 v[34:37], v[164:167], v[214:217], v[34:37]
	v_mfma_f32_16x16x32_bf16 v[26:29], v[172:175], v[214:217], v[26:29]
	v_mfma_f32_16x16x32_bf16 v[18:21], v[164:167], v[222:225], v[18:21]
	v_mfma_f32_16x16x32_bf16 v[10:13], v[172:175], v[222:225], v[10:13]
	v_mfma_f32_16x16x32_bf16 v[54:57], v[178:181], v[194:197], v[54:57]
	v_mfma_f32_16x16x32_bf16 v[46:49], v[186:189], v[194:197], v[46:49]
	v_mfma_f32_16x16x32_bf16 v[38:41], v[178:181], v[202:205], v[38:41]
	v_mfma_f32_16x16x32_bf16 v[30:33], v[186:189], v[202:205], v[30:33]
	v_mfma_f32_16x16x32_bf16 v[22:25], v[178:181], v[210:213], v[22:25]
	v_mfma_f32_16x16x32_bf16 v[14:17], v[186:189], v[210:213], v[14:17]
	v_mfma_f32_16x16x32_bf16 v[6:9], v[178:181], v[218:221], v[6:9]
	v_mfma_f32_16x16x32_bf16 v[2:5], v[186:189], v[218:221], v[2:5]
	v_mfma_f32_16x16x32_bf16 v[54:57], v[182:185], v[198:201], v[54:57]
	v_mfma_f32_16x16x32_bf16 v[46:49], v[190:193], v[198:201], v[46:49]
	v_mfma_f32_16x16x32_bf16 v[38:41], v[182:185], v[206:209], v[38:41]
	v_mfma_f32_16x16x32_bf16 v[30:33], v[190:193], v[206:209], v[30:33]
	v_mfma_f32_16x16x32_bf16 v[22:25], v[182:185], v[214:217], v[22:25]
	v_mfma_f32_16x16x32_bf16 v[14:17], v[190:193], v[214:217], v[14:17]
	v_mfma_f32_16x16x32_bf16 v[6:9], v[182:185], v[222:225], v[6:9]
	v_mfma_f32_16x16x32_bf16 v[2:5], v[190:193], v[222:225], v[2:5]
	s_barrier
	s_setprio 0
	ds_read_b128 v[160:163], v139
	ds_read_b128 v[164:167], v139 offset:1024
	ds_read_b128 v[168:171], v139 offset:2048
	ds_read_b128 v[172:175], v139 offset:3072
	ds_read_b128 v[178:181], v158
	ds_read_b128 v[182:185], v158 offset:1024
	ds_read_b128 v[186:189], v158 offset:2048
	ds_read_b128 v[190:193], v158 offset:3072
	s_add_u32 s2, s2, 0x4000
	s_addc_u32 s3, s3, 0
	s_mov_b32 m0, s21
	v_lshl_add_u64 v[226:227], s[2:3], 0, v[140:141]
	ds_read_b128 v[194:197], v137 offset:32768
	ds_read_b128 v[198:201], v137 offset:33792
	ds_read_b128 v[202:205], v137 offset:34816
	ds_read_b128 v[206:209], v137 offset:35840
	ds_read_b128 v[210:213], v137 offset:36864
	ds_read_b128 v[214:217], v137 offset:37888
	ds_read_b128 v[218:221], v137 offset:38912
	ds_read_b128 v[222:225], v137 offset:39936
	global_load_lds_dwordx4 v[226:227], off
	v_lshl_add_u64 v[226:227], s[2:3], 0, v[144:145]
	s_mov_b32 m0, s22
	s_nop 0
	global_load_lds_dwordx4 v[226:227], off
	s_waitcnt vmcnt(8)
	s_waitcnt lgkmcnt(0)
	s_setprio 1
	s_barrier
	v_mfma_f32_16x16x32_bf16 v[126:129], v[160:163], v[194:197], v[126:129]
	v_mfma_f32_16x16x32_bf16 v[122:125], v[168:171], v[194:197], v[122:125]
	v_mfma_f32_16x16x32_bf16 v[114:117], v[160:163], v[202:205], v[114:117]
	v_mfma_f32_16x16x32_bf16 v[106:109], v[168:171], v[202:205], v[106:109]
	v_mfma_f32_16x16x32_bf16 v[98:101], v[160:163], v[210:213], v[98:101]
	v_mfma_f32_16x16x32_bf16 v[90:93], v[168:171], v[210:213], v[90:93]
	v_mfma_f32_16x16x32_bf16 v[82:85], v[160:163], v[218:221], v[82:85]
	v_mfma_f32_16x16x32_bf16 v[74:77], v[168:171], v[218:221], v[74:77]
	v_mfma_f32_16x16x32_bf16 v[126:129], v[164:167], v[198:201], v[126:129]
	v_mfma_f32_16x16x32_bf16 v[122:125], v[172:175], v[198:201], v[122:125]
	v_mfma_f32_16x16x32_bf16 v[114:117], v[164:167], v[206:209], v[114:117]
	v_mfma_f32_16x16x32_bf16 v[106:109], v[172:175], v[206:209], v[106:109]
	v_mfma_f32_16x16x32_bf16 v[98:101], v[164:167], v[214:217], v[98:101]
	v_mfma_f32_16x16x32_bf16 v[90:93], v[172:175], v[214:217], v[90:93]
	v_mfma_f32_16x16x32_bf16 v[82:85], v[164:167], v[222:225], v[82:85]
	v_mfma_f32_16x16x32_bf16 v[74:77], v[172:175], v[222:225], v[74:77]
	v_mfma_f32_16x16x32_bf16 v[118:121], v[178:181], v[194:197], v[118:121]
	v_mfma_f32_16x16x32_bf16 v[110:113], v[186:189], v[194:197], v[110:113]
	v_mfma_f32_16x16x32_bf16 v[102:105], v[178:181], v[202:205], v[102:105]
	v_mfma_f32_16x16x32_bf16 v[94:97], v[186:189], v[202:205], v[94:97]
	v_mfma_f32_16x16x32_bf16 v[86:89], v[178:181], v[210:213], v[86:89]
	v_mfma_f32_16x16x32_bf16 v[78:81], v[186:189], v[210:213], v[78:81]
	v_mfma_f32_16x16x32_bf16 v[70:73], v[178:181], v[218:221], v[70:73]
	v_mfma_f32_16x16x32_bf16 v[66:69], v[186:189], v[218:221], v[66:69]
	v_mfma_f32_16x16x32_bf16 v[118:121], v[182:185], v[198:201], v[118:121]
	v_mfma_f32_16x16x32_bf16 v[110:113], v[190:193], v[198:201], v[110:113]
	v_mfma_f32_16x16x32_bf16 v[102:105], v[182:185], v[206:209], v[102:105]
	v_mfma_f32_16x16x32_bf16 v[94:97], v[190:193], v[206:209], v[94:97]
	v_mfma_f32_16x16x32_bf16 v[86:89], v[182:185], v[214:217], v[86:89]
	v_mfma_f32_16x16x32_bf16 v[78:81], v[190:193], v[214:217], v[78:81]
	v_mfma_f32_16x16x32_bf16 v[70:73], v[182:185], v[222:225], v[70:73]
	v_mfma_f32_16x16x32_bf16 v[66:69], v[190:193], v[222:225], v[66:69]
	s_barrier
	s_setprio 0
	s_add_u32 s2, s14, 0x8000
	s_addc_u32 s3, s15, 0
	s_mov_b32 m0, s35
	v_lshl_add_u64 v[226:227], s[2:3], 0, v[142:143]
	ds_read_b128 v[194:197], v137 offset:49152
	ds_read_b128 v[198:201], v137 offset:50176
	ds_read_b128 v[202:205], v137 offset:51200
	ds_read_b128 v[206:209], v137 offset:52224
	ds_read_b128 v[210:213], v137 offset:53248
	ds_read_b128 v[214:217], v137 offset:54272
	ds_read_b128 v[218:221], v137 offset:55296
	ds_read_b128 v[222:225], v137 offset:56320
	global_load_lds_dwordx4 v[226:227], off
	v_lshl_add_u64 v[226:227], s[2:3], 0, v[146:147]
	s_add_u32 s2, s14, 0xc000
	s_mov_b32 m0, s36
	s_addc_u32 s3, s15, 0
	global_load_lds_dwordx4 v[226:227], off
	v_lshl_add_u64 v[226:227], s[2:3], 0, v[142:143]
	s_mov_b32 m0, s37
	s_nop 0
	global_load_lds_dwordx4 v[226:227], off
	v_lshl_add_u64 v[226:227], s[2:3], 0, v[146:147]
	s_mov_b32 m0, s38
	s_nop 0
	global_load_lds_dwordx4 v[226:227], off
	v_lshl_add_u64 v[226:227], s[12:13], 0, v[140:141]
	s_mov_b32 m0, s24
	s_nop 0
	global_load_lds_dwordx4 v[226:227], off
	v_lshl_add_u64 v[226:227], s[12:13], 0, v[144:145]
	s_mov_b32 m0, s25
	s_nop 0
	global_load_lds_dwordx4 v[226:227], off
	s_waitcnt vmcnt(8)
	s_waitcnt lgkmcnt(0)
	s_setprio 1
	s_barrier
	v_mfma_f32_16x16x32_bf16 v[62:65], v[160:163], v[194:197], v[62:65]
	v_mfma_f32_16x16x32_bf16 v[58:61], v[168:171], v[194:197], v[58:61]
	v_mfma_f32_16x16x32_bf16 v[50:53], v[160:163], v[202:205], v[50:53]
	v_mfma_f32_16x16x32_bf16 v[42:45], v[168:171], v[202:205], v[42:45]
	v_mfma_f32_16x16x32_bf16 v[34:37], v[160:163], v[210:213], v[34:37]
	v_mfma_f32_16x16x32_bf16 v[26:29], v[168:171], v[210:213], v[26:29]
	v_mfma_f32_16x16x32_bf16 v[18:21], v[160:163], v[218:221], v[18:21]
	v_mfma_f32_16x16x32_bf16 v[10:13], v[168:171], v[218:221], v[10:13]
	v_mfma_f32_16x16x32_bf16 v[62:65], v[164:167], v[198:201], v[62:65]
	v_mfma_f32_16x16x32_bf16 v[58:61], v[172:175], v[198:201], v[58:61]
	v_mfma_f32_16x16x32_bf16 v[50:53], v[164:167], v[206:209], v[50:53]
	v_mfma_f32_16x16x32_bf16 v[42:45], v[172:175], v[206:209], v[42:45]
	v_mfma_f32_16x16x32_bf16 v[34:37], v[164:167], v[214:217], v[34:37]
	v_mfma_f32_16x16x32_bf16 v[26:29], v[172:175], v[214:217], v[26:29]
	v_mfma_f32_16x16x32_bf16 v[18:21], v[164:167], v[222:225], v[18:21]
	v_mfma_f32_16x16x32_bf16 v[10:13], v[172:175], v[222:225], v[10:13]
	v_mfma_f32_16x16x32_bf16 v[54:57], v[178:181], v[194:197], v[54:57]
	v_mfma_f32_16x16x32_bf16 v[46:49], v[186:189], v[194:197], v[46:49]
	v_mfma_f32_16x16x32_bf16 v[38:41], v[178:181], v[202:205], v[38:41]
	v_mfma_f32_16x16x32_bf16 v[30:33], v[186:189], v[202:205], v[30:33]
	v_mfma_f32_16x16x32_bf16 v[22:25], v[178:181], v[210:213], v[22:25]
	v_mfma_f32_16x16x32_bf16 v[14:17], v[186:189], v[210:213], v[14:17]
	v_mfma_f32_16x16x32_bf16 v[6:9], v[178:181], v[218:221], v[6:9]
	v_mfma_f32_16x16x32_bf16 v[2:5], v[186:189], v[218:221], v[2:5]
	v_mfma_f32_16x16x32_bf16 v[54:57], v[182:185], v[198:201], v[54:57]
	v_mfma_f32_16x16x32_bf16 v[46:49], v[190:193], v[198:201], v[46:49]
	v_mfma_f32_16x16x32_bf16 v[38:41], v[182:185], v[206:209], v[38:41]
	v_mfma_f32_16x16x32_bf16 v[30:33], v[190:193], v[206:209], v[30:33]
	v_mfma_f32_16x16x32_bf16 v[22:25], v[182:185], v[214:217], v[22:25]
	v_mfma_f32_16x16x32_bf16 v[14:17], v[190:193], v[214:217], v[14:17]
	v_mfma_f32_16x16x32_bf16 v[6:9], v[182:185], v[222:225], v[6:9]
	v_mfma_f32_16x16x32_bf16 v[2:5], v[190:193], v[222:225], v[2:5]
	s_barrier
	s_setprio 0
	s_add_i32 s26, s26, 2
	s_add_u32 s8, s8, 0x10000
	s_addc_u32 s9, s9, 0
	s_cmp_gt_u32 s26, 41
	s_cbranch_scc0 .LBB0_1386
	s_cmpk_lt_u32 s16, 0x100
	s_cbranch_scc0 .LBB0_1389
	s_barrier

.Lpk1400_peel:
	ds_read_b128 v[152:155], v1
	ds_read_b128 v[156:159], v1 offset:1024
	ds_read_b128 v[160:163], v1 offset:2048
	ds_read_b128 v[164:167], v1 offset:3072
	ds_read_b128 v[168:171], v149
	ds_read_b128 v[172:175], v149 offset:1024
	ds_read_b128 v[178:181], v149 offset:2048
	ds_read_b128 v[182:185], v149 offset:3072
	s_add_u32 s2, s28, 0xfffc0080
	s_addc_u32 s3, s29, -1
	s_cmp_eq_u32 s55, 12
	s_cselect_b32 s3, s11, s3
	s_cselect_b32 s2, s13, s2
	s_cselect_b32 s31, s47, s54
	s_cselect_b32 s30, s52, s53
	v_lshl_add_u64 v[146:147], s[28:29], 0, v[140:141]
	s_add_i32 m0, s25, 0xc000
	ds_read_b128 v[186:189], v150
	ds_read_b128 v[190:193], v150 offset:1024
	ds_read_b128 v[194:197], v150 offset:2048
	ds_read_b128 v[198:201], v150 offset:3072
	ds_read_b128 v[202:205], v150 offset:4096
	ds_read_b128 v[206:209], v150 offset:5120
	ds_read_b128 v[210:213], v150 offset:6144
	ds_read_b128 v[214:217], v150 offset:7168
	global_load_lds_dwordx4 v[146:147], off
	v_lshl_add_u64 v[146:147], s[28:29], 0, v[142:143]
	s_add_i32 m0, s25, 0xe000
	s_nop 0
	global_load_lds_dwordx4 v[146:147], off
	s_waitcnt vmcnt(8)
	s_waitcnt lgkmcnt(0)
	s_setprio 1
	s_barrier
	v_mfma_f32_16x16x32_bf16 v[126:129], v[152:155], v[186:189], 0
	v_mfma_f32_16x16x32_bf16 v[122:125], v[160:163], v[186:189], 0
	v_mfma_f32_16x16x32_bf16 v[110:113], v[152:155], v[194:197], 0
	v_mfma_f32_16x16x32_bf16 v[106:109], v[160:163], v[194:197], 0
	v_mfma_f32_16x16x32_bf16 v[94:97], v[152:155], v[202:205], 0
	v_mfma_f32_16x16x32_bf16 v[90:93], v[160:163], v[202:205], 0
	v_mfma_f32_16x16x32_bf16 v[78:81], v[152:155], v[210:213], 0
	v_mfma_f32_16x16x32_bf16 v[74:77], v[160:163], v[210:213], 0
	v_mfma_f32_16x16x32_bf16 v[126:129], v[156:159], v[190:193], v[126:129]
	v_mfma_f32_16x16x32_bf16 v[122:125], v[164:167], v[190:193], v[122:125]
	v_mfma_f32_16x16x32_bf16 v[110:113], v[156:159], v[198:201], v[110:113]
	v_mfma_f32_16x16x32_bf16 v[106:109], v[164:167], v[198:201], v[106:109]
	v_mfma_f32_16x16x32_bf16 v[94:97], v[156:159], v[206:209], v[94:97]
	v_mfma_f32_16x16x32_bf16 v[90:93], v[164:167], v[206:209], v[90:93]
	v_mfma_f32_16x16x32_bf16 v[78:81], v[156:159], v[214:217], v[78:81]
	v_mfma_f32_16x16x32_bf16 v[74:77], v[164:167], v[214:217], v[74:77]
	v_mfma_f32_16x16x32_bf16 v[118:121], v[168:171], v[186:189], 0
	v_mfma_f32_16x16x32_bf16 v[114:117], v[178:181], v[186:189], 0
	v_mfma_f32_16x16x32_bf16 v[102:105], v[168:171], v[194:197], 0
	v_mfma_f32_16x16x32_bf16 v[98:101], v[178:181], v[194:197], 0
	v_mfma_f32_16x16x32_bf16 v[86:89], v[168:171], v[202:205], 0
	v_mfma_f32_16x16x32_bf16 v[82:85], v[178:181], v[202:205], 0
	v_mfma_f32_16x16x32_bf16 v[70:73], v[168:171], v[210:213], 0
	v_mfma_f32_16x16x32_bf16 v[66:69], v[178:181], v[210:213], 0
	v_mfma_f32_16x16x32_bf16 v[118:121], v[172:175], v[190:193], v[118:121]
	v_mfma_f32_16x16x32_bf16 v[114:117], v[182:185], v[190:193], v[114:117]
	v_mfma_f32_16x16x32_bf16 v[102:105], v[172:175], v[198:201], v[102:105]
	v_mfma_f32_16x16x32_bf16 v[98:101], v[182:185], v[198:201], v[98:101]
	v_mfma_f32_16x16x32_bf16 v[86:89], v[172:175], v[206:209], v[86:89]
	v_mfma_f32_16x16x32_bf16 v[82:85], v[182:185], v[206:209], v[82:85]
	v_mfma_f32_16x16x32_bf16 v[70:73], v[172:175], v[214:217], v[70:73]
	v_mfma_f32_16x16x32_bf16 v[66:69], v[182:185], v[214:217], v[66:69]
	s_barrier
	s_setprio 0
	s_add_i32 s56, s43, s34
	v_lshl_add_u64 v[146:147], s[30:31], 0, v[132:133]
	s_mov_b32 m0, s56
	ds_read_b128 v[186:189], v150 offset:16384
	ds_read_b128 v[190:193], v150 offset:17408
	ds_read_b128 v[194:197], v150 offset:18432
	ds_read_b128 v[198:201], v150 offset:19456
	ds_read_b128 v[202:205], v150 offset:20480
	ds_read_b128 v[206:209], v150 offset:21504
	ds_read_b128 v[210:213], v150 offset:22528
	ds_read_b128 v[214:217], v150 offset:23552
	global_load_lds_dwordx4 v[146:147], off
	s_add_i32 m0, s56, 0x2000
	s_add_u32 s56, s30, 0x40000
	v_lshl_add_u64 v[218:219], s[30:31], 0, v[136:137]
	s_addc_u32 s57, s31, 0
	s_add_i32 s58, s44, s34
	global_load_lds_dwordx4 v[218:219], off
	v_lshl_add_u64 v[220:221], s[56:57], 0, v[132:133]
	s_mov_b32 m0, s58
	v_lshl_add_u64 v[222:223], s[2:3], 0, v[134:135]
	global_load_lds_dwordx4 v[220:221], off
	v_lshl_add_u64 v[220:221], s[56:57], 0, v[136:137]
	s_add_i32 m0, s58, 0x2000
	s_nop 0
	global_load_lds_dwordx4 v[220:221], off
	v_lshl_add_u64 v[220:221], s[2:3], 0, v[130:131]
	s_mov_b32 m0, s25
	s_nop 0
	global_load_lds_dwordx4 v[220:221], off
	s_mov_b32 m0, s27
	s_nop 0
	global_load_lds_dwordx4 v[222:223], off
	s_waitcnt vmcnt(8)
	s_waitcnt lgkmcnt(0)
	s_setprio 1
	s_barrier
	v_mfma_f32_16x16x32_bf16 v[62:65], v[152:155], v[186:189], 0
	v_mfma_f32_16x16x32_bf16 v[58:61], v[160:163], v[186:189], 0
	v_mfma_f32_16x16x32_bf16 v[46:49], v[152:155], v[194:197], 0
	v_mfma_f32_16x16x32_bf16 v[42:45], v[160:163], v[194:197], 0
	v_mfma_f32_16x16x32_bf16 v[30:33], v[152:155], v[202:205], 0
	v_mfma_f32_16x16x32_bf16 v[26:29], v[160:163], v[202:205], 0
	v_mfma_f32_16x16x32_bf16 v[14:17], v[152:155], v[210:213], 0
	v_mfma_f32_16x16x32_bf16 v[10:13], v[160:163], v[210:213], 0
	v_mfma_f32_16x16x32_bf16 v[62:65], v[156:159], v[190:193], v[62:65]
	v_mfma_f32_16x16x32_bf16 v[58:61], v[164:167], v[190:193], v[58:61]
	v_mfma_f32_16x16x32_bf16 v[46:49], v[156:159], v[198:201], v[46:49]
	v_mfma_f32_16x16x32_bf16 v[42:45], v[164:167], v[198:201], v[42:45]
	v_mfma_f32_16x16x32_bf16 v[30:33], v[156:159], v[206:209], v[30:33]
	v_mfma_f32_16x16x32_bf16 v[26:29], v[164:167], v[206:209], v[26:29]
	v_mfma_f32_16x16x32_bf16 v[14:17], v[156:159], v[214:217], v[14:17]
	v_mfma_f32_16x16x32_bf16 v[10:13], v[164:167], v[214:217], v[10:13]
	v_mfma_f32_16x16x32_bf16 v[54:57], v[168:171], v[186:189], 0
	v_mfma_f32_16x16x32_bf16 v[50:53], v[178:181], v[186:189], 0
	v_mfma_f32_16x16x32_bf16 v[38:41], v[168:171], v[194:197], 0
	v_mfma_f32_16x16x32_bf16 v[34:37], v[178:181], v[194:197], 0
	v_mfma_f32_16x16x32_bf16 v[22:25], v[168:171], v[202:205], 0
	v_mfma_f32_16x16x32_bf16 v[18:21], v[178:181], v[202:205], 0
	v_mfma_f32_16x16x32_bf16 v[6:9], v[168:171], v[210:213], 0
	v_mfma_f32_16x16x32_bf16 v[2:5], v[178:181], v[210:213], 0
	v_mfma_f32_16x16x32_bf16 v[54:57], v[172:175], v[190:193], v[54:57]
	v_mfma_f32_16x16x32_bf16 v[50:53], v[182:185], v[190:193], v[50:53]
	v_mfma_f32_16x16x32_bf16 v[38:41], v[172:175], v[198:201], v[38:41]
	v_mfma_f32_16x16x32_bf16 v[34:37], v[182:185], v[198:201], v[34:37]
	v_mfma_f32_16x16x32_bf16 v[22:25], v[172:175], v[206:209], v[22:25]
	v_mfma_f32_16x16x32_bf16 v[18:21], v[182:185], v[206:209], v[18:21]
	v_mfma_f32_16x16x32_bf16 v[6:9], v[172:175], v[214:217], v[6:9]
	v_mfma_f32_16x16x32_bf16 v[2:5], v[182:185], v[214:217], v[2:5]
	s_barrier
	s_setprio 0
	s_add_i32 s56, 0, 0x18000
	v_add_u32_e32 v151, s56, v148
	s_add_i32 s57, 0, 0x1c000
	ds_read_b128 v[152:155], v151
	ds_read_b128 v[156:159], v151 offset:1024
	ds_read_b128 v[160:163], v151 offset:2048
	ds_read_b128 v[164:167], v151 offset:3072
	v_add_u32_e32 v151, s57, v148
	ds_read_b128 v[168:171], v151
	ds_read_b128 v[172:175], v151 offset:1024
	ds_read_b128 v[178:181], v151 offset:2048
	ds_read_b128 v[182:185], v151 offset:3072
	s_add_u32 s2, s2, 0x40000
	s_addc_u32 s3, s3, 0
	s_mov_b32 m0, s36
	v_lshl_add_u64 v[224:225], s[2:3], 0, v[130:131]
	ds_read_b128 v[186:189], v150 offset:32768
	ds_read_b128 v[190:193], v150 offset:33792
	ds_read_b128 v[194:197], v150 offset:34816
	ds_read_b128 v[198:201], v150 offset:35840
	ds_read_b128 v[202:205], v150 offset:36864
	ds_read_b128 v[206:209], v150 offset:37888
	ds_read_b128 v[210:213], v150 offset:38912
	ds_read_b128 v[214:217], v150 offset:39936
	global_load_lds_dwordx4 v[224:225], off
	v_lshl_add_u64 v[224:225], s[2:3], 0, v[134:135]
	s_mov_b32 m0, s37
	s_nop 0
	global_load_lds_dwordx4 v[224:225], off
	s_waitcnt vmcnt(8)
	s_waitcnt lgkmcnt(0)
	s_setprio 1
	s_barrier
	v_mfma_f32_16x16x32_bf16 v[126:129], v[152:155], v[186:189], v[126:129]
	v_mfma_f32_16x16x32_bf16 v[122:125], v[160:163], v[186:189], v[122:125]
	v_mfma_f32_16x16x32_bf16 v[110:113], v[152:155], v[194:197], v[110:113]
	v_mfma_f32_16x16x32_bf16 v[106:109], v[160:163], v[194:197], v[106:109]
	v_mfma_f32_16x16x32_bf16 v[94:97], v[152:155], v[202:205], v[94:97]
	v_mfma_f32_16x16x32_bf16 v[90:93], v[160:163], v[202:205], v[90:93]
	v_mfma_f32_16x16x32_bf16 v[78:81], v[152:155], v[210:213], v[78:81]
	v_mfma_f32_16x16x32_bf16 v[74:77], v[160:163], v[210:213], v[74:77]
	v_mfma_f32_16x16x32_bf16 v[126:129], v[156:159], v[190:193], v[126:129]
	v_mfma_f32_16x16x32_bf16 v[122:125], v[164:167], v[190:193], v[122:125]
	v_mfma_f32_16x16x32_bf16 v[110:113], v[156:159], v[198:201], v[110:113]
	v_mfma_f32_16x16x32_bf16 v[106:109], v[164:167], v[198:201], v[106:109]
	v_mfma_f32_16x16x32_bf16 v[94:97], v[156:159], v[206:209], v[94:97]
	v_mfma_f32_16x16x32_bf16 v[90:93], v[164:167], v[206:209], v[90:93]
	v_mfma_f32_16x16x32_bf16 v[78:81], v[156:159], v[214:217], v[78:81]
	v_mfma_f32_16x16x32_bf16 v[74:77], v[164:167], v[214:217], v[74:77]
	v_mfma_f32_16x16x32_bf16 v[118:121], v[168:171], v[186:189], v[118:121]
	v_mfma_f32_16x16x32_bf16 v[114:117], v[178:181], v[186:189], v[114:117]
	v_mfma_f32_16x16x32_bf16 v[102:105], v[168:171], v[194:197], v[102:105]
	v_mfma_f32_16x16x32_bf16 v[98:101], v[178:181], v[194:197], v[98:101]
	v_mfma_f32_16x16x32_bf16 v[86:89], v[168:171], v[202:205], v[86:89]
	v_mfma_f32_16x16x32_bf16 v[82:85], v[178:181], v[202:205], v[82:85]
	v_mfma_f32_16x16x32_bf16 v[70:73], v[168:171], v[210:213], v[70:73]
	v_mfma_f32_16x16x32_bf16 v[66:69], v[178:181], v[210:213], v[66:69]
	v_mfma_f32_16x16x32_bf16 v[118:121], v[172:175], v[190:193], v[118:121]
	v_mfma_f32_16x16x32_bf16 v[114:117], v[182:185], v[190:193], v[114:117]
	v_mfma_f32_16x16x32_bf16 v[102:105], v[172:175], v[198:201], v[102:105]
	v_mfma_f32_16x16x32_bf16 v[98:101], v[182:185], v[198:201], v[98:101]
	v_mfma_f32_16x16x32_bf16 v[86:89], v[172:175], v[206:209], v[86:89]
	v_mfma_f32_16x16x32_bf16 v[82:85], v[182:185], v[206:209], v[82:85]
	v_mfma_f32_16x16x32_bf16 v[70:73], v[172:175], v[214:217], v[70:73]
	v_mfma_f32_16x16x32_bf16 v[66:69], v[182:185], v[214:217], v[66:69]
	s_barrier
	s_setprio 0
	s_add_i32 s2, s56, s34
	v_lshl_add_u64 v[146:147], v[146:147], 0, s[6:7]
	s_mov_b32 m0, s2
	ds_read_b128 v[186:189], v150 offset:49152
	ds_read_b128 v[190:193], v150 offset:50176
	ds_read_b128 v[194:197], v150 offset:51200
	ds_read_b128 v[198:201], v150 offset:52224
	ds_read_b128 v[202:205], v150 offset:53248
	ds_read_b128 v[206:209], v150 offset:54272
	ds_read_b128 v[210:213], v150 offset:55296
	ds_read_b128 v[214:217], v150 offset:56320
	global_load_lds_dwordx4 v[146:147], off
	s_add_i32 m0, s2, 0x2000
	s_add_u32 s2, s30, 0x40080
	v_lshl_add_u64 v[146:147], v[218:219], 0, s[6:7]
	s_addc_u32 s3, s31, 0
	s_add_i32 s30, s57, s34
	global_load_lds_dwordx4 v[146:147], off
	v_lshl_add_u64 v[146:147], s[2:3], 0, v[132:133]
	s_mov_b32 m0, s30
	s_nop 0
	global_load_lds_dwordx4 v[146:147], off
	v_lshl_add_u64 v[146:147], s[2:3], 0, v[136:137]
	s_add_i32 m0, s30, 0x2000
	s_nop 0
	global_load_lds_dwordx4 v[146:147], off
	v_lshl_add_u64 v[146:147], v[220:221], 0, s[6:7]
	s_mov_b32 m0, s40
	s_nop 0
	global_load_lds_dwordx4 v[146:147], off
	v_lshl_add_u64 v[146:147], v[222:223], 0, s[6:7]
	s_mov_b32 m0, s41
	s_nop 0
	global_load_lds_dwordx4 v[146:147], off
	s_waitcnt vmcnt(8)
	s_waitcnt lgkmcnt(0)
	s_setprio 1
	s_barrier
	v_mfma_f32_16x16x32_bf16 v[62:65], v[152:155], v[186:189], v[62:65]
	v_mfma_f32_16x16x32_bf16 v[58:61], v[160:163], v[186:189], v[58:61]
	v_mfma_f32_16x16x32_bf16 v[46:49], v[152:155], v[194:197], v[46:49]
	v_mfma_f32_16x16x32_bf16 v[42:45], v[160:163], v[194:197], v[42:45]
	v_mfma_f32_16x16x32_bf16 v[30:33], v[152:155], v[202:205], v[30:33]
	v_mfma_f32_16x16x32_bf16 v[26:29], v[160:163], v[202:205], v[26:29]
	v_mfma_f32_16x16x32_bf16 v[14:17], v[152:155], v[210:213], v[14:17]
	v_mfma_f32_16x16x32_bf16 v[10:13], v[160:163], v[210:213], v[10:13]
	v_mfma_f32_16x16x32_bf16 v[62:65], v[156:159], v[190:193], v[62:65]
	v_mfma_f32_16x16x32_bf16 v[58:61], v[164:167], v[190:193], v[58:61]
	v_mfma_f32_16x16x32_bf16 v[46:49], v[156:159], v[198:201], v[46:49]
	v_mfma_f32_16x16x32_bf16 v[42:45], v[164:167], v[198:201], v[42:45]
	v_mfma_f32_16x16x32_bf16 v[30:33], v[156:159], v[206:209], v[30:33]
	v_mfma_f32_16x16x32_bf16 v[26:29], v[164:167], v[206:209], v[26:29]
	v_mfma_f32_16x16x32_bf16 v[14:17], v[156:159], v[214:217], v[14:17]
	v_mfma_f32_16x16x32_bf16 v[10:13], v[164:167], v[214:217], v[10:13]
	v_mfma_f32_16x16x32_bf16 v[54:57], v[168:171], v[186:189], v[54:57]
	v_mfma_f32_16x16x32_bf16 v[50:53], v[178:181], v[186:189], v[50:53]
	v_mfma_f32_16x16x32_bf16 v[38:41], v[168:171], v[194:197], v[38:41]
	v_mfma_f32_16x16x32_bf16 v[34:37], v[178:181], v[194:197], v[34:37]
	v_mfma_f32_16x16x32_bf16 v[22:25], v[168:171], v[202:205], v[22:25]
	v_mfma_f32_16x16x32_bf16 v[18:21], v[178:181], v[202:205], v[18:21]
	v_mfma_f32_16x16x32_bf16 v[6:9], v[168:171], v[210:213], v[6:9]
	v_mfma_f32_16x16x32_bf16 v[2:5], v[178:181], v[210:213], v[2:5]
	v_mfma_f32_16x16x32_bf16 v[54:57], v[172:175], v[190:193], v[54:57]
	v_mfma_f32_16x16x32_bf16 v[50:53], v[182:185], v[190:193], v[50:53]
	v_mfma_f32_16x16x32_bf16 v[38:41], v[172:175], v[198:201], v[38:41]
	v_mfma_f32_16x16x32_bf16 v[34:37], v[182:185], v[198:201], v[34:37]
	v_mfma_f32_16x16x32_bf16 v[22:25], v[172:175], v[206:209], v[22:25]
	v_mfma_f32_16x16x32_bf16 v[18:21], v[182:185], v[206:209], v[18:21]
	v_mfma_f32_16x16x32_bf16 v[6:9], v[172:175], v[214:217], v[6:9]
	v_mfma_f32_16x16x32_bf16 v[2:5], v[182:185], v[214:217], v[2:5]
	s_barrier
	s_setprio 0
	s_add_i32 s55, s55, 2
	s_add_u32 s28, s28, 0x100
	s_addc_u32 s29, s29, 0
	s_add_u32 s53, s53, 0x100
	s_addc_u32 s54, s54, 0
	s_cmp_gt_u32 s55, 13
	s_cbranch_scc0 .LBB0_1400
	s_branch .Lpk1400_exit
.LBB0_1400:
	ds_read_b128 v[152:155], v1
	ds_read_b128 v[156:159], v1 offset:1024
	ds_read_b128 v[160:163], v1 offset:2048
	ds_read_b128 v[164:167], v1 offset:3072
	ds_read_b128 v[168:171], v149
	ds_read_b128 v[172:175], v149 offset:1024
	ds_read_b128 v[178:181], v149 offset:2048
	ds_read_b128 v[182:185], v149 offset:3072
	s_add_u32 s2, s28, 0xfffc0080
	s_addc_u32 s3, s29, -1
	s_cmp_eq_u32 s55, 12
	s_cselect_b32 s3, s11, s3
	s_cselect_b32 s2, s13, s2
	s_cselect_b32 s31, s47, s54
	s_cselect_b32 s30, s52, s53
	v_lshl_add_u64 v[146:147], s[28:29], 0, v[140:141]
	s_add_i32 m0, s25, 0xc000
	ds_read_b128 v[186:189], v150
	ds_read_b128 v[190:193], v150 offset:1024
	ds_read_b128 v[194:197], v150 offset:2048
	ds_read_b128 v[198:201], v150 offset:3072
	ds_read_b128 v[202:205], v150 offset:4096
	ds_read_b128 v[206:209], v150 offset:5120
	ds_read_b128 v[210:213], v150 offset:6144
	ds_read_b128 v[214:217], v150 offset:7168
	global_load_lds_dwordx4 v[146:147], off
	v_lshl_add_u64 v[146:147], s[28:29], 0, v[142:143]
	s_add_i32 m0, s25, 0xe000
	s_nop 0
	global_load_lds_dwordx4 v[146:147], off
	s_waitcnt vmcnt(8)
	s_waitcnt lgkmcnt(0)
	s_setprio 1
	s_barrier
	v_mfma_f32_16x16x32_bf16 v[126:129], v[152:155], v[186:189], v[126:129]
	v_mfma_f32_16x16x32_bf16 v[122:125], v[160:163], v[186:189], v[122:125]
	v_mfma_f32_16x16x32_bf16 v[110:113], v[152:155], v[194:197], v[110:113]
	v_mfma_f32_16x16x32_bf16 v[106:109], v[160:163], v[194:197], v[106:109]
	v_mfma_f32_16x16x32_bf16 v[94:97], v[152:155], v[202:205], v[94:97]
	v_mfma_f32_16x16x32_bf16 v[90:93], v[160:163], v[202:205], v[90:93]
	v_mfma_f32_16x16x32_bf16 v[78:81], v[152:155], v[210:213], v[78:81]
	v_mfma_f32_16x16x32_bf16 v[74:77], v[160:163], v[210:213], v[74:77]
	v_mfma_f32_16x16x32_bf16 v[126:129], v[156:159], v[190:193], v[126:129]
	v_mfma_f32_16x16x32_bf16 v[122:125], v[164:167], v[190:193], v[122:125]
	v_mfma_f32_16x16x32_bf16 v[110:113], v[156:159], v[198:201], v[110:113]
	v_mfma_f32_16x16x32_bf16 v[106:109], v[164:167], v[198:201], v[106:109]
	v_mfma_f32_16x16x32_bf16 v[94:97], v[156:159], v[206:209], v[94:97]
	v_mfma_f32_16x16x32_bf16 v[90:93], v[164:167], v[206:209], v[90:93]
	v_mfma_f32_16x16x32_bf16 v[78:81], v[156:159], v[214:217], v[78:81]
	v_mfma_f32_16x16x32_bf16 v[74:77], v[164:167], v[214:217], v[74:77]
	v_mfma_f32_16x16x32_bf16 v[118:121], v[168:171], v[186:189], v[118:121]
	v_mfma_f32_16x16x32_bf16 v[114:117], v[178:181], v[186:189], v[114:117]
	v_mfma_f32_16x16x32_bf16 v[102:105], v[168:171], v[194:197], v[102:105]
	v_mfma_f32_16x16x32_bf16 v[98:101], v[178:181], v[194:197], v[98:101]
	v_mfma_f32_16x16x32_bf16 v[86:89], v[168:171], v[202:205], v[86:89]
	v_mfma_f32_16x16x32_bf16 v[82:85], v[178:181], v[202:205], v[82:85]
	v_mfma_f32_16x16x32_bf16 v[70:73], v[168:171], v[210:213], v[70:73]
	v_mfma_f32_16x16x32_bf16 v[66:69], v[178:181], v[210:213], v[66:69]
	v_mfma_f32_16x16x32_bf16 v[118:121], v[172:175], v[190:193], v[118:121]
	v_mfma_f32_16x16x32_bf16 v[114:117], v[182:185], v[190:193], v[114:117]
	v_mfma_f32_16x16x32_bf16 v[102:105], v[172:175], v[198:201], v[102:105]
	v_mfma_f32_16x16x32_bf16 v[98:101], v[182:185], v[198:201], v[98:101]
	v_mfma_f32_16x16x32_bf16 v[86:89], v[172:175], v[206:209], v[86:89]
	v_mfma_f32_16x16x32_bf16 v[82:85], v[182:185], v[206:209], v[82:85]
	v_mfma_f32_16x16x32_bf16 v[70:73], v[172:175], v[214:217], v[70:73]
	v_mfma_f32_16x16x32_bf16 v[66:69], v[182:185], v[214:217], v[66:69]
	s_barrier
	s_setprio 0
	s_add_i32 s56, s43, s34
	v_lshl_add_u64 v[146:147], s[30:31], 0, v[132:133]
	s_mov_b32 m0, s56
	ds_read_b128 v[186:189], v150 offset:16384
	ds_read_b128 v[190:193], v150 offset:17408
	ds_read_b128 v[194:197], v150 offset:18432
	ds_read_b128 v[198:201], v150 offset:19456
	ds_read_b128 v[202:205], v150 offset:20480
	ds_read_b128 v[206:209], v150 offset:21504
	ds_read_b128 v[210:213], v150 offset:22528
	ds_read_b128 v[214:217], v150 offset:23552
	global_load_lds_dwordx4 v[146:147], off
	s_add_i32 m0, s56, 0x2000
	s_add_u32 s56, s30, 0x40000
	v_lshl_add_u64 v[218:219], s[30:31], 0, v[136:137]
	s_addc_u32 s57, s31, 0
	s_add_i32 s58, s44, s34
	global_load_lds_dwordx4 v[218:219], off
	v_lshl_add_u64 v[220:221], s[56:57], 0, v[132:133]
	s_mov_b32 m0, s58
	v_lshl_add_u64 v[222:223], s[2:3], 0, v[134:135]
	global_load_lds_dwordx4 v[220:221], off
	v_lshl_add_u64 v[220:221], s[56:57], 0, v[136:137]
	s_add_i32 m0, s58, 0x2000
	s_nop 0
	global_load_lds_dwordx4 v[220:221], off
	v_lshl_add_u64 v[220:221], s[2:3], 0, v[130:131]
	s_mov_b32 m0, s25
	s_nop 0
	global_load_lds_dwordx4 v[220:221], off
	s_mov_b32 m0, s27
	s_nop 0
	global_load_lds_dwordx4 v[222:223], off
	s_waitcnt vmcnt(8)
	s_waitcnt lgkmcnt(0)
	s_setprio 1
	s_barrier
	v_mfma_f32_16x16x32_bf16 v[62:65], v[152:155], v[186:189], v[62:65]
	v_mfma_f32_16x16x32_bf16 v[58:61], v[160:163], v[186:189], v[58:61]
	v_mfma_f32_16x16x32_bf16 v[46:49], v[152:155], v[194:197], v[46:49]
	v_mfma_f32_16x16x32_bf16 v[42:45], v[160:163], v[194:197], v[42:45]
	v_mfma_f32_16x16x32_bf16 v[30:33], v[152:155], v[202:205], v[30:33]
	v_mfma_f32_16x16x32_bf16 v[26:29], v[160:163], v[202:205], v[26:29]
	v_mfma_f32_16x16x32_bf16 v[14:17], v[152:155], v[210:213], v[14:17]
	v_mfma_f32_16x16x32_bf16 v[10:13], v[160:163], v[210:213], v[10:13]
	v_mfma_f32_16x16x32_bf16 v[62:65], v[156:159], v[190:193], v[62:65]
	v_mfma_f32_16x16x32_bf16 v[58:61], v[164:167], v[190:193], v[58:61]
	v_mfma_f32_16x16x32_bf16 v[46:49], v[156:159], v[198:201], v[46:49]
	v_mfma_f32_16x16x32_bf16 v[42:45], v[164:167], v[198:201], v[42:45]
	v_mfma_f32_16x16x32_bf16 v[30:33], v[156:159], v[206:209], v[30:33]
	v_mfma_f32_16x16x32_bf16 v[26:29], v[164:167], v[206:209], v[26:29]
	v_mfma_f32_16x16x32_bf16 v[14:17], v[156:159], v[214:217], v[14:17]
	v_mfma_f32_16x16x32_bf16 v[10:13], v[164:167], v[214:217], v[10:13]
	v_mfma_f32_16x16x32_bf16 v[54:57], v[168:171], v[186:189], v[54:57]
	v_mfma_f32_16x16x32_bf16 v[50:53], v[178:181], v[186:189], v[50:53]
	v_mfma_f32_16x16x32_bf16 v[38:41], v[168:171], v[194:197], v[38:41]
	v_mfma_f32_16x16x32_bf16 v[34:37], v[178:181], v[194:197], v[34:37]
	v_mfma_f32_16x16x32_bf16 v[22:25], v[168:171], v[202:205], v[22:25]
	v_mfma_f32_16x16x32_bf16 v[18:21], v[178:181], v[202:205], v[18:21]
	v_mfma_f32_16x16x32_bf16 v[6:9], v[168:171], v[210:213], v[6:9]
	v_mfma_f32_16x16x32_bf16 v[2:5], v[178:181], v[210:213], v[2:5]
	v_mfma_f32_16x16x32_bf16 v[54:57], v[172:175], v[190:193], v[54:57]
	v_mfma_f32_16x16x32_bf16 v[50:53], v[182:185], v[190:193], v[50:53]
	v_mfma_f32_16x16x32_bf16 v[38:41], v[172:175], v[198:201], v[38:41]
	v_mfma_f32_16x16x32_bf16 v[34:37], v[182:185], v[198:201], v[34:37]
	v_mfma_f32_16x16x32_bf16 v[22:25], v[172:175], v[206:209], v[22:25]
	v_mfma_f32_16x16x32_bf16 v[18:21], v[182:185], v[206:209], v[18:21]
	v_mfma_f32_16x16x32_bf16 v[6:9], v[172:175], v[214:217], v[6:9]
	v_mfma_f32_16x16x32_bf16 v[2:5], v[182:185], v[214:217], v[2:5]
	s_barrier
	s_setprio 0
	s_add_i32 s56, 0, 0x18000
	v_add_u32_e32 v151, s56, v148
	s_add_i32 s57, 0, 0x1c000
	ds_read_b128 v[152:155], v151
	ds_read_b128 v[156:159], v151 offset:1024
	ds_read_b128 v[160:163], v151 offset:2048
	ds_read_b128 v[164:167], v151 offset:3072
	v_add_u32_e32 v151, s57, v148
	ds_read_b128 v[168:171], v151
	ds_read_b128 v[172:175], v151 offset:1024
	ds_read_b128 v[178:181], v151 offset:2048
	ds_read_b128 v[182:185], v151 offset:3072
	s_add_u32 s2, s2, 0x40000
	s_addc_u32 s3, s3, 0
	s_mov_b32 m0, s36
	v_lshl_add_u64 v[224:225], s[2:3], 0, v[130:131]
	ds_read_b128 v[186:189], v150 offset:32768
	ds_read_b128 v[190:193], v150 offset:33792
	ds_read_b128 v[194:197], v150 offset:34816
	ds_read_b128 v[198:201], v150 offset:35840
	ds_read_b128 v[202:205], v150 offset:36864
	ds_read_b128 v[206:209], v150 offset:37888
	ds_read_b128 v[210:213], v150 offset:38912
	ds_read_b128 v[214:217], v150 offset:39936
	global_load_lds_dwordx4 v[224:225], off
	v_lshl_add_u64 v[224:225], s[2:3], 0, v[134:135]
	s_mov_b32 m0, s37
	s_nop 0
	global_load_lds_dwordx4 v[224:225], off
	s_waitcnt vmcnt(8)
	s_waitcnt lgkmcnt(0)
	s_setprio 1
	s_barrier
	v_mfma_f32_16x16x32_bf16 v[126:129], v[152:155], v[186:189], v[126:129]
	v_mfma_f32_16x16x32_bf16 v[122:125], v[160:163], v[186:189], v[122:125]
	v_mfma_f32_16x16x32_bf16 v[110:113], v[152:155], v[194:197], v[110:113]
	v_mfma_f32_16x16x32_bf16 v[106:109], v[160:163], v[194:197], v[106:109]
	v_mfma_f32_16x16x32_bf16 v[94:97], v[152:155], v[202:205], v[94:97]
	v_mfma_f32_16x16x32_bf16 v[90:93], v[160:163], v[202:205], v[90:93]
	v_mfma_f32_16x16x32_bf16 v[78:81], v[152:155], v[210:213], v[78:81]
	v_mfma_f32_16x16x32_bf16 v[74:77], v[160:163], v[210:213], v[74:77]
	v_mfma_f32_16x16x32_bf16 v[126:129], v[156:159], v[190:193], v[126:129]
	v_mfma_f32_16x16x32_bf16 v[122:125], v[164:167], v[190:193], v[122:125]
	v_mfma_f32_16x16x32_bf16 v[110:113], v[156:159], v[198:201], v[110:113]
	v_mfma_f32_16x16x32_bf16 v[106:109], v[164:167], v[198:201], v[106:109]
	v_mfma_f32_16x16x32_bf16 v[94:97], v[156:159], v[206:209], v[94:97]
	v_mfma_f32_16x16x32_bf16 v[90:93], v[164:167], v[206:209], v[90:93]
	v_mfma_f32_16x16x32_bf16 v[78:81], v[156:159], v[214:217], v[78:81]
	v_mfma_f32_16x16x32_bf16 v[74:77], v[164:167], v[214:217], v[74:77]
	v_mfma_f32_16x16x32_bf16 v[118:121], v[168:171], v[186:189], v[118:121]
	v_mfma_f32_16x16x32_bf16 v[114:117], v[178:181], v[186:189], v[114:117]
	v_mfma_f32_16x16x32_bf16 v[102:105], v[168:171], v[194:197], v[102:105]
	v_mfma_f32_16x16x32_bf16 v[98:101], v[178:181], v[194:197], v[98:101]
	v_mfma_f32_16x16x32_bf16 v[86:89], v[168:171], v[202:205], v[86:89]
	v_mfma_f32_16x16x32_bf16 v[82:85], v[178:181], v[202:205], v[82:85]
	v_mfma_f32_16x16x32_bf16 v[70:73], v[168:171], v[210:213], v[70:73]
	v_mfma_f32_16x16x32_bf16 v[66:69], v[178:181], v[210:213], v[66:69]
	v_mfma_f32_16x16x32_bf16 v[118:121], v[172:175], v[190:193], v[118:121]
	v_mfma_f32_16x16x32_bf16 v[114:117], v[182:185], v[190:193], v[114:117]
	v_mfma_f32_16x16x32_bf16 v[102:105], v[172:175], v[198:201], v[102:105]
	v_mfma_f32_16x16x32_bf16 v[98:101], v[182:185], v[198:201], v[98:101]
	v_mfma_f32_16x16x32_bf16 v[86:89], v[172:175], v[206:209], v[86:89]
	v_mfma_f32_16x16x32_bf16 v[82:85], v[182:185], v[206:209], v[82:85]
	v_mfma_f32_16x16x32_bf16 v[70:73], v[172:175], v[214:217], v[70:73]
	v_mfma_f32_16x16x32_bf16 v[66:69], v[182:185], v[214:217], v[66:69]
	s_barrier
	s_setprio 0
	s_add_i32 s2, s56, s34
	v_lshl_add_u64 v[146:147], v[146:147], 0, s[6:7]
	s_mov_b32 m0, s2
	ds_read_b128 v[186:189], v150 offset:49152
	ds_read_b128 v[190:193], v150 offset:50176
	ds_read_b128 v[194:197], v150 offset:51200
	ds_read_b128 v[198:201], v150 offset:52224
	ds_read_b128 v[202:205], v150 offset:53248
	ds_read_b128 v[206:209], v150 offset:54272
	ds_read_b128 v[210:213], v150 offset:55296
	ds_read_b128 v[214:217], v150 offset:56320
	global_load_lds_dwordx4 v[146:147], off
	s_add_i32 m0, s2, 0x2000
	s_add_u32 s2, s30, 0x40080
	v_lshl_add_u64 v[146:147], v[218:219], 0, s[6:7]
	s_addc_u32 s3, s31, 0
	s_add_i32 s30, s57, s34
	global_load_lds_dwordx4 v[146:147], off
	v_lshl_add_u64 v[146:147], s[2:3], 0, v[132:133]
	s_mov_b32 m0, s30
	s_nop 0
	global_load_lds_dwordx4 v[146:147], off
	v_lshl_add_u64 v[146:147], s[2:3], 0, v[136:137]
	s_add_i32 m0, s30, 0x2000
	s_nop 0
	global_load_lds_dwordx4 v[146:147], off
	v_lshl_add_u64 v[146:147], v[220:221], 0, s[6:7]
	s_mov_b32 m0, s40
	s_nop 0
	global_load_lds_dwordx4 v[146:147], off
	v_lshl_add_u64 v[146:147], v[222:223], 0, s[6:7]
	s_mov_b32 m0, s41
	s_nop 0
	global_load_lds_dwordx4 v[146:147], off
	s_waitcnt vmcnt(8)
	s_waitcnt lgkmcnt(0)
	s_setprio 1
	s_barrier
	v_mfma_f32_16x16x32_bf16 v[62:65], v[152:155], v[186:189], v[62:65]
	v_mfma_f32_16x16x32_bf16 v[58:61], v[160:163], v[186:189], v[58:61]
	v_mfma_f32_16x16x32_bf16 v[46:49], v[152:155], v[194:197], v[46:49]
	v_mfma_f32_16x16x32_bf16 v[42:45], v[160:163], v[194:197], v[42:45]
	v_mfma_f32_16x16x32_bf16 v[30:33], v[152:155], v[202:205], v[30:33]
	v_mfma_f32_16x16x32_bf16 v[26:29], v[160:163], v[202:205], v[26:29]
	v_mfma_f32_16x16x32_bf16 v[14:17], v[152:155], v[210:213], v[14:17]
	v_mfma_f32_16x16x32_bf16 v[10:13], v[160:163], v[210:213], v[10:13]
	v_mfma_f32_16x16x32_bf16 v[62:65], v[156:159], v[190:193], v[62:65]
	v_mfma_f32_16x16x32_bf16 v[58:61], v[164:167], v[190:193], v[58:61]
	v_mfma_f32_16x16x32_bf16 v[46:49], v[156:159], v[198:201], v[46:49]
	v_mfma_f32_16x16x32_bf16 v[42:45], v[164:167], v[198:201], v[42:45]
	v_mfma_f32_16x16x32_bf16 v[30:33], v[156:159], v[206:209], v[30:33]
	v_mfma_f32_16x16x32_bf16 v[26:29], v[164:167], v[206:209], v[26:29]
	v_mfma_f32_16x16x32_bf16 v[14:17], v[156:159], v[214:217], v[14:17]
	v_mfma_f32_16x16x32_bf16 v[10:13], v[164:167], v[214:217], v[10:13]
	v_mfma_f32_16x16x32_bf16 v[54:57], v[168:171], v[186:189], v[54:57]
	v_mfma_f32_16x16x32_bf16 v[50:53], v[178:181], v[186:189], v[50:53]
	v_mfma_f32_16x16x32_bf16 v[38:41], v[168:171], v[194:197], v[38:41]
	v_mfma_f32_16x16x32_bf16 v[34:37], v[178:181], v[194:197], v[34:37]
	v_mfma_f32_16x16x32_bf16 v[22:25], v[168:171], v[202:205], v[22:25]
	v_mfma_f32_16x16x32_bf16 v[18:21], v[178:181], v[202:205], v[18:21]
	v_mfma_f32_16x16x32_bf16 v[6:9], v[168:171], v[210:213], v[6:9]
	v_mfma_f32_16x16x32_bf16 v[2:5], v[178:181], v[210:213], v[2:5]
	v_mfma_f32_16x16x32_bf16 v[54:57], v[172:175], v[190:193], v[54:57]
	v_mfma_f32_16x16x32_bf16 v[50:53], v[182:185], v[190:193], v[50:53]
	v_mfma_f32_16x16x32_bf16 v[38:41], v[172:175], v[198:201], v[38:41]
	v_mfma_f32_16x16x32_bf16 v[34:37], v[182:185], v[198:201], v[34:37]
	v_mfma_f32_16x16x32_bf16 v[22:25], v[172:175], v[206:209], v[22:25]
	v_mfma_f32_16x16x32_bf16 v[18:21], v[182:185], v[206:209], v[18:21]
	v_mfma_f32_16x16x32_bf16 v[6:9], v[172:175], v[214:217], v[6:9]
	v_mfma_f32_16x16x32_bf16 v[2:5], v[182:185], v[214:217], v[2:5]
	s_barrier
	s_setprio 0
	s_add_i32 s55, s55, 2
	s_add_u32 s28, s28, 0x100
	s_addc_u32 s29, s29, 0
	s_add_u32 s53, s53, 0x100
	s_addc_u32 s54, s54, 0
	s_cmp_gt_u32 s55, 13
	s_cbranch_scc0 .LBB0_1400

.Lpk1444_peel:
	ds_read_b128 v[152:155], v148
	ds_read_b128 v[156:159], v148 offset:1024
	ds_read_b128 v[160:163], v148 offset:2048
	ds_read_b128 v[164:167], v148 offset:3072
	ds_read_b128 v[168:171], v149
	ds_read_b128 v[172:175], v149 offset:1024
	ds_read_b128 v[178:181], v149 offset:2048
	ds_read_b128 v[182:185], v149 offset:3072
	s_add_u32 s2, s26, 0x4000
	s_addc_u32 s3, s27, 0
	s_cmp_eq_u32 s62, 40
	s_cselect_b32 s2, s57, s2
	s_cselect_b32 s3, s56, s3
	s_cselect_b32 s31, s58, s61
	s_cselect_b32 s30, s59, s60
	s_add_u32 s28, s2, 0x8000
	s_addc_u32 s29, s3, 0
	v_lshl_add_u64 v[144:145], s[26:27], 0, v[138:139]
	s_add_i32 m0, s39, 0xc000
	ds_read_b128 v[186:189], v150
	ds_read_b128 v[190:193], v150 offset:1024
	ds_read_b128 v[194:197], v150 offset:2048
	ds_read_b128 v[198:201], v150 offset:3072
	ds_read_b128 v[202:205], v150 offset:4096
	ds_read_b128 v[206:209], v150 offset:5120
	ds_read_b128 v[210:213], v150 offset:6144
	ds_read_b128 v[214:217], v150 offset:7168
	global_load_lds_dwordx4 v[144:145], off
	v_lshl_add_u64 v[144:145], s[26:27], 0, v[140:141]
	s_add_i32 m0, s39, 0xe000
	s_nop 0
	global_load_lds_dwordx4 v[144:145], off
	s_waitcnt vmcnt(8)
	s_waitcnt lgkmcnt(0)
	s_setprio 1
	s_barrier
	v_mfma_f32_16x16x32_bf16 v[126:129], v[152:155], v[186:189], 0
	v_mfma_f32_16x16x32_bf16 v[122:125], v[160:163], v[186:189], 0
	v_mfma_f32_16x16x32_bf16 v[114:117], v[152:155], v[194:197], 0
	v_mfma_f32_16x16x32_bf16 v[106:109], v[160:163], v[194:197], 0
	v_mfma_f32_16x16x32_bf16 v[98:101], v[152:155], v[202:205], 0
	v_mfma_f32_16x16x32_bf16 v[90:93], v[160:163], v[202:205], 0
	v_mfma_f32_16x16x32_bf16 v[82:85], v[152:155], v[210:213], 0
	v_mfma_f32_16x16x32_bf16 v[74:77], v[160:163], v[210:213], 0
	v_mfma_f32_16x16x32_bf16 v[126:129], v[156:159], v[190:193], v[126:129]
	v_mfma_f32_16x16x32_bf16 v[122:125], v[164:167], v[190:193], v[122:125]
	v_mfma_f32_16x16x32_bf16 v[114:117], v[156:159], v[198:201], v[114:117]
	v_mfma_f32_16x16x32_bf16 v[106:109], v[164:167], v[198:201], v[106:109]
	v_mfma_f32_16x16x32_bf16 v[98:101], v[156:159], v[206:209], v[98:101]
	v_mfma_f32_16x16x32_bf16 v[90:93], v[164:167], v[206:209], v[90:93]
	v_mfma_f32_16x16x32_bf16 v[82:85], v[156:159], v[214:217], v[82:85]
	v_mfma_f32_16x16x32_bf16 v[74:77], v[164:167], v[214:217], v[74:77]
	v_mfma_f32_16x16x32_bf16 v[118:121], v[168:171], v[186:189], 0
	v_mfma_f32_16x16x32_bf16 v[110:113], v[178:181], v[186:189], 0
	v_mfma_f32_16x16x32_bf16 v[102:105], v[168:171], v[194:197], 0
	v_mfma_f32_16x16x32_bf16 v[94:97], v[178:181], v[194:197], 0
	v_mfma_f32_16x16x32_bf16 v[86:89], v[168:171], v[202:205], 0
	v_mfma_f32_16x16x32_bf16 v[78:81], v[178:181], v[202:205], 0
	v_mfma_f32_16x16x32_bf16 v[70:73], v[168:171], v[210:213], 0
	v_mfma_f32_16x16x32_bf16 v[66:69], v[178:181], v[210:213], 0
	v_mfma_f32_16x16x32_bf16 v[118:121], v[172:175], v[190:193], v[118:121]
	v_mfma_f32_16x16x32_bf16 v[110:113], v[182:185], v[190:193], v[110:113]
	v_mfma_f32_16x16x32_bf16 v[102:105], v[172:175], v[198:201], v[102:105]
	v_mfma_f32_16x16x32_bf16 v[94:97], v[182:185], v[198:201], v[94:97]
	v_mfma_f32_16x16x32_bf16 v[86:89], v[172:175], v[206:209], v[86:89]
	v_mfma_f32_16x16x32_bf16 v[78:81], v[182:185], v[206:209], v[78:81]
	v_mfma_f32_16x16x32_bf16 v[70:73], v[172:175], v[214:217], v[70:73]
	v_mfma_f32_16x16x32_bf16 v[66:69], v[182:185], v[214:217], v[66:69]
	s_barrier
	s_setprio 0
	s_add_i32 s63, s46, s38
	v_lshl_add_u64 v[144:145], s[30:31], 0, v[132:133]
	s_mov_b32 m0, s63
	ds_read_b128 v[186:189], v150 offset:16384
	ds_read_b128 v[190:193], v150 offset:17408
	ds_read_b128 v[194:197], v150 offset:18432
	ds_read_b128 v[198:201], v150 offset:19456
	ds_read_b128 v[202:205], v150 offset:20480
	ds_read_b128 v[206:209], v150 offset:21504
	ds_read_b128 v[210:213], v150 offset:22528
	ds_read_b128 v[214:217], v150 offset:23552
	global_load_lds_dwordx4 v[144:145], off
	s_add_i32 m0, s63, 0x2000
	s_add_u32 s64, s30, 0x4000
	v_lshl_add_u64 v[144:145], s[30:31], 0, v[136:137]
	s_addc_u32 s65, s31, 0
	s_add_i32 s63, s47, s38
	global_load_lds_dwordx4 v[144:145], off
	v_lshl_add_u64 v[144:145], s[64:65], 0, v[132:133]
	s_mov_b32 m0, s63
	s_nop 0
	global_load_lds_dwordx4 v[144:145], off
	v_lshl_add_u64 v[144:145], s[64:65], 0, v[136:137]
	s_add_i32 m0, s63, 0x2000
	s_nop 0
	global_load_lds_dwordx4 v[144:145], off
	v_lshl_add_u64 v[144:145], s[2:3], 0, v[130:131]
	s_mov_b32 m0, s39
	s_nop 0
	global_load_lds_dwordx4 v[144:145], off
	v_lshl_add_u64 v[144:145], s[2:3], 0, v[134:135]
	s_mov_b32 m0, s40
	s_nop 0
	global_load_lds_dwordx4 v[144:145], off
	s_waitcnt vmcnt(8)
	s_waitcnt lgkmcnt(0)
	s_setprio 1
	s_barrier
	v_mfma_f32_16x16x32_bf16 v[62:65], v[152:155], v[186:189], 0
	v_mfma_f32_16x16x32_bf16 v[58:61], v[160:163], v[186:189], 0
	v_mfma_f32_16x16x32_bf16 v[50:53], v[152:155], v[194:197], 0
	v_mfma_f32_16x16x32_bf16 v[42:45], v[160:163], v[194:197], 0
	v_mfma_f32_16x16x32_bf16 v[34:37], v[152:155], v[202:205], 0
	v_mfma_f32_16x16x32_bf16 v[26:29], v[160:163], v[202:205], 0
	v_mfma_f32_16x16x32_bf16 v[18:21], v[152:155], v[210:213], 0
	v_mfma_f32_16x16x32_bf16 v[10:13], v[160:163], v[210:213], 0
	v_mfma_f32_16x16x32_bf16 v[62:65], v[156:159], v[190:193], v[62:65]
	v_mfma_f32_16x16x32_bf16 v[58:61], v[164:167], v[190:193], v[58:61]
	v_mfma_f32_16x16x32_bf16 v[50:53], v[156:159], v[198:201], v[50:53]
	v_mfma_f32_16x16x32_bf16 v[42:45], v[164:167], v[198:201], v[42:45]
	v_mfma_f32_16x16x32_bf16 v[34:37], v[156:159], v[206:209], v[34:37]
	v_mfma_f32_16x16x32_bf16 v[26:29], v[164:167], v[206:209], v[26:29]
	v_mfma_f32_16x16x32_bf16 v[18:21], v[156:159], v[214:217], v[18:21]
	v_mfma_f32_16x16x32_bf16 v[10:13], v[164:167], v[214:217], v[10:13]
	v_mfma_f32_16x16x32_bf16 v[54:57], v[168:171], v[186:189], 0
	v_mfma_f32_16x16x32_bf16 v[46:49], v[178:181], v[186:189], 0
	v_mfma_f32_16x16x32_bf16 v[38:41], v[168:171], v[194:197], 0
	v_mfma_f32_16x16x32_bf16 v[30:33], v[178:181], v[194:197], 0
	v_mfma_f32_16x16x32_bf16 v[22:25], v[168:171], v[202:205], 0
	v_mfma_f32_16x16x32_bf16 v[14:17], v[178:181], v[202:205], 0
	v_mfma_f32_16x16x32_bf16 v[6:9], v[168:171], v[210:213], 0
	v_mfma_f32_16x16x32_bf16 v[2:5], v[178:181], v[210:213], 0
	v_mfma_f32_16x16x32_bf16 v[54:57], v[172:175], v[190:193], v[54:57]
	v_mfma_f32_16x16x32_bf16 v[46:49], v[182:185], v[190:193], v[46:49]
	v_mfma_f32_16x16x32_bf16 v[38:41], v[172:175], v[198:201], v[38:41]
	v_mfma_f32_16x16x32_bf16 v[30:33], v[182:185], v[198:201], v[30:33]
	v_mfma_f32_16x16x32_bf16 v[22:25], v[172:175], v[206:209], v[22:25]
	v_mfma_f32_16x16x32_bf16 v[14:17], v[182:185], v[206:209], v[14:17]
	v_mfma_f32_16x16x32_bf16 v[6:9], v[172:175], v[214:217], v[6:9]
	v_mfma_f32_16x16x32_bf16 v[2:5], v[182:185], v[214:217], v[2:5]
	s_barrier
	s_setprio 0
	s_add_i32 s63, 0, 0x18000
	v_add_u32_e32 v144, s63, v146
	s_add_i32 s64, 0, 0x1c000
	ds_read_b128 v[152:155], v144
	ds_read_b128 v[156:159], v144 offset:1024
	ds_read_b128 v[160:163], v144 offset:2048
	ds_read_b128 v[164:167], v144 offset:3072
	v_add_u32_e32 v144, s64, v146
	ds_read_b128 v[168:171], v144
	ds_read_b128 v[172:175], v144 offset:1024
	ds_read_b128 v[178:181], v144 offset:2048
	ds_read_b128 v[182:185], v144 offset:3072
	s_add_u32 s2, s2, 0x4000
	s_addc_u32 s3, s3, 0
	s_mov_b32 m0, s41
	v_lshl_add_u64 v[144:145], s[2:3], 0, v[130:131]
	ds_read_b128 v[186:189], v150 offset:32768
	ds_read_b128 v[190:193], v150 offset:33792
	ds_read_b128 v[194:197], v150 offset:34816
	ds_read_b128 v[198:201], v150 offset:35840
	ds_read_b128 v[202:205], v150 offset:36864
	ds_read_b128 v[206:209], v150 offset:37888
	ds_read_b128 v[210:213], v150 offset:38912
	ds_read_b128 v[214:217], v150 offset:39936
	global_load_lds_dwordx4 v[144:145], off
	v_lshl_add_u64 v[144:145], s[2:3], 0, v[134:135]
	s_mov_b32 m0, s42
	s_nop 0
	global_load_lds_dwordx4 v[144:145], off
	s_waitcnt vmcnt(8)
	s_waitcnt lgkmcnt(0)
	s_setprio 1
	s_barrier
	v_mfma_f32_16x16x32_bf16 v[126:129], v[152:155], v[186:189], v[126:129]
	v_mfma_f32_16x16x32_bf16 v[122:125], v[160:163], v[186:189], v[122:125]
	v_mfma_f32_16x16x32_bf16 v[114:117], v[152:155], v[194:197], v[114:117]
	v_mfma_f32_16x16x32_bf16 v[106:109], v[160:163], v[194:197], v[106:109]
	v_mfma_f32_16x16x32_bf16 v[98:101], v[152:155], v[202:205], v[98:101]
	v_mfma_f32_16x16x32_bf16 v[90:93], v[160:163], v[202:205], v[90:93]
	v_mfma_f32_16x16x32_bf16 v[82:85], v[152:155], v[210:213], v[82:85]
	v_mfma_f32_16x16x32_bf16 v[74:77], v[160:163], v[210:213], v[74:77]
	v_mfma_f32_16x16x32_bf16 v[126:129], v[156:159], v[190:193], v[126:129]
	v_mfma_f32_16x16x32_bf16 v[122:125], v[164:167], v[190:193], v[122:125]
	v_mfma_f32_16x16x32_bf16 v[114:117], v[156:159], v[198:201], v[114:117]
	v_mfma_f32_16x16x32_bf16 v[106:109], v[164:167], v[198:201], v[106:109]
	v_mfma_f32_16x16x32_bf16 v[98:101], v[156:159], v[206:209], v[98:101]
	v_mfma_f32_16x16x32_bf16 v[90:93], v[164:167], v[206:209], v[90:93]
	v_mfma_f32_16x16x32_bf16 v[82:85], v[156:159], v[214:217], v[82:85]
	v_mfma_f32_16x16x32_bf16 v[74:77], v[164:167], v[214:217], v[74:77]
	v_mfma_f32_16x16x32_bf16 v[118:121], v[168:171], v[186:189], v[118:121]
	v_mfma_f32_16x16x32_bf16 v[110:113], v[178:181], v[186:189], v[110:113]
	v_mfma_f32_16x16x32_bf16 v[102:105], v[168:171], v[194:197], v[102:105]
	v_mfma_f32_16x16x32_bf16 v[94:97], v[178:181], v[194:197], v[94:97]
	v_mfma_f32_16x16x32_bf16 v[86:89], v[168:171], v[202:205], v[86:89]
	v_mfma_f32_16x16x32_bf16 v[78:81], v[178:181], v[202:205], v[78:81]
	v_mfma_f32_16x16x32_bf16 v[70:73], v[168:171], v[210:213], v[70:73]
	v_mfma_f32_16x16x32_bf16 v[66:69], v[178:181], v[210:213], v[66:69]
	v_mfma_f32_16x16x32_bf16 v[118:121], v[172:175], v[190:193], v[118:121]
	v_mfma_f32_16x16x32_bf16 v[110:113], v[182:185], v[190:193], v[110:113]
	v_mfma_f32_16x16x32_bf16 v[102:105], v[172:175], v[198:201], v[102:105]
	v_mfma_f32_16x16x32_bf16 v[94:97], v[182:185], v[198:201], v[94:97]
	v_mfma_f32_16x16x32_bf16 v[86:89], v[172:175], v[206:209], v[86:89]
	v_mfma_f32_16x16x32_bf16 v[78:81], v[182:185], v[206:209], v[78:81]
	v_mfma_f32_16x16x32_bf16 v[70:73], v[172:175], v[214:217], v[70:73]
	v_mfma_f32_16x16x32_bf16 v[66:69], v[182:185], v[214:217], v[66:69]
	s_barrier
	s_setprio 0
	s_add_u32 s2, s30, 0x8000
	s_addc_u32 s3, s31, 0
	s_add_i32 s63, s63, s38
	v_lshl_add_u64 v[144:145], s[2:3], 0, v[132:133]
	s_mov_b32 m0, s63
	ds_read_b128 v[186:189], v150 offset:49152
	ds_read_b128 v[190:193], v150 offset:50176
	ds_read_b128 v[194:197], v150 offset:51200
	ds_read_b128 v[198:201], v150 offset:52224
	ds_read_b128 v[202:205], v150 offset:53248
	ds_read_b128 v[206:209], v150 offset:54272
	ds_read_b128 v[210:213], v150 offset:55296
	ds_read_b128 v[214:217], v150 offset:56320
	global_load_lds_dwordx4 v[144:145], off
	s_add_i32 m0, s63, 0x2000
	v_lshl_add_u64 v[144:145], s[2:3], 0, v[136:137]
	s_add_u32 s2, s30, 0xc000
	s_addc_u32 s3, s31, 0
	s_add_i32 s30, s64, s38
	global_load_lds_dwordx4 v[144:145], off
	v_lshl_add_u64 v[144:145], s[2:3], 0, v[132:133]
	s_mov_b32 m0, s30
	s_nop 0
	global_load_lds_dwordx4 v[144:145], off
	v_lshl_add_u64 v[144:145], s[2:3], 0, v[136:137]
	s_add_i32 m0, s30, 0x2000
	s_nop 0
	global_load_lds_dwordx4 v[144:145], off
	v_lshl_add_u64 v[144:145], s[28:29], 0, v[130:131]
	s_mov_b32 m0, s44
	s_nop 0
	global_load_lds_dwordx4 v[144:145], off
	v_lshl_add_u64 v[144:145], s[28:29], 0, v[134:135]
	s_mov_b32 m0, s45
	s_nop 0
	global_load_lds_dwordx4 v[144:145], off
	s_waitcnt vmcnt(8)
	s_waitcnt lgkmcnt(0)
	s_setprio 1
	s_barrier
	v_mfma_f32_16x16x32_bf16 v[62:65], v[152:155], v[186:189], v[62:65]
	v_mfma_f32_16x16x32_bf16 v[58:61], v[160:163], v[186:189], v[58:61]
	v_mfma_f32_16x16x32_bf16 v[50:53], v[152:155], v[194:197], v[50:53]
	v_mfma_f32_16x16x32_bf16 v[42:45], v[160:163], v[194:197], v[42:45]
	v_mfma_f32_16x16x32_bf16 v[34:37], v[152:155], v[202:205], v[34:37]
	v_mfma_f32_16x16x32_bf16 v[26:29], v[160:163], v[202:205], v[26:29]
	v_mfma_f32_16x16x32_bf16 v[18:21], v[152:155], v[210:213], v[18:21]
	v_mfma_f32_16x16x32_bf16 v[10:13], v[160:163], v[210:213], v[10:13]
	v_mfma_f32_16x16x32_bf16 v[62:65], v[156:159], v[190:193], v[62:65]
	v_mfma_f32_16x16x32_bf16 v[58:61], v[164:167], v[190:193], v[58:61]
	v_mfma_f32_16x16x32_bf16 v[50:53], v[156:159], v[198:201], v[50:53]
	v_mfma_f32_16x16x32_bf16 v[42:45], v[164:167], v[198:201], v[42:45]
	v_mfma_f32_16x16x32_bf16 v[34:37], v[156:159], v[206:209], v[34:37]
	v_mfma_f32_16x16x32_bf16 v[26:29], v[164:167], v[206:209], v[26:29]
	v_mfma_f32_16x16x32_bf16 v[18:21], v[156:159], v[214:217], v[18:21]
	v_mfma_f32_16x16x32_bf16 v[10:13], v[164:167], v[214:217], v[10:13]
	v_mfma_f32_16x16x32_bf16 v[54:57], v[168:171], v[186:189], v[54:57]
	v_mfma_f32_16x16x32_bf16 v[46:49], v[178:181], v[186:189], v[46:49]
	v_mfma_f32_16x16x32_bf16 v[38:41], v[168:171], v[194:197], v[38:41]
	v_mfma_f32_16x16x32_bf16 v[30:33], v[178:181], v[194:197], v[30:33]
	v_mfma_f32_16x16x32_bf16 v[22:25], v[168:171], v[202:205], v[22:25]
	v_mfma_f32_16x16x32_bf16 v[14:17], v[178:181], v[202:205], v[14:17]
	v_mfma_f32_16x16x32_bf16 v[6:9], v[168:171], v[210:213], v[6:9]
	v_mfma_f32_16x16x32_bf16 v[2:5], v[178:181], v[210:213], v[2:5]
	v_mfma_f32_16x16x32_bf16 v[54:57], v[172:175], v[190:193], v[54:57]
	v_mfma_f32_16x16x32_bf16 v[46:49], v[182:185], v[190:193], v[46:49]
	v_mfma_f32_16x16x32_bf16 v[38:41], v[172:175], v[198:201], v[38:41]
	v_mfma_f32_16x16x32_bf16 v[30:33], v[182:185], v[198:201], v[30:33]
	v_mfma_f32_16x16x32_bf16 v[22:25], v[172:175], v[206:209], v[22:25]
	v_mfma_f32_16x16x32_bf16 v[14:17], v[182:185], v[206:209], v[14:17]
	v_mfma_f32_16x16x32_bf16 v[6:9], v[172:175], v[214:217], v[6:9]
	v_mfma_f32_16x16x32_bf16 v[2:5], v[182:185], v[214:217], v[2:5]
	s_barrier
	s_setprio 0
	s_add_i32 s62, s62, 2
	s_add_u32 s26, s26, 0x10000
	s_addc_u32 s27, s27, 0
	s_add_u32 s60, s60, 0x10000
	s_addc_u32 s61, s61, 0
	s_cmp_gt_u32 s62, 41
	s_cbranch_scc0 .LBB0_1444
	s_branch .Lpk1444_exit
.LBB0_1444:
	ds_read_b128 v[152:155], v148
	ds_read_b128 v[156:159], v148 offset:1024
	ds_read_b128 v[160:163], v148 offset:2048
	ds_read_b128 v[164:167], v148 offset:3072
	ds_read_b128 v[168:171], v149
	ds_read_b128 v[172:175], v149 offset:1024
	ds_read_b128 v[178:181], v149 offset:2048
	ds_read_b128 v[182:185], v149 offset:3072
	s_add_u32 s2, s26, 0x4000
	s_addc_u32 s3, s27, 0
	s_cmp_eq_u32 s62, 40
	s_cselect_b32 s2, s57, s2
	s_cselect_b32 s3, s56, s3
	s_cselect_b32 s31, s58, s61
	s_cselect_b32 s30, s59, s60
	s_add_u32 s28, s2, 0x8000
	s_addc_u32 s29, s3, 0
	v_lshl_add_u64 v[144:145], s[26:27], 0, v[138:139]
	s_add_i32 m0, s39, 0xc000
	ds_read_b128 v[186:189], v150
	ds_read_b128 v[190:193], v150 offset:1024
	ds_read_b128 v[194:197], v150 offset:2048
	ds_read_b128 v[198:201], v150 offset:3072
	ds_read_b128 v[202:205], v150 offset:4096
	ds_read_b128 v[206:209], v150 offset:5120
	ds_read_b128 v[210:213], v150 offset:6144
	ds_read_b128 v[214:217], v150 offset:7168
	global_load_lds_dwordx4 v[144:145], off
	v_lshl_add_u64 v[144:145], s[26:27], 0, v[140:141]
	s_add_i32 m0, s39, 0xe000
	s_nop 0
	global_load_lds_dwordx4 v[144:145], off
	s_waitcnt vmcnt(8)
	s_waitcnt lgkmcnt(0)
	s_setprio 1
	s_barrier
	v_mfma_f32_16x16x32_bf16 v[126:129], v[152:155], v[186:189], v[126:129]
	v_mfma_f32_16x16x32_bf16 v[122:125], v[160:163], v[186:189], v[122:125]
	v_mfma_f32_16x16x32_bf16 v[114:117], v[152:155], v[194:197], v[114:117]
	v_mfma_f32_16x16x32_bf16 v[106:109], v[160:163], v[194:197], v[106:109]
	v_mfma_f32_16x16x32_bf16 v[98:101], v[152:155], v[202:205], v[98:101]
	v_mfma_f32_16x16x32_bf16 v[90:93], v[160:163], v[202:205], v[90:93]
	v_mfma_f32_16x16x32_bf16 v[82:85], v[152:155], v[210:213], v[82:85]
	v_mfma_f32_16x16x32_bf16 v[74:77], v[160:163], v[210:213], v[74:77]
	v_mfma_f32_16x16x32_bf16 v[126:129], v[156:159], v[190:193], v[126:129]
	v_mfma_f32_16x16x32_bf16 v[122:125], v[164:167], v[190:193], v[122:125]
	v_mfma_f32_16x16x32_bf16 v[114:117], v[156:159], v[198:201], v[114:117]
	v_mfma_f32_16x16x32_bf16 v[106:109], v[164:167], v[198:201], v[106:109]
	v_mfma_f32_16x16x32_bf16 v[98:101], v[156:159], v[206:209], v[98:101]
	v_mfma_f32_16x16x32_bf16 v[90:93], v[164:167], v[206:209], v[90:93]
	v_mfma_f32_16x16x32_bf16 v[82:85], v[156:159], v[214:217], v[82:85]
	v_mfma_f32_16x16x32_bf16 v[74:77], v[164:167], v[214:217], v[74:77]
	v_mfma_f32_16x16x32_bf16 v[118:121], v[168:171], v[186:189], v[118:121]
	v_mfma_f32_16x16x32_bf16 v[110:113], v[178:181], v[186:189], v[110:113]
	v_mfma_f32_16x16x32_bf16 v[102:105], v[168:171], v[194:197], v[102:105]
	v_mfma_f32_16x16x32_bf16 v[94:97], v[178:181], v[194:197], v[94:97]
	v_mfma_f32_16x16x32_bf16 v[86:89], v[168:171], v[202:205], v[86:89]
	v_mfma_f32_16x16x32_bf16 v[78:81], v[178:181], v[202:205], v[78:81]
	v_mfma_f32_16x16x32_bf16 v[70:73], v[168:171], v[210:213], v[70:73]
	v_mfma_f32_16x16x32_bf16 v[66:69], v[178:181], v[210:213], v[66:69]
	v_mfma_f32_16x16x32_bf16 v[118:121], v[172:175], v[190:193], v[118:121]
	v_mfma_f32_16x16x32_bf16 v[110:113], v[182:185], v[190:193], v[110:113]
	v_mfma_f32_16x16x32_bf16 v[102:105], v[172:175], v[198:201], v[102:105]
	v_mfma_f32_16x16x32_bf16 v[94:97], v[182:185], v[198:201], v[94:97]
	v_mfma_f32_16x16x32_bf16 v[86:89], v[172:175], v[206:209], v[86:89]
	v_mfma_f32_16x16x32_bf16 v[78:81], v[182:185], v[206:209], v[78:81]
	v_mfma_f32_16x16x32_bf16 v[70:73], v[172:175], v[214:217], v[70:73]
	v_mfma_f32_16x16x32_bf16 v[66:69], v[182:185], v[214:217], v[66:69]
	s_barrier
	s_setprio 0
	s_add_i32 s63, s46, s38
	v_lshl_add_u64 v[144:145], s[30:31], 0, v[132:133]
	s_mov_b32 m0, s63
	ds_read_b128 v[186:189], v150 offset:16384
	ds_read_b128 v[190:193], v150 offset:17408
	ds_read_b128 v[194:197], v150 offset:18432
	ds_read_b128 v[198:201], v150 offset:19456
	ds_read_b128 v[202:205], v150 offset:20480
	ds_read_b128 v[206:209], v150 offset:21504
	ds_read_b128 v[210:213], v150 offset:22528
	ds_read_b128 v[214:217], v150 offset:23552
	global_load_lds_dwordx4 v[144:145], off
	s_add_i32 m0, s63, 0x2000
	s_add_u32 s64, s30, 0x4000
	v_lshl_add_u64 v[144:145], s[30:31], 0, v[136:137]
	s_addc_u32 s65, s31, 0
	s_add_i32 s63, s47, s38
	global_load_lds_dwordx4 v[144:145], off
	v_lshl_add_u64 v[144:145], s[64:65], 0, v[132:133]
	s_mov_b32 m0, s63
	s_nop 0
	global_load_lds_dwordx4 v[144:145], off
	v_lshl_add_u64 v[144:145], s[64:65], 0, v[136:137]
	s_add_i32 m0, s63, 0x2000
	s_nop 0
	global_load_lds_dwordx4 v[144:145], off
	v_lshl_add_u64 v[144:145], s[2:3], 0, v[130:131]
	s_mov_b32 m0, s39
	s_nop 0
	global_load_lds_dwordx4 v[144:145], off
	v_lshl_add_u64 v[144:145], s[2:3], 0, v[134:135]
	s_mov_b32 m0, s40
	s_nop 0
	global_load_lds_dwordx4 v[144:145], off
	s_waitcnt vmcnt(8)
	s_waitcnt lgkmcnt(0)
	s_setprio 1
	s_barrier
	v_mfma_f32_16x16x32_bf16 v[62:65], v[152:155], v[186:189], v[62:65]
	v_mfma_f32_16x16x32_bf16 v[58:61], v[160:163], v[186:189], v[58:61]
	v_mfma_f32_16x16x32_bf16 v[50:53], v[152:155], v[194:197], v[50:53]
	v_mfma_f32_16x16x32_bf16 v[42:45], v[160:163], v[194:197], v[42:45]
	v_mfma_f32_16x16x32_bf16 v[34:37], v[152:155], v[202:205], v[34:37]
	v_mfma_f32_16x16x32_bf16 v[26:29], v[160:163], v[202:205], v[26:29]
	v_mfma_f32_16x16x32_bf16 v[18:21], v[152:155], v[210:213], v[18:21]
	v_mfma_f32_16x16x32_bf16 v[10:13], v[160:163], v[210:213], v[10:13]
	v_mfma_f32_16x16x32_bf16 v[62:65], v[156:159], v[190:193], v[62:65]
	v_mfma_f32_16x16x32_bf16 v[58:61], v[164:167], v[190:193], v[58:61]
	v_mfma_f32_16x16x32_bf16 v[50:53], v[156:159], v[198:201], v[50:53]
	v_mfma_f32_16x16x32_bf16 v[42:45], v[164:167], v[198:201], v[42:45]
	v_mfma_f32_16x16x32_bf16 v[34:37], v[156:159], v[206:209], v[34:37]
	v_mfma_f32_16x16x32_bf16 v[26:29], v[164:167], v[206:209], v[26:29]
	v_mfma_f32_16x16x32_bf16 v[18:21], v[156:159], v[214:217], v[18:21]
	v_mfma_f32_16x16x32_bf16 v[10:13], v[164:167], v[214:217], v[10:13]
	v_mfma_f32_16x16x32_bf16 v[54:57], v[168:171], v[186:189], v[54:57]
	v_mfma_f32_16x16x32_bf16 v[46:49], v[178:181], v[186:189], v[46:49]
	v_mfma_f32_16x16x32_bf16 v[38:41], v[168:171], v[194:197], v[38:41]
	v_mfma_f32_16x16x32_bf16 v[30:33], v[178:181], v[194:197], v[30:33]
	v_mfma_f32_16x16x32_bf16 v[22:25], v[168:171], v[202:205], v[22:25]
	v_mfma_f32_16x16x32_bf16 v[14:17], v[178:181], v[202:205], v[14:17]
	v_mfma_f32_16x16x32_bf16 v[6:9], v[168:171], v[210:213], v[6:9]
	v_mfma_f32_16x16x32_bf16 v[2:5], v[178:181], v[210:213], v[2:5]
	v_mfma_f32_16x16x32_bf16 v[54:57], v[172:175], v[190:193], v[54:57]
	v_mfma_f32_16x16x32_bf16 v[46:49], v[182:185], v[190:193], v[46:49]
	v_mfma_f32_16x16x32_bf16 v[38:41], v[172:175], v[198:201], v[38:41]
	v_mfma_f32_16x16x32_bf16 v[30:33], v[182:185], v[198:201], v[30:33]
	v_mfma_f32_16x16x32_bf16 v[22:25], v[172:175], v[206:209], v[22:25]
	v_mfma_f32_16x16x32_bf16 v[14:17], v[182:185], v[206:209], v[14:17]
	v_mfma_f32_16x16x32_bf16 v[6:9], v[172:175], v[214:217], v[6:9]
	v_mfma_f32_16x16x32_bf16 v[2:5], v[182:185], v[214:217], v[2:5]
	s_barrier
	s_setprio 0
	s_add_i32 s63, 0, 0x18000
	v_add_u32_e32 v144, s63, v146
	s_add_i32 s64, 0, 0x1c000
	ds_read_b128 v[152:155], v144
	ds_read_b128 v[156:159], v144 offset:1024
	ds_read_b128 v[160:163], v144 offset:2048
	ds_read_b128 v[164:167], v144 offset:3072
	v_add_u32_e32 v144, s64, v146
	ds_read_b128 v[168:171], v144
	ds_read_b128 v[172:175], v144 offset:1024
	ds_read_b128 v[178:181], v144 offset:2048
	ds_read_b128 v[182:185], v144 offset:3072
	s_add_u32 s2, s2, 0x4000
	s_addc_u32 s3, s3, 0
	s_mov_b32 m0, s41
	v_lshl_add_u64 v[144:145], s[2:3], 0, v[130:131]
	ds_read_b128 v[186:189], v150 offset:32768
	ds_read_b128 v[190:193], v150 offset:33792
	ds_read_b128 v[194:197], v150 offset:34816
	ds_read_b128 v[198:201], v150 offset:35840
	ds_read_b128 v[202:205], v150 offset:36864
	ds_read_b128 v[206:209], v150 offset:37888
	ds_read_b128 v[210:213], v150 offset:38912
	ds_read_b128 v[214:217], v150 offset:39936
	global_load_lds_dwordx4 v[144:145], off
	v_lshl_add_u64 v[144:145], s[2:3], 0, v[134:135]
	s_mov_b32 m0, s42
	s_nop 0
	global_load_lds_dwordx4 v[144:145], off
	s_waitcnt vmcnt(8)
	s_waitcnt lgkmcnt(0)
	s_setprio 1
	s_barrier
	v_mfma_f32_16x16x32_bf16 v[126:129], v[152:155], v[186:189], v[126:129]
	v_mfma_f32_16x16x32_bf16 v[122:125], v[160:163], v[186:189], v[122:125]
	v_mfma_f32_16x16x32_bf16 v[114:117], v[152:155], v[194:197], v[114:117]
	v_mfma_f32_16x16x32_bf16 v[106:109], v[160:163], v[194:197], v[106:109]
	v_mfma_f32_16x16x32_bf16 v[98:101], v[152:155], v[202:205], v[98:101]
	v_mfma_f32_16x16x32_bf16 v[90:93], v[160:163], v[202:205], v[90:93]
	v_mfma_f32_16x16x32_bf16 v[82:85], v[152:155], v[210:213], v[82:85]
	v_mfma_f32_16x16x32_bf16 v[74:77], v[160:163], v[210:213], v[74:77]
	v_mfma_f32_16x16x32_bf16 v[126:129], v[156:159], v[190:193], v[126:129]
	v_mfma_f32_16x16x32_bf16 v[122:125], v[164:167], v[190:193], v[122:125]
	v_mfma_f32_16x16x32_bf16 v[114:117], v[156:159], v[198:201], v[114:117]
	v_mfma_f32_16x16x32_bf16 v[106:109], v[164:167], v[198:201], v[106:109]
	v_mfma_f32_16x16x32_bf16 v[98:101], v[156:159], v[206:209], v[98:101]
	v_mfma_f32_16x16x32_bf16 v[90:93], v[164:167], v[206:209], v[90:93]
	v_mfma_f32_16x16x32_bf16 v[82:85], v[156:159], v[214:217], v[82:85]
	v_mfma_f32_16x16x32_bf16 v[74:77], v[164:167], v[214:217], v[74:77]
	v_mfma_f32_16x16x32_bf16 v[118:121], v[168:171], v[186:189], v[118:121]
	v_mfma_f32_16x16x32_bf16 v[110:113], v[178:181], v[186:189], v[110:113]
	v_mfma_f32_16x16x32_bf16 v[102:105], v[168:171], v[194:197], v[102:105]
	v_mfma_f32_16x16x32_bf16 v[94:97], v[178:181], v[194:197], v[94:97]
	v_mfma_f32_16x16x32_bf16 v[86:89], v[168:171], v[202:205], v[86:89]
	v_mfma_f32_16x16x32_bf16 v[78:81], v[178:181], v[202:205], v[78:81]
	v_mfma_f32_16x16x32_bf16 v[70:73], v[168:171], v[210:213], v[70:73]
	v_mfma_f32_16x16x32_bf16 v[66:69], v[178:181], v[210:213], v[66:69]
	v_mfma_f32_16x16x32_bf16 v[118:121], v[172:175], v[190:193], v[118:121]
	v_mfma_f32_16x16x32_bf16 v[110:113], v[182:185], v[190:193], v[110:113]
	v_mfma_f32_16x16x32_bf16 v[102:105], v[172:175], v[198:201], v[102:105]
	v_mfma_f32_16x16x32_bf16 v[94:97], v[182:185], v[198:201], v[94:97]
	v_mfma_f32_16x16x32_bf16 v[86:89], v[172:175], v[206:209], v[86:89]
	v_mfma_f32_16x16x32_bf16 v[78:81], v[182:185], v[206:209], v[78:81]
	v_mfma_f32_16x16x32_bf16 v[70:73], v[172:175], v[214:217], v[70:73]
	v_mfma_f32_16x16x32_bf16 v[66:69], v[182:185], v[214:217], v[66:69]
	s_barrier
	s_setprio 0
	s_add_u32 s2, s30, 0x8000
	s_addc_u32 s3, s31, 0
	s_add_i32 s63, s63, s38
	v_lshl_add_u64 v[144:145], s[2:3], 0, v[132:133]
	s_mov_b32 m0, s63
	ds_read_b128 v[186:189], v150 offset:49152
	ds_read_b128 v[190:193], v150 offset:50176
	ds_read_b128 v[194:197], v150 offset:51200
	ds_read_b128 v[198:201], v150 offset:52224
	ds_read_b128 v[202:205], v150 offset:53248
	ds_read_b128 v[206:209], v150 offset:54272
	ds_read_b128 v[210:213], v150 offset:55296
	ds_read_b128 v[214:217], v150 offset:56320
	global_load_lds_dwordx4 v[144:145], off
	s_add_i32 m0, s63, 0x2000
	v_lshl_add_u64 v[144:145], s[2:3], 0, v[136:137]
	s_add_u32 s2, s30, 0xc000
	s_addc_u32 s3, s31, 0
	s_add_i32 s30, s64, s38
	global_load_lds_dwordx4 v[144:145], off
	v_lshl_add_u64 v[144:145], s[2:3], 0, v[132:133]
	s_mov_b32 m0, s30
	s_nop 0
	global_load_lds_dwordx4 v[144:145], off
	v_lshl_add_u64 v[144:145], s[2:3], 0, v[136:137]
	s_add_i32 m0, s30, 0x2000
	s_nop 0
	global_load_lds_dwordx4 v[144:145], off
	v_lshl_add_u64 v[144:145], s[28:29], 0, v[130:131]
	s_mov_b32 m0, s44
	s_nop 0
	global_load_lds_dwordx4 v[144:145], off
	v_lshl_add_u64 v[144:145], s[28:29], 0, v[134:135]
	s_mov_b32 m0, s45
	s_nop 0
	global_load_lds_dwordx4 v[144:145], off
	s_waitcnt vmcnt(8)
	s_waitcnt lgkmcnt(0)
	s_setprio 1
	s_barrier
	v_mfma_f32_16x16x32_bf16 v[62:65], v[152:155], v[186:189], v[62:65]
	v_mfma_f32_16x16x32_bf16 v[58:61], v[160:163], v[186:189], v[58:61]
	v_mfma_f32_16x16x32_bf16 v[50:53], v[152:155], v[194:197], v[50:53]
	v_mfma_f32_16x16x32_bf16 v[42:45], v[160:163], v[194:197], v[42:45]
	v_mfma_f32_16x16x32_bf16 v[34:37], v[152:155], v[202:205], v[34:37]
	v_mfma_f32_16x16x32_bf16 v[26:29], v[160:163], v[202:205], v[26:29]
	v_mfma_f32_16x16x32_bf16 v[18:21], v[152:155], v[210:213], v[18:21]
	v_mfma_f32_16x16x32_bf16 v[10:13], v[160:163], v[210:213], v[10:13]
	v_mfma_f32_16x16x32_bf16 v[62:65], v[156:159], v[190:193], v[62:65]
	v_mfma_f32_16x16x32_bf16 v[58:61], v[164:167], v[190:193], v[58:61]
	v_mfma_f32_16x16x32_bf16 v[50:53], v[156:159], v[198:201], v[50:53]
	v_mfma_f32_16x16x32_bf16 v[42:45], v[164:167], v[198:201], v[42:45]
	v_mfma_f32_16x16x32_bf16 v[34:37], v[156:159], v[206:209], v[34:37]
	v_mfma_f32_16x16x32_bf16 v[26:29], v[164:167], v[206:209], v[26:29]
	v_mfma_f32_16x16x32_bf16 v[18:21], v[156:159], v[214:217], v[18:21]
	v_mfma_f32_16x16x32_bf16 v[10:13], v[164:167], v[214:217], v[10:13]
	v_mfma_f32_16x16x32_bf16 v[54:57], v[168:171], v[186:189], v[54:57]
	v_mfma_f32_16x16x32_bf16 v[46:49], v[178:181], v[186:189], v[46:49]
	v_mfma_f32_16x16x32_bf16 v[38:41], v[168:171], v[194:197], v[38:41]
	v_mfma_f32_16x16x32_bf16 v[30:33], v[178:181], v[194:197], v[30:33]
	v_mfma_f32_16x16x32_bf16 v[22:25], v[168:171], v[202:205], v[22:25]
	v_mfma_f32_16x16x32_bf16 v[14:17], v[178:181], v[202:205], v[14:17]
	v_mfma_f32_16x16x32_bf16 v[6:9], v[168:171], v[210:213], v[6:9]
	v_mfma_f32_16x16x32_bf16 v[2:5], v[178:181], v[210:213], v[2:5]
	v_mfma_f32_16x16x32_bf16 v[54:57], v[172:175], v[190:193], v[54:57]
	v_mfma_f32_16x16x32_bf16 v[46:49], v[182:185], v[190:193], v[46:49]
	v_mfma_f32_16x16x32_bf16 v[38:41], v[172:175], v[198:201], v[38:41]
	v_mfma_f32_16x16x32_bf16 v[30:33], v[182:185], v[198:201], v[30:33]
	v_mfma_f32_16x16x32_bf16 v[22:25], v[172:175], v[206:209], v[22:25]
	v_mfma_f32_16x16x32_bf16 v[14:17], v[182:185], v[206:209], v[14:17]
	v_mfma_f32_16x16x32_bf16 v[6:9], v[172:175], v[214:217], v[6:9]
	v_mfma_f32_16x16x32_bf16 v[2:5], v[182:185], v[214:217], v[2:5]
	s_barrier
	s_setprio 0
	s_add_i32 s62, s62, 2
	s_add_u32 s26, s26, 0x10000
	s_addc_u32 s27, s27, 0
	s_add_u32 s60, s60, 0x10000
	s_addc_u32 s61, s61, 0
	s_cmp_gt_u32 s62, 41
	s_cbranch_scc0 .LBB0_1444
